# decay-absorbed scan with operand-scaling loads hoisted to step C start and cumulative-product exchange overlapped in step B
# speedup vs baseline: 1.0229x; 1.0026x over previous
.LBB0_127:
	s_andn2_b64 vcc, exec, s[10:11]
	s_cbranch_vccnz .LBB0_129
	v_mul_f32_e32 v4, 0xbf60028a, v4
	v_mul_f32_e32 v5, 0xbf60028a, v5
	v_exp_f32_e32 v4, v4
	v_exp_f32_e32 v5, v5
	v_mul_f32_e32 v6, 0xbf60028a, v6
	v_mul_f32_e32 v7, 0xbf60028a, v7
	v_exp_f32_e32 v6, v6
	v_exp_f32_e32 v7, v7
	v_mul_f32_e32 v8, 0xbf60028a, v8
	v_mul_f32_e32 v9, 0xbf60028a, v9
	v_exp_f32_e32 v8, v8
	v_exp_f32_e32 v9, v9
	v_mul_f32_e32 v10, 0xbf60028a, v10
	v_mul_f32_e32 v11, 0xbf60028a, v11
	v_exp_f32_e32 v10, v10
	v_exp_f32_e32 v11, v11
	s_nop 1
	v_mul_f32_e32 v198, v7, v6
	v_mul_f32_e32 v201, v11, v10
	v_mul_f32_e32 v199, v198, v5
	v_mul_f32_e32 v202, v201, v9
	v_mul_f32_e32 v200, v199, v4
	v_mul_f32_e32 v203, v202, v8
	v_mbcnt_lo_u32_b32 v204, -1, 0
	v_mbcnt_hi_u32_b32 v204, -1, v204
	v_and_b32_e32 v205, 15, v204
	v_lshlrev_b32_e32 v205, 2, v205
	v_add_u32_e32 v206, 64, v205
	v_add_u32_e32 v207, 128, v205
	v_add_u32_e32 v208, 192, v205
	v_mov_b32_e32 v217, 1.0
	ds_bpermute_b32 v209, v205, v200
	ds_bpermute_b32 v210, v206, v200
	ds_bpermute_b32 v211, v207, v200
	ds_bpermute_b32 v212, v208, v200
	ds_bpermute_b32 v213, v205, v203
	ds_bpermute_b32 v214, v206, v203
	ds_bpermute_b32 v215, v207, v203
	ds_bpermute_b32 v216, v208, v203
	s_waitcnt lgkmcnt(7)
	v_mul_f32_e32 v15, v29, v4
	s_waitcnt lgkmcnt(7)
	v_mul_f32_e32 v4, v28, v5
	ds_write2st64_b32 v163, v15, v4 offset0:128 offset1:129
	s_waitcnt lgkmcnt(7)
	v_mul_f32_e32 v4, v26, v6
	s_waitcnt lgkmcnt(6)
	v_mul_f32_e32 v5, v25, v7
	ds_write2st64_b32 v163, v4, v5 offset0:130 offset1:131
	s_waitcnt lgkmcnt(6)
	v_mul_f32_e32 v4, v24, v8
	s_waitcnt lgkmcnt(5)
	v_mul_f32_e32 v5, v14, v9
	ds_write2st64_b32 v163, v4, v5 offset0:144 offset1:145
	s_waitcnt lgkmcnt(5)
	v_mul_f32_e32 v4, v13, v10
	s_waitcnt lgkmcnt(4)
	v_mul_f32_e32 v5, v12, v11
	ds_write2st64_b32 v163, v4, v5 offset0:146 offset1:147
	s_waitcnt lgkmcnt(0)
	v_cmp_gt_u32_e32 vcc, 16, v204
	v_cndmask_b32_e32 v218, v217, v210, vcc
	v_cndmask_b32_e32 v221, v217, v214, vcc
	v_cmp_gt_u32_e32 vcc, 32, v204
	v_cndmask_b32_e32 v219, v217, v211, vcc
	v_cndmask_b32_e32 v222, v217, v215, vcc
	v_cmp_gt_u32_e32 vcc, 48, v204
	v_cndmask_b32_e32 v220, v217, v212, vcc
	v_cndmask_b32_e32 v223, v217, v216, vcc
	v_mul_f32_e32 v225, v221, v222
	v_mul_f32_e32 v224, v218, v219
	v_mul_f32_e32 v226, v213, v214
	v_mul_f32_e32 v225, v225, v223
	v_mul_f32_e32 v224, v224, v220
	v_mul_f32_e32 v226, v226, v215
	v_mul_f32_e32 v226, v226, v216
	v_mul_f32_e32 v224, v224, v226
	v_mul_f32_e32 v230, v200, v224
	v_mul_f32_e32 v231, v199, v224
	v_mul_f32_e32 v232, v198, v224
	v_mul_f32_e32 v233, v7, v224
	v_mul_f32_e32 v234, v203, v225
	v_mul_f32_e32 v235, v202, v225
	v_mul_f32_e32 v236, v201, v225
	v_mul_f32_e32 v237, v11, v225
	ds_write2st64_b32 v163, v230, v231 offset0:224 offset1:225
	ds_write2st64_b32 v163, v232, v233 offset0:226 offset1:227
	ds_write2st64_b32 v163, v234, v235 offset0:240 offset1:241
	ds_write2st64_b32 v163, v236, v237 offset0:242 offset1:243
.LBB0_129:
	s_waitcnt lgkmcnt(0)
	s_barrier
	v_add_u32_e32 v227, 0x100, v156
	ds_read_b128 v[198:201], v156 offset:57344
	ds_read_b128 v[202:205], v227 offset:57344
	ds_read_b128 v[206:209], v156 offset:8192
	ds_read_b128 v[210:213], v156 offset:16384
	ds_read_b128 v[214:217], v156 offset:24576
	ds_read_b128 v[4:7], v156 offset:40960
	ds_read_b128 v[8:11], v156 offset:16384
	s_waitcnt lgkmcnt(2)
	ds_read_b128 v[12:15], v156 offset:24576
	ds_read_b128 v[16:19], v159
	s_sub_i32 s10, s95, s69
	s_addk_i32 s10, 0x7e0
	s_waitcnt lgkmcnt(2)
	v_pk_mul_f32 v[8:9], v[4:5], v[8:9]
	s_waitcnt lgkmcnt(1)
	v_pk_mul_f32 v[4:5], v[4:5], v[12:13]
	v_add_f32_e32 v8, 0, v8
	v_pk_mul_f32 v[10:11], v[6:7], v[10:11]
	v_add_f32_e32 v8, v9, v8
	v_add_f32_e32 v9, 0, v4
	s_waitcnt lgkmcnt(0)
	v_fma_f32 v4, v16, v4, 0
	v_add_f32_e32 v9, v5, v9
	v_fmac_f32_e32 v4, v17, v5
	v_add_f32_e32 v5, v10, v8
	v_add_f32_e32 v5, v11, v5
	v_pk_mul_f32 v[6:7], v[6:7], v[14:15]
	v_add_u32_e32 v128, s10, v73
	v_add_f32_dpp v5, v5, v5 quad_perm:[1,0,3,2] row_mask:0xf bank_mask:0xf bound_ctrl:1
	v_add_f32_e32 v8, v6, v9
	v_fmac_f32_e32 v4, v18, v6
	v_add_f32_dpp v5, v5, v5 quad_perm:[2,3,0,1] row_mask:0xf bank_mask:0xf bound_ctrl:1
	v_add_f32_e32 v6, v7, v8
	v_fmac_f32_e32 v4, v19, v7
	v_add_f32_dpp v5, v5, v5 row_half_mirror row_mask:0xf bank_mask:0xf bound_ctrl:1
	v_ashrrev_i32_e32 v129, 31, v128
	v_add_f32_dpp v4, v4, v4 quad_perm:[1,0,3,2] row_mask:0xf bank_mask:0xf bound_ctrl:1
	v_add_f32_dpp v14, v5, v5 row_mirror row_mask:0xf bank_mask:0xf bound_ctrl:1
	v_add_f32_dpp v5, v6, v6 quad_perm:[1,0,3,2] row_mask:0xf bank_mask:0xf bound_ctrl:1
	ds_read_b128 v[6:9], v156 offset:8192
	ds_read_b128 v[10:13], v156 offset:32768
	v_add_f32_dpp v5, v5, v5 quad_perm:[2,3,0,1] row_mask:0xf bank_mask:0xf bound_ctrl:1
	v_add_f32_dpp v4, v4, v4 quad_perm:[2,3,0,1] row_mask:0xf bank_mask:0xf bound_ctrl:1
	s_waitcnt lgkmcnt(0)
	v_pk_fma_f32 v[8:9], v[14:15], v[8:9], v[12:13] op_sel_hi:[0,1,1]
	v_pk_fma_f32 v[6:7], v[14:15], v[6:7], v[10:11] op_sel_hi:[0,1,1]
	s_waitcnt lgkmcnt(0)
	v_mov_b32_e32 v226, 1.0
	v_cmp_lt_u32_e32 vcc, 495, v134
	v_rcp_f32_e32 v222, v198
	v_rcp_f32_e32 v223, v199
	v_rcp_f32_e32 v224, v200
	v_rcp_f32_e32 v225, v201
	v_cndmask_b32_e32 v202, v202, v226, vcc
	v_cndmask_b32_e32 v203, v203, v226, vcc
	v_cndmask_b32_e32 v204, v204, v226, vcc
	v_cndmask_b32_e32 v205, v205, v226, vcc
	v_mul_f32_e32 v206, v206, v202
	v_mul_f32_e32 v207, v207, v203
	v_mul_f32_e32 v208, v208, v204
	v_mul_f32_e32 v209, v209, v205
	v_mul_f32_e32 v6, v6, v202
	v_mul_f32_e32 v7, v7, v203
	v_mul_f32_e32 v8, v8, v204
	v_mul_f32_e32 v9, v9, v205
	v_mul_f32_e32 v210, v210, v222
	v_mul_f32_e32 v211, v211, v223
	v_mul_f32_e32 v212, v212, v224
	v_mul_f32_e32 v213, v213, v225
	v_mul_f32_e32 v214, v214, v222
	v_mul_f32_e32 v215, v215, v223
	v_mul_f32_e32 v216, v216, v224
	v_mul_f32_e32 v217, v217, v225
	ds_write_b128 v156, v[206:209] offset:8192
	ds_write_b128 v156, v[210:213] offset:16384
	ds_write_b128 v156, v[214:217] offset:24576
	ds_write_b128 v156, v[6:9] offset:32768
	ds_read_b128 v[6:9], v156 offset:49152
	v_add_f32_dpp v5, v5, v5 row_half_mirror row_mask:0xf bank_mask:0xf bound_ctrl:1
	v_add_f32_dpp v4, v4, v4 row_half_mirror row_mask:0xf bank_mask:0xf bound_ctrl:1
	s_nop 0
	v_add_f32_dpp v16, v5, v5 row_mirror row_mask:0xf bank_mask:0xf bound_ctrl:1
	v_mov_b32_dpp v5, v4 row_mirror row_mask:0xf bank_mask:0xf bound_ctrl:1
	s_waitcnt lgkmcnt(0)
	v_pk_mul_f32 v[8:9], v[16:17], v[8:9] op_sel_hi:[0,1]
	v_pk_mul_f32 v[6:7], v[16:17], v[6:7] op_sel_hi:[0,1]
	ds_write_b128 v160, v[6:9]
	s_and_saveexec_b64 s[10:11], s[6:7]
	s_cbranch_execz .LBB0_131
	v_lshlrev_b64 v[6:7], 6, v[128:129]
	v_lshl_add_u64 v[6:7], s[12:13], 0, v[6:7]
	v_add_f32_e32 v4, v4, v5
	global_store_dword v[6:7], v4, off
.LBB0_131:
	s_or_b64 exec, exec, s[10:11]
	s_waitcnt lgkmcnt(0)
	s_barrier
	v_mbcnt_lo_u32_b32 v197, -1, 0
	v_mbcnt_hi_u32_b32 v197, -1, v197
	v_lshlrev_b32_e32 v197, 3, v197
	v_add_u32_e32 v197, 0xe000, v197
	v_cndmask_b32_e64 v196, v197, v161, s[8:9]
	v_add_u32_e32 v69, 0xffffe800, v185
	ds_read_b128 v[8:11], v152 offset:16128
	ds_read_b128 v[12:15], v152 offset:24320
	ds_read_b128 v[16:19], v152 offset:32512
	ds_read_b128 v[20:23], v152 offset:40704
	ds_read_b64 v[64:65], v69 offset:7936
	ds_read_b128 v[28:31], v152 offset:15872
	ds_read_b128 v[32:35], v152 offset:24064
	ds_read_b128 v[36:39], v152 offset:32256
	ds_read_b128 v[40:43], v152 offset:40448
	ds_read_b64 v[66:67], v69 offset:7680
	ds_read_b128 v[48:51], v152 offset:15616
	ds_read_b128 v[52:55], v152 offset:23808
	ds_read_b128 v[56:59], v152 offset:32000
	ds_read_b128 v[60:63], v152 offset:40192
	ds_read_b64 v[130:131], v69 offset:7424
	s_waitcnt lgkmcnt(10)
	v_mul_f32_e32 v194, v186, v8
	v_mul_f32_e32 v195, v190, v8
	v_mul_f32_e32 v132, v186, v20
	v_mul_f32_e32 v133, v190, v20
	v_fmac_f32_e32 v194, v187, v9
	v_fmac_f32_e32 v195, v191, v9
	v_fmac_f32_e32 v132, v187, v21
	v_fmac_f32_e32 v133, v191, v21
	v_fmac_f32_e32 v194, v188, v10
	v_fmac_f32_e32 v195, v192, v10
	v_fmac_f32_e32 v132, v188, v22
	v_fmac_f32_e32 v133, v192, v22
	v_fmac_f32_e32 v194, v189, v11
	v_fmac_f32_e32 v195, v193, v11
	v_fmac_f32_e32 v132, v189, v23
	v_fmac_f32_e32 v133, v193, v23
	v_add_f32_dpp v194, v194, v194 quad_perm:[1,0,3,2] row_mask:0xf bank_mask:0xf bound_ctrl:1
	v_add_f32_dpp v195, v195, v195 quad_perm:[1,0,3,2] row_mask:0xf bank_mask:0xf bound_ctrl:1
	v_add_f32_dpp v132, v132, v132 quad_perm:[1,0,3,2] row_mask:0xf bank_mask:0xf bound_ctrl:1
	v_add_f32_dpp v133, v133, v133 quad_perm:[1,0,3,2] row_mask:0xf bank_mask:0xf bound_ctrl:1
	v_add_f32_dpp v194, v194, v194 quad_perm:[2,3,0,1] row_mask:0xf bank_mask:0xf bound_ctrl:1
	v_add_f32_dpp v195, v195, v195 quad_perm:[2,3,0,1] row_mask:0xf bank_mask:0xf bound_ctrl:1
	v_add_f32_dpp v132, v132, v132 quad_perm:[2,3,0,1] row_mask:0xf bank_mask:0xf bound_ctrl:1
	v_add_f32_dpp v133, v133, v133 quad_perm:[2,3,0,1] row_mask:0xf bank_mask:0xf bound_ctrl:1
	v_add_f32_dpp v194, v194, v194 row_half_mirror row_mask:0xf bank_mask:0xf bound_ctrl:1
	v_add_f32_dpp v195, v195, v195 row_half_mirror row_mask:0xf bank_mask:0xf bound_ctrl:1
	v_add_f32_dpp v132, v132, v132 row_half_mirror row_mask:0xf bank_mask:0xf bound_ctrl:1
	v_add_f32_dpp v133, v133, v133 row_half_mirror row_mask:0xf bank_mask:0xf bound_ctrl:1
	v_add_f32_dpp v194, v194, v194 row_mirror row_mask:0xf bank_mask:0xf bound_ctrl:1
	v_add_f32_dpp v195, v195, v195 row_mirror row_mask:0xf bank_mask:0xf bound_ctrl:1
	v_fmac_f32_e32 v186, v64, v16
	v_fmac_f32_e32 v187, v64, v17
	v_fmac_f32_e32 v188, v64, v18
	v_fmac_f32_e32 v189, v64, v19
	v_fmac_f32_e32 v190, v65, v16
	v_fmac_f32_e32 v191, v65, v17
	v_fmac_f32_e32 v192, v65, v18
	v_fmac_f32_e32 v193, v65, v19
	v_fmac_f32_e32 v186, v194, v12
	v_fmac_f32_e32 v187, v194, v13
	v_fmac_f32_e32 v188, v194, v14
	v_fmac_f32_e32 v189, v194, v15
	v_fmac_f32_e32 v190, v195, v12
	v_fmac_f32_e32 v191, v195, v13
	v_fmac_f32_e32 v192, v195, v14
	v_fmac_f32_e32 v193, v195, v15
	ds_read_b128 v[8:11], v152 offset:15360
	ds_read_b128 v[12:15], v152 offset:23552
	ds_read_b128 v[16:19], v152 offset:31744
	ds_read_b128 v[20:23], v152 offset:39936
	ds_read_b64 v[64:65], v69 offset:7168
	s_waitcnt lgkmcnt(10)
	v_mul_f32_e32 v194, v186, v28
	v_mul_f32_e32 v195, v190, v28
	v_mul_f32_e32 v238, v186, v40
	v_mul_f32_e32 v239, v190, v40
	v_fmac_f32_e32 v194, v187, v29
	v_fmac_f32_e32 v195, v191, v29
	v_fmac_f32_e32 v238, v187, v41
	v_fmac_f32_e32 v239, v191, v41
	v_fmac_f32_e32 v194, v188, v30
	v_fmac_f32_e32 v195, v192, v30
	v_fmac_f32_e32 v238, v188, v42
	v_fmac_f32_e32 v239, v192, v42
	v_fmac_f32_e32 v194, v189, v31
	v_fmac_f32_e32 v195, v193, v31
	v_fmac_f32_e32 v238, v189, v43
	v_fmac_f32_e32 v239, v193, v43
	v_add_f32_dpp v194, v194, v194 quad_perm:[1,0,3,2] row_mask:0xf bank_mask:0xf bound_ctrl:1
	v_add_f32_dpp v195, v195, v195 quad_perm:[1,0,3,2] row_mask:0xf bank_mask:0xf bound_ctrl:1
	v_add_f32_dpp v238, v238, v238 quad_perm:[1,0,3,2] row_mask:0xf bank_mask:0xf bound_ctrl:1
	v_add_f32_dpp v239, v239, v239 quad_perm:[1,0,3,2] row_mask:0xf bank_mask:0xf bound_ctrl:1
	v_add_f32_dpp v194, v194, v194 quad_perm:[2,3,0,1] row_mask:0xf bank_mask:0xf bound_ctrl:1
	v_add_f32_dpp v195, v195, v195 quad_perm:[2,3,0,1] row_mask:0xf bank_mask:0xf bound_ctrl:1
	v_add_f32_dpp v238, v238, v238 quad_perm:[2,3,0,1] row_mask:0xf bank_mask:0xf bound_ctrl:1
	v_add_f32_dpp v239, v239, v239 quad_perm:[2,3,0,1] row_mask:0xf bank_mask:0xf bound_ctrl:1
	v_add_f32_dpp v194, v194, v194 row_half_mirror row_mask:0xf bank_mask:0xf bound_ctrl:1
	v_add_f32_dpp v195, v195, v195 row_half_mirror row_mask:0xf bank_mask:0xf bound_ctrl:1
	v_add_f32_dpp v238, v238, v238 row_half_mirror row_mask:0xf bank_mask:0xf bound_ctrl:1
	v_add_f32_dpp v239, v239, v239 row_half_mirror row_mask:0xf bank_mask:0xf bound_ctrl:1
	v_add_f32_dpp v194, v194, v194 row_mirror row_mask:0xf bank_mask:0xf bound_ctrl:1
	v_add_f32_dpp v195, v195, v195 row_mirror row_mask:0xf bank_mask:0xf bound_ctrl:1
	v_fmac_f32_e32 v186, v66, v36
	v_fmac_f32_e32 v187, v66, v37
	v_fmac_f32_e32 v188, v66, v38
	v_fmac_f32_e32 v189, v66, v39
	v_fmac_f32_e32 v190, v67, v36
	v_fmac_f32_e32 v191, v67, v37
	v_fmac_f32_e32 v192, v67, v38
	v_fmac_f32_e32 v193, v67, v39
	v_fmac_f32_e32 v186, v194, v32
	v_fmac_f32_e32 v187, v194, v33
	v_fmac_f32_e32 v188, v194, v34
	v_fmac_f32_e32 v189, v194, v35
	v_fmac_f32_e32 v190, v195, v32
	v_fmac_f32_e32 v191, v195, v33
	v_fmac_f32_e32 v192, v195, v34
	v_fmac_f32_e32 v193, v195, v35
	s_mov_b64 exec, s[8:9]
	ds_write2st64_b64 v161, v[132:133], v[238:239] offset0:31 offset1:30
	s_mov_b64 exec, -1
	ds_read_b128 v[28:31], v152 offset:15104
	ds_read_b128 v[32:35], v152 offset:23296
	ds_read_b128 v[36:39], v152 offset:31488
	ds_read_b128 v[40:43], v152 offset:39680
	ds_read_b64 v[66:67], v69 offset:6912
	s_waitcnt lgkmcnt(11)
	v_mul_f32_e32 v194, v186, v48
	v_mul_f32_e32 v195, v190, v48
	v_mul_f32_e32 v132, v186, v60
	v_mul_f32_e32 v133, v190, v60
	v_fmac_f32_e32 v194, v187, v49
	v_fmac_f32_e32 v195, v191, v49
	v_fmac_f32_e32 v132, v187, v61
	v_fmac_f32_e32 v133, v191, v61
	v_fmac_f32_e32 v194, v188, v50
	v_fmac_f32_e32 v195, v192, v50
	v_fmac_f32_e32 v132, v188, v62
	v_fmac_f32_e32 v133, v192, v62
	v_fmac_f32_e32 v194, v189, v51
	v_fmac_f32_e32 v195, v193, v51
	v_fmac_f32_e32 v132, v189, v63
	v_fmac_f32_e32 v133, v193, v63
	v_add_f32_dpp v194, v194, v194 quad_perm:[1,0,3,2] row_mask:0xf bank_mask:0xf bound_ctrl:1
	v_add_f32_dpp v195, v195, v195 quad_perm:[1,0,3,2] row_mask:0xf bank_mask:0xf bound_ctrl:1
	v_add_f32_dpp v132, v132, v132 quad_perm:[1,0,3,2] row_mask:0xf bank_mask:0xf bound_ctrl:1
	v_add_f32_dpp v133, v133, v133 quad_perm:[1,0,3,2] row_mask:0xf bank_mask:0xf bound_ctrl:1
	v_add_f32_dpp v194, v194, v194 quad_perm:[2,3,0,1] row_mask:0xf bank_mask:0xf bound_ctrl:1
	v_add_f32_dpp v195, v195, v195 quad_perm:[2,3,0,1] row_mask:0xf bank_mask:0xf bound_ctrl:1
	v_add_f32_dpp v132, v132, v132 quad_perm:[2,3,0,1] row_mask:0xf bank_mask:0xf bound_ctrl:1
	v_add_f32_dpp v133, v133, v133 quad_perm:[2,3,0,1] row_mask:0xf bank_mask:0xf bound_ctrl:1
	v_add_f32_dpp v194, v194, v194 row_half_mirror row_mask:0xf bank_mask:0xf bound_ctrl:1
	v_add_f32_dpp v195, v195, v195 row_half_mirror row_mask:0xf bank_mask:0xf bound_ctrl:1
	v_add_f32_dpp v132, v132, v132 row_half_mirror row_mask:0xf bank_mask:0xf bound_ctrl:1
	v_add_f32_dpp v133, v133, v133 row_half_mirror row_mask:0xf bank_mask:0xf bound_ctrl:1
	v_add_f32_dpp v194, v194, v194 row_mirror row_mask:0xf bank_mask:0xf bound_ctrl:1
	v_add_f32_dpp v195, v195, v195 row_mirror row_mask:0xf bank_mask:0xf bound_ctrl:1
	v_fmac_f32_e32 v186, v130, v56
	v_fmac_f32_e32 v187, v130, v57
	v_fmac_f32_e32 v188, v130, v58
	v_fmac_f32_e32 v189, v130, v59
	v_fmac_f32_e32 v190, v131, v56
	v_fmac_f32_e32 v191, v131, v57
	v_fmac_f32_e32 v192, v131, v58
	v_fmac_f32_e32 v193, v131, v59
	v_fmac_f32_e32 v186, v194, v52
	v_fmac_f32_e32 v187, v194, v53
	v_fmac_f32_e32 v188, v194, v54
	v_fmac_f32_e32 v189, v194, v55
	v_fmac_f32_e32 v190, v195, v52
	v_fmac_f32_e32 v191, v195, v53
	v_fmac_f32_e32 v192, v195, v54
	v_fmac_f32_e32 v193, v195, v55
	ds_read_b128 v[48:51], v152 offset:14848
	ds_read_b128 v[52:55], v152 offset:23040
	ds_read_b128 v[56:59], v152 offset:31232
	ds_read_b128 v[60:63], v152 offset:39424
	ds_read_b64 v[130:131], v69 offset:6656
	s_waitcnt lgkmcnt(11)
	v_mul_f32_e32 v194, v186, v8
	v_mul_f32_e32 v195, v190, v8
	v_mul_f32_e32 v238, v186, v20
	v_mul_f32_e32 v239, v190, v20
	v_fmac_f32_e32 v194, v187, v9
	v_fmac_f32_e32 v195, v191, v9
	v_fmac_f32_e32 v238, v187, v21
	v_fmac_f32_e32 v239, v191, v21
	v_fmac_f32_e32 v194, v188, v10
	v_fmac_f32_e32 v195, v192, v10
	v_fmac_f32_e32 v238, v188, v22
	v_fmac_f32_e32 v239, v192, v22
	v_fmac_f32_e32 v194, v189, v11
	v_fmac_f32_e32 v195, v193, v11
	v_fmac_f32_e32 v238, v189, v23
	v_fmac_f32_e32 v239, v193, v23
	v_add_f32_dpp v194, v194, v194 quad_perm:[1,0,3,2] row_mask:0xf bank_mask:0xf bound_ctrl:1
	v_add_f32_dpp v195, v195, v195 quad_perm:[1,0,3,2] row_mask:0xf bank_mask:0xf bound_ctrl:1
	v_add_f32_dpp v238, v238, v238 quad_perm:[1,0,3,2] row_mask:0xf bank_mask:0xf bound_ctrl:1
	v_add_f32_dpp v239, v239, v239 quad_perm:[1,0,3,2] row_mask:0xf bank_mask:0xf bound_ctrl:1
	v_add_f32_dpp v194, v194, v194 quad_perm:[2,3,0,1] row_mask:0xf bank_mask:0xf bound_ctrl:1
	v_add_f32_dpp v195, v195, v195 quad_perm:[2,3,0,1] row_mask:0xf bank_mask:0xf bound_ctrl:1
	v_add_f32_dpp v238, v238, v238 quad_perm:[2,3,0,1] row_mask:0xf bank_mask:0xf bound_ctrl:1
	v_add_f32_dpp v239, v239, v239 quad_perm:[2,3,0,1] row_mask:0xf bank_mask:0xf bound_ctrl:1
	v_add_f32_dpp v194, v194, v194 row_half_mirror row_mask:0xf bank_mask:0xf bound_ctrl:1
	v_add_f32_dpp v195, v195, v195 row_half_mirror row_mask:0xf bank_mask:0xf bound_ctrl:1
	v_add_f32_dpp v238, v238, v238 row_half_mirror row_mask:0xf bank_mask:0xf bound_ctrl:1
	v_add_f32_dpp v239, v239, v239 row_half_mirror row_mask:0xf bank_mask:0xf bound_ctrl:1
	v_add_f32_dpp v194, v194, v194 row_mirror row_mask:0xf bank_mask:0xf bound_ctrl:1
	v_add_f32_dpp v195, v195, v195 row_mirror row_mask:0xf bank_mask:0xf bound_ctrl:1
	v_fmac_f32_e32 v186, v64, v16
	v_fmac_f32_e32 v187, v64, v17
	v_fmac_f32_e32 v188, v64, v18
	v_fmac_f32_e32 v189, v64, v19
	v_fmac_f32_e32 v190, v65, v16
	v_fmac_f32_e32 v191, v65, v17
	v_fmac_f32_e32 v192, v65, v18
	v_fmac_f32_e32 v193, v65, v19
	v_fmac_f32_e32 v186, v194, v12
	v_fmac_f32_e32 v187, v194, v13
	v_fmac_f32_e32 v188, v194, v14
	v_fmac_f32_e32 v189, v194, v15
	v_fmac_f32_e32 v190, v195, v12
	v_fmac_f32_e32 v191, v195, v13
	v_fmac_f32_e32 v192, v195, v14
	v_fmac_f32_e32 v193, v195, v15
	s_mov_b64 exec, s[8:9]
	ds_write2st64_b64 v161, v[132:133], v[238:239] offset0:29 offset1:28
	s_mov_b64 exec, -1
	ds_read_b128 v[8:11], v152 offset:14592
	ds_read_b128 v[12:15], v152 offset:22784
	ds_read_b128 v[16:19], v152 offset:30976
	ds_read_b128 v[20:23], v152 offset:39168
	ds_read_b64 v[64:65], v69 offset:6400
	s_waitcnt lgkmcnt(11)
	v_mul_f32_e32 v194, v186, v28
	v_mul_f32_e32 v195, v190, v28
	v_mul_f32_e32 v132, v186, v40
	v_mul_f32_e32 v133, v190, v40
	v_fmac_f32_e32 v194, v187, v29
	v_fmac_f32_e32 v195, v191, v29
	v_fmac_f32_e32 v132, v187, v41
	v_fmac_f32_e32 v133, v191, v41
	v_fmac_f32_e32 v194, v188, v30
	v_fmac_f32_e32 v195, v192, v30
	v_fmac_f32_e32 v132, v188, v42
	v_fmac_f32_e32 v133, v192, v42
	v_fmac_f32_e32 v194, v189, v31
	v_fmac_f32_e32 v195, v193, v31
	v_fmac_f32_e32 v132, v189, v43
	v_fmac_f32_e32 v133, v193, v43
	v_add_f32_dpp v194, v194, v194 quad_perm:[1,0,3,2] row_mask:0xf bank_mask:0xf bound_ctrl:1
	v_add_f32_dpp v195, v195, v195 quad_perm:[1,0,3,2] row_mask:0xf bank_mask:0xf bound_ctrl:1
	v_add_f32_dpp v132, v132, v132 quad_perm:[1,0,3,2] row_mask:0xf bank_mask:0xf bound_ctrl:1
	v_add_f32_dpp v133, v133, v133 quad_perm:[1,0,3,2] row_mask:0xf bank_mask:0xf bound_ctrl:1
	v_add_f32_dpp v194, v194, v194 quad_perm:[2,3,0,1] row_mask:0xf bank_mask:0xf bound_ctrl:1
	v_add_f32_dpp v195, v195, v195 quad_perm:[2,3,0,1] row_mask:0xf bank_mask:0xf bound_ctrl:1
	v_add_f32_dpp v132, v132, v132 quad_perm:[2,3,0,1] row_mask:0xf bank_mask:0xf bound_ctrl:1
	v_add_f32_dpp v133, v133, v133 quad_perm:[2,3,0,1] row_mask:0xf bank_mask:0xf bound_ctrl:1
	v_add_f32_dpp v194, v194, v194 row_half_mirror row_mask:0xf bank_mask:0xf bound_ctrl:1
	v_add_f32_dpp v195, v195, v195 row_half_mirror row_mask:0xf bank_mask:0xf bound_ctrl:1
	v_add_f32_dpp v132, v132, v132 row_half_mirror row_mask:0xf bank_mask:0xf bound_ctrl:1
	v_add_f32_dpp v133, v133, v133 row_half_mirror row_mask:0xf bank_mask:0xf bound_ctrl:1
	v_add_f32_dpp v194, v194, v194 row_mirror row_mask:0xf bank_mask:0xf bound_ctrl:1
	v_add_f32_dpp v195, v195, v195 row_mirror row_mask:0xf bank_mask:0xf bound_ctrl:1
	v_fmac_f32_e32 v186, v66, v36
	v_fmac_f32_e32 v187, v66, v37
	v_fmac_f32_e32 v188, v66, v38
	v_fmac_f32_e32 v189, v66, v39
	v_fmac_f32_e32 v190, v67, v36
	v_fmac_f32_e32 v191, v67, v37
	v_fmac_f32_e32 v192, v67, v38
	v_fmac_f32_e32 v193, v67, v39
	v_fmac_f32_e32 v186, v194, v32
	v_fmac_f32_e32 v187, v194, v33
	v_fmac_f32_e32 v188, v194, v34
	v_fmac_f32_e32 v189, v194, v35
	v_fmac_f32_e32 v190, v195, v32
	v_fmac_f32_e32 v191, v195, v33
	v_fmac_f32_e32 v192, v195, v34
	v_fmac_f32_e32 v193, v195, v35
	ds_read_b128 v[28:31], v152 offset:14336
	ds_read_b128 v[32:35], v152 offset:22528
	ds_read_b128 v[36:39], v152 offset:30720
	ds_read_b128 v[40:43], v152 offset:38912
	ds_read_b64 v[66:67], v69 offset:6144
	s_waitcnt lgkmcnt(11)
	v_mul_f32_e32 v194, v186, v48
	v_mul_f32_e32 v195, v190, v48
	v_mul_f32_e32 v238, v186, v60
	v_mul_f32_e32 v239, v190, v60
	v_fmac_f32_e32 v194, v187, v49
	v_fmac_f32_e32 v195, v191, v49
	v_fmac_f32_e32 v238, v187, v61
	v_fmac_f32_e32 v239, v191, v61
	v_fmac_f32_e32 v194, v188, v50
	v_fmac_f32_e32 v195, v192, v50
	v_fmac_f32_e32 v238, v188, v62
	v_fmac_f32_e32 v239, v192, v62
	v_fmac_f32_e32 v194, v189, v51
	v_fmac_f32_e32 v195, v193, v51
	v_fmac_f32_e32 v238, v189, v63
	v_fmac_f32_e32 v239, v193, v63
	v_add_f32_dpp v194, v194, v194 quad_perm:[1,0,3,2] row_mask:0xf bank_mask:0xf bound_ctrl:1
	v_add_f32_dpp v195, v195, v195 quad_perm:[1,0,3,2] row_mask:0xf bank_mask:0xf bound_ctrl:1
	v_add_f32_dpp v238, v238, v238 quad_perm:[1,0,3,2] row_mask:0xf bank_mask:0xf bound_ctrl:1
	v_add_f32_dpp v239, v239, v239 quad_perm:[1,0,3,2] row_mask:0xf bank_mask:0xf bound_ctrl:1
	v_add_f32_dpp v194, v194, v194 quad_perm:[2,3,0,1] row_mask:0xf bank_mask:0xf bound_ctrl:1
	v_add_f32_dpp v195, v195, v195 quad_perm:[2,3,0,1] row_mask:0xf bank_mask:0xf bound_ctrl:1
	v_add_f32_dpp v238, v238, v238 quad_perm:[2,3,0,1] row_mask:0xf bank_mask:0xf bound_ctrl:1
	v_add_f32_dpp v239, v239, v239 quad_perm:[2,3,0,1] row_mask:0xf bank_mask:0xf bound_ctrl:1
	v_add_f32_dpp v194, v194, v194 row_half_mirror row_mask:0xf bank_mask:0xf bound_ctrl:1
	v_add_f32_dpp v195, v195, v195 row_half_mirror row_mask:0xf bank_mask:0xf bound_ctrl:1
	v_add_f32_dpp v238, v238, v238 row_half_mirror row_mask:0xf bank_mask:0xf bound_ctrl:1
	v_add_f32_dpp v239, v239, v239 row_half_mirror row_mask:0xf bank_mask:0xf bound_ctrl:1
	v_add_f32_dpp v194, v194, v194 row_mirror row_mask:0xf bank_mask:0xf bound_ctrl:1
	v_add_f32_dpp v195, v195, v195 row_mirror row_mask:0xf bank_mask:0xf bound_ctrl:1
	v_fmac_f32_e32 v186, v130, v56
	v_fmac_f32_e32 v187, v130, v57
	v_fmac_f32_e32 v188, v130, v58
	v_fmac_f32_e32 v189, v130, v59
	v_fmac_f32_e32 v190, v131, v56
	v_fmac_f32_e32 v191, v131, v57
	v_fmac_f32_e32 v192, v131, v58
	v_fmac_f32_e32 v193, v131, v59
	v_fmac_f32_e32 v186, v194, v52
	v_fmac_f32_e32 v187, v194, v53
	v_fmac_f32_e32 v188, v194, v54
	v_fmac_f32_e32 v189, v194, v55
	v_fmac_f32_e32 v190, v195, v52
	v_fmac_f32_e32 v191, v195, v53
	v_fmac_f32_e32 v192, v195, v54
	v_fmac_f32_e32 v193, v195, v55
	s_mov_b64 exec, s[8:9]
	ds_write2st64_b64 v161, v[132:133], v[238:239] offset0:27 offset1:26
	s_mov_b64 exec, -1
	ds_read_b128 v[48:51], v152 offset:14080
	ds_read_b128 v[52:55], v152 offset:22272
	ds_read_b128 v[56:59], v152 offset:30464
	ds_read_b128 v[60:63], v152 offset:38656
	ds_read_b64 v[130:131], v69 offset:5888
	s_waitcnt lgkmcnt(11)
	v_mul_f32_e32 v194, v186, v8
	v_mul_f32_e32 v195, v190, v8
	v_mul_f32_e32 v132, v186, v20
	v_mul_f32_e32 v133, v190, v20
	v_fmac_f32_e32 v194, v187, v9
	v_fmac_f32_e32 v195, v191, v9
	v_fmac_f32_e32 v132, v187, v21
	v_fmac_f32_e32 v133, v191, v21
	v_fmac_f32_e32 v194, v188, v10
	v_fmac_f32_e32 v195, v192, v10
	v_fmac_f32_e32 v132, v188, v22
	v_fmac_f32_e32 v133, v192, v22
	v_fmac_f32_e32 v194, v189, v11
	v_fmac_f32_e32 v195, v193, v11
	v_fmac_f32_e32 v132, v189, v23
	v_fmac_f32_e32 v133, v193, v23
	v_add_f32_dpp v194, v194, v194 quad_perm:[1,0,3,2] row_mask:0xf bank_mask:0xf bound_ctrl:1
	v_add_f32_dpp v195, v195, v195 quad_perm:[1,0,3,2] row_mask:0xf bank_mask:0xf bound_ctrl:1
	v_add_f32_dpp v132, v132, v132 quad_perm:[1,0,3,2] row_mask:0xf bank_mask:0xf bound_ctrl:1
	v_add_f32_dpp v133, v133, v133 quad_perm:[1,0,3,2] row_mask:0xf bank_mask:0xf bound_ctrl:1
	v_add_f32_dpp v194, v194, v194 quad_perm:[2,3,0,1] row_mask:0xf bank_mask:0xf bound_ctrl:1
	v_add_f32_dpp v195, v195, v195 quad_perm:[2,3,0,1] row_mask:0xf bank_mask:0xf bound_ctrl:1
	v_add_f32_dpp v132, v132, v132 quad_perm:[2,3,0,1] row_mask:0xf bank_mask:0xf bound_ctrl:1
	v_add_f32_dpp v133, v133, v133 quad_perm:[2,3,0,1] row_mask:0xf bank_mask:0xf bound_ctrl:1
	v_add_f32_dpp v194, v194, v194 row_half_mirror row_mask:0xf bank_mask:0xf bound_ctrl:1
	v_add_f32_dpp v195, v195, v195 row_half_mirror row_mask:0xf bank_mask:0xf bound_ctrl:1
	v_add_f32_dpp v132, v132, v132 row_half_mirror row_mask:0xf bank_mask:0xf bound_ctrl:1
	v_add_f32_dpp v133, v133, v133 row_half_mirror row_mask:0xf bank_mask:0xf bound_ctrl:1
	v_add_f32_dpp v194, v194, v194 row_mirror row_mask:0xf bank_mask:0xf bound_ctrl:1
	v_add_f32_dpp v195, v195, v195 row_mirror row_mask:0xf bank_mask:0xf bound_ctrl:1
	v_fmac_f32_e32 v186, v64, v16
	v_fmac_f32_e32 v187, v64, v17
	v_fmac_f32_e32 v188, v64, v18
	v_fmac_f32_e32 v189, v64, v19
	v_fmac_f32_e32 v190, v65, v16
	v_fmac_f32_e32 v191, v65, v17
	v_fmac_f32_e32 v192, v65, v18
	v_fmac_f32_e32 v193, v65, v19
	v_fmac_f32_e32 v186, v194, v12
	v_fmac_f32_e32 v187, v194, v13
	v_fmac_f32_e32 v188, v194, v14
	v_fmac_f32_e32 v189, v194, v15
	v_fmac_f32_e32 v190, v195, v12
	v_fmac_f32_e32 v191, v195, v13
	v_fmac_f32_e32 v192, v195, v14
	v_fmac_f32_e32 v193, v195, v15
	ds_read_b128 v[8:11], v152 offset:13824
	ds_read_b128 v[12:15], v152 offset:22016
	ds_read_b128 v[16:19], v152 offset:30208
	ds_read_b128 v[20:23], v152 offset:38400
	ds_read_b64 v[64:65], v69 offset:5632
	s_waitcnt lgkmcnt(11)
	v_mul_f32_e32 v194, v186, v28
	v_mul_f32_e32 v195, v190, v28
	v_mul_f32_e32 v238, v186, v40
	v_mul_f32_e32 v239, v190, v40
	v_fmac_f32_e32 v194, v187, v29
	v_fmac_f32_e32 v195, v191, v29
	v_fmac_f32_e32 v238, v187, v41
	v_fmac_f32_e32 v239, v191, v41
	v_fmac_f32_e32 v194, v188, v30
	v_fmac_f32_e32 v195, v192, v30
	v_fmac_f32_e32 v238, v188, v42
	v_fmac_f32_e32 v239, v192, v42
	v_fmac_f32_e32 v194, v189, v31
	v_fmac_f32_e32 v195, v193, v31
	v_fmac_f32_e32 v238, v189, v43
	v_fmac_f32_e32 v239, v193, v43
	v_add_f32_dpp v194, v194, v194 quad_perm:[1,0,3,2] row_mask:0xf bank_mask:0xf bound_ctrl:1
	v_add_f32_dpp v195, v195, v195 quad_perm:[1,0,3,2] row_mask:0xf bank_mask:0xf bound_ctrl:1
	v_add_f32_dpp v238, v238, v238 quad_perm:[1,0,3,2] row_mask:0xf bank_mask:0xf bound_ctrl:1
	v_add_f32_dpp v239, v239, v239 quad_perm:[1,0,3,2] row_mask:0xf bank_mask:0xf bound_ctrl:1
	v_add_f32_dpp v194, v194, v194 quad_perm:[2,3,0,1] row_mask:0xf bank_mask:0xf bound_ctrl:1
	v_add_f32_dpp v195, v195, v195 quad_perm:[2,3,0,1] row_mask:0xf bank_mask:0xf bound_ctrl:1
	v_add_f32_dpp v238, v238, v238 quad_perm:[2,3,0,1] row_mask:0xf bank_mask:0xf bound_ctrl:1
	v_add_f32_dpp v239, v239, v239 quad_perm:[2,3,0,1] row_mask:0xf bank_mask:0xf bound_ctrl:1
	v_add_f32_dpp v194, v194, v194 row_half_mirror row_mask:0xf bank_mask:0xf bound_ctrl:1
	v_add_f32_dpp v195, v195, v195 row_half_mirror row_mask:0xf bank_mask:0xf bound_ctrl:1
	v_add_f32_dpp v238, v238, v238 row_half_mirror row_mask:0xf bank_mask:0xf bound_ctrl:1
	v_add_f32_dpp v239, v239, v239 row_half_mirror row_mask:0xf bank_mask:0xf bound_ctrl:1
	v_add_f32_dpp v194, v194, v194 row_mirror row_mask:0xf bank_mask:0xf bound_ctrl:1
	v_add_f32_dpp v195, v195, v195 row_mirror row_mask:0xf bank_mask:0xf bound_ctrl:1
	v_fmac_f32_e32 v186, v66, v36
	v_fmac_f32_e32 v187, v66, v37
	v_fmac_f32_e32 v188, v66, v38
	v_fmac_f32_e32 v189, v66, v39
	v_fmac_f32_e32 v190, v67, v36
	v_fmac_f32_e32 v191, v67, v37
	v_fmac_f32_e32 v192, v67, v38
	v_fmac_f32_e32 v193, v67, v39
	v_fmac_f32_e32 v186, v194, v32
	v_fmac_f32_e32 v187, v194, v33
	v_fmac_f32_e32 v188, v194, v34
	v_fmac_f32_e32 v189, v194, v35
	v_fmac_f32_e32 v190, v195, v32
	v_fmac_f32_e32 v191, v195, v33
	v_fmac_f32_e32 v192, v195, v34
	v_fmac_f32_e32 v193, v195, v35
	s_mov_b64 exec, s[8:9]
	ds_write2st64_b64 v161, v[132:133], v[238:239] offset0:25 offset1:24
	s_mov_b64 exec, -1
	ds_read_b128 v[28:31], v152 offset:13568
	ds_read_b128 v[32:35], v152 offset:21760
	ds_read_b128 v[36:39], v152 offset:29952
	ds_read_b128 v[40:43], v152 offset:38144
	ds_read_b64 v[66:67], v69 offset:5376
	s_waitcnt lgkmcnt(11)
	v_mul_f32_e32 v194, v186, v48
	v_mul_f32_e32 v195, v190, v48
	v_mul_f32_e32 v132, v186, v60
	v_mul_f32_e32 v133, v190, v60
	v_fmac_f32_e32 v194, v187, v49
	v_fmac_f32_e32 v195, v191, v49
	v_fmac_f32_e32 v132, v187, v61
	v_fmac_f32_e32 v133, v191, v61
	v_fmac_f32_e32 v194, v188, v50
	v_fmac_f32_e32 v195, v192, v50
	v_fmac_f32_e32 v132, v188, v62
	v_fmac_f32_e32 v133, v192, v62
	v_fmac_f32_e32 v194, v189, v51
	v_fmac_f32_e32 v195, v193, v51
	v_fmac_f32_e32 v132, v189, v63
	v_fmac_f32_e32 v133, v193, v63
	v_add_f32_dpp v194, v194, v194 quad_perm:[1,0,3,2] row_mask:0xf bank_mask:0xf bound_ctrl:1
	v_add_f32_dpp v195, v195, v195 quad_perm:[1,0,3,2] row_mask:0xf bank_mask:0xf bound_ctrl:1
	v_add_f32_dpp v132, v132, v132 quad_perm:[1,0,3,2] row_mask:0xf bank_mask:0xf bound_ctrl:1
	v_add_f32_dpp v133, v133, v133 quad_perm:[1,0,3,2] row_mask:0xf bank_mask:0xf bound_ctrl:1
	v_add_f32_dpp v194, v194, v194 quad_perm:[2,3,0,1] row_mask:0xf bank_mask:0xf bound_ctrl:1
	v_add_f32_dpp v195, v195, v195 quad_perm:[2,3,0,1] row_mask:0xf bank_mask:0xf bound_ctrl:1
	v_add_f32_dpp v132, v132, v132 quad_perm:[2,3,0,1] row_mask:0xf bank_mask:0xf bound_ctrl:1
	v_add_f32_dpp v133, v133, v133 quad_perm:[2,3,0,1] row_mask:0xf bank_mask:0xf bound_ctrl:1
	v_add_f32_dpp v194, v194, v194 row_half_mirror row_mask:0xf bank_mask:0xf bound_ctrl:1
	v_add_f32_dpp v195, v195, v195 row_half_mirror row_mask:0xf bank_mask:0xf bound_ctrl:1
	v_add_f32_dpp v132, v132, v132 row_half_mirror row_mask:0xf bank_mask:0xf bound_ctrl:1
	v_add_f32_dpp v133, v133, v133 row_half_mirror row_mask:0xf bank_mask:0xf bound_ctrl:1
	v_add_f32_dpp v194, v194, v194 row_mirror row_mask:0xf bank_mask:0xf bound_ctrl:1
	v_add_f32_dpp v195, v195, v195 row_mirror row_mask:0xf bank_mask:0xf bound_ctrl:1
	v_fmac_f32_e32 v186, v130, v56
	v_fmac_f32_e32 v187, v130, v57
	v_fmac_f32_e32 v188, v130, v58
	v_fmac_f32_e32 v189, v130, v59
	v_fmac_f32_e32 v190, v131, v56
	v_fmac_f32_e32 v191, v131, v57
	v_fmac_f32_e32 v192, v131, v58
	v_fmac_f32_e32 v193, v131, v59
	v_fmac_f32_e32 v186, v194, v52
	v_fmac_f32_e32 v187, v194, v53
	v_fmac_f32_e32 v188, v194, v54
	v_fmac_f32_e32 v189, v194, v55
	v_fmac_f32_e32 v190, v195, v52
	v_fmac_f32_e32 v191, v195, v53
	v_fmac_f32_e32 v192, v195, v54
	v_fmac_f32_e32 v193, v195, v55
	ds_read_b128 v[48:51], v152 offset:13312
	ds_read_b128 v[52:55], v152 offset:21504
	ds_read_b128 v[56:59], v152 offset:29696
	ds_read_b128 v[60:63], v152 offset:37888
	ds_read_b64 v[130:131], v69 offset:5120
	s_waitcnt lgkmcnt(11)
	v_mul_f32_e32 v194, v186, v8
	v_mul_f32_e32 v195, v190, v8
	v_mul_f32_e32 v238, v186, v20
	v_mul_f32_e32 v239, v190, v20
	v_fmac_f32_e32 v194, v187, v9
	v_fmac_f32_e32 v195, v191, v9
	v_fmac_f32_e32 v238, v187, v21
	v_fmac_f32_e32 v239, v191, v21
	v_fmac_f32_e32 v194, v188, v10
	v_fmac_f32_e32 v195, v192, v10
	v_fmac_f32_e32 v238, v188, v22
	v_fmac_f32_e32 v239, v192, v22
	v_fmac_f32_e32 v194, v189, v11
	v_fmac_f32_e32 v195, v193, v11
	v_fmac_f32_e32 v238, v189, v23
	v_fmac_f32_e32 v239, v193, v23
	v_add_f32_dpp v194, v194, v194 quad_perm:[1,0,3,2] row_mask:0xf bank_mask:0xf bound_ctrl:1
	v_add_f32_dpp v195, v195, v195 quad_perm:[1,0,3,2] row_mask:0xf bank_mask:0xf bound_ctrl:1
	v_add_f32_dpp v238, v238, v238 quad_perm:[1,0,3,2] row_mask:0xf bank_mask:0xf bound_ctrl:1
	v_add_f32_dpp v239, v239, v239 quad_perm:[1,0,3,2] row_mask:0xf bank_mask:0xf bound_ctrl:1
	v_add_f32_dpp v194, v194, v194 quad_perm:[2,3,0,1] row_mask:0xf bank_mask:0xf bound_ctrl:1
	v_add_f32_dpp v195, v195, v195 quad_perm:[2,3,0,1] row_mask:0xf bank_mask:0xf bound_ctrl:1
	v_add_f32_dpp v238, v238, v238 quad_perm:[2,3,0,1] row_mask:0xf bank_mask:0xf bound_ctrl:1
	v_add_f32_dpp v239, v239, v239 quad_perm:[2,3,0,1] row_mask:0xf bank_mask:0xf bound_ctrl:1
	v_add_f32_dpp v194, v194, v194 row_half_mirror row_mask:0xf bank_mask:0xf bound_ctrl:1
	v_add_f32_dpp v195, v195, v195 row_half_mirror row_mask:0xf bank_mask:0xf bound_ctrl:1
	v_add_f32_dpp v238, v238, v238 row_half_mirror row_mask:0xf bank_mask:0xf bound_ctrl:1
	v_add_f32_dpp v239, v239, v239 row_half_mirror row_mask:0xf bank_mask:0xf bound_ctrl:1
	v_add_f32_dpp v194, v194, v194 row_mirror row_mask:0xf bank_mask:0xf bound_ctrl:1
	v_add_f32_dpp v195, v195, v195 row_mirror row_mask:0xf bank_mask:0xf bound_ctrl:1
	v_fmac_f32_e32 v186, v64, v16
	v_fmac_f32_e32 v187, v64, v17
	v_fmac_f32_e32 v188, v64, v18
	v_fmac_f32_e32 v189, v64, v19
	v_fmac_f32_e32 v190, v65, v16
	v_fmac_f32_e32 v191, v65, v17
	v_fmac_f32_e32 v192, v65, v18
	v_fmac_f32_e32 v193, v65, v19
	v_fmac_f32_e32 v186, v194, v12
	v_fmac_f32_e32 v187, v194, v13
	v_fmac_f32_e32 v188, v194, v14
	v_fmac_f32_e32 v189, v194, v15
	v_fmac_f32_e32 v190, v195, v12
	v_fmac_f32_e32 v191, v195, v13
	v_fmac_f32_e32 v192, v195, v14
	v_fmac_f32_e32 v193, v195, v15
	s_mov_b64 exec, s[8:9]
	ds_write2st64_b64 v161, v[132:133], v[238:239] offset0:23 offset1:22
	s_mov_b64 exec, -1
	ds_read_b128 v[8:11], v152 offset:13056
	ds_read_b128 v[12:15], v152 offset:21248
	ds_read_b128 v[16:19], v152 offset:29440
	ds_read_b128 v[20:23], v152 offset:37632
	ds_read_b64 v[64:65], v69 offset:4864
	s_waitcnt lgkmcnt(11)
	v_mul_f32_e32 v194, v186, v28
	v_mul_f32_e32 v195, v190, v28
	v_mul_f32_e32 v132, v186, v40
	v_mul_f32_e32 v133, v190, v40
	v_fmac_f32_e32 v194, v187, v29
	v_fmac_f32_e32 v195, v191, v29
	v_fmac_f32_e32 v132, v187, v41
	v_fmac_f32_e32 v133, v191, v41
	v_fmac_f32_e32 v194, v188, v30
	v_fmac_f32_e32 v195, v192, v30
	v_fmac_f32_e32 v132, v188, v42
	v_fmac_f32_e32 v133, v192, v42
	v_fmac_f32_e32 v194, v189, v31
	v_fmac_f32_e32 v195, v193, v31
	v_fmac_f32_e32 v132, v189, v43
	v_fmac_f32_e32 v133, v193, v43
	v_add_f32_dpp v194, v194, v194 quad_perm:[1,0,3,2] row_mask:0xf bank_mask:0xf bound_ctrl:1
	v_add_f32_dpp v195, v195, v195 quad_perm:[1,0,3,2] row_mask:0xf bank_mask:0xf bound_ctrl:1
	v_add_f32_dpp v132, v132, v132 quad_perm:[1,0,3,2] row_mask:0xf bank_mask:0xf bound_ctrl:1
	v_add_f32_dpp v133, v133, v133 quad_perm:[1,0,3,2] row_mask:0xf bank_mask:0xf bound_ctrl:1
	v_add_f32_dpp v194, v194, v194 quad_perm:[2,3,0,1] row_mask:0xf bank_mask:0xf bound_ctrl:1
	v_add_f32_dpp v195, v195, v195 quad_perm:[2,3,0,1] row_mask:0xf bank_mask:0xf bound_ctrl:1
	v_add_f32_dpp v132, v132, v132 quad_perm:[2,3,0,1] row_mask:0xf bank_mask:0xf bound_ctrl:1
	v_add_f32_dpp v133, v133, v133 quad_perm:[2,3,0,1] row_mask:0xf bank_mask:0xf bound_ctrl:1
	v_add_f32_dpp v194, v194, v194 row_half_mirror row_mask:0xf bank_mask:0xf bound_ctrl:1
	v_add_f32_dpp v195, v195, v195 row_half_mirror row_mask:0xf bank_mask:0xf bound_ctrl:1
	v_add_f32_dpp v132, v132, v132 row_half_mirror row_mask:0xf bank_mask:0xf bound_ctrl:1
	v_add_f32_dpp v133, v133, v133 row_half_mirror row_mask:0xf bank_mask:0xf bound_ctrl:1
	v_add_f32_dpp v194, v194, v194 row_mirror row_mask:0xf bank_mask:0xf bound_ctrl:1
	v_add_f32_dpp v195, v195, v195 row_mirror row_mask:0xf bank_mask:0xf bound_ctrl:1
	v_fmac_f32_e32 v186, v66, v36
	v_fmac_f32_e32 v187, v66, v37
	v_fmac_f32_e32 v188, v66, v38
	v_fmac_f32_e32 v189, v66, v39
	v_fmac_f32_e32 v190, v67, v36
	v_fmac_f32_e32 v191, v67, v37
	v_fmac_f32_e32 v192, v67, v38
	v_fmac_f32_e32 v193, v67, v39
	v_fmac_f32_e32 v186, v194, v32
	v_fmac_f32_e32 v187, v194, v33
	v_fmac_f32_e32 v188, v194, v34
	v_fmac_f32_e32 v189, v194, v35
	v_fmac_f32_e32 v190, v195, v32
	v_fmac_f32_e32 v191, v195, v33
	v_fmac_f32_e32 v192, v195, v34
	v_fmac_f32_e32 v193, v195, v35
	ds_read_b128 v[28:31], v152 offset:12800
	ds_read_b128 v[32:35], v152 offset:20992
	ds_read_b128 v[36:39], v152 offset:29184
	ds_read_b128 v[40:43], v152 offset:37376
	ds_read_b64 v[66:67], v69 offset:4608
	s_waitcnt lgkmcnt(11)
	v_mul_f32_e32 v194, v186, v48
	v_mul_f32_e32 v195, v190, v48
	v_mul_f32_e32 v238, v186, v60
	v_mul_f32_e32 v239, v190, v60
	v_fmac_f32_e32 v194, v187, v49
	v_fmac_f32_e32 v195, v191, v49
	v_fmac_f32_e32 v238, v187, v61
	v_fmac_f32_e32 v239, v191, v61
	v_fmac_f32_e32 v194, v188, v50
	v_fmac_f32_e32 v195, v192, v50
	v_fmac_f32_e32 v238, v188, v62
	v_fmac_f32_e32 v239, v192, v62
	v_fmac_f32_e32 v194, v189, v51
	v_fmac_f32_e32 v195, v193, v51
	v_fmac_f32_e32 v238, v189, v63
	v_fmac_f32_e32 v239, v193, v63
	v_add_f32_dpp v194, v194, v194 quad_perm:[1,0,3,2] row_mask:0xf bank_mask:0xf bound_ctrl:1
	v_add_f32_dpp v195, v195, v195 quad_perm:[1,0,3,2] row_mask:0xf bank_mask:0xf bound_ctrl:1
	v_add_f32_dpp v238, v238, v238 quad_perm:[1,0,3,2] row_mask:0xf bank_mask:0xf bound_ctrl:1
	v_add_f32_dpp v239, v239, v239 quad_perm:[1,0,3,2] row_mask:0xf bank_mask:0xf bound_ctrl:1
	v_add_f32_dpp v194, v194, v194 quad_perm:[2,3,0,1] row_mask:0xf bank_mask:0xf bound_ctrl:1
	v_add_f32_dpp v195, v195, v195 quad_perm:[2,3,0,1] row_mask:0xf bank_mask:0xf bound_ctrl:1
	v_add_f32_dpp v238, v238, v238 quad_perm:[2,3,0,1] row_mask:0xf bank_mask:0xf bound_ctrl:1
	v_add_f32_dpp v239, v239, v239 quad_perm:[2,3,0,1] row_mask:0xf bank_mask:0xf bound_ctrl:1
	v_add_f32_dpp v194, v194, v194 row_half_mirror row_mask:0xf bank_mask:0xf bound_ctrl:1
	v_add_f32_dpp v195, v195, v195 row_half_mirror row_mask:0xf bank_mask:0xf bound_ctrl:1
	v_add_f32_dpp v238, v238, v238 row_half_mirror row_mask:0xf bank_mask:0xf bound_ctrl:1
	v_add_f32_dpp v239, v239, v239 row_half_mirror row_mask:0xf bank_mask:0xf bound_ctrl:1
	v_add_f32_dpp v194, v194, v194 row_mirror row_mask:0xf bank_mask:0xf bound_ctrl:1
	v_add_f32_dpp v195, v195, v195 row_mirror row_mask:0xf bank_mask:0xf bound_ctrl:1
	v_fmac_f32_e32 v186, v130, v56
	v_fmac_f32_e32 v187, v130, v57
	v_fmac_f32_e32 v188, v130, v58
	v_fmac_f32_e32 v189, v130, v59
	v_fmac_f32_e32 v190, v131, v56
	v_fmac_f32_e32 v191, v131, v57
	v_fmac_f32_e32 v192, v131, v58
	v_fmac_f32_e32 v193, v131, v59
	v_fmac_f32_e32 v186, v194, v52
	v_fmac_f32_e32 v187, v194, v53
	v_fmac_f32_e32 v188, v194, v54
	v_fmac_f32_e32 v189, v194, v55
	v_fmac_f32_e32 v190, v195, v52
	v_fmac_f32_e32 v191, v195, v53
	v_fmac_f32_e32 v192, v195, v54
	v_fmac_f32_e32 v193, v195, v55
	s_mov_b64 exec, s[8:9]
	ds_write2st64_b64 v161, v[132:133], v[238:239] offset0:21 offset1:20
	s_mov_b64 exec, -1
	ds_read_b128 v[48:51], v152 offset:12544
	ds_read_b128 v[52:55], v152 offset:20736
	ds_read_b128 v[56:59], v152 offset:28928
	ds_read_b128 v[60:63], v152 offset:37120
	ds_read_b64 v[130:131], v69 offset:4352
	s_waitcnt lgkmcnt(11)
	v_mul_f32_e32 v194, v186, v8
	v_mul_f32_e32 v195, v190, v8
	v_mul_f32_e32 v132, v186, v20
	v_mul_f32_e32 v133, v190, v20
	v_fmac_f32_e32 v194, v187, v9
	v_fmac_f32_e32 v195, v191, v9
	v_fmac_f32_e32 v132, v187, v21
	v_fmac_f32_e32 v133, v191, v21
	v_fmac_f32_e32 v194, v188, v10
	v_fmac_f32_e32 v195, v192, v10
	v_fmac_f32_e32 v132, v188, v22
	v_fmac_f32_e32 v133, v192, v22
	v_fmac_f32_e32 v194, v189, v11
	v_fmac_f32_e32 v195, v193, v11
	v_fmac_f32_e32 v132, v189, v23
	v_fmac_f32_e32 v133, v193, v23
	v_add_f32_dpp v194, v194, v194 quad_perm:[1,0,3,2] row_mask:0xf bank_mask:0xf bound_ctrl:1
	v_add_f32_dpp v195, v195, v195 quad_perm:[1,0,3,2] row_mask:0xf bank_mask:0xf bound_ctrl:1
	v_add_f32_dpp v132, v132, v132 quad_perm:[1,0,3,2] row_mask:0xf bank_mask:0xf bound_ctrl:1
	v_add_f32_dpp v133, v133, v133 quad_perm:[1,0,3,2] row_mask:0xf bank_mask:0xf bound_ctrl:1
	v_add_f32_dpp v194, v194, v194 quad_perm:[2,3,0,1] row_mask:0xf bank_mask:0xf bound_ctrl:1
	v_add_f32_dpp v195, v195, v195 quad_perm:[2,3,0,1] row_mask:0xf bank_mask:0xf bound_ctrl:1
	v_add_f32_dpp v132, v132, v132 quad_perm:[2,3,0,1] row_mask:0xf bank_mask:0xf bound_ctrl:1
	v_add_f32_dpp v133, v133, v133 quad_perm:[2,3,0,1] row_mask:0xf bank_mask:0xf bound_ctrl:1
	v_add_f32_dpp v194, v194, v194 row_half_mirror row_mask:0xf bank_mask:0xf bound_ctrl:1
	v_add_f32_dpp v195, v195, v195 row_half_mirror row_mask:0xf bank_mask:0xf bound_ctrl:1
	v_add_f32_dpp v132, v132, v132 row_half_mirror row_mask:0xf bank_mask:0xf bound_ctrl:1
	v_add_f32_dpp v133, v133, v133 row_half_mirror row_mask:0xf bank_mask:0xf bound_ctrl:1
	v_add_f32_dpp v194, v194, v194 row_mirror row_mask:0xf bank_mask:0xf bound_ctrl:1
	v_add_f32_dpp v195, v195, v195 row_mirror row_mask:0xf bank_mask:0xf bound_ctrl:1
	v_fmac_f32_e32 v186, v64, v16
	v_fmac_f32_e32 v187, v64, v17
	v_fmac_f32_e32 v188, v64, v18
	v_fmac_f32_e32 v189, v64, v19
	v_fmac_f32_e32 v190, v65, v16
	v_fmac_f32_e32 v191, v65, v17
	v_fmac_f32_e32 v192, v65, v18
	v_fmac_f32_e32 v193, v65, v19
	v_fmac_f32_e32 v186, v194, v12
	v_fmac_f32_e32 v187, v194, v13
	v_fmac_f32_e32 v188, v194, v14
	v_fmac_f32_e32 v189, v194, v15
	v_fmac_f32_e32 v190, v195, v12
	v_fmac_f32_e32 v191, v195, v13
	v_fmac_f32_e32 v192, v195, v14
	v_fmac_f32_e32 v193, v195, v15
	ds_read_b128 v[8:11], v152 offset:12288
	ds_read_b128 v[12:15], v152 offset:20480
	ds_read_b128 v[16:19], v152 offset:28672
	ds_read_b128 v[20:23], v152 offset:36864
	ds_read_b64 v[64:65], v69 offset:4096
	s_waitcnt lgkmcnt(11)
	v_mul_f32_e32 v194, v186, v28
	v_mul_f32_e32 v195, v190, v28
	v_mul_f32_e32 v238, v186, v40
	v_mul_f32_e32 v239, v190, v40
	v_fmac_f32_e32 v194, v187, v29
	v_fmac_f32_e32 v195, v191, v29
	v_fmac_f32_e32 v238, v187, v41
	v_fmac_f32_e32 v239, v191, v41
	v_fmac_f32_e32 v194, v188, v30
	v_fmac_f32_e32 v195, v192, v30
	v_fmac_f32_e32 v238, v188, v42
	v_fmac_f32_e32 v239, v192, v42
	v_fmac_f32_e32 v194, v189, v31
	v_fmac_f32_e32 v195, v193, v31
	v_fmac_f32_e32 v238, v189, v43
	v_fmac_f32_e32 v239, v193, v43
	v_add_f32_dpp v194, v194, v194 quad_perm:[1,0,3,2] row_mask:0xf bank_mask:0xf bound_ctrl:1
	v_add_f32_dpp v195, v195, v195 quad_perm:[1,0,3,2] row_mask:0xf bank_mask:0xf bound_ctrl:1
	v_add_f32_dpp v238, v238, v238 quad_perm:[1,0,3,2] row_mask:0xf bank_mask:0xf bound_ctrl:1
	v_add_f32_dpp v239, v239, v239 quad_perm:[1,0,3,2] row_mask:0xf bank_mask:0xf bound_ctrl:1
	v_add_f32_dpp v194, v194, v194 quad_perm:[2,3,0,1] row_mask:0xf bank_mask:0xf bound_ctrl:1
	v_add_f32_dpp v195, v195, v195 quad_perm:[2,3,0,1] row_mask:0xf bank_mask:0xf bound_ctrl:1
	v_add_f32_dpp v238, v238, v238 quad_perm:[2,3,0,1] row_mask:0xf bank_mask:0xf bound_ctrl:1
	v_add_f32_dpp v239, v239, v239 quad_perm:[2,3,0,1] row_mask:0xf bank_mask:0xf bound_ctrl:1
	v_add_f32_dpp v194, v194, v194 row_half_mirror row_mask:0xf bank_mask:0xf bound_ctrl:1
	v_add_f32_dpp v195, v195, v195 row_half_mirror row_mask:0xf bank_mask:0xf bound_ctrl:1
	v_add_f32_dpp v238, v238, v238 row_half_mirror row_mask:0xf bank_mask:0xf bound_ctrl:1
	v_add_f32_dpp v239, v239, v239 row_half_mirror row_mask:0xf bank_mask:0xf bound_ctrl:1
	v_add_f32_dpp v194, v194, v194 row_mirror row_mask:0xf bank_mask:0xf bound_ctrl:1
	v_add_f32_dpp v195, v195, v195 row_mirror row_mask:0xf bank_mask:0xf bound_ctrl:1
	v_fmac_f32_e32 v186, v66, v36
	v_fmac_f32_e32 v187, v66, v37
	v_fmac_f32_e32 v188, v66, v38
	v_fmac_f32_e32 v189, v66, v39
	v_fmac_f32_e32 v190, v67, v36
	v_fmac_f32_e32 v191, v67, v37
	v_fmac_f32_e32 v192, v67, v38
	v_fmac_f32_e32 v193, v67, v39
	v_fmac_f32_e32 v186, v194, v32
	v_fmac_f32_e32 v187, v194, v33
	v_fmac_f32_e32 v188, v194, v34
	v_fmac_f32_e32 v189, v194, v35
	v_fmac_f32_e32 v190, v195, v32
	v_fmac_f32_e32 v191, v195, v33
	v_fmac_f32_e32 v192, v195, v34
	v_fmac_f32_e32 v193, v195, v35
	s_mov_b64 exec, s[8:9]
	ds_write2st64_b64 v161, v[132:133], v[238:239] offset0:19 offset1:18
	s_mov_b64 exec, -1
	ds_read_b128 v[28:31], v152 offset:12032
	ds_read_b128 v[32:35], v152 offset:20224
	ds_read_b128 v[36:39], v152 offset:28416
	ds_read_b128 v[40:43], v152 offset:36608
	ds_read_b64 v[66:67], v69 offset:3840
	s_waitcnt lgkmcnt(11)
	v_mul_f32_e32 v194, v186, v48
	v_mul_f32_e32 v195, v190, v48
	v_mul_f32_e32 v132, v186, v60
	v_mul_f32_e32 v133, v190, v60
	v_fmac_f32_e32 v194, v187, v49
	v_fmac_f32_e32 v195, v191, v49
	v_fmac_f32_e32 v132, v187, v61
	v_fmac_f32_e32 v133, v191, v61
	v_fmac_f32_e32 v194, v188, v50
	v_fmac_f32_e32 v195, v192, v50
	v_fmac_f32_e32 v132, v188, v62
	v_fmac_f32_e32 v133, v192, v62
	v_fmac_f32_e32 v194, v189, v51
	v_fmac_f32_e32 v195, v193, v51
	v_fmac_f32_e32 v132, v189, v63
	v_fmac_f32_e32 v133, v193, v63
	v_add_f32_dpp v194, v194, v194 quad_perm:[1,0,3,2] row_mask:0xf bank_mask:0xf bound_ctrl:1
	v_add_f32_dpp v195, v195, v195 quad_perm:[1,0,3,2] row_mask:0xf bank_mask:0xf bound_ctrl:1
	v_add_f32_dpp v132, v132, v132 quad_perm:[1,0,3,2] row_mask:0xf bank_mask:0xf bound_ctrl:1
	v_add_f32_dpp v133, v133, v133 quad_perm:[1,0,3,2] row_mask:0xf bank_mask:0xf bound_ctrl:1
	v_add_f32_dpp v194, v194, v194 quad_perm:[2,3,0,1] row_mask:0xf bank_mask:0xf bound_ctrl:1
	v_add_f32_dpp v195, v195, v195 quad_perm:[2,3,0,1] row_mask:0xf bank_mask:0xf bound_ctrl:1
	v_add_f32_dpp v132, v132, v132 quad_perm:[2,3,0,1] row_mask:0xf bank_mask:0xf bound_ctrl:1
	v_add_f32_dpp v133, v133, v133 quad_perm:[2,3,0,1] row_mask:0xf bank_mask:0xf bound_ctrl:1
	v_add_f32_dpp v194, v194, v194 row_half_mirror row_mask:0xf bank_mask:0xf bound_ctrl:1
	v_add_f32_dpp v195, v195, v195 row_half_mirror row_mask:0xf bank_mask:0xf bound_ctrl:1
	v_add_f32_dpp v132, v132, v132 row_half_mirror row_mask:0xf bank_mask:0xf bound_ctrl:1
	v_add_f32_dpp v133, v133, v133 row_half_mirror row_mask:0xf bank_mask:0xf bound_ctrl:1
	v_add_f32_dpp v194, v194, v194 row_mirror row_mask:0xf bank_mask:0xf bound_ctrl:1
	v_add_f32_dpp v195, v195, v195 row_mirror row_mask:0xf bank_mask:0xf bound_ctrl:1
	v_fmac_f32_e32 v186, v130, v56
	v_fmac_f32_e32 v187, v130, v57
	v_fmac_f32_e32 v188, v130, v58
	v_fmac_f32_e32 v189, v130, v59
	v_fmac_f32_e32 v190, v131, v56
	v_fmac_f32_e32 v191, v131, v57
	v_fmac_f32_e32 v192, v131, v58
	v_fmac_f32_e32 v193, v131, v59
	v_fmac_f32_e32 v186, v194, v52
	v_fmac_f32_e32 v187, v194, v53
	v_fmac_f32_e32 v188, v194, v54
	v_fmac_f32_e32 v189, v194, v55
	v_fmac_f32_e32 v190, v195, v52
	v_fmac_f32_e32 v191, v195, v53
	v_fmac_f32_e32 v192, v195, v54
	v_fmac_f32_e32 v193, v195, v55
	ds_read_b128 v[48:51], v152 offset:11776
	ds_read_b128 v[52:55], v152 offset:19968
	ds_read_b128 v[56:59], v152 offset:28160
	ds_read_b128 v[60:63], v152 offset:36352
	ds_read_b64 v[130:131], v69 offset:3584
	s_waitcnt lgkmcnt(11)
	v_mul_f32_e32 v194, v186, v8
	v_mul_f32_e32 v195, v190, v8
	v_mul_f32_e32 v238, v186, v20
	v_mul_f32_e32 v239, v190, v20
	v_fmac_f32_e32 v194, v187, v9
	v_fmac_f32_e32 v195, v191, v9
	v_fmac_f32_e32 v238, v187, v21
	v_fmac_f32_e32 v239, v191, v21
	v_fmac_f32_e32 v194, v188, v10
	v_fmac_f32_e32 v195, v192, v10
	v_fmac_f32_e32 v238, v188, v22
	v_fmac_f32_e32 v239, v192, v22
	v_fmac_f32_e32 v194, v189, v11
	v_fmac_f32_e32 v195, v193, v11
	v_fmac_f32_e32 v238, v189, v23
	v_fmac_f32_e32 v239, v193, v23
	v_add_f32_dpp v194, v194, v194 quad_perm:[1,0,3,2] row_mask:0xf bank_mask:0xf bound_ctrl:1
	v_add_f32_dpp v195, v195, v195 quad_perm:[1,0,3,2] row_mask:0xf bank_mask:0xf bound_ctrl:1
	v_add_f32_dpp v238, v238, v238 quad_perm:[1,0,3,2] row_mask:0xf bank_mask:0xf bound_ctrl:1
	v_add_f32_dpp v239, v239, v239 quad_perm:[1,0,3,2] row_mask:0xf bank_mask:0xf bound_ctrl:1
	v_add_f32_dpp v194, v194, v194 quad_perm:[2,3,0,1] row_mask:0xf bank_mask:0xf bound_ctrl:1
	v_add_f32_dpp v195, v195, v195 quad_perm:[2,3,0,1] row_mask:0xf bank_mask:0xf bound_ctrl:1
	v_add_f32_dpp v238, v238, v238 quad_perm:[2,3,0,1] row_mask:0xf bank_mask:0xf bound_ctrl:1
	v_add_f32_dpp v239, v239, v239 quad_perm:[2,3,0,1] row_mask:0xf bank_mask:0xf bound_ctrl:1
	v_add_f32_dpp v194, v194, v194 row_half_mirror row_mask:0xf bank_mask:0xf bound_ctrl:1
	v_add_f32_dpp v195, v195, v195 row_half_mirror row_mask:0xf bank_mask:0xf bound_ctrl:1
	v_add_f32_dpp v238, v238, v238 row_half_mirror row_mask:0xf bank_mask:0xf bound_ctrl:1
	v_add_f32_dpp v239, v239, v239 row_half_mirror row_mask:0xf bank_mask:0xf bound_ctrl:1
	v_add_f32_dpp v194, v194, v194 row_mirror row_mask:0xf bank_mask:0xf bound_ctrl:1
	v_add_f32_dpp v195, v195, v195 row_mirror row_mask:0xf bank_mask:0xf bound_ctrl:1
	v_fmac_f32_e32 v186, v64, v16
	v_fmac_f32_e32 v187, v64, v17
	v_fmac_f32_e32 v188, v64, v18
	v_fmac_f32_e32 v189, v64, v19
	v_fmac_f32_e32 v190, v65, v16
	v_fmac_f32_e32 v191, v65, v17
	v_fmac_f32_e32 v192, v65, v18
	v_fmac_f32_e32 v193, v65, v19
	v_fmac_f32_e32 v186, v194, v12
	v_fmac_f32_e32 v187, v194, v13
	v_fmac_f32_e32 v188, v194, v14
	v_fmac_f32_e32 v189, v194, v15
	v_fmac_f32_e32 v190, v195, v12
	v_fmac_f32_e32 v191, v195, v13
	v_fmac_f32_e32 v192, v195, v14
	v_fmac_f32_e32 v193, v195, v15
	s_mov_b64 exec, s[8:9]
	ds_write2st64_b64 v161, v[132:133], v[238:239] offset0:17 offset1:16
	s_mov_b64 exec, -1
	ds_read_b128 v[8:11], v152 offset:11520
	ds_read_b128 v[12:15], v152 offset:19712
	ds_read_b128 v[16:19], v152 offset:27904
	ds_read_b128 v[20:23], v152 offset:36096
	ds_read_b64 v[64:65], v69 offset:3328
	s_waitcnt lgkmcnt(11)
	v_mul_f32_e32 v194, v186, v28
	v_mul_f32_e32 v195, v190, v28
	v_mul_f32_e32 v132, v186, v40
	v_mul_f32_e32 v133, v190, v40
	v_fmac_f32_e32 v194, v187, v29
	v_fmac_f32_e32 v195, v191, v29
	v_fmac_f32_e32 v132, v187, v41
	v_fmac_f32_e32 v133, v191, v41
	v_fmac_f32_e32 v194, v188, v30
	v_fmac_f32_e32 v195, v192, v30
	v_fmac_f32_e32 v132, v188, v42
	v_fmac_f32_e32 v133, v192, v42
	v_fmac_f32_e32 v194, v189, v31
	v_fmac_f32_e32 v195, v193, v31
	v_fmac_f32_e32 v132, v189, v43
	v_fmac_f32_e32 v133, v193, v43
	v_add_f32_dpp v194, v194, v194 quad_perm:[1,0,3,2] row_mask:0xf bank_mask:0xf bound_ctrl:1
	v_add_f32_dpp v195, v195, v195 quad_perm:[1,0,3,2] row_mask:0xf bank_mask:0xf bound_ctrl:1
	v_add_f32_dpp v132, v132, v132 quad_perm:[1,0,3,2] row_mask:0xf bank_mask:0xf bound_ctrl:1
	v_add_f32_dpp v133, v133, v133 quad_perm:[1,0,3,2] row_mask:0xf bank_mask:0xf bound_ctrl:1
	v_add_f32_dpp v194, v194, v194 quad_perm:[2,3,0,1] row_mask:0xf bank_mask:0xf bound_ctrl:1
	v_add_f32_dpp v195, v195, v195 quad_perm:[2,3,0,1] row_mask:0xf bank_mask:0xf bound_ctrl:1
	v_add_f32_dpp v132, v132, v132 quad_perm:[2,3,0,1] row_mask:0xf bank_mask:0xf bound_ctrl:1
	v_add_f32_dpp v133, v133, v133 quad_perm:[2,3,0,1] row_mask:0xf bank_mask:0xf bound_ctrl:1
	v_add_f32_dpp v194, v194, v194 row_half_mirror row_mask:0xf bank_mask:0xf bound_ctrl:1
	v_add_f32_dpp v195, v195, v195 row_half_mirror row_mask:0xf bank_mask:0xf bound_ctrl:1
	v_add_f32_dpp v132, v132, v132 row_half_mirror row_mask:0xf bank_mask:0xf bound_ctrl:1
	v_add_f32_dpp v133, v133, v133 row_half_mirror row_mask:0xf bank_mask:0xf bound_ctrl:1
	v_add_f32_dpp v194, v194, v194 row_mirror row_mask:0xf bank_mask:0xf bound_ctrl:1
	v_add_f32_dpp v195, v195, v195 row_mirror row_mask:0xf bank_mask:0xf bound_ctrl:1
	v_fmac_f32_e32 v186, v66, v36
	v_fmac_f32_e32 v187, v66, v37
	v_fmac_f32_e32 v188, v66, v38
	v_fmac_f32_e32 v189, v66, v39
	v_fmac_f32_e32 v190, v67, v36
	v_fmac_f32_e32 v191, v67, v37
	v_fmac_f32_e32 v192, v67, v38
	v_fmac_f32_e32 v193, v67, v39
	v_fmac_f32_e32 v186, v194, v32
	v_fmac_f32_e32 v187, v194, v33
	v_fmac_f32_e32 v188, v194, v34
	v_fmac_f32_e32 v189, v194, v35
	v_fmac_f32_e32 v190, v195, v32
	v_fmac_f32_e32 v191, v195, v33
	v_fmac_f32_e32 v192, v195, v34
	v_fmac_f32_e32 v193, v195, v35
	ds_read_b128 v[28:31], v152 offset:11264
	ds_read_b128 v[32:35], v152 offset:19456
	ds_read_b128 v[36:39], v152 offset:27648
	ds_read_b128 v[40:43], v152 offset:35840
	ds_read_b64 v[66:67], v69 offset:3072
	s_waitcnt lgkmcnt(11)
	v_mul_f32_e32 v194, v186, v48
	v_mul_f32_e32 v195, v190, v48
	v_mul_f32_e32 v238, v186, v60
	v_mul_f32_e32 v239, v190, v60
	v_fmac_f32_e32 v194, v187, v49
	v_fmac_f32_e32 v195, v191, v49
	v_fmac_f32_e32 v238, v187, v61
	v_fmac_f32_e32 v239, v191, v61
	v_fmac_f32_e32 v194, v188, v50
	v_fmac_f32_e32 v195, v192, v50
	v_fmac_f32_e32 v238, v188, v62
	v_fmac_f32_e32 v239, v192, v62
	v_fmac_f32_e32 v194, v189, v51
	v_fmac_f32_e32 v195, v193, v51
	v_fmac_f32_e32 v238, v189, v63
	v_fmac_f32_e32 v239, v193, v63
	v_add_f32_dpp v194, v194, v194 quad_perm:[1,0,3,2] row_mask:0xf bank_mask:0xf bound_ctrl:1
	v_add_f32_dpp v195, v195, v195 quad_perm:[1,0,3,2] row_mask:0xf bank_mask:0xf bound_ctrl:1
	v_add_f32_dpp v238, v238, v238 quad_perm:[1,0,3,2] row_mask:0xf bank_mask:0xf bound_ctrl:1
	v_add_f32_dpp v239, v239, v239 quad_perm:[1,0,3,2] row_mask:0xf bank_mask:0xf bound_ctrl:1
	v_add_f32_dpp v194, v194, v194 quad_perm:[2,3,0,1] row_mask:0xf bank_mask:0xf bound_ctrl:1
	v_add_f32_dpp v195, v195, v195 quad_perm:[2,3,0,1] row_mask:0xf bank_mask:0xf bound_ctrl:1
	v_add_f32_dpp v238, v238, v238 quad_perm:[2,3,0,1] row_mask:0xf bank_mask:0xf bound_ctrl:1
	v_add_f32_dpp v239, v239, v239 quad_perm:[2,3,0,1] row_mask:0xf bank_mask:0xf bound_ctrl:1
	v_add_f32_dpp v194, v194, v194 row_half_mirror row_mask:0xf bank_mask:0xf bound_ctrl:1
	v_add_f32_dpp v195, v195, v195 row_half_mirror row_mask:0xf bank_mask:0xf bound_ctrl:1
	v_add_f32_dpp v238, v238, v238 row_half_mirror row_mask:0xf bank_mask:0xf bound_ctrl:1
	v_add_f32_dpp v239, v239, v239 row_half_mirror row_mask:0xf bank_mask:0xf bound_ctrl:1
	v_add_f32_dpp v194, v194, v194 row_mirror row_mask:0xf bank_mask:0xf bound_ctrl:1
	v_add_f32_dpp v195, v195, v195 row_mirror row_mask:0xf bank_mask:0xf bound_ctrl:1
	v_fmac_f32_e32 v186, v130, v56
	v_fmac_f32_e32 v187, v130, v57
	v_fmac_f32_e32 v188, v130, v58
	v_fmac_f32_e32 v189, v130, v59
	v_fmac_f32_e32 v190, v131, v56
	v_fmac_f32_e32 v191, v131, v57
	v_fmac_f32_e32 v192, v131, v58
	v_fmac_f32_e32 v193, v131, v59
	v_fmac_f32_e32 v186, v194, v52
	v_fmac_f32_e32 v187, v194, v53
	v_fmac_f32_e32 v188, v194, v54
	v_fmac_f32_e32 v189, v194, v55
	v_fmac_f32_e32 v190, v195, v52
	v_fmac_f32_e32 v191, v195, v53
	v_fmac_f32_e32 v192, v195, v54
	v_fmac_f32_e32 v193, v195, v55
	s_mov_b64 exec, s[8:9]
	ds_write2st64_b64 v161, v[132:133], v[238:239] offset0:15 offset1:14
	s_mov_b64 exec, -1
	ds_read_b128 v[48:51], v152 offset:11008
	ds_read_b128 v[52:55], v152 offset:19200
	ds_read_b128 v[56:59], v152 offset:27392
	ds_read_b128 v[60:63], v152 offset:35584
	ds_read_b64 v[130:131], v69 offset:2816
	s_waitcnt lgkmcnt(11)
	v_mul_f32_e32 v194, v186, v8
	v_mul_f32_e32 v195, v190, v8
	v_mul_f32_e32 v132, v186, v20
	v_mul_f32_e32 v133, v190, v20
	v_fmac_f32_e32 v194, v187, v9
	v_fmac_f32_e32 v195, v191, v9
	v_fmac_f32_e32 v132, v187, v21
	v_fmac_f32_e32 v133, v191, v21
	v_fmac_f32_e32 v194, v188, v10
	v_fmac_f32_e32 v195, v192, v10
	v_fmac_f32_e32 v132, v188, v22
	v_fmac_f32_e32 v133, v192, v22
	v_fmac_f32_e32 v194, v189, v11
	v_fmac_f32_e32 v195, v193, v11
	v_fmac_f32_e32 v132, v189, v23
	v_fmac_f32_e32 v133, v193, v23
	v_add_f32_dpp v194, v194, v194 quad_perm:[1,0,3,2] row_mask:0xf bank_mask:0xf bound_ctrl:1
	v_add_f32_dpp v195, v195, v195 quad_perm:[1,0,3,2] row_mask:0xf bank_mask:0xf bound_ctrl:1
	v_add_f32_dpp v132, v132, v132 quad_perm:[1,0,3,2] row_mask:0xf bank_mask:0xf bound_ctrl:1
	v_add_f32_dpp v133, v133, v133 quad_perm:[1,0,3,2] row_mask:0xf bank_mask:0xf bound_ctrl:1
	v_add_f32_dpp v194, v194, v194 quad_perm:[2,3,0,1] row_mask:0xf bank_mask:0xf bound_ctrl:1
	v_add_f32_dpp v195, v195, v195 quad_perm:[2,3,0,1] row_mask:0xf bank_mask:0xf bound_ctrl:1
	v_add_f32_dpp v132, v132, v132 quad_perm:[2,3,0,1] row_mask:0xf bank_mask:0xf bound_ctrl:1
	v_add_f32_dpp v133, v133, v133 quad_perm:[2,3,0,1] row_mask:0xf bank_mask:0xf bound_ctrl:1
	v_add_f32_dpp v194, v194, v194 row_half_mirror row_mask:0xf bank_mask:0xf bound_ctrl:1
	v_add_f32_dpp v195, v195, v195 row_half_mirror row_mask:0xf bank_mask:0xf bound_ctrl:1
	v_add_f32_dpp v132, v132, v132 row_half_mirror row_mask:0xf bank_mask:0xf bound_ctrl:1
	v_add_f32_dpp v133, v133, v133 row_half_mirror row_mask:0xf bank_mask:0xf bound_ctrl:1
	v_add_f32_dpp v194, v194, v194 row_mirror row_mask:0xf bank_mask:0xf bound_ctrl:1
	v_add_f32_dpp v195, v195, v195 row_mirror row_mask:0xf bank_mask:0xf bound_ctrl:1
	v_fmac_f32_e32 v186, v64, v16
	v_fmac_f32_e32 v187, v64, v17
	v_fmac_f32_e32 v188, v64, v18
	v_fmac_f32_e32 v189, v64, v19
	v_fmac_f32_e32 v190, v65, v16
	v_fmac_f32_e32 v191, v65, v17
	v_fmac_f32_e32 v192, v65, v18
	v_fmac_f32_e32 v193, v65, v19
	v_fmac_f32_e32 v186, v194, v12
	v_fmac_f32_e32 v187, v194, v13
	v_fmac_f32_e32 v188, v194, v14
	v_fmac_f32_e32 v189, v194, v15
	v_fmac_f32_e32 v190, v195, v12
	v_fmac_f32_e32 v191, v195, v13
	v_fmac_f32_e32 v192, v195, v14
	v_fmac_f32_e32 v193, v195, v15
	ds_read_b128 v[8:11], v152 offset:10752
	ds_read_b128 v[12:15], v152 offset:18944
	ds_read_b128 v[16:19], v152 offset:27136
	ds_read_b128 v[20:23], v152 offset:35328
	ds_read_b64 v[64:65], v69 offset:2560
	s_waitcnt lgkmcnt(11)
	v_mul_f32_e32 v194, v186, v28
	v_mul_f32_e32 v195, v190, v28
	v_mul_f32_e32 v238, v186, v40
	v_mul_f32_e32 v239, v190, v40
	v_fmac_f32_e32 v194, v187, v29
	v_fmac_f32_e32 v195, v191, v29
	v_fmac_f32_e32 v238, v187, v41
	v_fmac_f32_e32 v239, v191, v41
	v_fmac_f32_e32 v194, v188, v30
	v_fmac_f32_e32 v195, v192, v30
	v_fmac_f32_e32 v238, v188, v42
	v_fmac_f32_e32 v239, v192, v42
	v_fmac_f32_e32 v194, v189, v31
	v_fmac_f32_e32 v195, v193, v31
	v_fmac_f32_e32 v238, v189, v43
	v_fmac_f32_e32 v239, v193, v43
	v_add_f32_dpp v194, v194, v194 quad_perm:[1,0,3,2] row_mask:0xf bank_mask:0xf bound_ctrl:1
	v_add_f32_dpp v195, v195, v195 quad_perm:[1,0,3,2] row_mask:0xf bank_mask:0xf bound_ctrl:1
	v_add_f32_dpp v238, v238, v238 quad_perm:[1,0,3,2] row_mask:0xf bank_mask:0xf bound_ctrl:1
	v_add_f32_dpp v239, v239, v239 quad_perm:[1,0,3,2] row_mask:0xf bank_mask:0xf bound_ctrl:1
	v_add_f32_dpp v194, v194, v194 quad_perm:[2,3,0,1] row_mask:0xf bank_mask:0xf bound_ctrl:1
	v_add_f32_dpp v195, v195, v195 quad_perm:[2,3,0,1] row_mask:0xf bank_mask:0xf bound_ctrl:1
	v_add_f32_dpp v238, v238, v238 quad_perm:[2,3,0,1] row_mask:0xf bank_mask:0xf bound_ctrl:1
	v_add_f32_dpp v239, v239, v239 quad_perm:[2,3,0,1] row_mask:0xf bank_mask:0xf bound_ctrl:1
	v_add_f32_dpp v194, v194, v194 row_half_mirror row_mask:0xf bank_mask:0xf bound_ctrl:1
	v_add_f32_dpp v195, v195, v195 row_half_mirror row_mask:0xf bank_mask:0xf bound_ctrl:1
	v_add_f32_dpp v238, v238, v238 row_half_mirror row_mask:0xf bank_mask:0xf bound_ctrl:1
	v_add_f32_dpp v239, v239, v239 row_half_mirror row_mask:0xf bank_mask:0xf bound_ctrl:1
	v_add_f32_dpp v194, v194, v194 row_mirror row_mask:0xf bank_mask:0xf bound_ctrl:1
	v_add_f32_dpp v195, v195, v195 row_mirror row_mask:0xf bank_mask:0xf bound_ctrl:1
	v_fmac_f32_e32 v186, v66, v36
	v_fmac_f32_e32 v187, v66, v37
	v_fmac_f32_e32 v188, v66, v38
	v_fmac_f32_e32 v189, v66, v39
	v_fmac_f32_e32 v190, v67, v36
	v_fmac_f32_e32 v191, v67, v37
	v_fmac_f32_e32 v192, v67, v38
	v_fmac_f32_e32 v193, v67, v39
	v_fmac_f32_e32 v186, v194, v32
	v_fmac_f32_e32 v187, v194, v33
	v_fmac_f32_e32 v188, v194, v34
	v_fmac_f32_e32 v189, v194, v35
	v_fmac_f32_e32 v190, v195, v32
	v_fmac_f32_e32 v191, v195, v33
	v_fmac_f32_e32 v192, v195, v34
	v_fmac_f32_e32 v193, v195, v35
	s_mov_b64 exec, s[8:9]
	ds_write2st64_b64 v161, v[132:133], v[238:239] offset0:13 offset1:12
	s_mov_b64 exec, -1
	ds_read_b128 v[28:31], v152 offset:10496
	ds_read_b128 v[32:35], v152 offset:18688
	ds_read_b128 v[36:39], v152 offset:26880
	ds_read_b128 v[40:43], v152 offset:35072
	ds_read_b64 v[66:67], v69 offset:2304
	s_waitcnt lgkmcnt(11)
	v_mul_f32_e32 v194, v186, v48
	v_mul_f32_e32 v195, v190, v48
	v_mul_f32_e32 v132, v186, v60
	v_mul_f32_e32 v133, v190, v60
	v_fmac_f32_e32 v194, v187, v49
	v_fmac_f32_e32 v195, v191, v49
	v_fmac_f32_e32 v132, v187, v61
	v_fmac_f32_e32 v133, v191, v61
	v_fmac_f32_e32 v194, v188, v50
	v_fmac_f32_e32 v195, v192, v50
	v_fmac_f32_e32 v132, v188, v62
	v_fmac_f32_e32 v133, v192, v62
	v_fmac_f32_e32 v194, v189, v51
	v_fmac_f32_e32 v195, v193, v51
	v_fmac_f32_e32 v132, v189, v63
	v_fmac_f32_e32 v133, v193, v63
	v_add_f32_dpp v194, v194, v194 quad_perm:[1,0,3,2] row_mask:0xf bank_mask:0xf bound_ctrl:1
	v_add_f32_dpp v195, v195, v195 quad_perm:[1,0,3,2] row_mask:0xf bank_mask:0xf bound_ctrl:1
	v_add_f32_dpp v132, v132, v132 quad_perm:[1,0,3,2] row_mask:0xf bank_mask:0xf bound_ctrl:1
	v_add_f32_dpp v133, v133, v133 quad_perm:[1,0,3,2] row_mask:0xf bank_mask:0xf bound_ctrl:1
	v_add_f32_dpp v194, v194, v194 quad_perm:[2,3,0,1] row_mask:0xf bank_mask:0xf bound_ctrl:1
	v_add_f32_dpp v195, v195, v195 quad_perm:[2,3,0,1] row_mask:0xf bank_mask:0xf bound_ctrl:1
	v_add_f32_dpp v132, v132, v132 quad_perm:[2,3,0,1] row_mask:0xf bank_mask:0xf bound_ctrl:1
	v_add_f32_dpp v133, v133, v133 quad_perm:[2,3,0,1] row_mask:0xf bank_mask:0xf bound_ctrl:1
	v_add_f32_dpp v194, v194, v194 row_half_mirror row_mask:0xf bank_mask:0xf bound_ctrl:1
	v_add_f32_dpp v195, v195, v195 row_half_mirror row_mask:0xf bank_mask:0xf bound_ctrl:1
	v_add_f32_dpp v132, v132, v132 row_half_mirror row_mask:0xf bank_mask:0xf bound_ctrl:1
	v_add_f32_dpp v133, v133, v133 row_half_mirror row_mask:0xf bank_mask:0xf bound_ctrl:1
	v_add_f32_dpp v194, v194, v194 row_mirror row_mask:0xf bank_mask:0xf bound_ctrl:1
	v_add_f32_dpp v195, v195, v195 row_mirror row_mask:0xf bank_mask:0xf bound_ctrl:1
	v_fmac_f32_e32 v186, v130, v56
	v_fmac_f32_e32 v187, v130, v57
	v_fmac_f32_e32 v188, v130, v58
	v_fmac_f32_e32 v189, v130, v59
	v_fmac_f32_e32 v190, v131, v56
	v_fmac_f32_e32 v191, v131, v57
	v_fmac_f32_e32 v192, v131, v58
	v_fmac_f32_e32 v193, v131, v59
	v_fmac_f32_e32 v186, v194, v52
	v_fmac_f32_e32 v187, v194, v53
	v_fmac_f32_e32 v188, v194, v54
	v_fmac_f32_e32 v189, v194, v55
	v_fmac_f32_e32 v190, v195, v52
	v_fmac_f32_e32 v191, v195, v53
	v_fmac_f32_e32 v192, v195, v54
	v_fmac_f32_e32 v193, v195, v55
	ds_read_b128 v[48:51], v152 offset:10240
	ds_read_b128 v[52:55], v152 offset:18432
	ds_read_b128 v[56:59], v152 offset:26624
	ds_read_b128 v[60:63], v152 offset:34816
	ds_read_b64 v[130:131], v69 offset:2048
	s_waitcnt lgkmcnt(11)
	v_mul_f32_e32 v194, v186, v8
	v_mul_f32_e32 v195, v190, v8
	v_mul_f32_e32 v238, v186, v20
	v_mul_f32_e32 v239, v190, v20
	v_fmac_f32_e32 v194, v187, v9
	v_fmac_f32_e32 v195, v191, v9
	v_fmac_f32_e32 v238, v187, v21
	v_fmac_f32_e32 v239, v191, v21
	v_fmac_f32_e32 v194, v188, v10
	v_fmac_f32_e32 v195, v192, v10
	v_fmac_f32_e32 v238, v188, v22
	v_fmac_f32_e32 v239, v192, v22
	v_fmac_f32_e32 v194, v189, v11
	v_fmac_f32_e32 v195, v193, v11
	v_fmac_f32_e32 v238, v189, v23
	v_fmac_f32_e32 v239, v193, v23
	v_add_f32_dpp v194, v194, v194 quad_perm:[1,0,3,2] row_mask:0xf bank_mask:0xf bound_ctrl:1
	v_add_f32_dpp v195, v195, v195 quad_perm:[1,0,3,2] row_mask:0xf bank_mask:0xf bound_ctrl:1
	v_add_f32_dpp v238, v238, v238 quad_perm:[1,0,3,2] row_mask:0xf bank_mask:0xf bound_ctrl:1
	v_add_f32_dpp v239, v239, v239 quad_perm:[1,0,3,2] row_mask:0xf bank_mask:0xf bound_ctrl:1
	v_add_f32_dpp v194, v194, v194 quad_perm:[2,3,0,1] row_mask:0xf bank_mask:0xf bound_ctrl:1
	v_add_f32_dpp v195, v195, v195 quad_perm:[2,3,0,1] row_mask:0xf bank_mask:0xf bound_ctrl:1
	v_add_f32_dpp v238, v238, v238 quad_perm:[2,3,0,1] row_mask:0xf bank_mask:0xf bound_ctrl:1
	v_add_f32_dpp v239, v239, v239 quad_perm:[2,3,0,1] row_mask:0xf bank_mask:0xf bound_ctrl:1
	v_add_f32_dpp v194, v194, v194 row_half_mirror row_mask:0xf bank_mask:0xf bound_ctrl:1
	v_add_f32_dpp v195, v195, v195 row_half_mirror row_mask:0xf bank_mask:0xf bound_ctrl:1
	v_add_f32_dpp v238, v238, v238 row_half_mirror row_mask:0xf bank_mask:0xf bound_ctrl:1
	v_add_f32_dpp v239, v239, v239 row_half_mirror row_mask:0xf bank_mask:0xf bound_ctrl:1
	v_add_f32_dpp v194, v194, v194 row_mirror row_mask:0xf bank_mask:0xf bound_ctrl:1
	v_add_f32_dpp v195, v195, v195 row_mirror row_mask:0xf bank_mask:0xf bound_ctrl:1
	v_fmac_f32_e32 v186, v64, v16
	v_fmac_f32_e32 v187, v64, v17
	v_fmac_f32_e32 v188, v64, v18
	v_fmac_f32_e32 v189, v64, v19
	v_fmac_f32_e32 v190, v65, v16
	v_fmac_f32_e32 v191, v65, v17
	v_fmac_f32_e32 v192, v65, v18
	v_fmac_f32_e32 v193, v65, v19
	v_fmac_f32_e32 v186, v194, v12
	v_fmac_f32_e32 v187, v194, v13
	v_fmac_f32_e32 v188, v194, v14
	v_fmac_f32_e32 v189, v194, v15
	v_fmac_f32_e32 v190, v195, v12
	v_fmac_f32_e32 v191, v195, v13
	v_fmac_f32_e32 v192, v195, v14
	v_fmac_f32_e32 v193, v195, v15
	s_mov_b64 exec, s[8:9]
	ds_write2st64_b64 v161, v[132:133], v[238:239] offset0:11 offset1:10
	s_mov_b64 exec, -1
	ds_read_b128 v[8:11], v152 offset:9984
	ds_read_b128 v[12:15], v152 offset:18176
	ds_read_b128 v[16:19], v152 offset:26368
	ds_read_b128 v[20:23], v152 offset:34560
	ds_read_b64 v[64:65], v69 offset:1792
	s_waitcnt lgkmcnt(11)
	v_mul_f32_e32 v194, v186, v28
	v_mul_f32_e32 v195, v190, v28
	v_mul_f32_e32 v132, v186, v40
	v_mul_f32_e32 v133, v190, v40
	v_fmac_f32_e32 v194, v187, v29
	v_fmac_f32_e32 v195, v191, v29
	v_fmac_f32_e32 v132, v187, v41
	v_fmac_f32_e32 v133, v191, v41
	v_fmac_f32_e32 v194, v188, v30
	v_fmac_f32_e32 v195, v192, v30
	v_fmac_f32_e32 v132, v188, v42
	v_fmac_f32_e32 v133, v192, v42
	v_fmac_f32_e32 v194, v189, v31
	v_fmac_f32_e32 v195, v193, v31
	v_fmac_f32_e32 v132, v189, v43
	v_fmac_f32_e32 v133, v193, v43
	v_add_f32_dpp v194, v194, v194 quad_perm:[1,0,3,2] row_mask:0xf bank_mask:0xf bound_ctrl:1
	v_add_f32_dpp v195, v195, v195 quad_perm:[1,0,3,2] row_mask:0xf bank_mask:0xf bound_ctrl:1
	v_add_f32_dpp v132, v132, v132 quad_perm:[1,0,3,2] row_mask:0xf bank_mask:0xf bound_ctrl:1
	v_add_f32_dpp v133, v133, v133 quad_perm:[1,0,3,2] row_mask:0xf bank_mask:0xf bound_ctrl:1
	v_add_f32_dpp v194, v194, v194 quad_perm:[2,3,0,1] row_mask:0xf bank_mask:0xf bound_ctrl:1
	v_add_f32_dpp v195, v195, v195 quad_perm:[2,3,0,1] row_mask:0xf bank_mask:0xf bound_ctrl:1
	v_add_f32_dpp v132, v132, v132 quad_perm:[2,3,0,1] row_mask:0xf bank_mask:0xf bound_ctrl:1
	v_add_f32_dpp v133, v133, v133 quad_perm:[2,3,0,1] row_mask:0xf bank_mask:0xf bound_ctrl:1
	v_add_f32_dpp v194, v194, v194 row_half_mirror row_mask:0xf bank_mask:0xf bound_ctrl:1
	v_add_f32_dpp v195, v195, v195 row_half_mirror row_mask:0xf bank_mask:0xf bound_ctrl:1
	v_add_f32_dpp v132, v132, v132 row_half_mirror row_mask:0xf bank_mask:0xf bound_ctrl:1
	v_add_f32_dpp v133, v133, v133 row_half_mirror row_mask:0xf bank_mask:0xf bound_ctrl:1
	v_add_f32_dpp v194, v194, v194 row_mirror row_mask:0xf bank_mask:0xf bound_ctrl:1
	v_add_f32_dpp v195, v195, v195 row_mirror row_mask:0xf bank_mask:0xf bound_ctrl:1
	v_fmac_f32_e32 v186, v66, v36
	v_fmac_f32_e32 v187, v66, v37
	v_fmac_f32_e32 v188, v66, v38
	v_fmac_f32_e32 v189, v66, v39
	v_fmac_f32_e32 v190, v67, v36
	v_fmac_f32_e32 v191, v67, v37
	v_fmac_f32_e32 v192, v67, v38
	v_fmac_f32_e32 v193, v67, v39
	v_fmac_f32_e32 v186, v194, v32
	v_fmac_f32_e32 v187, v194, v33
	v_fmac_f32_e32 v188, v194, v34
	v_fmac_f32_e32 v189, v194, v35
	v_fmac_f32_e32 v190, v195, v32
	v_fmac_f32_e32 v191, v195, v33
	v_fmac_f32_e32 v192, v195, v34
	v_fmac_f32_e32 v193, v195, v35
	ds_read_b128 v[28:31], v152 offset:9728
	ds_read_b128 v[32:35], v152 offset:17920
	ds_read_b128 v[36:39], v152 offset:26112
	ds_read_b128 v[40:43], v152 offset:34304
	ds_read_b64 v[66:67], v69 offset:1536
	s_waitcnt lgkmcnt(11)
	v_mul_f32_e32 v194, v186, v48
	v_mul_f32_e32 v195, v190, v48
	v_mul_f32_e32 v238, v186, v60
	v_mul_f32_e32 v239, v190, v60
	v_fmac_f32_e32 v194, v187, v49
	v_fmac_f32_e32 v195, v191, v49
	v_fmac_f32_e32 v238, v187, v61
	v_fmac_f32_e32 v239, v191, v61
	v_fmac_f32_e32 v194, v188, v50
	v_fmac_f32_e32 v195, v192, v50
	v_fmac_f32_e32 v238, v188, v62
	v_fmac_f32_e32 v239, v192, v62
	v_fmac_f32_e32 v194, v189, v51
	v_fmac_f32_e32 v195, v193, v51
	v_fmac_f32_e32 v238, v189, v63
	v_fmac_f32_e32 v239, v193, v63
	v_add_f32_dpp v194, v194, v194 quad_perm:[1,0,3,2] row_mask:0xf bank_mask:0xf bound_ctrl:1
	v_add_f32_dpp v195, v195, v195 quad_perm:[1,0,3,2] row_mask:0xf bank_mask:0xf bound_ctrl:1
	v_add_f32_dpp v238, v238, v238 quad_perm:[1,0,3,2] row_mask:0xf bank_mask:0xf bound_ctrl:1
	v_add_f32_dpp v239, v239, v239 quad_perm:[1,0,3,2] row_mask:0xf bank_mask:0xf bound_ctrl:1
	v_add_f32_dpp v194, v194, v194 quad_perm:[2,3,0,1] row_mask:0xf bank_mask:0xf bound_ctrl:1
	v_add_f32_dpp v195, v195, v195 quad_perm:[2,3,0,1] row_mask:0xf bank_mask:0xf bound_ctrl:1
	v_add_f32_dpp v238, v238, v238 quad_perm:[2,3,0,1] row_mask:0xf bank_mask:0xf bound_ctrl:1
	v_add_f32_dpp v239, v239, v239 quad_perm:[2,3,0,1] row_mask:0xf bank_mask:0xf bound_ctrl:1
	v_add_f32_dpp v194, v194, v194 row_half_mirror row_mask:0xf bank_mask:0xf bound_ctrl:1
	v_add_f32_dpp v195, v195, v195 row_half_mirror row_mask:0xf bank_mask:0xf bound_ctrl:1
	v_add_f32_dpp v238, v238, v238 row_half_mirror row_mask:0xf bank_mask:0xf bound_ctrl:1
	v_add_f32_dpp v239, v239, v239 row_half_mirror row_mask:0xf bank_mask:0xf bound_ctrl:1
	v_add_f32_dpp v194, v194, v194 row_mirror row_mask:0xf bank_mask:0xf bound_ctrl:1
	v_add_f32_dpp v195, v195, v195 row_mirror row_mask:0xf bank_mask:0xf bound_ctrl:1
	v_fmac_f32_e32 v186, v130, v56
	v_fmac_f32_e32 v187, v130, v57
	v_fmac_f32_e32 v188, v130, v58
	v_fmac_f32_e32 v189, v130, v59
	v_fmac_f32_e32 v190, v131, v56
	v_fmac_f32_e32 v191, v131, v57
	v_fmac_f32_e32 v192, v131, v58
	v_fmac_f32_e32 v193, v131, v59
	v_fmac_f32_e32 v186, v194, v52
	v_fmac_f32_e32 v187, v194, v53
	v_fmac_f32_e32 v188, v194, v54
	v_fmac_f32_e32 v189, v194, v55
	v_fmac_f32_e32 v190, v195, v52
	v_fmac_f32_e32 v191, v195, v53
	v_fmac_f32_e32 v192, v195, v54
	v_fmac_f32_e32 v193, v195, v55
	s_mov_b64 exec, s[8:9]
	ds_write2st64_b64 v161, v[132:133], v[238:239] offset0:9 offset1:8
	s_mov_b64 exec, -1
	ds_read_b128 v[48:51], v152 offset:9472
	ds_read_b128 v[52:55], v152 offset:17664
	ds_read_b128 v[56:59], v152 offset:25856
	ds_read_b128 v[60:63], v152 offset:34048
	ds_read_b64 v[130:131], v69 offset:1280
	s_waitcnt lgkmcnt(11)
	v_mul_f32_e32 v194, v186, v8
	v_mul_f32_e32 v195, v190, v8
	v_mul_f32_e32 v132, v186, v20
	v_mul_f32_e32 v133, v190, v20
	v_fmac_f32_e32 v194, v187, v9
	v_fmac_f32_e32 v195, v191, v9
	v_fmac_f32_e32 v132, v187, v21
	v_fmac_f32_e32 v133, v191, v21
	v_fmac_f32_e32 v194, v188, v10
	v_fmac_f32_e32 v195, v192, v10
	v_fmac_f32_e32 v132, v188, v22
	v_fmac_f32_e32 v133, v192, v22
	v_fmac_f32_e32 v194, v189, v11
	v_fmac_f32_e32 v195, v193, v11
	v_fmac_f32_e32 v132, v189, v23
	v_fmac_f32_e32 v133, v193, v23
	v_add_f32_dpp v194, v194, v194 quad_perm:[1,0,3,2] row_mask:0xf bank_mask:0xf bound_ctrl:1
	v_add_f32_dpp v195, v195, v195 quad_perm:[1,0,3,2] row_mask:0xf bank_mask:0xf bound_ctrl:1
	v_add_f32_dpp v132, v132, v132 quad_perm:[1,0,3,2] row_mask:0xf bank_mask:0xf bound_ctrl:1
	v_add_f32_dpp v133, v133, v133 quad_perm:[1,0,3,2] row_mask:0xf bank_mask:0xf bound_ctrl:1
	v_add_f32_dpp v194, v194, v194 quad_perm:[2,3,0,1] row_mask:0xf bank_mask:0xf bound_ctrl:1
	v_add_f32_dpp v195, v195, v195 quad_perm:[2,3,0,1] row_mask:0xf bank_mask:0xf bound_ctrl:1
	v_add_f32_dpp v132, v132, v132 quad_perm:[2,3,0,1] row_mask:0xf bank_mask:0xf bound_ctrl:1
	v_add_f32_dpp v133, v133, v133 quad_perm:[2,3,0,1] row_mask:0xf bank_mask:0xf bound_ctrl:1
	v_add_f32_dpp v194, v194, v194 row_half_mirror row_mask:0xf bank_mask:0xf bound_ctrl:1
	v_add_f32_dpp v195, v195, v195 row_half_mirror row_mask:0xf bank_mask:0xf bound_ctrl:1
	v_add_f32_dpp v132, v132, v132 row_half_mirror row_mask:0xf bank_mask:0xf bound_ctrl:1
	v_add_f32_dpp v133, v133, v133 row_half_mirror row_mask:0xf bank_mask:0xf bound_ctrl:1
	v_add_f32_dpp v194, v194, v194 row_mirror row_mask:0xf bank_mask:0xf bound_ctrl:1
	v_add_f32_dpp v195, v195, v195 row_mirror row_mask:0xf bank_mask:0xf bound_ctrl:1
	v_fmac_f32_e32 v186, v64, v16
	v_fmac_f32_e32 v187, v64, v17
	v_fmac_f32_e32 v188, v64, v18
	v_fmac_f32_e32 v189, v64, v19
	v_fmac_f32_e32 v190, v65, v16
	v_fmac_f32_e32 v191, v65, v17
	v_fmac_f32_e32 v192, v65, v18
	v_fmac_f32_e32 v193, v65, v19
	v_fmac_f32_e32 v186, v194, v12
	v_fmac_f32_e32 v187, v194, v13
	v_fmac_f32_e32 v188, v194, v14
	v_fmac_f32_e32 v189, v194, v15
	v_fmac_f32_e32 v190, v195, v12
	v_fmac_f32_e32 v191, v195, v13
	v_fmac_f32_e32 v192, v195, v14
	v_fmac_f32_e32 v193, v195, v15
	ds_read_b128 v[8:11], v152 offset:9216
	ds_read_b128 v[12:15], v152 offset:17408
	ds_read_b128 v[16:19], v152 offset:25600
	ds_read_b128 v[20:23], v152 offset:33792
	ds_read_b64 v[64:65], v69 offset:1024
	s_waitcnt lgkmcnt(11)
	v_mul_f32_e32 v194, v186, v28
	v_mul_f32_e32 v195, v190, v28
	v_mul_f32_e32 v238, v186, v40
	v_mul_f32_e32 v239, v190, v40
	v_fmac_f32_e32 v194, v187, v29
	v_fmac_f32_e32 v195, v191, v29
	v_fmac_f32_e32 v238, v187, v41
	v_fmac_f32_e32 v239, v191, v41
	v_fmac_f32_e32 v194, v188, v30
	v_fmac_f32_e32 v195, v192, v30
	v_fmac_f32_e32 v238, v188, v42
	v_fmac_f32_e32 v239, v192, v42
	v_fmac_f32_e32 v194, v189, v31
	v_fmac_f32_e32 v195, v193, v31
	v_fmac_f32_e32 v238, v189, v43
	v_fmac_f32_e32 v239, v193, v43
	v_add_f32_dpp v194, v194, v194 quad_perm:[1,0,3,2] row_mask:0xf bank_mask:0xf bound_ctrl:1
	v_add_f32_dpp v195, v195, v195 quad_perm:[1,0,3,2] row_mask:0xf bank_mask:0xf bound_ctrl:1
	v_add_f32_dpp v238, v238, v238 quad_perm:[1,0,3,2] row_mask:0xf bank_mask:0xf bound_ctrl:1
	v_add_f32_dpp v239, v239, v239 quad_perm:[1,0,3,2] row_mask:0xf bank_mask:0xf bound_ctrl:1
	v_add_f32_dpp v194, v194, v194 quad_perm:[2,3,0,1] row_mask:0xf bank_mask:0xf bound_ctrl:1
	v_add_f32_dpp v195, v195, v195 quad_perm:[2,3,0,1] row_mask:0xf bank_mask:0xf bound_ctrl:1
	v_add_f32_dpp v238, v238, v238 quad_perm:[2,3,0,1] row_mask:0xf bank_mask:0xf bound_ctrl:1
	v_add_f32_dpp v239, v239, v239 quad_perm:[2,3,0,1] row_mask:0xf bank_mask:0xf bound_ctrl:1
	v_add_f32_dpp v194, v194, v194 row_half_mirror row_mask:0xf bank_mask:0xf bound_ctrl:1
	v_add_f32_dpp v195, v195, v195 row_half_mirror row_mask:0xf bank_mask:0xf bound_ctrl:1
	v_add_f32_dpp v238, v238, v238 row_half_mirror row_mask:0xf bank_mask:0xf bound_ctrl:1
	v_add_f32_dpp v239, v239, v239 row_half_mirror row_mask:0xf bank_mask:0xf bound_ctrl:1
	v_add_f32_dpp v194, v194, v194 row_mirror row_mask:0xf bank_mask:0xf bound_ctrl:1
	v_add_f32_dpp v195, v195, v195 row_mirror row_mask:0xf bank_mask:0xf bound_ctrl:1
	v_fmac_f32_e32 v186, v66, v36
	v_fmac_f32_e32 v187, v66, v37
	v_fmac_f32_e32 v188, v66, v38
	v_fmac_f32_e32 v189, v66, v39
	v_fmac_f32_e32 v190, v67, v36
	v_fmac_f32_e32 v191, v67, v37
	v_fmac_f32_e32 v192, v67, v38
	v_fmac_f32_e32 v193, v67, v39
	v_fmac_f32_e32 v186, v194, v32
	v_fmac_f32_e32 v187, v194, v33
	v_fmac_f32_e32 v188, v194, v34
	v_fmac_f32_e32 v189, v194, v35
	v_fmac_f32_e32 v190, v195, v32
	v_fmac_f32_e32 v191, v195, v33
	v_fmac_f32_e32 v192, v195, v34
	v_fmac_f32_e32 v193, v195, v35
	s_mov_b64 exec, s[8:9]
	ds_write2st64_b64 v161, v[132:133], v[238:239] offset0:7 offset1:6
	s_mov_b64 exec, -1
	ds_read_b128 v[28:31], v152 offset:8960
	ds_read_b128 v[32:35], v152 offset:17152
	ds_read_b128 v[36:39], v152 offset:25344
	ds_read_b128 v[40:43], v152 offset:33536
	ds_read_b64 v[66:67], v69 offset:768
	s_waitcnt lgkmcnt(11)
	v_mul_f32_e32 v194, v186, v48
	v_mul_f32_e32 v195, v190, v48
	v_mul_f32_e32 v132, v186, v60
	v_mul_f32_e32 v133, v190, v60
	v_fmac_f32_e32 v194, v187, v49
	v_fmac_f32_e32 v195, v191, v49
	v_fmac_f32_e32 v132, v187, v61
	v_fmac_f32_e32 v133, v191, v61
	v_fmac_f32_e32 v194, v188, v50
	v_fmac_f32_e32 v195, v192, v50
	v_fmac_f32_e32 v132, v188, v62
	v_fmac_f32_e32 v133, v192, v62
	v_fmac_f32_e32 v194, v189, v51
	v_fmac_f32_e32 v195, v193, v51
	v_fmac_f32_e32 v132, v189, v63
	v_fmac_f32_e32 v133, v193, v63
	v_add_f32_dpp v194, v194, v194 quad_perm:[1,0,3,2] row_mask:0xf bank_mask:0xf bound_ctrl:1
	v_add_f32_dpp v195, v195, v195 quad_perm:[1,0,3,2] row_mask:0xf bank_mask:0xf bound_ctrl:1
	v_add_f32_dpp v132, v132, v132 quad_perm:[1,0,3,2] row_mask:0xf bank_mask:0xf bound_ctrl:1
	v_add_f32_dpp v133, v133, v133 quad_perm:[1,0,3,2] row_mask:0xf bank_mask:0xf bound_ctrl:1
	v_add_f32_dpp v194, v194, v194 quad_perm:[2,3,0,1] row_mask:0xf bank_mask:0xf bound_ctrl:1
	v_add_f32_dpp v195, v195, v195 quad_perm:[2,3,0,1] row_mask:0xf bank_mask:0xf bound_ctrl:1
	v_add_f32_dpp v132, v132, v132 quad_perm:[2,3,0,1] row_mask:0xf bank_mask:0xf bound_ctrl:1
	v_add_f32_dpp v133, v133, v133 quad_perm:[2,3,0,1] row_mask:0xf bank_mask:0xf bound_ctrl:1
	v_add_f32_dpp v194, v194, v194 row_half_mirror row_mask:0xf bank_mask:0xf bound_ctrl:1
	v_add_f32_dpp v195, v195, v195 row_half_mirror row_mask:0xf bank_mask:0xf bound_ctrl:1
	v_add_f32_dpp v132, v132, v132 row_half_mirror row_mask:0xf bank_mask:0xf bound_ctrl:1
	v_add_f32_dpp v133, v133, v133 row_half_mirror row_mask:0xf bank_mask:0xf bound_ctrl:1
	v_add_f32_dpp v194, v194, v194 row_mirror row_mask:0xf bank_mask:0xf bound_ctrl:1
	v_add_f32_dpp v195, v195, v195 row_mirror row_mask:0xf bank_mask:0xf bound_ctrl:1
	v_fmac_f32_e32 v186, v130, v56
	v_fmac_f32_e32 v187, v130, v57
	v_fmac_f32_e32 v188, v130, v58
	v_fmac_f32_e32 v189, v130, v59
	v_fmac_f32_e32 v190, v131, v56
	v_fmac_f32_e32 v191, v131, v57
	v_fmac_f32_e32 v192, v131, v58
	v_fmac_f32_e32 v193, v131, v59
	v_fmac_f32_e32 v186, v194, v52
	v_fmac_f32_e32 v187, v194, v53
	v_fmac_f32_e32 v188, v194, v54
	v_fmac_f32_e32 v189, v194, v55
	v_fmac_f32_e32 v190, v195, v52
	v_fmac_f32_e32 v191, v195, v53
	v_fmac_f32_e32 v192, v195, v54
	v_fmac_f32_e32 v193, v195, v55
	ds_read_b128 v[48:51], v152 offset:8704
	ds_read_b128 v[52:55], v152 offset:16896
	ds_read_b128 v[56:59], v152 offset:25088
	ds_read_b128 v[60:63], v152 offset:33280
	ds_read_b64 v[130:131], v69 offset:512
	s_waitcnt lgkmcnt(11)
	v_mul_f32_e32 v194, v186, v8
	v_mul_f32_e32 v195, v190, v8
	v_mul_f32_e32 v238, v186, v20
	v_mul_f32_e32 v239, v190, v20
	v_fmac_f32_e32 v194, v187, v9
	v_fmac_f32_e32 v195, v191, v9
	v_fmac_f32_e32 v238, v187, v21
	v_fmac_f32_e32 v239, v191, v21
	v_fmac_f32_e32 v194, v188, v10
	v_fmac_f32_e32 v195, v192, v10
	v_fmac_f32_e32 v238, v188, v22
	v_fmac_f32_e32 v239, v192, v22
	v_fmac_f32_e32 v194, v189, v11
	v_fmac_f32_e32 v195, v193, v11
	v_fmac_f32_e32 v238, v189, v23
	v_fmac_f32_e32 v239, v193, v23
	v_add_f32_dpp v194, v194, v194 quad_perm:[1,0,3,2] row_mask:0xf bank_mask:0xf bound_ctrl:1
	v_add_f32_dpp v195, v195, v195 quad_perm:[1,0,3,2] row_mask:0xf bank_mask:0xf bound_ctrl:1
	v_add_f32_dpp v238, v238, v238 quad_perm:[1,0,3,2] row_mask:0xf bank_mask:0xf bound_ctrl:1
	v_add_f32_dpp v239, v239, v239 quad_perm:[1,0,3,2] row_mask:0xf bank_mask:0xf bound_ctrl:1
	v_add_f32_dpp v194, v194, v194 quad_perm:[2,3,0,1] row_mask:0xf bank_mask:0xf bound_ctrl:1
	v_add_f32_dpp v195, v195, v195 quad_perm:[2,3,0,1] row_mask:0xf bank_mask:0xf bound_ctrl:1
	v_add_f32_dpp v238, v238, v238 quad_perm:[2,3,0,1] row_mask:0xf bank_mask:0xf bound_ctrl:1
	v_add_f32_dpp v239, v239, v239 quad_perm:[2,3,0,1] row_mask:0xf bank_mask:0xf bound_ctrl:1
	v_add_f32_dpp v194, v194, v194 row_half_mirror row_mask:0xf bank_mask:0xf bound_ctrl:1
	v_add_f32_dpp v195, v195, v195 row_half_mirror row_mask:0xf bank_mask:0xf bound_ctrl:1
	v_add_f32_dpp v238, v238, v238 row_half_mirror row_mask:0xf bank_mask:0xf bound_ctrl:1
	v_add_f32_dpp v239, v239, v239 row_half_mirror row_mask:0xf bank_mask:0xf bound_ctrl:1
	v_add_f32_dpp v194, v194, v194 row_mirror row_mask:0xf bank_mask:0xf bound_ctrl:1
	v_add_f32_dpp v195, v195, v195 row_mirror row_mask:0xf bank_mask:0xf bound_ctrl:1
	v_fmac_f32_e32 v186, v64, v16
	v_fmac_f32_e32 v187, v64, v17
	v_fmac_f32_e32 v188, v64, v18
	v_fmac_f32_e32 v189, v64, v19
	v_fmac_f32_e32 v190, v65, v16
	v_fmac_f32_e32 v191, v65, v17
	v_fmac_f32_e32 v192, v65, v18
	v_fmac_f32_e32 v193, v65, v19
	v_fmac_f32_e32 v186, v194, v12
	v_fmac_f32_e32 v187, v194, v13
	v_fmac_f32_e32 v188, v194, v14
	v_fmac_f32_e32 v189, v194, v15
	v_fmac_f32_e32 v190, v195, v12
	v_fmac_f32_e32 v191, v195, v13
	v_fmac_f32_e32 v192, v195, v14
	v_fmac_f32_e32 v193, v195, v15
	s_mov_b64 exec, s[8:9]
	ds_write2st64_b64 v161, v[132:133], v[238:239] offset0:5 offset1:4
	s_mov_b64 exec, -1
	ds_read_b128 v[8:11], v152 offset:8448
	ds_read_b128 v[12:15], v152 offset:16640
	ds_read_b128 v[16:19], v152 offset:24832
	ds_read_b128 v[20:23], v152 offset:33024
	ds_read_b64 v[64:65], v69 offset:256
	s_waitcnt lgkmcnt(11)
	v_mul_f32_e32 v194, v186, v28
	v_mul_f32_e32 v195, v190, v28
	v_mul_f32_e32 v132, v186, v40
	v_mul_f32_e32 v133, v190, v40
	v_fmac_f32_e32 v194, v187, v29
	v_fmac_f32_e32 v195, v191, v29
	v_fmac_f32_e32 v132, v187, v41
	v_fmac_f32_e32 v133, v191, v41
	v_fmac_f32_e32 v194, v188, v30
	v_fmac_f32_e32 v195, v192, v30
	v_fmac_f32_e32 v132, v188, v42
	v_fmac_f32_e32 v133, v192, v42
	v_fmac_f32_e32 v194, v189, v31
	v_fmac_f32_e32 v195, v193, v31
	v_fmac_f32_e32 v132, v189, v43
	v_fmac_f32_e32 v133, v193, v43
	v_add_f32_dpp v194, v194, v194 quad_perm:[1,0,3,2] row_mask:0xf bank_mask:0xf bound_ctrl:1
	v_add_f32_dpp v195, v195, v195 quad_perm:[1,0,3,2] row_mask:0xf bank_mask:0xf bound_ctrl:1
	v_add_f32_dpp v132, v132, v132 quad_perm:[1,0,3,2] row_mask:0xf bank_mask:0xf bound_ctrl:1
	v_add_f32_dpp v133, v133, v133 quad_perm:[1,0,3,2] row_mask:0xf bank_mask:0xf bound_ctrl:1
	v_add_f32_dpp v194, v194, v194 quad_perm:[2,3,0,1] row_mask:0xf bank_mask:0xf bound_ctrl:1
	v_add_f32_dpp v195, v195, v195 quad_perm:[2,3,0,1] row_mask:0xf bank_mask:0xf bound_ctrl:1
	v_add_f32_dpp v132, v132, v132 quad_perm:[2,3,0,1] row_mask:0xf bank_mask:0xf bound_ctrl:1
	v_add_f32_dpp v133, v133, v133 quad_perm:[2,3,0,1] row_mask:0xf bank_mask:0xf bound_ctrl:1
	v_add_f32_dpp v194, v194, v194 row_half_mirror row_mask:0xf bank_mask:0xf bound_ctrl:1
	v_add_f32_dpp v195, v195, v195 row_half_mirror row_mask:0xf bank_mask:0xf bound_ctrl:1
	v_add_f32_dpp v132, v132, v132 row_half_mirror row_mask:0xf bank_mask:0xf bound_ctrl:1
	v_add_f32_dpp v133, v133, v133 row_half_mirror row_mask:0xf bank_mask:0xf bound_ctrl:1
	v_add_f32_dpp v194, v194, v194 row_mirror row_mask:0xf bank_mask:0xf bound_ctrl:1
	v_add_f32_dpp v195, v195, v195 row_mirror row_mask:0xf bank_mask:0xf bound_ctrl:1
	v_fmac_f32_e32 v186, v66, v36
	v_fmac_f32_e32 v187, v66, v37
	v_fmac_f32_e32 v188, v66, v38
	v_fmac_f32_e32 v189, v66, v39
	v_fmac_f32_e32 v190, v67, v36
	v_fmac_f32_e32 v191, v67, v37
	v_fmac_f32_e32 v192, v67, v38
	v_fmac_f32_e32 v193, v67, v39
	v_fmac_f32_e32 v186, v194, v32
	v_fmac_f32_e32 v187, v194, v33
	v_fmac_f32_e32 v188, v194, v34
	v_fmac_f32_e32 v189, v194, v35
	v_fmac_f32_e32 v190, v195, v32
	v_fmac_f32_e32 v191, v195, v33
	v_fmac_f32_e32 v192, v195, v34
	v_fmac_f32_e32 v193, v195, v35
	ds_read_b128 v[28:31], v152 offset:8192
	ds_read_b128 v[32:35], v152 offset:16384
	ds_read_b128 v[36:39], v152 offset:24576
	ds_read_b128 v[40:43], v152 offset:32768
	ds_read_b64 v[66:67], v69
	s_waitcnt lgkmcnt(11)
	v_mul_f32_e32 v194, v186, v48
	v_mul_f32_e32 v195, v190, v48
	v_mul_f32_e32 v238, v186, v60
	v_mul_f32_e32 v239, v190, v60
	v_fmac_f32_e32 v194, v187, v49
	v_fmac_f32_e32 v195, v191, v49
	v_fmac_f32_e32 v238, v187, v61
	v_fmac_f32_e32 v239, v191, v61
	v_fmac_f32_e32 v194, v188, v50
	v_fmac_f32_e32 v195, v192, v50
	v_fmac_f32_e32 v238, v188, v62
	v_fmac_f32_e32 v239, v192, v62
	v_fmac_f32_e32 v194, v189, v51
	v_fmac_f32_e32 v195, v193, v51
	v_fmac_f32_e32 v238, v189, v63
	v_fmac_f32_e32 v239, v193, v63
	v_add_f32_dpp v194, v194, v194 quad_perm:[1,0,3,2] row_mask:0xf bank_mask:0xf bound_ctrl:1
	v_add_f32_dpp v195, v195, v195 quad_perm:[1,0,3,2] row_mask:0xf bank_mask:0xf bound_ctrl:1
	v_add_f32_dpp v238, v238, v238 quad_perm:[1,0,3,2] row_mask:0xf bank_mask:0xf bound_ctrl:1
	v_add_f32_dpp v239, v239, v239 quad_perm:[1,0,3,2] row_mask:0xf bank_mask:0xf bound_ctrl:1
	v_add_f32_dpp v194, v194, v194 quad_perm:[2,3,0,1] row_mask:0xf bank_mask:0xf bound_ctrl:1
	v_add_f32_dpp v195, v195, v195 quad_perm:[2,3,0,1] row_mask:0xf bank_mask:0xf bound_ctrl:1
	v_add_f32_dpp v238, v238, v238 quad_perm:[2,3,0,1] row_mask:0xf bank_mask:0xf bound_ctrl:1
	v_add_f32_dpp v239, v239, v239 quad_perm:[2,3,0,1] row_mask:0xf bank_mask:0xf bound_ctrl:1
	v_add_f32_dpp v194, v194, v194 row_half_mirror row_mask:0xf bank_mask:0xf bound_ctrl:1
	v_add_f32_dpp v195, v195, v195 row_half_mirror row_mask:0xf bank_mask:0xf bound_ctrl:1
	v_add_f32_dpp v238, v238, v238 row_half_mirror row_mask:0xf bank_mask:0xf bound_ctrl:1
	v_add_f32_dpp v239, v239, v239 row_half_mirror row_mask:0xf bank_mask:0xf bound_ctrl:1
	v_add_f32_dpp v194, v194, v194 row_mirror row_mask:0xf bank_mask:0xf bound_ctrl:1
	v_add_f32_dpp v195, v195, v195 row_mirror row_mask:0xf bank_mask:0xf bound_ctrl:1
	v_fmac_f32_e32 v186, v130, v56
	v_fmac_f32_e32 v187, v130, v57
	v_fmac_f32_e32 v188, v130, v58
	v_fmac_f32_e32 v189, v130, v59
	v_fmac_f32_e32 v190, v131, v56
	v_fmac_f32_e32 v191, v131, v57
	v_fmac_f32_e32 v192, v131, v58
	v_fmac_f32_e32 v193, v131, v59
	v_fmac_f32_e32 v186, v194, v52
	v_fmac_f32_e32 v187, v194, v53
	v_fmac_f32_e32 v188, v194, v54
	v_fmac_f32_e32 v189, v194, v55
	v_fmac_f32_e32 v190, v195, v52
	v_fmac_f32_e32 v191, v195, v53
	v_fmac_f32_e32 v192, v195, v54
	v_fmac_f32_e32 v193, v195, v55
	s_mov_b64 exec, s[8:9]
	ds_write2st64_b64 v161, v[132:133], v[238:239] offset0:3 offset1:2
	s_mov_b64 exec, -1
	s_waitcnt lgkmcnt(6)
	v_mul_f32_e32 v194, v186, v8
	v_mul_f32_e32 v195, v190, v8
	v_mul_f32_e32 v132, v186, v20
	v_mul_f32_e32 v133, v190, v20
	v_fmac_f32_e32 v194, v187, v9
	v_fmac_f32_e32 v195, v191, v9
	v_fmac_f32_e32 v132, v187, v21
	v_fmac_f32_e32 v133, v191, v21
	v_fmac_f32_e32 v194, v188, v10
	v_fmac_f32_e32 v195, v192, v10
	v_fmac_f32_e32 v132, v188, v22
	v_fmac_f32_e32 v133, v192, v22
	v_fmac_f32_e32 v194, v189, v11
	v_fmac_f32_e32 v195, v193, v11
	v_fmac_f32_e32 v132, v189, v23
	v_fmac_f32_e32 v133, v193, v23
	v_add_f32_dpp v194, v194, v194 quad_perm:[1,0,3,2] row_mask:0xf bank_mask:0xf bound_ctrl:1
	v_add_f32_dpp v195, v195, v195 quad_perm:[1,0,3,2] row_mask:0xf bank_mask:0xf bound_ctrl:1
	v_add_f32_dpp v132, v132, v132 quad_perm:[1,0,3,2] row_mask:0xf bank_mask:0xf bound_ctrl:1
	v_add_f32_dpp v133, v133, v133 quad_perm:[1,0,3,2] row_mask:0xf bank_mask:0xf bound_ctrl:1
	v_add_f32_dpp v194, v194, v194 quad_perm:[2,3,0,1] row_mask:0xf bank_mask:0xf bound_ctrl:1
	v_add_f32_dpp v195, v195, v195 quad_perm:[2,3,0,1] row_mask:0xf bank_mask:0xf bound_ctrl:1
	v_add_f32_dpp v132, v132, v132 quad_perm:[2,3,0,1] row_mask:0xf bank_mask:0xf bound_ctrl:1
	v_add_f32_dpp v133, v133, v133 quad_perm:[2,3,0,1] row_mask:0xf bank_mask:0xf bound_ctrl:1
	v_add_f32_dpp v194, v194, v194 row_half_mirror row_mask:0xf bank_mask:0xf bound_ctrl:1
	v_add_f32_dpp v195, v195, v195 row_half_mirror row_mask:0xf bank_mask:0xf bound_ctrl:1
	v_add_f32_dpp v132, v132, v132 row_half_mirror row_mask:0xf bank_mask:0xf bound_ctrl:1
	v_add_f32_dpp v133, v133, v133 row_half_mirror row_mask:0xf bank_mask:0xf bound_ctrl:1
	v_add_f32_dpp v194, v194, v194 row_mirror row_mask:0xf bank_mask:0xf bound_ctrl:1
	v_add_f32_dpp v195, v195, v195 row_mirror row_mask:0xf bank_mask:0xf bound_ctrl:1
	v_fmac_f32_e32 v186, v64, v16
	v_fmac_f32_e32 v187, v64, v17
	v_fmac_f32_e32 v188, v64, v18
	v_fmac_f32_e32 v189, v64, v19
	v_fmac_f32_e32 v190, v65, v16
	v_fmac_f32_e32 v191, v65, v17
	v_fmac_f32_e32 v192, v65, v18
	v_fmac_f32_e32 v193, v65, v19
	v_fmac_f32_e32 v186, v194, v12
	v_fmac_f32_e32 v187, v194, v13
	v_fmac_f32_e32 v188, v194, v14
	v_fmac_f32_e32 v189, v194, v15
	v_fmac_f32_e32 v190, v195, v12
	v_fmac_f32_e32 v191, v195, v13
	v_fmac_f32_e32 v192, v195, v14
	v_fmac_f32_e32 v193, v195, v15
	s_waitcnt lgkmcnt(1)
	v_mul_f32_e32 v194, v186, v28
	v_mul_f32_e32 v195, v190, v28
	v_mul_f32_e32 v238, v186, v40
	v_mul_f32_e32 v239, v190, v40
	v_fmac_f32_e32 v194, v187, v29
	v_fmac_f32_e32 v195, v191, v29
	v_fmac_f32_e32 v238, v187, v41
	v_fmac_f32_e32 v239, v191, v41
	v_fmac_f32_e32 v194, v188, v30
	v_fmac_f32_e32 v195, v192, v30
	v_fmac_f32_e32 v238, v188, v42
	v_fmac_f32_e32 v239, v192, v42
	v_fmac_f32_e32 v194, v189, v31
	v_fmac_f32_e32 v195, v193, v31
	v_fmac_f32_e32 v238, v189, v43
	v_fmac_f32_e32 v239, v193, v43
	v_add_f32_dpp v194, v194, v194 quad_perm:[1,0,3,2] row_mask:0xf bank_mask:0xf bound_ctrl:1
	v_add_f32_dpp v195, v195, v195 quad_perm:[1,0,3,2] row_mask:0xf bank_mask:0xf bound_ctrl:1
	v_add_f32_dpp v238, v238, v238 quad_perm:[1,0,3,2] row_mask:0xf bank_mask:0xf bound_ctrl:1
	v_add_f32_dpp v239, v239, v239 quad_perm:[1,0,3,2] row_mask:0xf bank_mask:0xf bound_ctrl:1
	v_add_f32_dpp v194, v194, v194 quad_perm:[2,3,0,1] row_mask:0xf bank_mask:0xf bound_ctrl:1
	v_add_f32_dpp v195, v195, v195 quad_perm:[2,3,0,1] row_mask:0xf bank_mask:0xf bound_ctrl:1
	v_add_f32_dpp v238, v238, v238 quad_perm:[2,3,0,1] row_mask:0xf bank_mask:0xf bound_ctrl:1
	v_add_f32_dpp v239, v239, v239 quad_perm:[2,3,0,1] row_mask:0xf bank_mask:0xf bound_ctrl:1
	v_add_f32_dpp v194, v194, v194 row_half_mirror row_mask:0xf bank_mask:0xf bound_ctrl:1
	v_add_f32_dpp v195, v195, v195 row_half_mirror row_mask:0xf bank_mask:0xf bound_ctrl:1
	v_add_f32_dpp v238, v238, v238 row_half_mirror row_mask:0xf bank_mask:0xf bound_ctrl:1
	v_add_f32_dpp v239, v239, v239 row_half_mirror row_mask:0xf bank_mask:0xf bound_ctrl:1
	v_add_f32_dpp v194, v194, v194 row_mirror row_mask:0xf bank_mask:0xf bound_ctrl:1
	v_add_f32_dpp v195, v195, v195 row_mirror row_mask:0xf bank_mask:0xf bound_ctrl:1
	v_fmac_f32_e32 v186, v66, v36
	v_fmac_f32_e32 v187, v66, v37
	v_fmac_f32_e32 v188, v66, v38
	v_fmac_f32_e32 v189, v66, v39
	v_fmac_f32_e32 v190, v67, v36
	v_fmac_f32_e32 v191, v67, v37
	v_fmac_f32_e32 v192, v67, v38
	v_fmac_f32_e32 v193, v67, v39
	v_fmac_f32_e32 v186, v194, v32
	v_fmac_f32_e32 v187, v194, v33
	v_fmac_f32_e32 v188, v194, v34
	v_fmac_f32_e32 v189, v194, v35
	v_fmac_f32_e32 v190, v195, v32
	v_fmac_f32_e32 v191, v195, v33
	v_fmac_f32_e32 v192, v195, v34
	v_fmac_f32_e32 v193, v195, v35
	s_mov_b64 exec, s[8:9]
	ds_write2st64_b64 v161, v[132:133], v[238:239] offset0:1 offset1:0
	s_mov_b64 exec, -1
	ds_read_b128 v[4:7], v152 offset:57344
	s_waitcnt lgkmcnt(0)
	v_mul_f32_e32 v186, v186, v4
	v_mul_f32_e32 v187, v187, v5
	v_mul_f32_e32 v188, v188, v6
	v_mul_f32_e32 v189, v189, v7
	v_mul_f32_e32 v190, v190, v4
	v_mul_f32_e32 v191, v191, v5
	v_mul_f32_e32 v192, v192, v6
	v_mul_f32_e32 v193, v193, v7
	s_branch .LBB0_100

.LBB0_209:
	s_andn2_b64 vcc, exec, s[10:11]
	s_cbranch_vccnz .LBB0_211
	v_mul_f32_e32 v4, 0xbf60028a, v4
	v_mul_f32_e32 v5, 0xbf60028a, v5
	v_exp_f32_e32 v4, v4
	v_exp_f32_e32 v5, v5
	v_mul_f32_e32 v6, 0xbf60028a, v6
	v_mul_f32_e32 v7, 0xbf60028a, v7
	v_exp_f32_e32 v6, v6
	v_exp_f32_e32 v7, v7
	v_mul_f32_e32 v8, 0xbf60028a, v8
	v_mul_f32_e32 v9, 0xbf60028a, v9
	v_exp_f32_e32 v8, v8
	v_exp_f32_e32 v9, v9
	v_mul_f32_e32 v10, 0xbf60028a, v10
	v_mul_f32_e32 v11, 0xbf60028a, v11
	v_exp_f32_e32 v10, v10
	v_exp_f32_e32 v11, v11
	s_nop 1
	v_mul_f32_e32 v198, v4, v5
	v_mul_f32_e32 v201, v8, v9
	v_mul_f32_e32 v199, v198, v6
	v_mul_f32_e32 v202, v201, v10
	v_mul_f32_e32 v200, v199, v7
	v_mul_f32_e32 v203, v202, v11
	v_mov_b32_e32 v227, v4
	v_mbcnt_lo_u32_b32 v204, -1, 0
	v_mbcnt_hi_u32_b32 v204, -1, v204
	v_and_b32_e32 v205, 15, v204
	v_lshlrev_b32_e32 v205, 2, v205
	v_add_u32_e32 v206, 64, v205
	v_add_u32_e32 v207, 128, v205
	v_add_u32_e32 v208, 192, v205
	v_mov_b32_e32 v217, 1.0
	ds_bpermute_b32 v209, v205, v200
	ds_bpermute_b32 v210, v206, v200
	ds_bpermute_b32 v211, v207, v200
	ds_bpermute_b32 v212, v208, v200
	ds_bpermute_b32 v213, v205, v203
	ds_bpermute_b32 v214, v206, v203
	ds_bpermute_b32 v215, v207, v203
	ds_bpermute_b32 v216, v208, v203
	s_waitcnt lgkmcnt(7)
	v_mul_f32_e32 v15, v29, v4
	s_waitcnt lgkmcnt(7)
	v_mul_f32_e32 v4, v28, v5
	ds_write2st64_b32 v145, v15, v4 offset0:128 offset1:129
	s_waitcnt lgkmcnt(7)
	v_mul_f32_e32 v4, v26, v6
	s_waitcnt lgkmcnt(6)
	v_mul_f32_e32 v5, v25, v7
	ds_write2st64_b32 v145, v4, v5 offset0:130 offset1:131
	s_waitcnt lgkmcnt(6)
	v_mul_f32_e32 v4, v24, v8
	s_waitcnt lgkmcnt(5)
	v_mul_f32_e32 v5, v14, v9
	ds_write2st64_b32 v145, v4, v5 offset0:144 offset1:145
	s_waitcnt lgkmcnt(5)
	v_mul_f32_e32 v4, v13, v10
	s_waitcnt lgkmcnt(4)
	v_mul_f32_e32 v5, v12, v11
	ds_write2st64_b32 v145, v4, v5 offset0:146 offset1:147
	s_waitcnt lgkmcnt(0)
	v_cmp_lt_u32_e32 vcc, 15, v204
	v_cndmask_b32_e32 v218, v217, v209, vcc
	v_cndmask_b32_e32 v221, v217, v213, vcc
	v_cmp_lt_u32_e32 vcc, 31, v204
	v_cndmask_b32_e32 v219, v217, v210, vcc
	v_cndmask_b32_e32 v222, v217, v214, vcc
	v_cmp_lt_u32_e32 vcc, 47, v204
	v_cndmask_b32_e32 v220, v217, v211, vcc
	v_cndmask_b32_e32 v223, v217, v215, vcc
	v_mul_f32_e32 v224, v218, v219
	v_mul_f32_e32 v225, v221, v222
	v_mul_f32_e32 v226, v209, v210
	v_mul_f32_e32 v224, v224, v220
	v_mul_f32_e32 v225, v225, v223
	v_mul_f32_e32 v226, v226, v211
	v_mul_f32_e32 v226, v226, v212
	v_mul_f32_e32 v225, v225, v226
	v_mul_f32_e32 v230, v227, v224
	v_mul_f32_e32 v231, v198, v224
	v_mul_f32_e32 v232, v199, v224
	v_mul_f32_e32 v233, v200, v224
	v_mul_f32_e32 v234, v8, v225
	v_mul_f32_e32 v235, v201, v225
	v_mul_f32_e32 v236, v202, v225
	v_mul_f32_e32 v237, v203, v225
	ds_write2st64_b32 v145, v230, v231 offset0:224 offset1:225
	ds_write2st64_b32 v145, v232, v233 offset0:226 offset1:227
	ds_write2st64_b32 v145, v234, v235 offset0:240 offset1:241
	ds_write2st64_b32 v145, v236, v237 offset0:242 offset1:243
.LBB0_211:
	s_waitcnt lgkmcnt(0)
	s_barrier
	v_add_u32_e32 v227, 0xffffff00, v152
	ds_read_b128 v[198:201], v152 offset:57344
	ds_read_b128 v[202:205], v227 offset:57344
	ds_read_b128 v[206:209], v152 offset:8192
	ds_read_b128 v[210:213], v152 offset:16384
	ds_read_b128 v[214:217], v152 offset:24576
	ds_read_b128 v[4:7], v152 offset:40960
	ds_read_b128 v[8:11], v152 offset:16384
	s_waitcnt lgkmcnt(2)
	ds_read_b128 v[12:15], v152 offset:24576
	ds_read_b128 v[16:19], v157
	s_lshl_b32 s10, s68, 5
	s_add_i32 s10, s10, s95
	s_waitcnt lgkmcnt(2)
	v_pk_mul_f32 v[8:9], v[4:5], v[8:9]
	s_waitcnt lgkmcnt(1)
	v_pk_mul_f32 v[4:5], v[4:5], v[12:13]
	v_add_f32_e32 v8, 0, v8
	v_pk_mul_f32 v[10:11], v[6:7], v[10:11]
	v_add_f32_e32 v8, v9, v8
	v_add_f32_e32 v9, 0, v4
	s_waitcnt lgkmcnt(0)
	v_fma_f32 v4, v16, v4, 0
	v_add_f32_e32 v9, v5, v9
	v_fmac_f32_e32 v4, v17, v5
	v_add_f32_e32 v5, v10, v8
	v_add_f32_e32 v5, v11, v5
	v_pk_mul_f32 v[6:7], v[6:7], v[14:15]
	v_add_u32_e32 v124, s10, v131
	v_add_f32_dpp v5, v5, v5 quad_perm:[1,0,3,2] row_mask:0xf bank_mask:0xf bound_ctrl:1
	v_add_f32_e32 v8, v6, v9
	v_fmac_f32_e32 v4, v18, v6
	v_add_f32_dpp v5, v5, v5 quad_perm:[2,3,0,1] row_mask:0xf bank_mask:0xf bound_ctrl:1
	v_add_f32_e32 v6, v7, v8
	v_fmac_f32_e32 v4, v19, v7
	v_add_f32_dpp v5, v5, v5 row_half_mirror row_mask:0xf bank_mask:0xf bound_ctrl:1
	v_ashrrev_i32_e32 v125, 31, v124
	v_add_f32_dpp v4, v4, v4 quad_perm:[1,0,3,2] row_mask:0xf bank_mask:0xf bound_ctrl:1
	v_add_f32_dpp v14, v5, v5 row_mirror row_mask:0xf bank_mask:0xf bound_ctrl:1
	v_add_f32_dpp v5, v6, v6 quad_perm:[1,0,3,2] row_mask:0xf bank_mask:0xf bound_ctrl:1
	ds_read_b128 v[6:9], v152 offset:8192
	ds_read_b128 v[10:13], v152 offset:32768
	v_add_f32_dpp v5, v5, v5 quad_perm:[2,3,0,1] row_mask:0xf bank_mask:0xf bound_ctrl:1
	v_add_f32_dpp v4, v4, v4 quad_perm:[2,3,0,1] row_mask:0xf bank_mask:0xf bound_ctrl:1
	s_waitcnt lgkmcnt(0)
	v_pk_fma_f32 v[8:9], v[14:15], v[8:9], v[12:13] op_sel_hi:[0,1,1]
	v_pk_fma_f32 v[6:7], v[14:15], v[6:7], v[10:11] op_sel_hi:[0,1,1]
	s_waitcnt lgkmcnt(0)
	v_mov_b32_e32 v226, 1.0
	v_cmp_gt_u32_e32 vcc, 16, v134
	v_rcp_f32_e32 v222, v198
	v_rcp_f32_e32 v223, v199
	v_rcp_f32_e32 v224, v200
	v_rcp_f32_e32 v225, v201
	v_cndmask_b32_e32 v202, v202, v226, vcc
	v_cndmask_b32_e32 v203, v203, v226, vcc
	v_cndmask_b32_e32 v204, v204, v226, vcc
	v_cndmask_b32_e32 v205, v205, v226, vcc
	v_mul_f32_e32 v206, v206, v202
	v_mul_f32_e32 v207, v207, v203
	v_mul_f32_e32 v208, v208, v204
	v_mul_f32_e32 v209, v209, v205
	v_mul_f32_e32 v6, v6, v202
	v_mul_f32_e32 v7, v7, v203
	v_mul_f32_e32 v8, v8, v204
	v_mul_f32_e32 v9, v9, v205
	v_mul_f32_e32 v210, v210, v222
	v_mul_f32_e32 v211, v211, v223
	v_mul_f32_e32 v212, v212, v224
	v_mul_f32_e32 v213, v213, v225
	v_mul_f32_e32 v214, v214, v222
	v_mul_f32_e32 v215, v215, v223
	v_mul_f32_e32 v216, v216, v224
	v_mul_f32_e32 v217, v217, v225
	ds_write_b128 v152, v[206:209] offset:8192
	ds_write_b128 v152, v[210:213] offset:16384
	ds_write_b128 v152, v[214:217] offset:24576
	ds_write_b128 v152, v[6:9] offset:32768
	ds_read_b128 v[6:9], v152 offset:49152
	v_add_f32_dpp v5, v5, v5 row_half_mirror row_mask:0xf bank_mask:0xf bound_ctrl:1
	v_add_f32_dpp v4, v4, v4 row_half_mirror row_mask:0xf bank_mask:0xf bound_ctrl:1
	s_nop 0
	v_add_f32_dpp v16, v5, v5 row_mirror row_mask:0xf bank_mask:0xf bound_ctrl:1
	v_mov_b32_dpp v5, v4 row_mirror row_mask:0xf bank_mask:0xf bound_ctrl:1
	s_waitcnt lgkmcnt(0)
	v_pk_mul_f32 v[8:9], v[16:17], v[8:9] op_sel_hi:[0,1]
	v_pk_mul_f32 v[6:7], v[16:17], v[6:7] op_sel_hi:[0,1]
	ds_write_b128 v158, v[6:9]
	s_and_saveexec_b64 s[10:11], s[6:7]
	s_cbranch_execz .LBB0_213
	v_lshlrev_b64 v[6:7], 6, v[124:125]
	v_lshl_add_u64 v[6:7], s[12:13], 0, v[6:7]
	v_add_f32_e32 v4, v4, v5
	global_store_dword v[6:7], v4, off
.LBB0_213:
	s_or_b64 exec, exec, s[10:11]
	s_waitcnt lgkmcnt(0)
	s_barrier
	v_mbcnt_lo_u32_b32 v193, -1, 0
	v_mbcnt_hi_u32_b32 v193, -1, v193
	v_lshlrev_b32_e32 v193, 3, v193
	v_add_u32_e32 v193, 0xe000, v193
	v_cndmask_b32_e64 v192, v193, v146, s[8:9]
	ds_read_b128 v[8:11], v151 offset:8192
	ds_read_b128 v[12:15], v151 offset:16384
	ds_read_b128 v[16:19], v151 offset:24576
	ds_read_b128 v[20:23], v151 offset:32768
	ds_read_b64 v[64:65], v181
	ds_read_b128 v[28:31], v151 offset:8448
	ds_read_b128 v[32:35], v151 offset:16640
	ds_read_b128 v[36:39], v151 offset:24832
	ds_read_b128 v[40:43], v151 offset:33024
	ds_read_b64 v[66:67], v181 offset:256
	ds_read_b128 v[48:51], v151 offset:8704
	ds_read_b128 v[52:55], v151 offset:16896
	ds_read_b128 v[56:59], v151 offset:25088
	ds_read_b128 v[60:63], v151 offset:33280
	ds_read_b64 v[126:127], v181 offset:512
	s_waitcnt lgkmcnt(10)
	v_mul_f32_e32 v190, v182, v8
	v_mul_f32_e32 v191, v186, v8
	v_mul_f32_e32 v128, v182, v20
	v_mul_f32_e32 v129, v186, v20
	v_fmac_f32_e32 v190, v183, v9
	v_fmac_f32_e32 v191, v187, v9
	v_fmac_f32_e32 v128, v183, v21
	v_fmac_f32_e32 v129, v187, v21
	v_fmac_f32_e32 v190, v184, v10
	v_fmac_f32_e32 v191, v188, v10
	v_fmac_f32_e32 v128, v184, v22
	v_fmac_f32_e32 v129, v188, v22
	v_fmac_f32_e32 v190, v185, v11
	v_fmac_f32_e32 v191, v189, v11
	v_fmac_f32_e32 v128, v185, v23
	v_fmac_f32_e32 v129, v189, v23
	v_add_f32_dpp v190, v190, v190 quad_perm:[1,0,3,2] row_mask:0xf bank_mask:0xf bound_ctrl:1
	v_add_f32_dpp v191, v191, v191 quad_perm:[1,0,3,2] row_mask:0xf bank_mask:0xf bound_ctrl:1
	v_add_f32_dpp v128, v128, v128 quad_perm:[1,0,3,2] row_mask:0xf bank_mask:0xf bound_ctrl:1
	v_add_f32_dpp v129, v129, v129 quad_perm:[1,0,3,2] row_mask:0xf bank_mask:0xf bound_ctrl:1
	v_add_f32_dpp v190, v190, v190 quad_perm:[2,3,0,1] row_mask:0xf bank_mask:0xf bound_ctrl:1
	v_add_f32_dpp v191, v191, v191 quad_perm:[2,3,0,1] row_mask:0xf bank_mask:0xf bound_ctrl:1
	v_add_f32_dpp v128, v128, v128 quad_perm:[2,3,0,1] row_mask:0xf bank_mask:0xf bound_ctrl:1
	v_add_f32_dpp v129, v129, v129 quad_perm:[2,3,0,1] row_mask:0xf bank_mask:0xf bound_ctrl:1
	v_add_f32_dpp v190, v190, v190 row_half_mirror row_mask:0xf bank_mask:0xf bound_ctrl:1
	v_add_f32_dpp v191, v191, v191 row_half_mirror row_mask:0xf bank_mask:0xf bound_ctrl:1
	v_add_f32_dpp v128, v128, v128 row_half_mirror row_mask:0xf bank_mask:0xf bound_ctrl:1
	v_add_f32_dpp v129, v129, v129 row_half_mirror row_mask:0xf bank_mask:0xf bound_ctrl:1
	v_add_f32_dpp v190, v190, v190 row_mirror row_mask:0xf bank_mask:0xf bound_ctrl:1
	v_add_f32_dpp v191, v191, v191 row_mirror row_mask:0xf bank_mask:0xf bound_ctrl:1
	v_fmac_f32_e32 v182, v64, v16
	v_fmac_f32_e32 v183, v64, v17
	v_fmac_f32_e32 v184, v64, v18
	v_fmac_f32_e32 v185, v64, v19
	v_fmac_f32_e32 v186, v65, v16
	v_fmac_f32_e32 v187, v65, v17
	v_fmac_f32_e32 v188, v65, v18
	v_fmac_f32_e32 v189, v65, v19
	v_fmac_f32_e32 v182, v190, v12
	v_fmac_f32_e32 v183, v190, v13
	v_fmac_f32_e32 v184, v190, v14
	v_fmac_f32_e32 v185, v190, v15
	v_fmac_f32_e32 v186, v191, v12
	v_fmac_f32_e32 v187, v191, v13
	v_fmac_f32_e32 v188, v191, v14
	v_fmac_f32_e32 v189, v191, v15
	ds_read_b128 v[8:11], v151 offset:8960
	ds_read_b128 v[12:15], v151 offset:17152
	ds_read_b128 v[16:19], v151 offset:25344
	ds_read_b128 v[20:23], v151 offset:33536
	ds_read_b64 v[64:65], v181 offset:768
	s_waitcnt lgkmcnt(10)
	v_mul_f32_e32 v190, v182, v28
	v_mul_f32_e32 v191, v186, v28
	v_mul_f32_e32 v238, v182, v40
	v_mul_f32_e32 v239, v186, v40
	v_fmac_f32_e32 v190, v183, v29
	v_fmac_f32_e32 v191, v187, v29
	v_fmac_f32_e32 v238, v183, v41
	v_fmac_f32_e32 v239, v187, v41
	v_fmac_f32_e32 v190, v184, v30
	v_fmac_f32_e32 v191, v188, v30
	v_fmac_f32_e32 v238, v184, v42
	v_fmac_f32_e32 v239, v188, v42
	v_fmac_f32_e32 v190, v185, v31
	v_fmac_f32_e32 v191, v189, v31
	v_fmac_f32_e32 v238, v185, v43
	v_fmac_f32_e32 v239, v189, v43
	v_add_f32_dpp v190, v190, v190 quad_perm:[1,0,3,2] row_mask:0xf bank_mask:0xf bound_ctrl:1
	v_add_f32_dpp v191, v191, v191 quad_perm:[1,0,3,2] row_mask:0xf bank_mask:0xf bound_ctrl:1
	v_add_f32_dpp v238, v238, v238 quad_perm:[1,0,3,2] row_mask:0xf bank_mask:0xf bound_ctrl:1
	v_add_f32_dpp v239, v239, v239 quad_perm:[1,0,3,2] row_mask:0xf bank_mask:0xf bound_ctrl:1
	v_add_f32_dpp v190, v190, v190 quad_perm:[2,3,0,1] row_mask:0xf bank_mask:0xf bound_ctrl:1
	v_add_f32_dpp v191, v191, v191 quad_perm:[2,3,0,1] row_mask:0xf bank_mask:0xf bound_ctrl:1
	v_add_f32_dpp v238, v238, v238 quad_perm:[2,3,0,1] row_mask:0xf bank_mask:0xf bound_ctrl:1
	v_add_f32_dpp v239, v239, v239 quad_perm:[2,3,0,1] row_mask:0xf bank_mask:0xf bound_ctrl:1
	v_add_f32_dpp v190, v190, v190 row_half_mirror row_mask:0xf bank_mask:0xf bound_ctrl:1
	v_add_f32_dpp v191, v191, v191 row_half_mirror row_mask:0xf bank_mask:0xf bound_ctrl:1
	v_add_f32_dpp v238, v238, v238 row_half_mirror row_mask:0xf bank_mask:0xf bound_ctrl:1
	v_add_f32_dpp v239, v239, v239 row_half_mirror row_mask:0xf bank_mask:0xf bound_ctrl:1
	v_add_f32_dpp v190, v190, v190 row_mirror row_mask:0xf bank_mask:0xf bound_ctrl:1
	v_add_f32_dpp v191, v191, v191 row_mirror row_mask:0xf bank_mask:0xf bound_ctrl:1
	v_fmac_f32_e32 v182, v66, v36
	v_fmac_f32_e32 v183, v66, v37
	v_fmac_f32_e32 v184, v66, v38
	v_fmac_f32_e32 v185, v66, v39
	v_fmac_f32_e32 v186, v67, v36
	v_fmac_f32_e32 v187, v67, v37
	v_fmac_f32_e32 v188, v67, v38
	v_fmac_f32_e32 v189, v67, v39
	v_fmac_f32_e32 v182, v190, v32
	v_fmac_f32_e32 v183, v190, v33
	v_fmac_f32_e32 v184, v190, v34
	v_fmac_f32_e32 v185, v190, v35
	v_fmac_f32_e32 v186, v191, v32
	v_fmac_f32_e32 v187, v191, v33
	v_fmac_f32_e32 v188, v191, v34
	v_fmac_f32_e32 v189, v191, v35
	s_mov_b64 exec, s[8:9]
	ds_write2st64_b64 v146, v[128:129], v[238:239] offset0:0 offset1:1
	s_mov_b64 exec, -1
	ds_read_b128 v[28:31], v151 offset:9216
	ds_read_b128 v[32:35], v151 offset:17408
	ds_read_b128 v[36:39], v151 offset:25600
	ds_read_b128 v[40:43], v151 offset:33792
	ds_read_b64 v[66:67], v181 offset:1024
	s_waitcnt lgkmcnt(11)
	v_mul_f32_e32 v190, v182, v48
	v_mul_f32_e32 v191, v186, v48
	v_mul_f32_e32 v128, v182, v60
	v_mul_f32_e32 v129, v186, v60
	v_fmac_f32_e32 v190, v183, v49
	v_fmac_f32_e32 v191, v187, v49
	v_fmac_f32_e32 v128, v183, v61
	v_fmac_f32_e32 v129, v187, v61
	v_fmac_f32_e32 v190, v184, v50
	v_fmac_f32_e32 v191, v188, v50
	v_fmac_f32_e32 v128, v184, v62
	v_fmac_f32_e32 v129, v188, v62
	v_fmac_f32_e32 v190, v185, v51
	v_fmac_f32_e32 v191, v189, v51
	v_fmac_f32_e32 v128, v185, v63
	v_fmac_f32_e32 v129, v189, v63
	v_add_f32_dpp v190, v190, v190 quad_perm:[1,0,3,2] row_mask:0xf bank_mask:0xf bound_ctrl:1
	v_add_f32_dpp v191, v191, v191 quad_perm:[1,0,3,2] row_mask:0xf bank_mask:0xf bound_ctrl:1
	v_add_f32_dpp v128, v128, v128 quad_perm:[1,0,3,2] row_mask:0xf bank_mask:0xf bound_ctrl:1
	v_add_f32_dpp v129, v129, v129 quad_perm:[1,0,3,2] row_mask:0xf bank_mask:0xf bound_ctrl:1
	v_add_f32_dpp v190, v190, v190 quad_perm:[2,3,0,1] row_mask:0xf bank_mask:0xf bound_ctrl:1
	v_add_f32_dpp v191, v191, v191 quad_perm:[2,3,0,1] row_mask:0xf bank_mask:0xf bound_ctrl:1
	v_add_f32_dpp v128, v128, v128 quad_perm:[2,3,0,1] row_mask:0xf bank_mask:0xf bound_ctrl:1
	v_add_f32_dpp v129, v129, v129 quad_perm:[2,3,0,1] row_mask:0xf bank_mask:0xf bound_ctrl:1
	v_add_f32_dpp v190, v190, v190 row_half_mirror row_mask:0xf bank_mask:0xf bound_ctrl:1
	v_add_f32_dpp v191, v191, v191 row_half_mirror row_mask:0xf bank_mask:0xf bound_ctrl:1
	v_add_f32_dpp v128, v128, v128 row_half_mirror row_mask:0xf bank_mask:0xf bound_ctrl:1
	v_add_f32_dpp v129, v129, v129 row_half_mirror row_mask:0xf bank_mask:0xf bound_ctrl:1
	v_add_f32_dpp v190, v190, v190 row_mirror row_mask:0xf bank_mask:0xf bound_ctrl:1
	v_add_f32_dpp v191, v191, v191 row_mirror row_mask:0xf bank_mask:0xf bound_ctrl:1
	v_fmac_f32_e32 v182, v126, v56
	v_fmac_f32_e32 v183, v126, v57
	v_fmac_f32_e32 v184, v126, v58
	v_fmac_f32_e32 v185, v126, v59
	v_fmac_f32_e32 v186, v127, v56
	v_fmac_f32_e32 v187, v127, v57
	v_fmac_f32_e32 v188, v127, v58
	v_fmac_f32_e32 v189, v127, v59
	v_fmac_f32_e32 v182, v190, v52
	v_fmac_f32_e32 v183, v190, v53
	v_fmac_f32_e32 v184, v190, v54
	v_fmac_f32_e32 v185, v190, v55
	v_fmac_f32_e32 v186, v191, v52
	v_fmac_f32_e32 v187, v191, v53
	v_fmac_f32_e32 v188, v191, v54
	v_fmac_f32_e32 v189, v191, v55
	ds_read_b128 v[48:51], v151 offset:9472
	ds_read_b128 v[52:55], v151 offset:17664
	ds_read_b128 v[56:59], v151 offset:25856
	ds_read_b128 v[60:63], v151 offset:34048
	ds_read_b64 v[126:127], v181 offset:1280
	s_waitcnt lgkmcnt(11)
	v_mul_f32_e32 v190, v182, v8
	v_mul_f32_e32 v191, v186, v8
	v_mul_f32_e32 v238, v182, v20
	v_mul_f32_e32 v239, v186, v20
	v_fmac_f32_e32 v190, v183, v9
	v_fmac_f32_e32 v191, v187, v9
	v_fmac_f32_e32 v238, v183, v21
	v_fmac_f32_e32 v239, v187, v21
	v_fmac_f32_e32 v190, v184, v10
	v_fmac_f32_e32 v191, v188, v10
	v_fmac_f32_e32 v238, v184, v22
	v_fmac_f32_e32 v239, v188, v22
	v_fmac_f32_e32 v190, v185, v11
	v_fmac_f32_e32 v191, v189, v11
	v_fmac_f32_e32 v238, v185, v23
	v_fmac_f32_e32 v239, v189, v23
	v_add_f32_dpp v190, v190, v190 quad_perm:[1,0,3,2] row_mask:0xf bank_mask:0xf bound_ctrl:1
	v_add_f32_dpp v191, v191, v191 quad_perm:[1,0,3,2] row_mask:0xf bank_mask:0xf bound_ctrl:1
	v_add_f32_dpp v238, v238, v238 quad_perm:[1,0,3,2] row_mask:0xf bank_mask:0xf bound_ctrl:1
	v_add_f32_dpp v239, v239, v239 quad_perm:[1,0,3,2] row_mask:0xf bank_mask:0xf bound_ctrl:1
	v_add_f32_dpp v190, v190, v190 quad_perm:[2,3,0,1] row_mask:0xf bank_mask:0xf bound_ctrl:1
	v_add_f32_dpp v191, v191, v191 quad_perm:[2,3,0,1] row_mask:0xf bank_mask:0xf bound_ctrl:1
	v_add_f32_dpp v238, v238, v238 quad_perm:[2,3,0,1] row_mask:0xf bank_mask:0xf bound_ctrl:1
	v_add_f32_dpp v239, v239, v239 quad_perm:[2,3,0,1] row_mask:0xf bank_mask:0xf bound_ctrl:1
	v_add_f32_dpp v190, v190, v190 row_half_mirror row_mask:0xf bank_mask:0xf bound_ctrl:1
	v_add_f32_dpp v191, v191, v191 row_half_mirror row_mask:0xf bank_mask:0xf bound_ctrl:1
	v_add_f32_dpp v238, v238, v238 row_half_mirror row_mask:0xf bank_mask:0xf bound_ctrl:1
	v_add_f32_dpp v239, v239, v239 row_half_mirror row_mask:0xf bank_mask:0xf bound_ctrl:1
	v_add_f32_dpp v190, v190, v190 row_mirror row_mask:0xf bank_mask:0xf bound_ctrl:1
	v_add_f32_dpp v191, v191, v191 row_mirror row_mask:0xf bank_mask:0xf bound_ctrl:1
	v_fmac_f32_e32 v182, v64, v16
	v_fmac_f32_e32 v183, v64, v17
	v_fmac_f32_e32 v184, v64, v18
	v_fmac_f32_e32 v185, v64, v19
	v_fmac_f32_e32 v186, v65, v16
	v_fmac_f32_e32 v187, v65, v17
	v_fmac_f32_e32 v188, v65, v18
	v_fmac_f32_e32 v189, v65, v19
	v_fmac_f32_e32 v182, v190, v12
	v_fmac_f32_e32 v183, v190, v13
	v_fmac_f32_e32 v184, v190, v14
	v_fmac_f32_e32 v185, v190, v15
	v_fmac_f32_e32 v186, v191, v12
	v_fmac_f32_e32 v187, v191, v13
	v_fmac_f32_e32 v188, v191, v14
	v_fmac_f32_e32 v189, v191, v15
	s_mov_b64 exec, s[8:9]
	ds_write2st64_b64 v146, v[128:129], v[238:239] offset0:2 offset1:3
	s_mov_b64 exec, -1
	ds_read_b128 v[8:11], v151 offset:9728
	ds_read_b128 v[12:15], v151 offset:17920
	ds_read_b128 v[16:19], v151 offset:26112
	ds_read_b128 v[20:23], v151 offset:34304
	ds_read_b64 v[64:65], v181 offset:1536
	s_waitcnt lgkmcnt(11)
	v_mul_f32_e32 v190, v182, v28
	v_mul_f32_e32 v191, v186, v28
	v_mul_f32_e32 v128, v182, v40
	v_mul_f32_e32 v129, v186, v40
	v_fmac_f32_e32 v190, v183, v29
	v_fmac_f32_e32 v191, v187, v29
	v_fmac_f32_e32 v128, v183, v41
	v_fmac_f32_e32 v129, v187, v41
	v_fmac_f32_e32 v190, v184, v30
	v_fmac_f32_e32 v191, v188, v30
	v_fmac_f32_e32 v128, v184, v42
	v_fmac_f32_e32 v129, v188, v42
	v_fmac_f32_e32 v190, v185, v31
	v_fmac_f32_e32 v191, v189, v31
	v_fmac_f32_e32 v128, v185, v43
	v_fmac_f32_e32 v129, v189, v43
	v_add_f32_dpp v190, v190, v190 quad_perm:[1,0,3,2] row_mask:0xf bank_mask:0xf bound_ctrl:1
	v_add_f32_dpp v191, v191, v191 quad_perm:[1,0,3,2] row_mask:0xf bank_mask:0xf bound_ctrl:1
	v_add_f32_dpp v128, v128, v128 quad_perm:[1,0,3,2] row_mask:0xf bank_mask:0xf bound_ctrl:1
	v_add_f32_dpp v129, v129, v129 quad_perm:[1,0,3,2] row_mask:0xf bank_mask:0xf bound_ctrl:1
	v_add_f32_dpp v190, v190, v190 quad_perm:[2,3,0,1] row_mask:0xf bank_mask:0xf bound_ctrl:1
	v_add_f32_dpp v191, v191, v191 quad_perm:[2,3,0,1] row_mask:0xf bank_mask:0xf bound_ctrl:1
	v_add_f32_dpp v128, v128, v128 quad_perm:[2,3,0,1] row_mask:0xf bank_mask:0xf bound_ctrl:1
	v_add_f32_dpp v129, v129, v129 quad_perm:[2,3,0,1] row_mask:0xf bank_mask:0xf bound_ctrl:1
	v_add_f32_dpp v190, v190, v190 row_half_mirror row_mask:0xf bank_mask:0xf bound_ctrl:1
	v_add_f32_dpp v191, v191, v191 row_half_mirror row_mask:0xf bank_mask:0xf bound_ctrl:1
	v_add_f32_dpp v128, v128, v128 row_half_mirror row_mask:0xf bank_mask:0xf bound_ctrl:1
	v_add_f32_dpp v129, v129, v129 row_half_mirror row_mask:0xf bank_mask:0xf bound_ctrl:1
	v_add_f32_dpp v190, v190, v190 row_mirror row_mask:0xf bank_mask:0xf bound_ctrl:1
	v_add_f32_dpp v191, v191, v191 row_mirror row_mask:0xf bank_mask:0xf bound_ctrl:1
	v_fmac_f32_e32 v182, v66, v36
	v_fmac_f32_e32 v183, v66, v37
	v_fmac_f32_e32 v184, v66, v38
	v_fmac_f32_e32 v185, v66, v39
	v_fmac_f32_e32 v186, v67, v36
	v_fmac_f32_e32 v187, v67, v37
	v_fmac_f32_e32 v188, v67, v38
	v_fmac_f32_e32 v189, v67, v39
	v_fmac_f32_e32 v182, v190, v32
	v_fmac_f32_e32 v183, v190, v33
	v_fmac_f32_e32 v184, v190, v34
	v_fmac_f32_e32 v185, v190, v35
	v_fmac_f32_e32 v186, v191, v32
	v_fmac_f32_e32 v187, v191, v33
	v_fmac_f32_e32 v188, v191, v34
	v_fmac_f32_e32 v189, v191, v35
	ds_read_b128 v[28:31], v151 offset:9984
	ds_read_b128 v[32:35], v151 offset:18176
	ds_read_b128 v[36:39], v151 offset:26368
	ds_read_b128 v[40:43], v151 offset:34560
	ds_read_b64 v[66:67], v181 offset:1792
	s_waitcnt lgkmcnt(11)
	v_mul_f32_e32 v190, v182, v48
	v_mul_f32_e32 v191, v186, v48
	v_mul_f32_e32 v238, v182, v60
	v_mul_f32_e32 v239, v186, v60
	v_fmac_f32_e32 v190, v183, v49
	v_fmac_f32_e32 v191, v187, v49
	v_fmac_f32_e32 v238, v183, v61
	v_fmac_f32_e32 v239, v187, v61
	v_fmac_f32_e32 v190, v184, v50
	v_fmac_f32_e32 v191, v188, v50
	v_fmac_f32_e32 v238, v184, v62
	v_fmac_f32_e32 v239, v188, v62
	v_fmac_f32_e32 v190, v185, v51
	v_fmac_f32_e32 v191, v189, v51
	v_fmac_f32_e32 v238, v185, v63
	v_fmac_f32_e32 v239, v189, v63
	v_add_f32_dpp v190, v190, v190 quad_perm:[1,0,3,2] row_mask:0xf bank_mask:0xf bound_ctrl:1
	v_add_f32_dpp v191, v191, v191 quad_perm:[1,0,3,2] row_mask:0xf bank_mask:0xf bound_ctrl:1
	v_add_f32_dpp v238, v238, v238 quad_perm:[1,0,3,2] row_mask:0xf bank_mask:0xf bound_ctrl:1
	v_add_f32_dpp v239, v239, v239 quad_perm:[1,0,3,2] row_mask:0xf bank_mask:0xf bound_ctrl:1
	v_add_f32_dpp v190, v190, v190 quad_perm:[2,3,0,1] row_mask:0xf bank_mask:0xf bound_ctrl:1
	v_add_f32_dpp v191, v191, v191 quad_perm:[2,3,0,1] row_mask:0xf bank_mask:0xf bound_ctrl:1
	v_add_f32_dpp v238, v238, v238 quad_perm:[2,3,0,1] row_mask:0xf bank_mask:0xf bound_ctrl:1
	v_add_f32_dpp v239, v239, v239 quad_perm:[2,3,0,1] row_mask:0xf bank_mask:0xf bound_ctrl:1
	v_add_f32_dpp v190, v190, v190 row_half_mirror row_mask:0xf bank_mask:0xf bound_ctrl:1
	v_add_f32_dpp v191, v191, v191 row_half_mirror row_mask:0xf bank_mask:0xf bound_ctrl:1
	v_add_f32_dpp v238, v238, v238 row_half_mirror row_mask:0xf bank_mask:0xf bound_ctrl:1
	v_add_f32_dpp v239, v239, v239 row_half_mirror row_mask:0xf bank_mask:0xf bound_ctrl:1
	v_add_f32_dpp v190, v190, v190 row_mirror row_mask:0xf bank_mask:0xf bound_ctrl:1
	v_add_f32_dpp v191, v191, v191 row_mirror row_mask:0xf bank_mask:0xf bound_ctrl:1
	v_fmac_f32_e32 v182, v126, v56
	v_fmac_f32_e32 v183, v126, v57
	v_fmac_f32_e32 v184, v126, v58
	v_fmac_f32_e32 v185, v126, v59
	v_fmac_f32_e32 v186, v127, v56
	v_fmac_f32_e32 v187, v127, v57
	v_fmac_f32_e32 v188, v127, v58
	v_fmac_f32_e32 v189, v127, v59
	v_fmac_f32_e32 v182, v190, v52
	v_fmac_f32_e32 v183, v190, v53
	v_fmac_f32_e32 v184, v190, v54
	v_fmac_f32_e32 v185, v190, v55
	v_fmac_f32_e32 v186, v191, v52
	v_fmac_f32_e32 v187, v191, v53
	v_fmac_f32_e32 v188, v191, v54
	v_fmac_f32_e32 v189, v191, v55
	s_mov_b64 exec, s[8:9]
	ds_write2st64_b64 v146, v[128:129], v[238:239] offset0:4 offset1:5
	s_mov_b64 exec, -1
	ds_read_b128 v[48:51], v151 offset:10240
	ds_read_b128 v[52:55], v151 offset:18432
	ds_read_b128 v[56:59], v151 offset:26624
	ds_read_b128 v[60:63], v151 offset:34816
	ds_read_b64 v[126:127], v181 offset:2048
	s_waitcnt lgkmcnt(11)
	v_mul_f32_e32 v190, v182, v8
	v_mul_f32_e32 v191, v186, v8
	v_mul_f32_e32 v128, v182, v20
	v_mul_f32_e32 v129, v186, v20
	v_fmac_f32_e32 v190, v183, v9
	v_fmac_f32_e32 v191, v187, v9
	v_fmac_f32_e32 v128, v183, v21
	v_fmac_f32_e32 v129, v187, v21
	v_fmac_f32_e32 v190, v184, v10
	v_fmac_f32_e32 v191, v188, v10
	v_fmac_f32_e32 v128, v184, v22
	v_fmac_f32_e32 v129, v188, v22
	v_fmac_f32_e32 v190, v185, v11
	v_fmac_f32_e32 v191, v189, v11
	v_fmac_f32_e32 v128, v185, v23
	v_fmac_f32_e32 v129, v189, v23
	v_add_f32_dpp v190, v190, v190 quad_perm:[1,0,3,2] row_mask:0xf bank_mask:0xf bound_ctrl:1
	v_add_f32_dpp v191, v191, v191 quad_perm:[1,0,3,2] row_mask:0xf bank_mask:0xf bound_ctrl:1
	v_add_f32_dpp v128, v128, v128 quad_perm:[1,0,3,2] row_mask:0xf bank_mask:0xf bound_ctrl:1
	v_add_f32_dpp v129, v129, v129 quad_perm:[1,0,3,2] row_mask:0xf bank_mask:0xf bound_ctrl:1
	v_add_f32_dpp v190, v190, v190 quad_perm:[2,3,0,1] row_mask:0xf bank_mask:0xf bound_ctrl:1
	v_add_f32_dpp v191, v191, v191 quad_perm:[2,3,0,1] row_mask:0xf bank_mask:0xf bound_ctrl:1
	v_add_f32_dpp v128, v128, v128 quad_perm:[2,3,0,1] row_mask:0xf bank_mask:0xf bound_ctrl:1
	v_add_f32_dpp v129, v129, v129 quad_perm:[2,3,0,1] row_mask:0xf bank_mask:0xf bound_ctrl:1
	v_add_f32_dpp v190, v190, v190 row_half_mirror row_mask:0xf bank_mask:0xf bound_ctrl:1
	v_add_f32_dpp v191, v191, v191 row_half_mirror row_mask:0xf bank_mask:0xf bound_ctrl:1
	v_add_f32_dpp v128, v128, v128 row_half_mirror row_mask:0xf bank_mask:0xf bound_ctrl:1
	v_add_f32_dpp v129, v129, v129 row_half_mirror row_mask:0xf bank_mask:0xf bound_ctrl:1
	v_add_f32_dpp v190, v190, v190 row_mirror row_mask:0xf bank_mask:0xf bound_ctrl:1
	v_add_f32_dpp v191, v191, v191 row_mirror row_mask:0xf bank_mask:0xf bound_ctrl:1
	v_fmac_f32_e32 v182, v64, v16
	v_fmac_f32_e32 v183, v64, v17
	v_fmac_f32_e32 v184, v64, v18
	v_fmac_f32_e32 v185, v64, v19
	v_fmac_f32_e32 v186, v65, v16
	v_fmac_f32_e32 v187, v65, v17
	v_fmac_f32_e32 v188, v65, v18
	v_fmac_f32_e32 v189, v65, v19
	v_fmac_f32_e32 v182, v190, v12
	v_fmac_f32_e32 v183, v190, v13
	v_fmac_f32_e32 v184, v190, v14
	v_fmac_f32_e32 v185, v190, v15
	v_fmac_f32_e32 v186, v191, v12
	v_fmac_f32_e32 v187, v191, v13
	v_fmac_f32_e32 v188, v191, v14
	v_fmac_f32_e32 v189, v191, v15
	ds_read_b128 v[8:11], v151 offset:10496
	ds_read_b128 v[12:15], v151 offset:18688
	ds_read_b128 v[16:19], v151 offset:26880
	ds_read_b128 v[20:23], v151 offset:35072
	ds_read_b64 v[64:65], v181 offset:2304
	s_waitcnt lgkmcnt(11)
	v_mul_f32_e32 v190, v182, v28
	v_mul_f32_e32 v191, v186, v28
	v_mul_f32_e32 v238, v182, v40
	v_mul_f32_e32 v239, v186, v40
	v_fmac_f32_e32 v190, v183, v29
	v_fmac_f32_e32 v191, v187, v29
	v_fmac_f32_e32 v238, v183, v41
	v_fmac_f32_e32 v239, v187, v41
	v_fmac_f32_e32 v190, v184, v30
	v_fmac_f32_e32 v191, v188, v30
	v_fmac_f32_e32 v238, v184, v42
	v_fmac_f32_e32 v239, v188, v42
	v_fmac_f32_e32 v190, v185, v31
	v_fmac_f32_e32 v191, v189, v31
	v_fmac_f32_e32 v238, v185, v43
	v_fmac_f32_e32 v239, v189, v43
	v_add_f32_dpp v190, v190, v190 quad_perm:[1,0,3,2] row_mask:0xf bank_mask:0xf bound_ctrl:1
	v_add_f32_dpp v191, v191, v191 quad_perm:[1,0,3,2] row_mask:0xf bank_mask:0xf bound_ctrl:1
	v_add_f32_dpp v238, v238, v238 quad_perm:[1,0,3,2] row_mask:0xf bank_mask:0xf bound_ctrl:1
	v_add_f32_dpp v239, v239, v239 quad_perm:[1,0,3,2] row_mask:0xf bank_mask:0xf bound_ctrl:1
	v_add_f32_dpp v190, v190, v190 quad_perm:[2,3,0,1] row_mask:0xf bank_mask:0xf bound_ctrl:1
	v_add_f32_dpp v191, v191, v191 quad_perm:[2,3,0,1] row_mask:0xf bank_mask:0xf bound_ctrl:1
	v_add_f32_dpp v238, v238, v238 quad_perm:[2,3,0,1] row_mask:0xf bank_mask:0xf bound_ctrl:1
	v_add_f32_dpp v239, v239, v239 quad_perm:[2,3,0,1] row_mask:0xf bank_mask:0xf bound_ctrl:1
	v_add_f32_dpp v190, v190, v190 row_half_mirror row_mask:0xf bank_mask:0xf bound_ctrl:1
	v_add_f32_dpp v191, v191, v191 row_half_mirror row_mask:0xf bank_mask:0xf bound_ctrl:1
	v_add_f32_dpp v238, v238, v238 row_half_mirror row_mask:0xf bank_mask:0xf bound_ctrl:1
	v_add_f32_dpp v239, v239, v239 row_half_mirror row_mask:0xf bank_mask:0xf bound_ctrl:1
	v_add_f32_dpp v190, v190, v190 row_mirror row_mask:0xf bank_mask:0xf bound_ctrl:1
	v_add_f32_dpp v191, v191, v191 row_mirror row_mask:0xf bank_mask:0xf bound_ctrl:1
	v_fmac_f32_e32 v182, v66, v36
	v_fmac_f32_e32 v183, v66, v37
	v_fmac_f32_e32 v184, v66, v38
	v_fmac_f32_e32 v185, v66, v39
	v_fmac_f32_e32 v186, v67, v36
	v_fmac_f32_e32 v187, v67, v37
	v_fmac_f32_e32 v188, v67, v38
	v_fmac_f32_e32 v189, v67, v39
	v_fmac_f32_e32 v182, v190, v32
	v_fmac_f32_e32 v183, v190, v33
	v_fmac_f32_e32 v184, v190, v34
	v_fmac_f32_e32 v185, v190, v35
	v_fmac_f32_e32 v186, v191, v32
	v_fmac_f32_e32 v187, v191, v33
	v_fmac_f32_e32 v188, v191, v34
	v_fmac_f32_e32 v189, v191, v35
	s_mov_b64 exec, s[8:9]
	ds_write2st64_b64 v146, v[128:129], v[238:239] offset0:6 offset1:7
	s_mov_b64 exec, -1
	ds_read_b128 v[28:31], v151 offset:10752
	ds_read_b128 v[32:35], v151 offset:18944
	ds_read_b128 v[36:39], v151 offset:27136
	ds_read_b128 v[40:43], v151 offset:35328
	ds_read_b64 v[66:67], v181 offset:2560
	s_waitcnt lgkmcnt(11)
	v_mul_f32_e32 v190, v182, v48
	v_mul_f32_e32 v191, v186, v48
	v_mul_f32_e32 v128, v182, v60
	v_mul_f32_e32 v129, v186, v60
	v_fmac_f32_e32 v190, v183, v49
	v_fmac_f32_e32 v191, v187, v49
	v_fmac_f32_e32 v128, v183, v61
	v_fmac_f32_e32 v129, v187, v61
	v_fmac_f32_e32 v190, v184, v50
	v_fmac_f32_e32 v191, v188, v50
	v_fmac_f32_e32 v128, v184, v62
	v_fmac_f32_e32 v129, v188, v62
	v_fmac_f32_e32 v190, v185, v51
	v_fmac_f32_e32 v191, v189, v51
	v_fmac_f32_e32 v128, v185, v63
	v_fmac_f32_e32 v129, v189, v63
	v_add_f32_dpp v190, v190, v190 quad_perm:[1,0,3,2] row_mask:0xf bank_mask:0xf bound_ctrl:1
	v_add_f32_dpp v191, v191, v191 quad_perm:[1,0,3,2] row_mask:0xf bank_mask:0xf bound_ctrl:1
	v_add_f32_dpp v128, v128, v128 quad_perm:[1,0,3,2] row_mask:0xf bank_mask:0xf bound_ctrl:1
	v_add_f32_dpp v129, v129, v129 quad_perm:[1,0,3,2] row_mask:0xf bank_mask:0xf bound_ctrl:1
	v_add_f32_dpp v190, v190, v190 quad_perm:[2,3,0,1] row_mask:0xf bank_mask:0xf bound_ctrl:1
	v_add_f32_dpp v191, v191, v191 quad_perm:[2,3,0,1] row_mask:0xf bank_mask:0xf bound_ctrl:1
	v_add_f32_dpp v128, v128, v128 quad_perm:[2,3,0,1] row_mask:0xf bank_mask:0xf bound_ctrl:1
	v_add_f32_dpp v129, v129, v129 quad_perm:[2,3,0,1] row_mask:0xf bank_mask:0xf bound_ctrl:1
	v_add_f32_dpp v190, v190, v190 row_half_mirror row_mask:0xf bank_mask:0xf bound_ctrl:1
	v_add_f32_dpp v191, v191, v191 row_half_mirror row_mask:0xf bank_mask:0xf bound_ctrl:1
	v_add_f32_dpp v128, v128, v128 row_half_mirror row_mask:0xf bank_mask:0xf bound_ctrl:1
	v_add_f32_dpp v129, v129, v129 row_half_mirror row_mask:0xf bank_mask:0xf bound_ctrl:1
	v_add_f32_dpp v190, v190, v190 row_mirror row_mask:0xf bank_mask:0xf bound_ctrl:1
	v_add_f32_dpp v191, v191, v191 row_mirror row_mask:0xf bank_mask:0xf bound_ctrl:1
	v_fmac_f32_e32 v182, v126, v56
	v_fmac_f32_e32 v183, v126, v57
	v_fmac_f32_e32 v184, v126, v58
	v_fmac_f32_e32 v185, v126, v59
	v_fmac_f32_e32 v186, v127, v56
	v_fmac_f32_e32 v187, v127, v57
	v_fmac_f32_e32 v188, v127, v58
	v_fmac_f32_e32 v189, v127, v59
	v_fmac_f32_e32 v182, v190, v52
	v_fmac_f32_e32 v183, v190, v53
	v_fmac_f32_e32 v184, v190, v54
	v_fmac_f32_e32 v185, v190, v55
	v_fmac_f32_e32 v186, v191, v52
	v_fmac_f32_e32 v187, v191, v53
	v_fmac_f32_e32 v188, v191, v54
	v_fmac_f32_e32 v189, v191, v55
	ds_read_b128 v[48:51], v151 offset:11008
	ds_read_b128 v[52:55], v151 offset:19200
	ds_read_b128 v[56:59], v151 offset:27392
	ds_read_b128 v[60:63], v151 offset:35584
	ds_read_b64 v[126:127], v181 offset:2816
	s_waitcnt lgkmcnt(11)
	v_mul_f32_e32 v190, v182, v8
	v_mul_f32_e32 v191, v186, v8
	v_mul_f32_e32 v238, v182, v20
	v_mul_f32_e32 v239, v186, v20
	v_fmac_f32_e32 v190, v183, v9
	v_fmac_f32_e32 v191, v187, v9
	v_fmac_f32_e32 v238, v183, v21
	v_fmac_f32_e32 v239, v187, v21
	v_fmac_f32_e32 v190, v184, v10
	v_fmac_f32_e32 v191, v188, v10
	v_fmac_f32_e32 v238, v184, v22
	v_fmac_f32_e32 v239, v188, v22
	v_fmac_f32_e32 v190, v185, v11
	v_fmac_f32_e32 v191, v189, v11
	v_fmac_f32_e32 v238, v185, v23
	v_fmac_f32_e32 v239, v189, v23
	v_add_f32_dpp v190, v190, v190 quad_perm:[1,0,3,2] row_mask:0xf bank_mask:0xf bound_ctrl:1
	v_add_f32_dpp v191, v191, v191 quad_perm:[1,0,3,2] row_mask:0xf bank_mask:0xf bound_ctrl:1
	v_add_f32_dpp v238, v238, v238 quad_perm:[1,0,3,2] row_mask:0xf bank_mask:0xf bound_ctrl:1
	v_add_f32_dpp v239, v239, v239 quad_perm:[1,0,3,2] row_mask:0xf bank_mask:0xf bound_ctrl:1
	v_add_f32_dpp v190, v190, v190 quad_perm:[2,3,0,1] row_mask:0xf bank_mask:0xf bound_ctrl:1
	v_add_f32_dpp v191, v191, v191 quad_perm:[2,3,0,1] row_mask:0xf bank_mask:0xf bound_ctrl:1
	v_add_f32_dpp v238, v238, v238 quad_perm:[2,3,0,1] row_mask:0xf bank_mask:0xf bound_ctrl:1
	v_add_f32_dpp v239, v239, v239 quad_perm:[2,3,0,1] row_mask:0xf bank_mask:0xf bound_ctrl:1
	v_add_f32_dpp v190, v190, v190 row_half_mirror row_mask:0xf bank_mask:0xf bound_ctrl:1
	v_add_f32_dpp v191, v191, v191 row_half_mirror row_mask:0xf bank_mask:0xf bound_ctrl:1
	v_add_f32_dpp v238, v238, v238 row_half_mirror row_mask:0xf bank_mask:0xf bound_ctrl:1
	v_add_f32_dpp v239, v239, v239 row_half_mirror row_mask:0xf bank_mask:0xf bound_ctrl:1
	v_add_f32_dpp v190, v190, v190 row_mirror row_mask:0xf bank_mask:0xf bound_ctrl:1
	v_add_f32_dpp v191, v191, v191 row_mirror row_mask:0xf bank_mask:0xf bound_ctrl:1
	v_fmac_f32_e32 v182, v64, v16
	v_fmac_f32_e32 v183, v64, v17
	v_fmac_f32_e32 v184, v64, v18
	v_fmac_f32_e32 v185, v64, v19
	v_fmac_f32_e32 v186, v65, v16
	v_fmac_f32_e32 v187, v65, v17
	v_fmac_f32_e32 v188, v65, v18
	v_fmac_f32_e32 v189, v65, v19
	v_fmac_f32_e32 v182, v190, v12
	v_fmac_f32_e32 v183, v190, v13
	v_fmac_f32_e32 v184, v190, v14
	v_fmac_f32_e32 v185, v190, v15
	v_fmac_f32_e32 v186, v191, v12
	v_fmac_f32_e32 v187, v191, v13
	v_fmac_f32_e32 v188, v191, v14
	v_fmac_f32_e32 v189, v191, v15
	s_mov_b64 exec, s[8:9]
	ds_write2st64_b64 v146, v[128:129], v[238:239] offset0:8 offset1:9
	s_mov_b64 exec, -1
	ds_read_b128 v[8:11], v151 offset:11264
	ds_read_b128 v[12:15], v151 offset:19456
	ds_read_b128 v[16:19], v151 offset:27648
	ds_read_b128 v[20:23], v151 offset:35840
	ds_read_b64 v[64:65], v181 offset:3072
	s_waitcnt lgkmcnt(11)
	v_mul_f32_e32 v190, v182, v28
	v_mul_f32_e32 v191, v186, v28
	v_mul_f32_e32 v128, v182, v40
	v_mul_f32_e32 v129, v186, v40
	v_fmac_f32_e32 v190, v183, v29
	v_fmac_f32_e32 v191, v187, v29
	v_fmac_f32_e32 v128, v183, v41
	v_fmac_f32_e32 v129, v187, v41
	v_fmac_f32_e32 v190, v184, v30
	v_fmac_f32_e32 v191, v188, v30
	v_fmac_f32_e32 v128, v184, v42
	v_fmac_f32_e32 v129, v188, v42
	v_fmac_f32_e32 v190, v185, v31
	v_fmac_f32_e32 v191, v189, v31
	v_fmac_f32_e32 v128, v185, v43
	v_fmac_f32_e32 v129, v189, v43
	v_add_f32_dpp v190, v190, v190 quad_perm:[1,0,3,2] row_mask:0xf bank_mask:0xf bound_ctrl:1
	v_add_f32_dpp v191, v191, v191 quad_perm:[1,0,3,2] row_mask:0xf bank_mask:0xf bound_ctrl:1
	v_add_f32_dpp v128, v128, v128 quad_perm:[1,0,3,2] row_mask:0xf bank_mask:0xf bound_ctrl:1
	v_add_f32_dpp v129, v129, v129 quad_perm:[1,0,3,2] row_mask:0xf bank_mask:0xf bound_ctrl:1
	v_add_f32_dpp v190, v190, v190 quad_perm:[2,3,0,1] row_mask:0xf bank_mask:0xf bound_ctrl:1
	v_add_f32_dpp v191, v191, v191 quad_perm:[2,3,0,1] row_mask:0xf bank_mask:0xf bound_ctrl:1
	v_add_f32_dpp v128, v128, v128 quad_perm:[2,3,0,1] row_mask:0xf bank_mask:0xf bound_ctrl:1
	v_add_f32_dpp v129, v129, v129 quad_perm:[2,3,0,1] row_mask:0xf bank_mask:0xf bound_ctrl:1
	v_add_f32_dpp v190, v190, v190 row_half_mirror row_mask:0xf bank_mask:0xf bound_ctrl:1
	v_add_f32_dpp v191, v191, v191 row_half_mirror row_mask:0xf bank_mask:0xf bound_ctrl:1
	v_add_f32_dpp v128, v128, v128 row_half_mirror row_mask:0xf bank_mask:0xf bound_ctrl:1
	v_add_f32_dpp v129, v129, v129 row_half_mirror row_mask:0xf bank_mask:0xf bound_ctrl:1
	v_add_f32_dpp v190, v190, v190 row_mirror row_mask:0xf bank_mask:0xf bound_ctrl:1
	v_add_f32_dpp v191, v191, v191 row_mirror row_mask:0xf bank_mask:0xf bound_ctrl:1
	v_fmac_f32_e32 v182, v66, v36
	v_fmac_f32_e32 v183, v66, v37
	v_fmac_f32_e32 v184, v66, v38
	v_fmac_f32_e32 v185, v66, v39
	v_fmac_f32_e32 v186, v67, v36
	v_fmac_f32_e32 v187, v67, v37
	v_fmac_f32_e32 v188, v67, v38
	v_fmac_f32_e32 v189, v67, v39
	v_fmac_f32_e32 v182, v190, v32
	v_fmac_f32_e32 v183, v190, v33
	v_fmac_f32_e32 v184, v190, v34
	v_fmac_f32_e32 v185, v190, v35
	v_fmac_f32_e32 v186, v191, v32
	v_fmac_f32_e32 v187, v191, v33
	v_fmac_f32_e32 v188, v191, v34
	v_fmac_f32_e32 v189, v191, v35
	ds_read_b128 v[28:31], v151 offset:11520
	ds_read_b128 v[32:35], v151 offset:19712
	ds_read_b128 v[36:39], v151 offset:27904
	ds_read_b128 v[40:43], v151 offset:36096
	ds_read_b64 v[66:67], v181 offset:3328
	s_waitcnt lgkmcnt(11)
	v_mul_f32_e32 v190, v182, v48
	v_mul_f32_e32 v191, v186, v48
	v_mul_f32_e32 v238, v182, v60
	v_mul_f32_e32 v239, v186, v60
	v_fmac_f32_e32 v190, v183, v49
	v_fmac_f32_e32 v191, v187, v49
	v_fmac_f32_e32 v238, v183, v61
	v_fmac_f32_e32 v239, v187, v61
	v_fmac_f32_e32 v190, v184, v50
	v_fmac_f32_e32 v191, v188, v50
	v_fmac_f32_e32 v238, v184, v62
	v_fmac_f32_e32 v239, v188, v62
	v_fmac_f32_e32 v190, v185, v51
	v_fmac_f32_e32 v191, v189, v51
	v_fmac_f32_e32 v238, v185, v63
	v_fmac_f32_e32 v239, v189, v63
	v_add_f32_dpp v190, v190, v190 quad_perm:[1,0,3,2] row_mask:0xf bank_mask:0xf bound_ctrl:1
	v_add_f32_dpp v191, v191, v191 quad_perm:[1,0,3,2] row_mask:0xf bank_mask:0xf bound_ctrl:1
	v_add_f32_dpp v238, v238, v238 quad_perm:[1,0,3,2] row_mask:0xf bank_mask:0xf bound_ctrl:1
	v_add_f32_dpp v239, v239, v239 quad_perm:[1,0,3,2] row_mask:0xf bank_mask:0xf bound_ctrl:1
	v_add_f32_dpp v190, v190, v190 quad_perm:[2,3,0,1] row_mask:0xf bank_mask:0xf bound_ctrl:1
	v_add_f32_dpp v191, v191, v191 quad_perm:[2,3,0,1] row_mask:0xf bank_mask:0xf bound_ctrl:1
	v_add_f32_dpp v238, v238, v238 quad_perm:[2,3,0,1] row_mask:0xf bank_mask:0xf bound_ctrl:1
	v_add_f32_dpp v239, v239, v239 quad_perm:[2,3,0,1] row_mask:0xf bank_mask:0xf bound_ctrl:1
	v_add_f32_dpp v190, v190, v190 row_half_mirror row_mask:0xf bank_mask:0xf bound_ctrl:1
	v_add_f32_dpp v191, v191, v191 row_half_mirror row_mask:0xf bank_mask:0xf bound_ctrl:1
	v_add_f32_dpp v238, v238, v238 row_half_mirror row_mask:0xf bank_mask:0xf bound_ctrl:1
	v_add_f32_dpp v239, v239, v239 row_half_mirror row_mask:0xf bank_mask:0xf bound_ctrl:1
	v_add_f32_dpp v190, v190, v190 row_mirror row_mask:0xf bank_mask:0xf bound_ctrl:1
	v_add_f32_dpp v191, v191, v191 row_mirror row_mask:0xf bank_mask:0xf bound_ctrl:1
	v_fmac_f32_e32 v182, v126, v56
	v_fmac_f32_e32 v183, v126, v57
	v_fmac_f32_e32 v184, v126, v58
	v_fmac_f32_e32 v185, v126, v59
	v_fmac_f32_e32 v186, v127, v56
	v_fmac_f32_e32 v187, v127, v57
	v_fmac_f32_e32 v188, v127, v58
	v_fmac_f32_e32 v189, v127, v59
	v_fmac_f32_e32 v182, v190, v52
	v_fmac_f32_e32 v183, v190, v53
	v_fmac_f32_e32 v184, v190, v54
	v_fmac_f32_e32 v185, v190, v55
	v_fmac_f32_e32 v186, v191, v52
	v_fmac_f32_e32 v187, v191, v53
	v_fmac_f32_e32 v188, v191, v54
	v_fmac_f32_e32 v189, v191, v55
	s_mov_b64 exec, s[8:9]
	ds_write2st64_b64 v146, v[128:129], v[238:239] offset0:10 offset1:11
	s_mov_b64 exec, -1
	ds_read_b128 v[48:51], v151 offset:11776
	ds_read_b128 v[52:55], v151 offset:19968
	ds_read_b128 v[56:59], v151 offset:28160
	ds_read_b128 v[60:63], v151 offset:36352
	ds_read_b64 v[126:127], v181 offset:3584
	s_waitcnt lgkmcnt(11)
	v_mul_f32_e32 v190, v182, v8
	v_mul_f32_e32 v191, v186, v8
	v_mul_f32_e32 v128, v182, v20
	v_mul_f32_e32 v129, v186, v20
	v_fmac_f32_e32 v190, v183, v9
	v_fmac_f32_e32 v191, v187, v9
	v_fmac_f32_e32 v128, v183, v21
	v_fmac_f32_e32 v129, v187, v21
	v_fmac_f32_e32 v190, v184, v10
	v_fmac_f32_e32 v191, v188, v10
	v_fmac_f32_e32 v128, v184, v22
	v_fmac_f32_e32 v129, v188, v22
	v_fmac_f32_e32 v190, v185, v11
	v_fmac_f32_e32 v191, v189, v11
	v_fmac_f32_e32 v128, v185, v23
	v_fmac_f32_e32 v129, v189, v23
	v_add_f32_dpp v190, v190, v190 quad_perm:[1,0,3,2] row_mask:0xf bank_mask:0xf bound_ctrl:1
	v_add_f32_dpp v191, v191, v191 quad_perm:[1,0,3,2] row_mask:0xf bank_mask:0xf bound_ctrl:1
	v_add_f32_dpp v128, v128, v128 quad_perm:[1,0,3,2] row_mask:0xf bank_mask:0xf bound_ctrl:1
	v_add_f32_dpp v129, v129, v129 quad_perm:[1,0,3,2] row_mask:0xf bank_mask:0xf bound_ctrl:1
	v_add_f32_dpp v190, v190, v190 quad_perm:[2,3,0,1] row_mask:0xf bank_mask:0xf bound_ctrl:1
	v_add_f32_dpp v191, v191, v191 quad_perm:[2,3,0,1] row_mask:0xf bank_mask:0xf bound_ctrl:1
	v_add_f32_dpp v128, v128, v128 quad_perm:[2,3,0,1] row_mask:0xf bank_mask:0xf bound_ctrl:1
	v_add_f32_dpp v129, v129, v129 quad_perm:[2,3,0,1] row_mask:0xf bank_mask:0xf bound_ctrl:1
	v_add_f32_dpp v190, v190, v190 row_half_mirror row_mask:0xf bank_mask:0xf bound_ctrl:1
	v_add_f32_dpp v191, v191, v191 row_half_mirror row_mask:0xf bank_mask:0xf bound_ctrl:1
	v_add_f32_dpp v128, v128, v128 row_half_mirror row_mask:0xf bank_mask:0xf bound_ctrl:1
	v_add_f32_dpp v129, v129, v129 row_half_mirror row_mask:0xf bank_mask:0xf bound_ctrl:1
	v_add_f32_dpp v190, v190, v190 row_mirror row_mask:0xf bank_mask:0xf bound_ctrl:1
	v_add_f32_dpp v191, v191, v191 row_mirror row_mask:0xf bank_mask:0xf bound_ctrl:1
	v_fmac_f32_e32 v182, v64, v16
	v_fmac_f32_e32 v183, v64, v17
	v_fmac_f32_e32 v184, v64, v18
	v_fmac_f32_e32 v185, v64, v19
	v_fmac_f32_e32 v186, v65, v16
	v_fmac_f32_e32 v187, v65, v17
	v_fmac_f32_e32 v188, v65, v18
	v_fmac_f32_e32 v189, v65, v19
	v_fmac_f32_e32 v182, v190, v12
	v_fmac_f32_e32 v183, v190, v13
	v_fmac_f32_e32 v184, v190, v14
	v_fmac_f32_e32 v185, v190, v15
	v_fmac_f32_e32 v186, v191, v12
	v_fmac_f32_e32 v187, v191, v13
	v_fmac_f32_e32 v188, v191, v14
	v_fmac_f32_e32 v189, v191, v15
	ds_read_b128 v[8:11], v151 offset:12032
	ds_read_b128 v[12:15], v151 offset:20224
	ds_read_b128 v[16:19], v151 offset:28416
	ds_read_b128 v[20:23], v151 offset:36608
	ds_read_b64 v[64:65], v181 offset:3840
	s_waitcnt lgkmcnt(11)
	v_mul_f32_e32 v190, v182, v28
	v_mul_f32_e32 v191, v186, v28
	v_mul_f32_e32 v238, v182, v40
	v_mul_f32_e32 v239, v186, v40
	v_fmac_f32_e32 v190, v183, v29
	v_fmac_f32_e32 v191, v187, v29
	v_fmac_f32_e32 v238, v183, v41
	v_fmac_f32_e32 v239, v187, v41
	v_fmac_f32_e32 v190, v184, v30
	v_fmac_f32_e32 v191, v188, v30
	v_fmac_f32_e32 v238, v184, v42
	v_fmac_f32_e32 v239, v188, v42
	v_fmac_f32_e32 v190, v185, v31
	v_fmac_f32_e32 v191, v189, v31
	v_fmac_f32_e32 v238, v185, v43
	v_fmac_f32_e32 v239, v189, v43
	v_add_f32_dpp v190, v190, v190 quad_perm:[1,0,3,2] row_mask:0xf bank_mask:0xf bound_ctrl:1
	v_add_f32_dpp v191, v191, v191 quad_perm:[1,0,3,2] row_mask:0xf bank_mask:0xf bound_ctrl:1
	v_add_f32_dpp v238, v238, v238 quad_perm:[1,0,3,2] row_mask:0xf bank_mask:0xf bound_ctrl:1
	v_add_f32_dpp v239, v239, v239 quad_perm:[1,0,3,2] row_mask:0xf bank_mask:0xf bound_ctrl:1
	v_add_f32_dpp v190, v190, v190 quad_perm:[2,3,0,1] row_mask:0xf bank_mask:0xf bound_ctrl:1
	v_add_f32_dpp v191, v191, v191 quad_perm:[2,3,0,1] row_mask:0xf bank_mask:0xf bound_ctrl:1
	v_add_f32_dpp v238, v238, v238 quad_perm:[2,3,0,1] row_mask:0xf bank_mask:0xf bound_ctrl:1
	v_add_f32_dpp v239, v239, v239 quad_perm:[2,3,0,1] row_mask:0xf bank_mask:0xf bound_ctrl:1
	v_add_f32_dpp v190, v190, v190 row_half_mirror row_mask:0xf bank_mask:0xf bound_ctrl:1
	v_add_f32_dpp v191, v191, v191 row_half_mirror row_mask:0xf bank_mask:0xf bound_ctrl:1
	v_add_f32_dpp v238, v238, v238 row_half_mirror row_mask:0xf bank_mask:0xf bound_ctrl:1
	v_add_f32_dpp v239, v239, v239 row_half_mirror row_mask:0xf bank_mask:0xf bound_ctrl:1
	v_add_f32_dpp v190, v190, v190 row_mirror row_mask:0xf bank_mask:0xf bound_ctrl:1
	v_add_f32_dpp v191, v191, v191 row_mirror row_mask:0xf bank_mask:0xf bound_ctrl:1
	v_fmac_f32_e32 v182, v66, v36
	v_fmac_f32_e32 v183, v66, v37
	v_fmac_f32_e32 v184, v66, v38
	v_fmac_f32_e32 v185, v66, v39
	v_fmac_f32_e32 v186, v67, v36
	v_fmac_f32_e32 v187, v67, v37
	v_fmac_f32_e32 v188, v67, v38
	v_fmac_f32_e32 v189, v67, v39
	v_fmac_f32_e32 v182, v190, v32
	v_fmac_f32_e32 v183, v190, v33
	v_fmac_f32_e32 v184, v190, v34
	v_fmac_f32_e32 v185, v190, v35
	v_fmac_f32_e32 v186, v191, v32
	v_fmac_f32_e32 v187, v191, v33
	v_fmac_f32_e32 v188, v191, v34
	v_fmac_f32_e32 v189, v191, v35
	s_mov_b64 exec, s[8:9]
	ds_write2st64_b64 v146, v[128:129], v[238:239] offset0:12 offset1:13
	s_mov_b64 exec, -1
	ds_read_b128 v[28:31], v151 offset:12288
	ds_read_b128 v[32:35], v151 offset:20480
	ds_read_b128 v[36:39], v151 offset:28672
	ds_read_b128 v[40:43], v151 offset:36864
	ds_read_b64 v[66:67], v181 offset:4096
	s_waitcnt lgkmcnt(11)
	v_mul_f32_e32 v190, v182, v48
	v_mul_f32_e32 v191, v186, v48
	v_mul_f32_e32 v128, v182, v60
	v_mul_f32_e32 v129, v186, v60
	v_fmac_f32_e32 v190, v183, v49
	v_fmac_f32_e32 v191, v187, v49
	v_fmac_f32_e32 v128, v183, v61
	v_fmac_f32_e32 v129, v187, v61
	v_fmac_f32_e32 v190, v184, v50
	v_fmac_f32_e32 v191, v188, v50
	v_fmac_f32_e32 v128, v184, v62
	v_fmac_f32_e32 v129, v188, v62
	v_fmac_f32_e32 v190, v185, v51
	v_fmac_f32_e32 v191, v189, v51
	v_fmac_f32_e32 v128, v185, v63
	v_fmac_f32_e32 v129, v189, v63
	v_add_f32_dpp v190, v190, v190 quad_perm:[1,0,3,2] row_mask:0xf bank_mask:0xf bound_ctrl:1
	v_add_f32_dpp v191, v191, v191 quad_perm:[1,0,3,2] row_mask:0xf bank_mask:0xf bound_ctrl:1
	v_add_f32_dpp v128, v128, v128 quad_perm:[1,0,3,2] row_mask:0xf bank_mask:0xf bound_ctrl:1
	v_add_f32_dpp v129, v129, v129 quad_perm:[1,0,3,2] row_mask:0xf bank_mask:0xf bound_ctrl:1
	v_add_f32_dpp v190, v190, v190 quad_perm:[2,3,0,1] row_mask:0xf bank_mask:0xf bound_ctrl:1
	v_add_f32_dpp v191, v191, v191 quad_perm:[2,3,0,1] row_mask:0xf bank_mask:0xf bound_ctrl:1
	v_add_f32_dpp v128, v128, v128 quad_perm:[2,3,0,1] row_mask:0xf bank_mask:0xf bound_ctrl:1
	v_add_f32_dpp v129, v129, v129 quad_perm:[2,3,0,1] row_mask:0xf bank_mask:0xf bound_ctrl:1
	v_add_f32_dpp v190, v190, v190 row_half_mirror row_mask:0xf bank_mask:0xf bound_ctrl:1
	v_add_f32_dpp v191, v191, v191 row_half_mirror row_mask:0xf bank_mask:0xf bound_ctrl:1
	v_add_f32_dpp v128, v128, v128 row_half_mirror row_mask:0xf bank_mask:0xf bound_ctrl:1
	v_add_f32_dpp v129, v129, v129 row_half_mirror row_mask:0xf bank_mask:0xf bound_ctrl:1
	v_add_f32_dpp v190, v190, v190 row_mirror row_mask:0xf bank_mask:0xf bound_ctrl:1
	v_add_f32_dpp v191, v191, v191 row_mirror row_mask:0xf bank_mask:0xf bound_ctrl:1
	v_fmac_f32_e32 v182, v126, v56
	v_fmac_f32_e32 v183, v126, v57
	v_fmac_f32_e32 v184, v126, v58
	v_fmac_f32_e32 v185, v126, v59
	v_fmac_f32_e32 v186, v127, v56
	v_fmac_f32_e32 v187, v127, v57
	v_fmac_f32_e32 v188, v127, v58
	v_fmac_f32_e32 v189, v127, v59
	v_fmac_f32_e32 v182, v190, v52
	v_fmac_f32_e32 v183, v190, v53
	v_fmac_f32_e32 v184, v190, v54
	v_fmac_f32_e32 v185, v190, v55
	v_fmac_f32_e32 v186, v191, v52
	v_fmac_f32_e32 v187, v191, v53
	v_fmac_f32_e32 v188, v191, v54
	v_fmac_f32_e32 v189, v191, v55
	ds_read_b128 v[48:51], v151 offset:12544
	ds_read_b128 v[52:55], v151 offset:20736
	ds_read_b128 v[56:59], v151 offset:28928
	ds_read_b128 v[60:63], v151 offset:37120
	ds_read_b64 v[126:127], v181 offset:4352
	s_waitcnt lgkmcnt(11)
	v_mul_f32_e32 v190, v182, v8
	v_mul_f32_e32 v191, v186, v8
	v_mul_f32_e32 v238, v182, v20
	v_mul_f32_e32 v239, v186, v20
	v_fmac_f32_e32 v190, v183, v9
	v_fmac_f32_e32 v191, v187, v9
	v_fmac_f32_e32 v238, v183, v21
	v_fmac_f32_e32 v239, v187, v21
	v_fmac_f32_e32 v190, v184, v10
	v_fmac_f32_e32 v191, v188, v10
	v_fmac_f32_e32 v238, v184, v22
	v_fmac_f32_e32 v239, v188, v22
	v_fmac_f32_e32 v190, v185, v11
	v_fmac_f32_e32 v191, v189, v11
	v_fmac_f32_e32 v238, v185, v23
	v_fmac_f32_e32 v239, v189, v23
	v_add_f32_dpp v190, v190, v190 quad_perm:[1,0,3,2] row_mask:0xf bank_mask:0xf bound_ctrl:1
	v_add_f32_dpp v191, v191, v191 quad_perm:[1,0,3,2] row_mask:0xf bank_mask:0xf bound_ctrl:1
	v_add_f32_dpp v238, v238, v238 quad_perm:[1,0,3,2] row_mask:0xf bank_mask:0xf bound_ctrl:1
	v_add_f32_dpp v239, v239, v239 quad_perm:[1,0,3,2] row_mask:0xf bank_mask:0xf bound_ctrl:1
	v_add_f32_dpp v190, v190, v190 quad_perm:[2,3,0,1] row_mask:0xf bank_mask:0xf bound_ctrl:1
	v_add_f32_dpp v191, v191, v191 quad_perm:[2,3,0,1] row_mask:0xf bank_mask:0xf bound_ctrl:1
	v_add_f32_dpp v238, v238, v238 quad_perm:[2,3,0,1] row_mask:0xf bank_mask:0xf bound_ctrl:1
	v_add_f32_dpp v239, v239, v239 quad_perm:[2,3,0,1] row_mask:0xf bank_mask:0xf bound_ctrl:1
	v_add_f32_dpp v190, v190, v190 row_half_mirror row_mask:0xf bank_mask:0xf bound_ctrl:1
	v_add_f32_dpp v191, v191, v191 row_half_mirror row_mask:0xf bank_mask:0xf bound_ctrl:1
	v_add_f32_dpp v238, v238, v238 row_half_mirror row_mask:0xf bank_mask:0xf bound_ctrl:1
	v_add_f32_dpp v239, v239, v239 row_half_mirror row_mask:0xf bank_mask:0xf bound_ctrl:1
	v_add_f32_dpp v190, v190, v190 row_mirror row_mask:0xf bank_mask:0xf bound_ctrl:1
	v_add_f32_dpp v191, v191, v191 row_mirror row_mask:0xf bank_mask:0xf bound_ctrl:1
	v_fmac_f32_e32 v182, v64, v16
	v_fmac_f32_e32 v183, v64, v17
	v_fmac_f32_e32 v184, v64, v18
	v_fmac_f32_e32 v185, v64, v19
	v_fmac_f32_e32 v186, v65, v16
	v_fmac_f32_e32 v187, v65, v17
	v_fmac_f32_e32 v188, v65, v18
	v_fmac_f32_e32 v189, v65, v19
	v_fmac_f32_e32 v182, v190, v12
	v_fmac_f32_e32 v183, v190, v13
	v_fmac_f32_e32 v184, v190, v14
	v_fmac_f32_e32 v185, v190, v15
	v_fmac_f32_e32 v186, v191, v12
	v_fmac_f32_e32 v187, v191, v13
	v_fmac_f32_e32 v188, v191, v14
	v_fmac_f32_e32 v189, v191, v15
	s_mov_b64 exec, s[8:9]
	ds_write2st64_b64 v146, v[128:129], v[238:239] offset0:14 offset1:15
	s_mov_b64 exec, -1
	ds_read_b128 v[8:11], v151 offset:12800
	ds_read_b128 v[12:15], v151 offset:20992
	ds_read_b128 v[16:19], v151 offset:29184
	ds_read_b128 v[20:23], v151 offset:37376
	ds_read_b64 v[64:65], v181 offset:4608
	s_waitcnt lgkmcnt(11)
	v_mul_f32_e32 v190, v182, v28
	v_mul_f32_e32 v191, v186, v28
	v_mul_f32_e32 v128, v182, v40
	v_mul_f32_e32 v129, v186, v40
	v_fmac_f32_e32 v190, v183, v29
	v_fmac_f32_e32 v191, v187, v29
	v_fmac_f32_e32 v128, v183, v41
	v_fmac_f32_e32 v129, v187, v41
	v_fmac_f32_e32 v190, v184, v30
	v_fmac_f32_e32 v191, v188, v30
	v_fmac_f32_e32 v128, v184, v42
	v_fmac_f32_e32 v129, v188, v42
	v_fmac_f32_e32 v190, v185, v31
	v_fmac_f32_e32 v191, v189, v31
	v_fmac_f32_e32 v128, v185, v43
	v_fmac_f32_e32 v129, v189, v43
	v_add_f32_dpp v190, v190, v190 quad_perm:[1,0,3,2] row_mask:0xf bank_mask:0xf bound_ctrl:1
	v_add_f32_dpp v191, v191, v191 quad_perm:[1,0,3,2] row_mask:0xf bank_mask:0xf bound_ctrl:1
	v_add_f32_dpp v128, v128, v128 quad_perm:[1,0,3,2] row_mask:0xf bank_mask:0xf bound_ctrl:1
	v_add_f32_dpp v129, v129, v129 quad_perm:[1,0,3,2] row_mask:0xf bank_mask:0xf bound_ctrl:1
	v_add_f32_dpp v190, v190, v190 quad_perm:[2,3,0,1] row_mask:0xf bank_mask:0xf bound_ctrl:1
	v_add_f32_dpp v191, v191, v191 quad_perm:[2,3,0,1] row_mask:0xf bank_mask:0xf bound_ctrl:1
	v_add_f32_dpp v128, v128, v128 quad_perm:[2,3,0,1] row_mask:0xf bank_mask:0xf bound_ctrl:1
	v_add_f32_dpp v129, v129, v129 quad_perm:[2,3,0,1] row_mask:0xf bank_mask:0xf bound_ctrl:1
	v_add_f32_dpp v190, v190, v190 row_half_mirror row_mask:0xf bank_mask:0xf bound_ctrl:1
	v_add_f32_dpp v191, v191, v191 row_half_mirror row_mask:0xf bank_mask:0xf bound_ctrl:1
	v_add_f32_dpp v128, v128, v128 row_half_mirror row_mask:0xf bank_mask:0xf bound_ctrl:1
	v_add_f32_dpp v129, v129, v129 row_half_mirror row_mask:0xf bank_mask:0xf bound_ctrl:1
	v_add_f32_dpp v190, v190, v190 row_mirror row_mask:0xf bank_mask:0xf bound_ctrl:1
	v_add_f32_dpp v191, v191, v191 row_mirror row_mask:0xf bank_mask:0xf bound_ctrl:1
	v_fmac_f32_e32 v182, v66, v36
	v_fmac_f32_e32 v183, v66, v37
	v_fmac_f32_e32 v184, v66, v38
	v_fmac_f32_e32 v185, v66, v39
	v_fmac_f32_e32 v186, v67, v36
	v_fmac_f32_e32 v187, v67, v37
	v_fmac_f32_e32 v188, v67, v38
	v_fmac_f32_e32 v189, v67, v39
	v_fmac_f32_e32 v182, v190, v32
	v_fmac_f32_e32 v183, v190, v33
	v_fmac_f32_e32 v184, v190, v34
	v_fmac_f32_e32 v185, v190, v35
	v_fmac_f32_e32 v186, v191, v32
	v_fmac_f32_e32 v187, v191, v33
	v_fmac_f32_e32 v188, v191, v34
	v_fmac_f32_e32 v189, v191, v35
	ds_read_b128 v[28:31], v151 offset:13056
	ds_read_b128 v[32:35], v151 offset:21248
	ds_read_b128 v[36:39], v151 offset:29440
	ds_read_b128 v[40:43], v151 offset:37632
	ds_read_b64 v[66:67], v181 offset:4864
	s_waitcnt lgkmcnt(11)
	v_mul_f32_e32 v190, v182, v48
	v_mul_f32_e32 v191, v186, v48
	v_mul_f32_e32 v238, v182, v60
	v_mul_f32_e32 v239, v186, v60
	v_fmac_f32_e32 v190, v183, v49
	v_fmac_f32_e32 v191, v187, v49
	v_fmac_f32_e32 v238, v183, v61
	v_fmac_f32_e32 v239, v187, v61
	v_fmac_f32_e32 v190, v184, v50
	v_fmac_f32_e32 v191, v188, v50
	v_fmac_f32_e32 v238, v184, v62
	v_fmac_f32_e32 v239, v188, v62
	v_fmac_f32_e32 v190, v185, v51
	v_fmac_f32_e32 v191, v189, v51
	v_fmac_f32_e32 v238, v185, v63
	v_fmac_f32_e32 v239, v189, v63
	v_add_f32_dpp v190, v190, v190 quad_perm:[1,0,3,2] row_mask:0xf bank_mask:0xf bound_ctrl:1
	v_add_f32_dpp v191, v191, v191 quad_perm:[1,0,3,2] row_mask:0xf bank_mask:0xf bound_ctrl:1
	v_add_f32_dpp v238, v238, v238 quad_perm:[1,0,3,2] row_mask:0xf bank_mask:0xf bound_ctrl:1
	v_add_f32_dpp v239, v239, v239 quad_perm:[1,0,3,2] row_mask:0xf bank_mask:0xf bound_ctrl:1
	v_add_f32_dpp v190, v190, v190 quad_perm:[2,3,0,1] row_mask:0xf bank_mask:0xf bound_ctrl:1
	v_add_f32_dpp v191, v191, v191 quad_perm:[2,3,0,1] row_mask:0xf bank_mask:0xf bound_ctrl:1
	v_add_f32_dpp v238, v238, v238 quad_perm:[2,3,0,1] row_mask:0xf bank_mask:0xf bound_ctrl:1
	v_add_f32_dpp v239, v239, v239 quad_perm:[2,3,0,1] row_mask:0xf bank_mask:0xf bound_ctrl:1
	v_add_f32_dpp v190, v190, v190 row_half_mirror row_mask:0xf bank_mask:0xf bound_ctrl:1
	v_add_f32_dpp v191, v191, v191 row_half_mirror row_mask:0xf bank_mask:0xf bound_ctrl:1
	v_add_f32_dpp v238, v238, v238 row_half_mirror row_mask:0xf bank_mask:0xf bound_ctrl:1
	v_add_f32_dpp v239, v239, v239 row_half_mirror row_mask:0xf bank_mask:0xf bound_ctrl:1
	v_add_f32_dpp v190, v190, v190 row_mirror row_mask:0xf bank_mask:0xf bound_ctrl:1
	v_add_f32_dpp v191, v191, v191 row_mirror row_mask:0xf bank_mask:0xf bound_ctrl:1
	v_fmac_f32_e32 v182, v126, v56
	v_fmac_f32_e32 v183, v126, v57
	v_fmac_f32_e32 v184, v126, v58
	v_fmac_f32_e32 v185, v126, v59
	v_fmac_f32_e32 v186, v127, v56
	v_fmac_f32_e32 v187, v127, v57
	v_fmac_f32_e32 v188, v127, v58
	v_fmac_f32_e32 v189, v127, v59
	v_fmac_f32_e32 v182, v190, v52
	v_fmac_f32_e32 v183, v190, v53
	v_fmac_f32_e32 v184, v190, v54
	v_fmac_f32_e32 v185, v190, v55
	v_fmac_f32_e32 v186, v191, v52
	v_fmac_f32_e32 v187, v191, v53
	v_fmac_f32_e32 v188, v191, v54
	v_fmac_f32_e32 v189, v191, v55
	s_mov_b64 exec, s[8:9]
	ds_write2st64_b64 v146, v[128:129], v[238:239] offset0:16 offset1:17
	s_mov_b64 exec, -1
	ds_read_b128 v[48:51], v151 offset:13312
	ds_read_b128 v[52:55], v151 offset:21504
	ds_read_b128 v[56:59], v151 offset:29696
	ds_read_b128 v[60:63], v151 offset:37888
	ds_read_b64 v[126:127], v181 offset:5120
	s_waitcnt lgkmcnt(11)
	v_mul_f32_e32 v190, v182, v8
	v_mul_f32_e32 v191, v186, v8
	v_mul_f32_e32 v128, v182, v20
	v_mul_f32_e32 v129, v186, v20
	v_fmac_f32_e32 v190, v183, v9
	v_fmac_f32_e32 v191, v187, v9
	v_fmac_f32_e32 v128, v183, v21
	v_fmac_f32_e32 v129, v187, v21
	v_fmac_f32_e32 v190, v184, v10
	v_fmac_f32_e32 v191, v188, v10
	v_fmac_f32_e32 v128, v184, v22
	v_fmac_f32_e32 v129, v188, v22
	v_fmac_f32_e32 v190, v185, v11
	v_fmac_f32_e32 v191, v189, v11
	v_fmac_f32_e32 v128, v185, v23
	v_fmac_f32_e32 v129, v189, v23
	v_add_f32_dpp v190, v190, v190 quad_perm:[1,0,3,2] row_mask:0xf bank_mask:0xf bound_ctrl:1
	v_add_f32_dpp v191, v191, v191 quad_perm:[1,0,3,2] row_mask:0xf bank_mask:0xf bound_ctrl:1
	v_add_f32_dpp v128, v128, v128 quad_perm:[1,0,3,2] row_mask:0xf bank_mask:0xf bound_ctrl:1
	v_add_f32_dpp v129, v129, v129 quad_perm:[1,0,3,2] row_mask:0xf bank_mask:0xf bound_ctrl:1
	v_add_f32_dpp v190, v190, v190 quad_perm:[2,3,0,1] row_mask:0xf bank_mask:0xf bound_ctrl:1
	v_add_f32_dpp v191, v191, v191 quad_perm:[2,3,0,1] row_mask:0xf bank_mask:0xf bound_ctrl:1
	v_add_f32_dpp v128, v128, v128 quad_perm:[2,3,0,1] row_mask:0xf bank_mask:0xf bound_ctrl:1
	v_add_f32_dpp v129, v129, v129 quad_perm:[2,3,0,1] row_mask:0xf bank_mask:0xf bound_ctrl:1
	v_add_f32_dpp v190, v190, v190 row_half_mirror row_mask:0xf bank_mask:0xf bound_ctrl:1
	v_add_f32_dpp v191, v191, v191 row_half_mirror row_mask:0xf bank_mask:0xf bound_ctrl:1
	v_add_f32_dpp v128, v128, v128 row_half_mirror row_mask:0xf bank_mask:0xf bound_ctrl:1
	v_add_f32_dpp v129, v129, v129 row_half_mirror row_mask:0xf bank_mask:0xf bound_ctrl:1
	v_add_f32_dpp v190, v190, v190 row_mirror row_mask:0xf bank_mask:0xf bound_ctrl:1
	v_add_f32_dpp v191, v191, v191 row_mirror row_mask:0xf bank_mask:0xf bound_ctrl:1
	v_fmac_f32_e32 v182, v64, v16
	v_fmac_f32_e32 v183, v64, v17
	v_fmac_f32_e32 v184, v64, v18
	v_fmac_f32_e32 v185, v64, v19
	v_fmac_f32_e32 v186, v65, v16
	v_fmac_f32_e32 v187, v65, v17
	v_fmac_f32_e32 v188, v65, v18
	v_fmac_f32_e32 v189, v65, v19
	v_fmac_f32_e32 v182, v190, v12
	v_fmac_f32_e32 v183, v190, v13
	v_fmac_f32_e32 v184, v190, v14
	v_fmac_f32_e32 v185, v190, v15
	v_fmac_f32_e32 v186, v191, v12
	v_fmac_f32_e32 v187, v191, v13
	v_fmac_f32_e32 v188, v191, v14
	v_fmac_f32_e32 v189, v191, v15
	ds_read_b128 v[8:11], v151 offset:13568
	ds_read_b128 v[12:15], v151 offset:21760
	ds_read_b128 v[16:19], v151 offset:29952
	ds_read_b128 v[20:23], v151 offset:38144
	ds_read_b64 v[64:65], v181 offset:5376
	s_waitcnt lgkmcnt(11)
	v_mul_f32_e32 v190, v182, v28
	v_mul_f32_e32 v191, v186, v28
	v_mul_f32_e32 v238, v182, v40
	v_mul_f32_e32 v239, v186, v40
	v_fmac_f32_e32 v190, v183, v29
	v_fmac_f32_e32 v191, v187, v29
	v_fmac_f32_e32 v238, v183, v41
	v_fmac_f32_e32 v239, v187, v41
	v_fmac_f32_e32 v190, v184, v30
	v_fmac_f32_e32 v191, v188, v30
	v_fmac_f32_e32 v238, v184, v42
	v_fmac_f32_e32 v239, v188, v42
	v_fmac_f32_e32 v190, v185, v31
	v_fmac_f32_e32 v191, v189, v31
	v_fmac_f32_e32 v238, v185, v43
	v_fmac_f32_e32 v239, v189, v43
	v_add_f32_dpp v190, v190, v190 quad_perm:[1,0,3,2] row_mask:0xf bank_mask:0xf bound_ctrl:1
	v_add_f32_dpp v191, v191, v191 quad_perm:[1,0,3,2] row_mask:0xf bank_mask:0xf bound_ctrl:1
	v_add_f32_dpp v238, v238, v238 quad_perm:[1,0,3,2] row_mask:0xf bank_mask:0xf bound_ctrl:1
	v_add_f32_dpp v239, v239, v239 quad_perm:[1,0,3,2] row_mask:0xf bank_mask:0xf bound_ctrl:1
	v_add_f32_dpp v190, v190, v190 quad_perm:[2,3,0,1] row_mask:0xf bank_mask:0xf bound_ctrl:1
	v_add_f32_dpp v191, v191, v191 quad_perm:[2,3,0,1] row_mask:0xf bank_mask:0xf bound_ctrl:1
	v_add_f32_dpp v238, v238, v238 quad_perm:[2,3,0,1] row_mask:0xf bank_mask:0xf bound_ctrl:1
	v_add_f32_dpp v239, v239, v239 quad_perm:[2,3,0,1] row_mask:0xf bank_mask:0xf bound_ctrl:1
	v_add_f32_dpp v190, v190, v190 row_half_mirror row_mask:0xf bank_mask:0xf bound_ctrl:1
	v_add_f32_dpp v191, v191, v191 row_half_mirror row_mask:0xf bank_mask:0xf bound_ctrl:1
	v_add_f32_dpp v238, v238, v238 row_half_mirror row_mask:0xf bank_mask:0xf bound_ctrl:1
	v_add_f32_dpp v239, v239, v239 row_half_mirror row_mask:0xf bank_mask:0xf bound_ctrl:1
	v_add_f32_dpp v190, v190, v190 row_mirror row_mask:0xf bank_mask:0xf bound_ctrl:1
	v_add_f32_dpp v191, v191, v191 row_mirror row_mask:0xf bank_mask:0xf bound_ctrl:1
	v_fmac_f32_e32 v182, v66, v36
	v_fmac_f32_e32 v183, v66, v37
	v_fmac_f32_e32 v184, v66, v38
	v_fmac_f32_e32 v185, v66, v39
	v_fmac_f32_e32 v186, v67, v36
	v_fmac_f32_e32 v187, v67, v37
	v_fmac_f32_e32 v188, v67, v38
	v_fmac_f32_e32 v189, v67, v39
	v_fmac_f32_e32 v182, v190, v32
	v_fmac_f32_e32 v183, v190, v33
	v_fmac_f32_e32 v184, v190, v34
	v_fmac_f32_e32 v185, v190, v35
	v_fmac_f32_e32 v186, v191, v32
	v_fmac_f32_e32 v187, v191, v33
	v_fmac_f32_e32 v188, v191, v34
	v_fmac_f32_e32 v189, v191, v35
	s_mov_b64 exec, s[8:9]
	ds_write2st64_b64 v146, v[128:129], v[238:239] offset0:18 offset1:19
	s_mov_b64 exec, -1
	ds_read_b128 v[28:31], v151 offset:13824
	ds_read_b128 v[32:35], v151 offset:22016
	ds_read_b128 v[36:39], v151 offset:30208
	ds_read_b128 v[40:43], v151 offset:38400
	ds_read_b64 v[66:67], v181 offset:5632
	s_waitcnt lgkmcnt(11)
	v_mul_f32_e32 v190, v182, v48
	v_mul_f32_e32 v191, v186, v48
	v_mul_f32_e32 v128, v182, v60
	v_mul_f32_e32 v129, v186, v60
	v_fmac_f32_e32 v190, v183, v49
	v_fmac_f32_e32 v191, v187, v49
	v_fmac_f32_e32 v128, v183, v61
	v_fmac_f32_e32 v129, v187, v61
	v_fmac_f32_e32 v190, v184, v50
	v_fmac_f32_e32 v191, v188, v50
	v_fmac_f32_e32 v128, v184, v62
	v_fmac_f32_e32 v129, v188, v62
	v_fmac_f32_e32 v190, v185, v51
	v_fmac_f32_e32 v191, v189, v51
	v_fmac_f32_e32 v128, v185, v63
	v_fmac_f32_e32 v129, v189, v63
	v_add_f32_dpp v190, v190, v190 quad_perm:[1,0,3,2] row_mask:0xf bank_mask:0xf bound_ctrl:1
	v_add_f32_dpp v191, v191, v191 quad_perm:[1,0,3,2] row_mask:0xf bank_mask:0xf bound_ctrl:1
	v_add_f32_dpp v128, v128, v128 quad_perm:[1,0,3,2] row_mask:0xf bank_mask:0xf bound_ctrl:1
	v_add_f32_dpp v129, v129, v129 quad_perm:[1,0,3,2] row_mask:0xf bank_mask:0xf bound_ctrl:1
	v_add_f32_dpp v190, v190, v190 quad_perm:[2,3,0,1] row_mask:0xf bank_mask:0xf bound_ctrl:1
	v_add_f32_dpp v191, v191, v191 quad_perm:[2,3,0,1] row_mask:0xf bank_mask:0xf bound_ctrl:1
	v_add_f32_dpp v128, v128, v128 quad_perm:[2,3,0,1] row_mask:0xf bank_mask:0xf bound_ctrl:1
	v_add_f32_dpp v129, v129, v129 quad_perm:[2,3,0,1] row_mask:0xf bank_mask:0xf bound_ctrl:1
	v_add_f32_dpp v190, v190, v190 row_half_mirror row_mask:0xf bank_mask:0xf bound_ctrl:1
	v_add_f32_dpp v191, v191, v191 row_half_mirror row_mask:0xf bank_mask:0xf bound_ctrl:1
	v_add_f32_dpp v128, v128, v128 row_half_mirror row_mask:0xf bank_mask:0xf bound_ctrl:1
	v_add_f32_dpp v129, v129, v129 row_half_mirror row_mask:0xf bank_mask:0xf bound_ctrl:1
	v_add_f32_dpp v190, v190, v190 row_mirror row_mask:0xf bank_mask:0xf bound_ctrl:1
	v_add_f32_dpp v191, v191, v191 row_mirror row_mask:0xf bank_mask:0xf bound_ctrl:1
	v_fmac_f32_e32 v182, v126, v56
	v_fmac_f32_e32 v183, v126, v57
	v_fmac_f32_e32 v184, v126, v58
	v_fmac_f32_e32 v185, v126, v59
	v_fmac_f32_e32 v186, v127, v56
	v_fmac_f32_e32 v187, v127, v57
	v_fmac_f32_e32 v188, v127, v58
	v_fmac_f32_e32 v189, v127, v59
	v_fmac_f32_e32 v182, v190, v52
	v_fmac_f32_e32 v183, v190, v53
	v_fmac_f32_e32 v184, v190, v54
	v_fmac_f32_e32 v185, v190, v55
	v_fmac_f32_e32 v186, v191, v52
	v_fmac_f32_e32 v187, v191, v53
	v_fmac_f32_e32 v188, v191, v54
	v_fmac_f32_e32 v189, v191, v55
	ds_read_b128 v[48:51], v151 offset:14080
	ds_read_b128 v[52:55], v151 offset:22272
	ds_read_b128 v[56:59], v151 offset:30464
	ds_read_b128 v[60:63], v151 offset:38656
	ds_read_b64 v[126:127], v181 offset:5888
	s_waitcnt lgkmcnt(11)
	v_mul_f32_e32 v190, v182, v8
	v_mul_f32_e32 v191, v186, v8
	v_mul_f32_e32 v238, v182, v20
	v_mul_f32_e32 v239, v186, v20
	v_fmac_f32_e32 v190, v183, v9
	v_fmac_f32_e32 v191, v187, v9
	v_fmac_f32_e32 v238, v183, v21
	v_fmac_f32_e32 v239, v187, v21
	v_fmac_f32_e32 v190, v184, v10
	v_fmac_f32_e32 v191, v188, v10
	v_fmac_f32_e32 v238, v184, v22
	v_fmac_f32_e32 v239, v188, v22
	v_fmac_f32_e32 v190, v185, v11
	v_fmac_f32_e32 v191, v189, v11
	v_fmac_f32_e32 v238, v185, v23
	v_fmac_f32_e32 v239, v189, v23
	v_add_f32_dpp v190, v190, v190 quad_perm:[1,0,3,2] row_mask:0xf bank_mask:0xf bound_ctrl:1
	v_add_f32_dpp v191, v191, v191 quad_perm:[1,0,3,2] row_mask:0xf bank_mask:0xf bound_ctrl:1
	v_add_f32_dpp v238, v238, v238 quad_perm:[1,0,3,2] row_mask:0xf bank_mask:0xf bound_ctrl:1
	v_add_f32_dpp v239, v239, v239 quad_perm:[1,0,3,2] row_mask:0xf bank_mask:0xf bound_ctrl:1
	v_add_f32_dpp v190, v190, v190 quad_perm:[2,3,0,1] row_mask:0xf bank_mask:0xf bound_ctrl:1
	v_add_f32_dpp v191, v191, v191 quad_perm:[2,3,0,1] row_mask:0xf bank_mask:0xf bound_ctrl:1
	v_add_f32_dpp v238, v238, v238 quad_perm:[2,3,0,1] row_mask:0xf bank_mask:0xf bound_ctrl:1
	v_add_f32_dpp v239, v239, v239 quad_perm:[2,3,0,1] row_mask:0xf bank_mask:0xf bound_ctrl:1
	v_add_f32_dpp v190, v190, v190 row_half_mirror row_mask:0xf bank_mask:0xf bound_ctrl:1
	v_add_f32_dpp v191, v191, v191 row_half_mirror row_mask:0xf bank_mask:0xf bound_ctrl:1
	v_add_f32_dpp v238, v238, v238 row_half_mirror row_mask:0xf bank_mask:0xf bound_ctrl:1
	v_add_f32_dpp v239, v239, v239 row_half_mirror row_mask:0xf bank_mask:0xf bound_ctrl:1
	v_add_f32_dpp v190, v190, v190 row_mirror row_mask:0xf bank_mask:0xf bound_ctrl:1
	v_add_f32_dpp v191, v191, v191 row_mirror row_mask:0xf bank_mask:0xf bound_ctrl:1
	v_fmac_f32_e32 v182, v64, v16
	v_fmac_f32_e32 v183, v64, v17
	v_fmac_f32_e32 v184, v64, v18
	v_fmac_f32_e32 v185, v64, v19
	v_fmac_f32_e32 v186, v65, v16
	v_fmac_f32_e32 v187, v65, v17
	v_fmac_f32_e32 v188, v65, v18
	v_fmac_f32_e32 v189, v65, v19
	v_fmac_f32_e32 v182, v190, v12
	v_fmac_f32_e32 v183, v190, v13
	v_fmac_f32_e32 v184, v190, v14
	v_fmac_f32_e32 v185, v190, v15
	v_fmac_f32_e32 v186, v191, v12
	v_fmac_f32_e32 v187, v191, v13
	v_fmac_f32_e32 v188, v191, v14
	v_fmac_f32_e32 v189, v191, v15
	s_mov_b64 exec, s[8:9]
	ds_write2st64_b64 v146, v[128:129], v[238:239] offset0:20 offset1:21
	s_mov_b64 exec, -1
	ds_read_b128 v[8:11], v151 offset:14336
	ds_read_b128 v[12:15], v151 offset:22528
	ds_read_b128 v[16:19], v151 offset:30720
	ds_read_b128 v[20:23], v151 offset:38912
	ds_read_b64 v[64:65], v181 offset:6144
	s_waitcnt lgkmcnt(11)
	v_mul_f32_e32 v190, v182, v28
	v_mul_f32_e32 v191, v186, v28
	v_mul_f32_e32 v128, v182, v40
	v_mul_f32_e32 v129, v186, v40
	v_fmac_f32_e32 v190, v183, v29
	v_fmac_f32_e32 v191, v187, v29
	v_fmac_f32_e32 v128, v183, v41
	v_fmac_f32_e32 v129, v187, v41
	v_fmac_f32_e32 v190, v184, v30
	v_fmac_f32_e32 v191, v188, v30
	v_fmac_f32_e32 v128, v184, v42
	v_fmac_f32_e32 v129, v188, v42
	v_fmac_f32_e32 v190, v185, v31
	v_fmac_f32_e32 v191, v189, v31
	v_fmac_f32_e32 v128, v185, v43
	v_fmac_f32_e32 v129, v189, v43
	v_add_f32_dpp v190, v190, v190 quad_perm:[1,0,3,2] row_mask:0xf bank_mask:0xf bound_ctrl:1
	v_add_f32_dpp v191, v191, v191 quad_perm:[1,0,3,2] row_mask:0xf bank_mask:0xf bound_ctrl:1
	v_add_f32_dpp v128, v128, v128 quad_perm:[1,0,3,2] row_mask:0xf bank_mask:0xf bound_ctrl:1
	v_add_f32_dpp v129, v129, v129 quad_perm:[1,0,3,2] row_mask:0xf bank_mask:0xf bound_ctrl:1
	v_add_f32_dpp v190, v190, v190 quad_perm:[2,3,0,1] row_mask:0xf bank_mask:0xf bound_ctrl:1
	v_add_f32_dpp v191, v191, v191 quad_perm:[2,3,0,1] row_mask:0xf bank_mask:0xf bound_ctrl:1
	v_add_f32_dpp v128, v128, v128 quad_perm:[2,3,0,1] row_mask:0xf bank_mask:0xf bound_ctrl:1
	v_add_f32_dpp v129, v129, v129 quad_perm:[2,3,0,1] row_mask:0xf bank_mask:0xf bound_ctrl:1
	v_add_f32_dpp v190, v190, v190 row_half_mirror row_mask:0xf bank_mask:0xf bound_ctrl:1
	v_add_f32_dpp v191, v191, v191 row_half_mirror row_mask:0xf bank_mask:0xf bound_ctrl:1
	v_add_f32_dpp v128, v128, v128 row_half_mirror row_mask:0xf bank_mask:0xf bound_ctrl:1
	v_add_f32_dpp v129, v129, v129 row_half_mirror row_mask:0xf bank_mask:0xf bound_ctrl:1
	v_add_f32_dpp v190, v190, v190 row_mirror row_mask:0xf bank_mask:0xf bound_ctrl:1
	v_add_f32_dpp v191, v191, v191 row_mirror row_mask:0xf bank_mask:0xf bound_ctrl:1
	v_fmac_f32_e32 v182, v66, v36
	v_fmac_f32_e32 v183, v66, v37
	v_fmac_f32_e32 v184, v66, v38
	v_fmac_f32_e32 v185, v66, v39
	v_fmac_f32_e32 v186, v67, v36
	v_fmac_f32_e32 v187, v67, v37
	v_fmac_f32_e32 v188, v67, v38
	v_fmac_f32_e32 v189, v67, v39
	v_fmac_f32_e32 v182, v190, v32
	v_fmac_f32_e32 v183, v190, v33
	v_fmac_f32_e32 v184, v190, v34
	v_fmac_f32_e32 v185, v190, v35
	v_fmac_f32_e32 v186, v191, v32
	v_fmac_f32_e32 v187, v191, v33
	v_fmac_f32_e32 v188, v191, v34
	v_fmac_f32_e32 v189, v191, v35
	ds_read_b128 v[28:31], v151 offset:14592
	ds_read_b128 v[32:35], v151 offset:22784
	ds_read_b128 v[36:39], v151 offset:30976
	ds_read_b128 v[40:43], v151 offset:39168
	ds_read_b64 v[66:67], v181 offset:6400
	s_waitcnt lgkmcnt(11)
	v_mul_f32_e32 v190, v182, v48
	v_mul_f32_e32 v191, v186, v48
	v_mul_f32_e32 v238, v182, v60
	v_mul_f32_e32 v239, v186, v60
	v_fmac_f32_e32 v190, v183, v49
	v_fmac_f32_e32 v191, v187, v49
	v_fmac_f32_e32 v238, v183, v61
	v_fmac_f32_e32 v239, v187, v61
	v_fmac_f32_e32 v190, v184, v50
	v_fmac_f32_e32 v191, v188, v50
	v_fmac_f32_e32 v238, v184, v62
	v_fmac_f32_e32 v239, v188, v62
	v_fmac_f32_e32 v190, v185, v51
	v_fmac_f32_e32 v191, v189, v51
	v_fmac_f32_e32 v238, v185, v63
	v_fmac_f32_e32 v239, v189, v63
	v_add_f32_dpp v190, v190, v190 quad_perm:[1,0,3,2] row_mask:0xf bank_mask:0xf bound_ctrl:1
	v_add_f32_dpp v191, v191, v191 quad_perm:[1,0,3,2] row_mask:0xf bank_mask:0xf bound_ctrl:1
	v_add_f32_dpp v238, v238, v238 quad_perm:[1,0,3,2] row_mask:0xf bank_mask:0xf bound_ctrl:1
	v_add_f32_dpp v239, v239, v239 quad_perm:[1,0,3,2] row_mask:0xf bank_mask:0xf bound_ctrl:1
	v_add_f32_dpp v190, v190, v190 quad_perm:[2,3,0,1] row_mask:0xf bank_mask:0xf bound_ctrl:1
	v_add_f32_dpp v191, v191, v191 quad_perm:[2,3,0,1] row_mask:0xf bank_mask:0xf bound_ctrl:1
	v_add_f32_dpp v238, v238, v238 quad_perm:[2,3,0,1] row_mask:0xf bank_mask:0xf bound_ctrl:1
	v_add_f32_dpp v239, v239, v239 quad_perm:[2,3,0,1] row_mask:0xf bank_mask:0xf bound_ctrl:1
	v_add_f32_dpp v190, v190, v190 row_half_mirror row_mask:0xf bank_mask:0xf bound_ctrl:1
	v_add_f32_dpp v191, v191, v191 row_half_mirror row_mask:0xf bank_mask:0xf bound_ctrl:1
	v_add_f32_dpp v238, v238, v238 row_half_mirror row_mask:0xf bank_mask:0xf bound_ctrl:1
	v_add_f32_dpp v239, v239, v239 row_half_mirror row_mask:0xf bank_mask:0xf bound_ctrl:1
	v_add_f32_dpp v190, v190, v190 row_mirror row_mask:0xf bank_mask:0xf bound_ctrl:1
	v_add_f32_dpp v191, v191, v191 row_mirror row_mask:0xf bank_mask:0xf bound_ctrl:1
	v_fmac_f32_e32 v182, v126, v56
	v_fmac_f32_e32 v183, v126, v57
	v_fmac_f32_e32 v184, v126, v58
	v_fmac_f32_e32 v185, v126, v59
	v_fmac_f32_e32 v186, v127, v56
	v_fmac_f32_e32 v187, v127, v57
	v_fmac_f32_e32 v188, v127, v58
	v_fmac_f32_e32 v189, v127, v59
	v_fmac_f32_e32 v182, v190, v52
	v_fmac_f32_e32 v183, v190, v53
	v_fmac_f32_e32 v184, v190, v54
	v_fmac_f32_e32 v185, v190, v55
	v_fmac_f32_e32 v186, v191, v52
	v_fmac_f32_e32 v187, v191, v53
	v_fmac_f32_e32 v188, v191, v54
	v_fmac_f32_e32 v189, v191, v55
	s_mov_b64 exec, s[8:9]
	ds_write2st64_b64 v146, v[128:129], v[238:239] offset0:22 offset1:23
	s_mov_b64 exec, -1
	ds_read_b128 v[48:51], v151 offset:14848
	ds_read_b128 v[52:55], v151 offset:23040
	ds_read_b128 v[56:59], v151 offset:31232
	ds_read_b128 v[60:63], v151 offset:39424
	ds_read_b64 v[126:127], v181 offset:6656
	s_waitcnt lgkmcnt(11)
	v_mul_f32_e32 v190, v182, v8
	v_mul_f32_e32 v191, v186, v8
	v_mul_f32_e32 v128, v182, v20
	v_mul_f32_e32 v129, v186, v20
	v_fmac_f32_e32 v190, v183, v9
	v_fmac_f32_e32 v191, v187, v9
	v_fmac_f32_e32 v128, v183, v21
	v_fmac_f32_e32 v129, v187, v21
	v_fmac_f32_e32 v190, v184, v10
	v_fmac_f32_e32 v191, v188, v10
	v_fmac_f32_e32 v128, v184, v22
	v_fmac_f32_e32 v129, v188, v22
	v_fmac_f32_e32 v190, v185, v11
	v_fmac_f32_e32 v191, v189, v11
	v_fmac_f32_e32 v128, v185, v23
	v_fmac_f32_e32 v129, v189, v23
	v_add_f32_dpp v190, v190, v190 quad_perm:[1,0,3,2] row_mask:0xf bank_mask:0xf bound_ctrl:1
	v_add_f32_dpp v191, v191, v191 quad_perm:[1,0,3,2] row_mask:0xf bank_mask:0xf bound_ctrl:1
	v_add_f32_dpp v128, v128, v128 quad_perm:[1,0,3,2] row_mask:0xf bank_mask:0xf bound_ctrl:1
	v_add_f32_dpp v129, v129, v129 quad_perm:[1,0,3,2] row_mask:0xf bank_mask:0xf bound_ctrl:1
	v_add_f32_dpp v190, v190, v190 quad_perm:[2,3,0,1] row_mask:0xf bank_mask:0xf bound_ctrl:1
	v_add_f32_dpp v191, v191, v191 quad_perm:[2,3,0,1] row_mask:0xf bank_mask:0xf bound_ctrl:1
	v_add_f32_dpp v128, v128, v128 quad_perm:[2,3,0,1] row_mask:0xf bank_mask:0xf bound_ctrl:1
	v_add_f32_dpp v129, v129, v129 quad_perm:[2,3,0,1] row_mask:0xf bank_mask:0xf bound_ctrl:1
	v_add_f32_dpp v190, v190, v190 row_half_mirror row_mask:0xf bank_mask:0xf bound_ctrl:1
	v_add_f32_dpp v191, v191, v191 row_half_mirror row_mask:0xf bank_mask:0xf bound_ctrl:1
	v_add_f32_dpp v128, v128, v128 row_half_mirror row_mask:0xf bank_mask:0xf bound_ctrl:1
	v_add_f32_dpp v129, v129, v129 row_half_mirror row_mask:0xf bank_mask:0xf bound_ctrl:1
	v_add_f32_dpp v190, v190, v190 row_mirror row_mask:0xf bank_mask:0xf bound_ctrl:1
	v_add_f32_dpp v191, v191, v191 row_mirror row_mask:0xf bank_mask:0xf bound_ctrl:1
	v_fmac_f32_e32 v182, v64, v16
	v_fmac_f32_e32 v183, v64, v17
	v_fmac_f32_e32 v184, v64, v18
	v_fmac_f32_e32 v185, v64, v19
	v_fmac_f32_e32 v186, v65, v16
	v_fmac_f32_e32 v187, v65, v17
	v_fmac_f32_e32 v188, v65, v18
	v_fmac_f32_e32 v189, v65, v19
	v_fmac_f32_e32 v182, v190, v12
	v_fmac_f32_e32 v183, v190, v13
	v_fmac_f32_e32 v184, v190, v14
	v_fmac_f32_e32 v185, v190, v15
	v_fmac_f32_e32 v186, v191, v12
	v_fmac_f32_e32 v187, v191, v13
	v_fmac_f32_e32 v188, v191, v14
	v_fmac_f32_e32 v189, v191, v15
	ds_read_b128 v[8:11], v151 offset:15104
	ds_read_b128 v[12:15], v151 offset:23296
	ds_read_b128 v[16:19], v151 offset:31488
	ds_read_b128 v[20:23], v151 offset:39680
	ds_read_b64 v[64:65], v181 offset:6912
	s_waitcnt lgkmcnt(11)
	v_mul_f32_e32 v190, v182, v28
	v_mul_f32_e32 v191, v186, v28
	v_mul_f32_e32 v238, v182, v40
	v_mul_f32_e32 v239, v186, v40
	v_fmac_f32_e32 v190, v183, v29
	v_fmac_f32_e32 v191, v187, v29
	v_fmac_f32_e32 v238, v183, v41
	v_fmac_f32_e32 v239, v187, v41
	v_fmac_f32_e32 v190, v184, v30
	v_fmac_f32_e32 v191, v188, v30
	v_fmac_f32_e32 v238, v184, v42
	v_fmac_f32_e32 v239, v188, v42
	v_fmac_f32_e32 v190, v185, v31
	v_fmac_f32_e32 v191, v189, v31
	v_fmac_f32_e32 v238, v185, v43
	v_fmac_f32_e32 v239, v189, v43
	v_add_f32_dpp v190, v190, v190 quad_perm:[1,0,3,2] row_mask:0xf bank_mask:0xf bound_ctrl:1
	v_add_f32_dpp v191, v191, v191 quad_perm:[1,0,3,2] row_mask:0xf bank_mask:0xf bound_ctrl:1
	v_add_f32_dpp v238, v238, v238 quad_perm:[1,0,3,2] row_mask:0xf bank_mask:0xf bound_ctrl:1
	v_add_f32_dpp v239, v239, v239 quad_perm:[1,0,3,2] row_mask:0xf bank_mask:0xf bound_ctrl:1
	v_add_f32_dpp v190, v190, v190 quad_perm:[2,3,0,1] row_mask:0xf bank_mask:0xf bound_ctrl:1
	v_add_f32_dpp v191, v191, v191 quad_perm:[2,3,0,1] row_mask:0xf bank_mask:0xf bound_ctrl:1
	v_add_f32_dpp v238, v238, v238 quad_perm:[2,3,0,1] row_mask:0xf bank_mask:0xf bound_ctrl:1
	v_add_f32_dpp v239, v239, v239 quad_perm:[2,3,0,1] row_mask:0xf bank_mask:0xf bound_ctrl:1
	v_add_f32_dpp v190, v190, v190 row_half_mirror row_mask:0xf bank_mask:0xf bound_ctrl:1
	v_add_f32_dpp v191, v191, v191 row_half_mirror row_mask:0xf bank_mask:0xf bound_ctrl:1
	v_add_f32_dpp v238, v238, v238 row_half_mirror row_mask:0xf bank_mask:0xf bound_ctrl:1
	v_add_f32_dpp v239, v239, v239 row_half_mirror row_mask:0xf bank_mask:0xf bound_ctrl:1
	v_add_f32_dpp v190, v190, v190 row_mirror row_mask:0xf bank_mask:0xf bound_ctrl:1
	v_add_f32_dpp v191, v191, v191 row_mirror row_mask:0xf bank_mask:0xf bound_ctrl:1
	v_fmac_f32_e32 v182, v66, v36
	v_fmac_f32_e32 v183, v66, v37
	v_fmac_f32_e32 v184, v66, v38
	v_fmac_f32_e32 v185, v66, v39
	v_fmac_f32_e32 v186, v67, v36
	v_fmac_f32_e32 v187, v67, v37
	v_fmac_f32_e32 v188, v67, v38
	v_fmac_f32_e32 v189, v67, v39
	v_fmac_f32_e32 v182, v190, v32
	v_fmac_f32_e32 v183, v190, v33
	v_fmac_f32_e32 v184, v190, v34
	v_fmac_f32_e32 v185, v190, v35
	v_fmac_f32_e32 v186, v191, v32
	v_fmac_f32_e32 v187, v191, v33
	v_fmac_f32_e32 v188, v191, v34
	v_fmac_f32_e32 v189, v191, v35
	s_mov_b64 exec, s[8:9]
	ds_write2st64_b64 v146, v[128:129], v[238:239] offset0:24 offset1:25
	s_mov_b64 exec, -1
	ds_read_b128 v[28:31], v151 offset:15360
	ds_read_b128 v[32:35], v151 offset:23552
	ds_read_b128 v[36:39], v151 offset:31744
	ds_read_b128 v[40:43], v151 offset:39936
	ds_read_b64 v[66:67], v181 offset:7168
	s_waitcnt lgkmcnt(11)
	v_mul_f32_e32 v190, v182, v48
	v_mul_f32_e32 v191, v186, v48
	v_mul_f32_e32 v128, v182, v60
	v_mul_f32_e32 v129, v186, v60
	v_fmac_f32_e32 v190, v183, v49
	v_fmac_f32_e32 v191, v187, v49
	v_fmac_f32_e32 v128, v183, v61
	v_fmac_f32_e32 v129, v187, v61
	v_fmac_f32_e32 v190, v184, v50
	v_fmac_f32_e32 v191, v188, v50
	v_fmac_f32_e32 v128, v184, v62
	v_fmac_f32_e32 v129, v188, v62
	v_fmac_f32_e32 v190, v185, v51
	v_fmac_f32_e32 v191, v189, v51
	v_fmac_f32_e32 v128, v185, v63
	v_fmac_f32_e32 v129, v189, v63
	v_add_f32_dpp v190, v190, v190 quad_perm:[1,0,3,2] row_mask:0xf bank_mask:0xf bound_ctrl:1
	v_add_f32_dpp v191, v191, v191 quad_perm:[1,0,3,2] row_mask:0xf bank_mask:0xf bound_ctrl:1
	v_add_f32_dpp v128, v128, v128 quad_perm:[1,0,3,2] row_mask:0xf bank_mask:0xf bound_ctrl:1
	v_add_f32_dpp v129, v129, v129 quad_perm:[1,0,3,2] row_mask:0xf bank_mask:0xf bound_ctrl:1
	v_add_f32_dpp v190, v190, v190 quad_perm:[2,3,0,1] row_mask:0xf bank_mask:0xf bound_ctrl:1
	v_add_f32_dpp v191, v191, v191 quad_perm:[2,3,0,1] row_mask:0xf bank_mask:0xf bound_ctrl:1
	v_add_f32_dpp v128, v128, v128 quad_perm:[2,3,0,1] row_mask:0xf bank_mask:0xf bound_ctrl:1
	v_add_f32_dpp v129, v129, v129 quad_perm:[2,3,0,1] row_mask:0xf bank_mask:0xf bound_ctrl:1
	v_add_f32_dpp v190, v190, v190 row_half_mirror row_mask:0xf bank_mask:0xf bound_ctrl:1
	v_add_f32_dpp v191, v191, v191 row_half_mirror row_mask:0xf bank_mask:0xf bound_ctrl:1
	v_add_f32_dpp v128, v128, v128 row_half_mirror row_mask:0xf bank_mask:0xf bound_ctrl:1
	v_add_f32_dpp v129, v129, v129 row_half_mirror row_mask:0xf bank_mask:0xf bound_ctrl:1
	v_add_f32_dpp v190, v190, v190 row_mirror row_mask:0xf bank_mask:0xf bound_ctrl:1
	v_add_f32_dpp v191, v191, v191 row_mirror row_mask:0xf bank_mask:0xf bound_ctrl:1
	v_fmac_f32_e32 v182, v126, v56
	v_fmac_f32_e32 v183, v126, v57
	v_fmac_f32_e32 v184, v126, v58
	v_fmac_f32_e32 v185, v126, v59
	v_fmac_f32_e32 v186, v127, v56
	v_fmac_f32_e32 v187, v127, v57
	v_fmac_f32_e32 v188, v127, v58
	v_fmac_f32_e32 v189, v127, v59
	v_fmac_f32_e32 v182, v190, v52
	v_fmac_f32_e32 v183, v190, v53
	v_fmac_f32_e32 v184, v190, v54
	v_fmac_f32_e32 v185, v190, v55
	v_fmac_f32_e32 v186, v191, v52
	v_fmac_f32_e32 v187, v191, v53
	v_fmac_f32_e32 v188, v191, v54
	v_fmac_f32_e32 v189, v191, v55
	ds_read_b128 v[48:51], v151 offset:15616
	ds_read_b128 v[52:55], v151 offset:23808
	ds_read_b128 v[56:59], v151 offset:32000
	ds_read_b128 v[60:63], v151 offset:40192
	ds_read_b64 v[126:127], v181 offset:7424
	s_waitcnt lgkmcnt(11)
	v_mul_f32_e32 v190, v182, v8
	v_mul_f32_e32 v191, v186, v8
	v_mul_f32_e32 v238, v182, v20
	v_mul_f32_e32 v239, v186, v20
	v_fmac_f32_e32 v190, v183, v9
	v_fmac_f32_e32 v191, v187, v9
	v_fmac_f32_e32 v238, v183, v21
	v_fmac_f32_e32 v239, v187, v21
	v_fmac_f32_e32 v190, v184, v10
	v_fmac_f32_e32 v191, v188, v10
	v_fmac_f32_e32 v238, v184, v22
	v_fmac_f32_e32 v239, v188, v22
	v_fmac_f32_e32 v190, v185, v11
	v_fmac_f32_e32 v191, v189, v11
	v_fmac_f32_e32 v238, v185, v23
	v_fmac_f32_e32 v239, v189, v23
	v_add_f32_dpp v190, v190, v190 quad_perm:[1,0,3,2] row_mask:0xf bank_mask:0xf bound_ctrl:1
	v_add_f32_dpp v191, v191, v191 quad_perm:[1,0,3,2] row_mask:0xf bank_mask:0xf bound_ctrl:1
	v_add_f32_dpp v238, v238, v238 quad_perm:[1,0,3,2] row_mask:0xf bank_mask:0xf bound_ctrl:1
	v_add_f32_dpp v239, v239, v239 quad_perm:[1,0,3,2] row_mask:0xf bank_mask:0xf bound_ctrl:1
	v_add_f32_dpp v190, v190, v190 quad_perm:[2,3,0,1] row_mask:0xf bank_mask:0xf bound_ctrl:1
	v_add_f32_dpp v191, v191, v191 quad_perm:[2,3,0,1] row_mask:0xf bank_mask:0xf bound_ctrl:1
	v_add_f32_dpp v238, v238, v238 quad_perm:[2,3,0,1] row_mask:0xf bank_mask:0xf bound_ctrl:1
	v_add_f32_dpp v239, v239, v239 quad_perm:[2,3,0,1] row_mask:0xf bank_mask:0xf bound_ctrl:1
	v_add_f32_dpp v190, v190, v190 row_half_mirror row_mask:0xf bank_mask:0xf bound_ctrl:1
	v_add_f32_dpp v191, v191, v191 row_half_mirror row_mask:0xf bank_mask:0xf bound_ctrl:1
	v_add_f32_dpp v238, v238, v238 row_half_mirror row_mask:0xf bank_mask:0xf bound_ctrl:1
	v_add_f32_dpp v239, v239, v239 row_half_mirror row_mask:0xf bank_mask:0xf bound_ctrl:1
	v_add_f32_dpp v190, v190, v190 row_mirror row_mask:0xf bank_mask:0xf bound_ctrl:1
	v_add_f32_dpp v191, v191, v191 row_mirror row_mask:0xf bank_mask:0xf bound_ctrl:1
	v_fmac_f32_e32 v182, v64, v16
	v_fmac_f32_e32 v183, v64, v17
	v_fmac_f32_e32 v184, v64, v18
	v_fmac_f32_e32 v185, v64, v19
	v_fmac_f32_e32 v186, v65, v16
	v_fmac_f32_e32 v187, v65, v17
	v_fmac_f32_e32 v188, v65, v18
	v_fmac_f32_e32 v189, v65, v19
	v_fmac_f32_e32 v182, v190, v12
	v_fmac_f32_e32 v183, v190, v13
	v_fmac_f32_e32 v184, v190, v14
	v_fmac_f32_e32 v185, v190, v15
	v_fmac_f32_e32 v186, v191, v12
	v_fmac_f32_e32 v187, v191, v13
	v_fmac_f32_e32 v188, v191, v14
	v_fmac_f32_e32 v189, v191, v15
	s_mov_b64 exec, s[8:9]
	ds_write2st64_b64 v146, v[128:129], v[238:239] offset0:26 offset1:27
	s_mov_b64 exec, -1
	ds_read_b128 v[8:11], v151 offset:15872
	ds_read_b128 v[12:15], v151 offset:24064
	ds_read_b128 v[16:19], v151 offset:32256
	ds_read_b128 v[20:23], v151 offset:40448
	ds_read_b64 v[64:65], v181 offset:7680
	s_waitcnt lgkmcnt(11)
	v_mul_f32_e32 v190, v182, v28
	v_mul_f32_e32 v191, v186, v28
	v_mul_f32_e32 v128, v182, v40
	v_mul_f32_e32 v129, v186, v40
	v_fmac_f32_e32 v190, v183, v29
	v_fmac_f32_e32 v191, v187, v29
	v_fmac_f32_e32 v128, v183, v41
	v_fmac_f32_e32 v129, v187, v41
	v_fmac_f32_e32 v190, v184, v30
	v_fmac_f32_e32 v191, v188, v30
	v_fmac_f32_e32 v128, v184, v42
	v_fmac_f32_e32 v129, v188, v42
	v_fmac_f32_e32 v190, v185, v31
	v_fmac_f32_e32 v191, v189, v31
	v_fmac_f32_e32 v128, v185, v43
	v_fmac_f32_e32 v129, v189, v43
	v_add_f32_dpp v190, v190, v190 quad_perm:[1,0,3,2] row_mask:0xf bank_mask:0xf bound_ctrl:1
	v_add_f32_dpp v191, v191, v191 quad_perm:[1,0,3,2] row_mask:0xf bank_mask:0xf bound_ctrl:1
	v_add_f32_dpp v128, v128, v128 quad_perm:[1,0,3,2] row_mask:0xf bank_mask:0xf bound_ctrl:1
	v_add_f32_dpp v129, v129, v129 quad_perm:[1,0,3,2] row_mask:0xf bank_mask:0xf bound_ctrl:1
	v_add_f32_dpp v190, v190, v190 quad_perm:[2,3,0,1] row_mask:0xf bank_mask:0xf bound_ctrl:1
	v_add_f32_dpp v191, v191, v191 quad_perm:[2,3,0,1] row_mask:0xf bank_mask:0xf bound_ctrl:1
	v_add_f32_dpp v128, v128, v128 quad_perm:[2,3,0,1] row_mask:0xf bank_mask:0xf bound_ctrl:1
	v_add_f32_dpp v129, v129, v129 quad_perm:[2,3,0,1] row_mask:0xf bank_mask:0xf bound_ctrl:1
	v_add_f32_dpp v190, v190, v190 row_half_mirror row_mask:0xf bank_mask:0xf bound_ctrl:1
	v_add_f32_dpp v191, v191, v191 row_half_mirror row_mask:0xf bank_mask:0xf bound_ctrl:1
	v_add_f32_dpp v128, v128, v128 row_half_mirror row_mask:0xf bank_mask:0xf bound_ctrl:1
	v_add_f32_dpp v129, v129, v129 row_half_mirror row_mask:0xf bank_mask:0xf bound_ctrl:1
	v_add_f32_dpp v190, v190, v190 row_mirror row_mask:0xf bank_mask:0xf bound_ctrl:1
	v_add_f32_dpp v191, v191, v191 row_mirror row_mask:0xf bank_mask:0xf bound_ctrl:1
	v_fmac_f32_e32 v182, v66, v36
	v_fmac_f32_e32 v183, v66, v37
	v_fmac_f32_e32 v184, v66, v38
	v_fmac_f32_e32 v185, v66, v39
	v_fmac_f32_e32 v186, v67, v36
	v_fmac_f32_e32 v187, v67, v37
	v_fmac_f32_e32 v188, v67, v38
	v_fmac_f32_e32 v189, v67, v39
	v_fmac_f32_e32 v182, v190, v32
	v_fmac_f32_e32 v183, v190, v33
	v_fmac_f32_e32 v184, v190, v34
	v_fmac_f32_e32 v185, v190, v35
	v_fmac_f32_e32 v186, v191, v32
	v_fmac_f32_e32 v187, v191, v33
	v_fmac_f32_e32 v188, v191, v34
	v_fmac_f32_e32 v189, v191, v35
	ds_read_b128 v[28:31], v151 offset:16128
	ds_read_b128 v[32:35], v151 offset:24320
	ds_read_b128 v[36:39], v151 offset:32512
	ds_read_b128 v[40:43], v151 offset:40704
	ds_read_b64 v[66:67], v181 offset:7936
	s_waitcnt lgkmcnt(11)
	v_mul_f32_e32 v190, v182, v48
	v_mul_f32_e32 v191, v186, v48
	v_mul_f32_e32 v238, v182, v60
	v_mul_f32_e32 v239, v186, v60
	v_fmac_f32_e32 v190, v183, v49
	v_fmac_f32_e32 v191, v187, v49
	v_fmac_f32_e32 v238, v183, v61
	v_fmac_f32_e32 v239, v187, v61
	v_fmac_f32_e32 v190, v184, v50
	v_fmac_f32_e32 v191, v188, v50
	v_fmac_f32_e32 v238, v184, v62
	v_fmac_f32_e32 v239, v188, v62
	v_fmac_f32_e32 v190, v185, v51
	v_fmac_f32_e32 v191, v189, v51
	v_fmac_f32_e32 v238, v185, v63
	v_fmac_f32_e32 v239, v189, v63
	v_add_f32_dpp v190, v190, v190 quad_perm:[1,0,3,2] row_mask:0xf bank_mask:0xf bound_ctrl:1
	v_add_f32_dpp v191, v191, v191 quad_perm:[1,0,3,2] row_mask:0xf bank_mask:0xf bound_ctrl:1
	v_add_f32_dpp v238, v238, v238 quad_perm:[1,0,3,2] row_mask:0xf bank_mask:0xf bound_ctrl:1
	v_add_f32_dpp v239, v239, v239 quad_perm:[1,0,3,2] row_mask:0xf bank_mask:0xf bound_ctrl:1
	v_add_f32_dpp v190, v190, v190 quad_perm:[2,3,0,1] row_mask:0xf bank_mask:0xf bound_ctrl:1
	v_add_f32_dpp v191, v191, v191 quad_perm:[2,3,0,1] row_mask:0xf bank_mask:0xf bound_ctrl:1
	v_add_f32_dpp v238, v238, v238 quad_perm:[2,3,0,1] row_mask:0xf bank_mask:0xf bound_ctrl:1
	v_add_f32_dpp v239, v239, v239 quad_perm:[2,3,0,1] row_mask:0xf bank_mask:0xf bound_ctrl:1
	v_add_f32_dpp v190, v190, v190 row_half_mirror row_mask:0xf bank_mask:0xf bound_ctrl:1
	v_add_f32_dpp v191, v191, v191 row_half_mirror row_mask:0xf bank_mask:0xf bound_ctrl:1
	v_add_f32_dpp v238, v238, v238 row_half_mirror row_mask:0xf bank_mask:0xf bound_ctrl:1
	v_add_f32_dpp v239, v239, v239 row_half_mirror row_mask:0xf bank_mask:0xf bound_ctrl:1
	v_add_f32_dpp v190, v190, v190 row_mirror row_mask:0xf bank_mask:0xf bound_ctrl:1
	v_add_f32_dpp v191, v191, v191 row_mirror row_mask:0xf bank_mask:0xf bound_ctrl:1
	v_fmac_f32_e32 v182, v126, v56
	v_fmac_f32_e32 v183, v126, v57
	v_fmac_f32_e32 v184, v126, v58
	v_fmac_f32_e32 v185, v126, v59
	v_fmac_f32_e32 v186, v127, v56
	v_fmac_f32_e32 v187, v127, v57
	v_fmac_f32_e32 v188, v127, v58
	v_fmac_f32_e32 v189, v127, v59
	v_fmac_f32_e32 v182, v190, v52
	v_fmac_f32_e32 v183, v190, v53
	v_fmac_f32_e32 v184, v190, v54
	v_fmac_f32_e32 v185, v190, v55
	v_fmac_f32_e32 v186, v191, v52
	v_fmac_f32_e32 v187, v191, v53
	v_fmac_f32_e32 v188, v191, v54
	v_fmac_f32_e32 v189, v191, v55
	s_mov_b64 exec, s[8:9]
	ds_write2st64_b64 v146, v[128:129], v[238:239] offset0:28 offset1:29
	s_mov_b64 exec, -1
	s_waitcnt lgkmcnt(6)
	v_mul_f32_e32 v190, v182, v8
	v_mul_f32_e32 v191, v186, v8
	v_mul_f32_e32 v128, v182, v20
	v_mul_f32_e32 v129, v186, v20
	v_fmac_f32_e32 v190, v183, v9
	v_fmac_f32_e32 v191, v187, v9
	v_fmac_f32_e32 v128, v183, v21
	v_fmac_f32_e32 v129, v187, v21
	v_fmac_f32_e32 v190, v184, v10
	v_fmac_f32_e32 v191, v188, v10
	v_fmac_f32_e32 v128, v184, v22
	v_fmac_f32_e32 v129, v188, v22
	v_fmac_f32_e32 v190, v185, v11
	v_fmac_f32_e32 v191, v189, v11
	v_fmac_f32_e32 v128, v185, v23
	v_fmac_f32_e32 v129, v189, v23
	v_add_f32_dpp v190, v190, v190 quad_perm:[1,0,3,2] row_mask:0xf bank_mask:0xf bound_ctrl:1
	v_add_f32_dpp v191, v191, v191 quad_perm:[1,0,3,2] row_mask:0xf bank_mask:0xf bound_ctrl:1
	v_add_f32_dpp v128, v128, v128 quad_perm:[1,0,3,2] row_mask:0xf bank_mask:0xf bound_ctrl:1
	v_add_f32_dpp v129, v129, v129 quad_perm:[1,0,3,2] row_mask:0xf bank_mask:0xf bound_ctrl:1
	v_add_f32_dpp v190, v190, v190 quad_perm:[2,3,0,1] row_mask:0xf bank_mask:0xf bound_ctrl:1
	v_add_f32_dpp v191, v191, v191 quad_perm:[2,3,0,1] row_mask:0xf bank_mask:0xf bound_ctrl:1
	v_add_f32_dpp v128, v128, v128 quad_perm:[2,3,0,1] row_mask:0xf bank_mask:0xf bound_ctrl:1
	v_add_f32_dpp v129, v129, v129 quad_perm:[2,3,0,1] row_mask:0xf bank_mask:0xf bound_ctrl:1
	v_add_f32_dpp v190, v190, v190 row_half_mirror row_mask:0xf bank_mask:0xf bound_ctrl:1
	v_add_f32_dpp v191, v191, v191 row_half_mirror row_mask:0xf bank_mask:0xf bound_ctrl:1
	v_add_f32_dpp v128, v128, v128 row_half_mirror row_mask:0xf bank_mask:0xf bound_ctrl:1
	v_add_f32_dpp v129, v129, v129 row_half_mirror row_mask:0xf bank_mask:0xf bound_ctrl:1
	v_add_f32_dpp v190, v190, v190 row_mirror row_mask:0xf bank_mask:0xf bound_ctrl:1
	v_add_f32_dpp v191, v191, v191 row_mirror row_mask:0xf bank_mask:0xf bound_ctrl:1
	v_fmac_f32_e32 v182, v64, v16
	v_fmac_f32_e32 v183, v64, v17
	v_fmac_f32_e32 v184, v64, v18
	v_fmac_f32_e32 v185, v64, v19
	v_fmac_f32_e32 v186, v65, v16
	v_fmac_f32_e32 v187, v65, v17
	v_fmac_f32_e32 v188, v65, v18
	v_fmac_f32_e32 v189, v65, v19
	v_fmac_f32_e32 v182, v190, v12
	v_fmac_f32_e32 v183, v190, v13
	v_fmac_f32_e32 v184, v190, v14
	v_fmac_f32_e32 v185, v190, v15
	v_fmac_f32_e32 v186, v191, v12
	v_fmac_f32_e32 v187, v191, v13
	v_fmac_f32_e32 v188, v191, v14
	v_fmac_f32_e32 v189, v191, v15
	s_waitcnt lgkmcnt(1)
	v_mul_f32_e32 v190, v182, v28
	v_mul_f32_e32 v191, v186, v28
	v_mul_f32_e32 v238, v182, v40
	v_mul_f32_e32 v239, v186, v40
	v_fmac_f32_e32 v190, v183, v29
	v_fmac_f32_e32 v191, v187, v29
	v_fmac_f32_e32 v238, v183, v41
	v_fmac_f32_e32 v239, v187, v41
	v_fmac_f32_e32 v190, v184, v30
	v_fmac_f32_e32 v191, v188, v30
	v_fmac_f32_e32 v238, v184, v42
	v_fmac_f32_e32 v239, v188, v42
	v_fmac_f32_e32 v190, v185, v31
	v_fmac_f32_e32 v191, v189, v31
	v_fmac_f32_e32 v238, v185, v43
	v_fmac_f32_e32 v239, v189, v43
	v_add_f32_dpp v190, v190, v190 quad_perm:[1,0,3,2] row_mask:0xf bank_mask:0xf bound_ctrl:1
	v_add_f32_dpp v191, v191, v191 quad_perm:[1,0,3,2] row_mask:0xf bank_mask:0xf bound_ctrl:1
	v_add_f32_dpp v238, v238, v238 quad_perm:[1,0,3,2] row_mask:0xf bank_mask:0xf bound_ctrl:1
	v_add_f32_dpp v239, v239, v239 quad_perm:[1,0,3,2] row_mask:0xf bank_mask:0xf bound_ctrl:1
	v_add_f32_dpp v190, v190, v190 quad_perm:[2,3,0,1] row_mask:0xf bank_mask:0xf bound_ctrl:1
	v_add_f32_dpp v191, v191, v191 quad_perm:[2,3,0,1] row_mask:0xf bank_mask:0xf bound_ctrl:1
	v_add_f32_dpp v238, v238, v238 quad_perm:[2,3,0,1] row_mask:0xf bank_mask:0xf bound_ctrl:1
	v_add_f32_dpp v239, v239, v239 quad_perm:[2,3,0,1] row_mask:0xf bank_mask:0xf bound_ctrl:1
	v_add_f32_dpp v190, v190, v190 row_half_mirror row_mask:0xf bank_mask:0xf bound_ctrl:1
	v_add_f32_dpp v191, v191, v191 row_half_mirror row_mask:0xf bank_mask:0xf bound_ctrl:1
	v_add_f32_dpp v238, v238, v238 row_half_mirror row_mask:0xf bank_mask:0xf bound_ctrl:1
	v_add_f32_dpp v239, v239, v239 row_half_mirror row_mask:0xf bank_mask:0xf bound_ctrl:1
	v_add_f32_dpp v190, v190, v190 row_mirror row_mask:0xf bank_mask:0xf bound_ctrl:1
	v_add_f32_dpp v191, v191, v191 row_mirror row_mask:0xf bank_mask:0xf bound_ctrl:1
	v_fmac_f32_e32 v182, v66, v36
	v_fmac_f32_e32 v183, v66, v37
	v_fmac_f32_e32 v184, v66, v38
	v_fmac_f32_e32 v185, v66, v39
	v_fmac_f32_e32 v186, v67, v36
	v_fmac_f32_e32 v187, v67, v37
	v_fmac_f32_e32 v188, v67, v38
	v_fmac_f32_e32 v189, v67, v39
	v_fmac_f32_e32 v182, v190, v32
	v_fmac_f32_e32 v183, v190, v33
	v_fmac_f32_e32 v184, v190, v34
	v_fmac_f32_e32 v185, v190, v35
	v_fmac_f32_e32 v186, v191, v32
	v_fmac_f32_e32 v187, v191, v33
	v_fmac_f32_e32 v188, v191, v34
	v_fmac_f32_e32 v189, v191, v35
	s_mov_b64 exec, s[8:9]
	ds_write2st64_b64 v146, v[128:129], v[238:239] offset0:30 offset1:31
	s_mov_b64 exec, -1
	ds_read_b128 v[4:7], v151 offset:65280
	s_waitcnt lgkmcnt(0)
	v_mul_f32_e32 v182, v182, v4
	v_mul_f32_e32 v183, v183, v5
	v_mul_f32_e32 v184, v184, v6
	v_mul_f32_e32 v185, v185, v7
	v_mul_f32_e32 v186, v186, v4
	v_mul_f32_e32 v187, v187, v5
	v_mul_f32_e32 v188, v188, v6
	v_mul_f32_e32 v189, v189, v7
	s_branch .LBB0_182

.LBB0_292:
	s_andn2_b64 vcc, exec, s[12:13]
	s_cbranch_vccnz .LBB0_294
	v_mul_f32_e32 v4, 0xbf60028a, v4
	v_mul_f32_e32 v5, 0xbf60028a, v5
	v_exp_f32_e32 v4, v4
	v_exp_f32_e32 v5, v5
	v_mul_f32_e32 v6, 0xbf60028a, v6
	v_mul_f32_e32 v7, 0xbf60028a, v7
	v_exp_f32_e32 v6, v6
	v_exp_f32_e32 v7, v7
	v_mul_f32_e32 v8, 0xbf60028a, v8
	v_mul_f32_e32 v9, 0xbf60028a, v9
	v_exp_f32_e32 v8, v8
	v_exp_f32_e32 v9, v9
	v_mul_f32_e32 v10, 0xbf60028a, v10
	v_mul_f32_e32 v11, 0xbf60028a, v11
	v_exp_f32_e32 v10, v10
	v_exp_f32_e32 v11, v11
	s_nop 1
	v_mul_f32_e32 v198, v7, v6
	v_mul_f32_e32 v201, v11, v10
	v_mul_f32_e32 v199, v198, v5
	v_mul_f32_e32 v202, v201, v9
	v_mul_f32_e32 v200, v199, v4
	v_mul_f32_e32 v203, v202, v8
	v_mbcnt_lo_u32_b32 v204, -1, 0
	v_mbcnt_hi_u32_b32 v204, -1, v204
	v_and_b32_e32 v205, 15, v204
	v_lshlrev_b32_e32 v205, 2, v205
	v_add_u32_e32 v206, 64, v205
	v_add_u32_e32 v207, 128, v205
	v_add_u32_e32 v208, 192, v205
	v_mov_b32_e32 v217, 1.0
	ds_bpermute_b32 v209, v205, v200
	ds_bpermute_b32 v210, v206, v200
	ds_bpermute_b32 v211, v207, v200
	ds_bpermute_b32 v212, v208, v200
	ds_bpermute_b32 v213, v205, v203
	ds_bpermute_b32 v214, v206, v203
	ds_bpermute_b32 v215, v207, v203
	ds_bpermute_b32 v216, v208, v203
	s_waitcnt lgkmcnt(7)
	v_mul_f32_e32 v15, v29, v4
	s_waitcnt lgkmcnt(7)
	v_mul_f32_e32 v4, v28, v5
	ds_write2st64_b32 v156, v15, v4 offset0:128 offset1:129
	s_waitcnt lgkmcnt(7)
	v_mul_f32_e32 v4, v26, v6
	s_waitcnt lgkmcnt(6)
	v_mul_f32_e32 v5, v25, v7
	ds_write2st64_b32 v156, v4, v5 offset0:130 offset1:131
	s_waitcnt lgkmcnt(6)
	v_mul_f32_e32 v4, v24, v8
	s_waitcnt lgkmcnt(5)
	v_mul_f32_e32 v5, v14, v9
	ds_write2st64_b32 v156, v4, v5 offset0:144 offset1:145
	s_waitcnt lgkmcnt(5)
	v_mul_f32_e32 v4, v13, v10
	s_waitcnt lgkmcnt(4)
	v_mul_f32_e32 v5, v12, v11
	ds_write2st64_b32 v156, v4, v5 offset0:146 offset1:147
	s_waitcnt lgkmcnt(0)
	v_cmp_gt_u32_e32 vcc, 16, v204
	v_cndmask_b32_e32 v218, v217, v210, vcc
	v_cndmask_b32_e32 v221, v217, v214, vcc
	v_cmp_gt_u32_e32 vcc, 32, v204
	v_cndmask_b32_e32 v219, v217, v211, vcc
	v_cndmask_b32_e32 v222, v217, v215, vcc
	v_cmp_gt_u32_e32 vcc, 48, v204
	v_cndmask_b32_e32 v220, v217, v212, vcc
	v_cndmask_b32_e32 v223, v217, v216, vcc
	v_mul_f32_e32 v225, v221, v222
	v_mul_f32_e32 v224, v218, v219
	v_mul_f32_e32 v226, v213, v214
	v_mul_f32_e32 v225, v225, v223
	v_mul_f32_e32 v224, v224, v220
	v_mul_f32_e32 v226, v226, v215
	v_mul_f32_e32 v226, v226, v216
	v_mul_f32_e32 v224, v224, v226
	v_mul_f32_e32 v230, v200, v224
	v_mul_f32_e32 v231, v199, v224
	v_mul_f32_e32 v232, v198, v224
	v_mul_f32_e32 v233, v7, v224
	v_mul_f32_e32 v234, v203, v225
	v_mul_f32_e32 v235, v202, v225
	v_mul_f32_e32 v236, v201, v225
	v_mul_f32_e32 v237, v11, v225
	ds_write2st64_b32 v156, v230, v231 offset0:224 offset1:225
	ds_write2st64_b32 v156, v232, v233 offset0:226 offset1:227
	ds_write2st64_b32 v156, v234, v235 offset0:240 offset1:241
	ds_write2st64_b32 v156, v236, v237 offset0:242 offset1:243
.LBB0_294:
	s_waitcnt lgkmcnt(0)
	s_barrier
	v_add_u32_e32 v227, 0x100, v146
	ds_read_b128 v[198:201], v146 offset:57344
	ds_read_b128 v[202:205], v227 offset:57344
	ds_read_b128 v[206:209], v146 offset:8192
	ds_read_b128 v[210:213], v146 offset:16384
	ds_read_b128 v[214:217], v146 offset:24576
	ds_read_b128 v[4:7], v146 offset:40960
	ds_read_b128 v[8:11], v146 offset:16384
	s_waitcnt lgkmcnt(2)
	ds_read_b128 v[12:15], v146 offset:24576
	ds_read_b128 v[16:19], v149
	s_sub_i32 s12, s86, s70
	s_addk_i32 s12, 0x3fe0
	s_waitcnt lgkmcnt(2)
	v_pk_mul_f32 v[8:9], v[4:5], v[8:9]
	s_waitcnt lgkmcnt(1)
	v_pk_mul_f32 v[4:5], v[4:5], v[12:13]
	v_add_f32_e32 v8, 0, v8
	v_pk_mul_f32 v[10:11], v[6:7], v[10:11]
	v_add_f32_e32 v8, v9, v8
	v_add_f32_e32 v9, 0, v4
	s_waitcnt lgkmcnt(0)
	v_fma_f32 v4, v16, v4, 0
	v_add_f32_e32 v9, v5, v9
	v_fmac_f32_e32 v4, v17, v5
	v_add_f32_e32 v5, v10, v8
	v_add_f32_e32 v5, v11, v5
	v_pk_mul_f32 v[6:7], v[6:7], v[14:15]
	v_add_u32_e32 v124, s12, v67
	v_add_f32_dpp v5, v5, v5 quad_perm:[1,0,3,2] row_mask:0xf bank_mask:0xf bound_ctrl:1
	v_add_f32_e32 v8, v6, v9
	v_fmac_f32_e32 v4, v18, v6
	v_add_f32_dpp v5, v5, v5 quad_perm:[2,3,0,1] row_mask:0xf bank_mask:0xf bound_ctrl:1
	v_add_f32_e32 v6, v7, v8
	v_fmac_f32_e32 v4, v19, v7
	v_add_f32_dpp v5, v5, v5 row_half_mirror row_mask:0xf bank_mask:0xf bound_ctrl:1
	v_ashrrev_i32_e32 v125, 31, v124
	v_add_f32_dpp v4, v4, v4 quad_perm:[1,0,3,2] row_mask:0xf bank_mask:0xf bound_ctrl:1
	v_add_f32_dpp v14, v5, v5 row_mirror row_mask:0xf bank_mask:0xf bound_ctrl:1
	v_add_f32_dpp v5, v6, v6 quad_perm:[1,0,3,2] row_mask:0xf bank_mask:0xf bound_ctrl:1
	ds_read_b128 v[6:9], v146 offset:8192
	ds_read_b128 v[10:13], v146 offset:32768
	v_add_f32_dpp v5, v5, v5 quad_perm:[2,3,0,1] row_mask:0xf bank_mask:0xf bound_ctrl:1
	v_add_f32_dpp v4, v4, v4 quad_perm:[2,3,0,1] row_mask:0xf bank_mask:0xf bound_ctrl:1
	s_waitcnt lgkmcnt(0)
	v_pk_fma_f32 v[8:9], v[14:15], v[8:9], v[12:13] op_sel_hi:[0,1,1]
	v_pk_fma_f32 v[6:7], v[14:15], v[6:7], v[10:11] op_sel_hi:[0,1,1]
	s_waitcnt lgkmcnt(0)
	v_mov_b32_e32 v226, 1.0
	v_cmp_lt_u32_e32 vcc, 495, v134
	v_rcp_f32_e32 v222, v198
	v_rcp_f32_e32 v223, v199
	v_rcp_f32_e32 v224, v200
	v_rcp_f32_e32 v225, v201
	v_cndmask_b32_e32 v202, v202, v226, vcc
	v_cndmask_b32_e32 v203, v203, v226, vcc
	v_cndmask_b32_e32 v204, v204, v226, vcc
	v_cndmask_b32_e32 v205, v205, v226, vcc
	v_mul_f32_e32 v206, v206, v202
	v_mul_f32_e32 v207, v207, v203
	v_mul_f32_e32 v208, v208, v204
	v_mul_f32_e32 v209, v209, v205
	v_mul_f32_e32 v6, v6, v202
	v_mul_f32_e32 v7, v7, v203
	v_mul_f32_e32 v8, v8, v204
	v_mul_f32_e32 v9, v9, v205
	v_mul_f32_e32 v210, v210, v222
	v_mul_f32_e32 v211, v211, v223
	v_mul_f32_e32 v212, v212, v224
	v_mul_f32_e32 v213, v213, v225
	v_mul_f32_e32 v214, v214, v222
	v_mul_f32_e32 v215, v215, v223
	v_mul_f32_e32 v216, v216, v224
	v_mul_f32_e32 v217, v217, v225
	ds_write_b128 v146, v[206:209] offset:8192
	ds_write_b128 v146, v[210:213] offset:16384
	ds_write_b128 v146, v[214:217] offset:24576
	ds_write_b128 v146, v[6:9] offset:32768
	ds_read_b128 v[6:9], v146 offset:49152
	v_add_f32_dpp v5, v5, v5 row_half_mirror row_mask:0xf bank_mask:0xf bound_ctrl:1
	v_add_f32_dpp v4, v4, v4 row_half_mirror row_mask:0xf bank_mask:0xf bound_ctrl:1
	s_nop 0
	v_add_f32_dpp v16, v5, v5 row_mirror row_mask:0xf bank_mask:0xf bound_ctrl:1
	v_mov_b32_dpp v5, v4 row_mirror row_mask:0xf bank_mask:0xf bound_ctrl:1
	s_waitcnt lgkmcnt(0)
	v_pk_mul_f32 v[8:9], v[16:17], v[8:9] op_sel_hi:[0,1]
	v_pk_mul_f32 v[6:7], v[16:17], v[6:7] op_sel_hi:[0,1]
	ds_write_b128 v150, v[6:9]
	s_and_saveexec_b64 s[12:13], s[6:7]
	s_cbranch_execz .LBB0_296
	v_lshlrev_b64 v[6:7], 6, v[124:125]
	v_lshl_add_u64 v[6:7], s[92:93], 0, v[6:7]
	v_add_f32_e32 v4, v4, v5
	global_store_dword v[6:7], v4, off
.LBB0_296:
	s_or_b64 exec, exec, s[12:13]
	s_waitcnt lgkmcnt(0)
	s_barrier
	v_mbcnt_lo_u32_b32 v186, -1, 0
	v_mbcnt_hi_u32_b32 v186, -1, v186
	v_lshlrev_b32_e32 v186, 2, v186
	v_add_u32_e32 v186, 0xe000, v186
	v_cndmask_b32_e64 v185, v186, v152, s[8:9]
	ds_read_b128 v[8:11], v145 offset:16128
	ds_read_b128 v[12:15], v145 offset:24320
	ds_read_b128 v[16:19], v145 offset:32512
	ds_read_b128 v[20:23], v145 offset:40704
	ds_read2st64_b32 v[240:241], v151 offset0:223 offset1:222
	ds_read_b128 v[28:31], v145 offset:15872
	ds_read_b128 v[32:35], v145 offset:24064
	ds_read_b128 v[36:39], v145 offset:32256
	ds_read_b128 v[40:43], v145 offset:40448
	ds_read_b128 v[48:51], v145 offset:15616
	ds_read_b128 v[52:55], v145 offset:23808
	ds_read_b128 v[56:59], v145 offset:32000
	ds_read_b128 v[60:63], v145 offset:40192
	ds_read2st64_b32 v[242:243], v151 offset0:221 offset1:220
	s_waitcnt lgkmcnt(9)
	v_mul_f32_e32 v183, v179, v8
	v_mul_f32_e32 v184, v179, v20
	v_fmac_f32_e32 v183, v180, v9
	v_fmac_f32_e32 v184, v180, v21
	v_fmac_f32_e32 v183, v181, v10
	v_fmac_f32_e32 v184, v181, v22
	v_fmac_f32_e32 v183, v182, v11
	v_fmac_f32_e32 v184, v182, v23
	v_fmac_f32_e32 v179, v240, v16
	v_add_f32_dpp v183, v183, v183 quad_perm:[1,0,3,2] row_mask:0xf bank_mask:0xf bound_ctrl:1
	v_add_f32_dpp v184, v184, v184 quad_perm:[1,0,3,2] row_mask:0xf bank_mask:0xf bound_ctrl:1
	v_fmac_f32_e32 v180, v240, v17
	v_add_f32_dpp v183, v183, v183 quad_perm:[2,3,0,1] row_mask:0xf bank_mask:0xf bound_ctrl:1
	v_add_f32_dpp v184, v184, v184 quad_perm:[2,3,0,1] row_mask:0xf bank_mask:0xf bound_ctrl:1
	v_fmac_f32_e32 v181, v240, v18
	v_add_f32_dpp v183, v183, v183 row_half_mirror row_mask:0xf bank_mask:0xf bound_ctrl:1
	v_add_f32_dpp v184, v184, v184 row_half_mirror row_mask:0xf bank_mask:0xf bound_ctrl:1
	v_fmac_f32_e32 v182, v240, v19
	v_add_f32_dpp v183, v183, v183 row_mirror row_mask:0xf bank_mask:0xf bound_ctrl:1
	v_fmac_f32_e32 v179, v183, v12
	v_fmac_f32_e32 v180, v183, v13
	v_fmac_f32_e32 v181, v183, v14
	v_fmac_f32_e32 v182, v183, v15
	ds_read_b128 v[8:11], v145 offset:15360
	ds_read_b128 v[12:15], v145 offset:23552
	ds_read_b128 v[16:19], v145 offset:31744
	ds_read_b128 v[20:23], v145 offset:39936
	s_waitcnt lgkmcnt(9)
	v_mul_f32_e32 v183, v179, v28
	v_mul_f32_e32 v238, v179, v40
	v_fmac_f32_e32 v183, v180, v29
	v_fmac_f32_e32 v238, v180, v41
	v_fmac_f32_e32 v183, v181, v30
	v_fmac_f32_e32 v238, v181, v42
	v_fmac_f32_e32 v183, v182, v31
	v_fmac_f32_e32 v238, v182, v43
	v_fmac_f32_e32 v179, v241, v36
	v_add_f32_dpp v183, v183, v183 quad_perm:[1,0,3,2] row_mask:0xf bank_mask:0xf bound_ctrl:1
	v_add_f32_dpp v238, v238, v238 quad_perm:[1,0,3,2] row_mask:0xf bank_mask:0xf bound_ctrl:1
	v_fmac_f32_e32 v180, v241, v37
	v_add_f32_dpp v183, v183, v183 quad_perm:[2,3,0,1] row_mask:0xf bank_mask:0xf bound_ctrl:1
	v_add_f32_dpp v238, v238, v238 quad_perm:[2,3,0,1] row_mask:0xf bank_mask:0xf bound_ctrl:1
	v_fmac_f32_e32 v181, v241, v38
	v_add_f32_dpp v183, v183, v183 row_half_mirror row_mask:0xf bank_mask:0xf bound_ctrl:1
	v_add_f32_dpp v238, v238, v238 row_half_mirror row_mask:0xf bank_mask:0xf bound_ctrl:1
	v_fmac_f32_e32 v182, v241, v39
	v_add_f32_dpp v183, v183, v183 row_mirror row_mask:0xf bank_mask:0xf bound_ctrl:1
	v_fmac_f32_e32 v179, v183, v32
	v_fmac_f32_e32 v180, v183, v33
	v_fmac_f32_e32 v181, v183, v34
	v_fmac_f32_e32 v182, v183, v35
	s_mov_b64 exec, s[8:9]
	ds_write2st64_b32 v152, v184, v238 offset0:62 offset1:60
	s_mov_b64 exec, -1
	ds_read_b128 v[28:31], v145 offset:15104
	ds_read_b128 v[32:35], v145 offset:23296
	ds_read_b128 v[36:39], v145 offset:31488
	ds_read_b128 v[40:43], v145 offset:39680
	ds_read2st64_b32 v[240:241], v151 offset0:219 offset1:218
	s_waitcnt lgkmcnt(10)
	v_mul_f32_e32 v183, v179, v48
	v_mul_f32_e32 v184, v179, v60
	v_fmac_f32_e32 v183, v180, v49
	v_fmac_f32_e32 v184, v180, v61
	v_fmac_f32_e32 v183, v181, v50
	v_fmac_f32_e32 v184, v181, v62
	v_fmac_f32_e32 v183, v182, v51
	v_fmac_f32_e32 v184, v182, v63
	v_fmac_f32_e32 v179, v242, v56
	v_add_f32_dpp v183, v183, v183 quad_perm:[1,0,3,2] row_mask:0xf bank_mask:0xf bound_ctrl:1
	v_add_f32_dpp v184, v184, v184 quad_perm:[1,0,3,2] row_mask:0xf bank_mask:0xf bound_ctrl:1
	v_fmac_f32_e32 v180, v242, v57
	v_add_f32_dpp v183, v183, v183 quad_perm:[2,3,0,1] row_mask:0xf bank_mask:0xf bound_ctrl:1
	v_add_f32_dpp v184, v184, v184 quad_perm:[2,3,0,1] row_mask:0xf bank_mask:0xf bound_ctrl:1
	v_fmac_f32_e32 v181, v242, v58
	v_add_f32_dpp v183, v183, v183 row_half_mirror row_mask:0xf bank_mask:0xf bound_ctrl:1
	v_add_f32_dpp v184, v184, v184 row_half_mirror row_mask:0xf bank_mask:0xf bound_ctrl:1
	v_fmac_f32_e32 v182, v242, v59
	v_add_f32_dpp v183, v183, v183 row_mirror row_mask:0xf bank_mask:0xf bound_ctrl:1
	v_fmac_f32_e32 v179, v183, v52
	v_fmac_f32_e32 v180, v183, v53
	v_fmac_f32_e32 v181, v183, v54
	v_fmac_f32_e32 v182, v183, v55
	ds_read_b128 v[48:51], v145 offset:14848
	ds_read_b128 v[52:55], v145 offset:23040
	ds_read_b128 v[56:59], v145 offset:31232
	ds_read_b128 v[60:63], v145 offset:39424
	s_waitcnt lgkmcnt(10)
	v_mul_f32_e32 v183, v179, v8
	v_mul_f32_e32 v238, v179, v20
	v_fmac_f32_e32 v183, v180, v9
	v_fmac_f32_e32 v238, v180, v21
	v_fmac_f32_e32 v183, v181, v10
	v_fmac_f32_e32 v238, v181, v22
	v_fmac_f32_e32 v183, v182, v11
	v_fmac_f32_e32 v238, v182, v23
	v_fmac_f32_e32 v179, v243, v16
	v_add_f32_dpp v183, v183, v183 quad_perm:[1,0,3,2] row_mask:0xf bank_mask:0xf bound_ctrl:1
	v_add_f32_dpp v238, v238, v238 quad_perm:[1,0,3,2] row_mask:0xf bank_mask:0xf bound_ctrl:1
	v_fmac_f32_e32 v180, v243, v17
	v_add_f32_dpp v183, v183, v183 quad_perm:[2,3,0,1] row_mask:0xf bank_mask:0xf bound_ctrl:1
	v_add_f32_dpp v238, v238, v238 quad_perm:[2,3,0,1] row_mask:0xf bank_mask:0xf bound_ctrl:1
	v_fmac_f32_e32 v181, v243, v18
	v_add_f32_dpp v183, v183, v183 row_half_mirror row_mask:0xf bank_mask:0xf bound_ctrl:1
	v_add_f32_dpp v238, v238, v238 row_half_mirror row_mask:0xf bank_mask:0xf bound_ctrl:1
	v_fmac_f32_e32 v182, v243, v19
	v_add_f32_dpp v183, v183, v183 row_mirror row_mask:0xf bank_mask:0xf bound_ctrl:1
	v_fmac_f32_e32 v179, v183, v12
	v_fmac_f32_e32 v180, v183, v13
	v_fmac_f32_e32 v181, v183, v14
	v_fmac_f32_e32 v182, v183, v15
	s_mov_b64 exec, s[8:9]
	ds_write2st64_b32 v152, v184, v238 offset0:58 offset1:56
	s_mov_b64 exec, -1
	ds_read_b128 v[8:11], v145 offset:14592
	ds_read_b128 v[12:15], v145 offset:22784
	ds_read_b128 v[16:19], v145 offset:30976
	ds_read_b128 v[20:23], v145 offset:39168
	ds_read2st64_b32 v[242:243], v151 offset0:217 offset1:216
	s_waitcnt lgkmcnt(10)
	v_mul_f32_e32 v183, v179, v28
	v_mul_f32_e32 v184, v179, v40
	v_fmac_f32_e32 v183, v180, v29
	v_fmac_f32_e32 v184, v180, v41
	v_fmac_f32_e32 v183, v181, v30
	v_fmac_f32_e32 v184, v181, v42
	v_fmac_f32_e32 v183, v182, v31
	v_fmac_f32_e32 v184, v182, v43
	v_fmac_f32_e32 v179, v240, v36
	v_add_f32_dpp v183, v183, v183 quad_perm:[1,0,3,2] row_mask:0xf bank_mask:0xf bound_ctrl:1
	v_add_f32_dpp v184, v184, v184 quad_perm:[1,0,3,2] row_mask:0xf bank_mask:0xf bound_ctrl:1
	v_fmac_f32_e32 v180, v240, v37
	v_add_f32_dpp v183, v183, v183 quad_perm:[2,3,0,1] row_mask:0xf bank_mask:0xf bound_ctrl:1
	v_add_f32_dpp v184, v184, v184 quad_perm:[2,3,0,1] row_mask:0xf bank_mask:0xf bound_ctrl:1
	v_fmac_f32_e32 v181, v240, v38
	v_add_f32_dpp v183, v183, v183 row_half_mirror row_mask:0xf bank_mask:0xf bound_ctrl:1
	v_add_f32_dpp v184, v184, v184 row_half_mirror row_mask:0xf bank_mask:0xf bound_ctrl:1
	v_fmac_f32_e32 v182, v240, v39
	v_add_f32_dpp v183, v183, v183 row_mirror row_mask:0xf bank_mask:0xf bound_ctrl:1
	v_fmac_f32_e32 v179, v183, v32
	v_fmac_f32_e32 v180, v183, v33
	v_fmac_f32_e32 v181, v183, v34
	v_fmac_f32_e32 v182, v183, v35
	ds_read_b128 v[28:31], v145 offset:14336
	ds_read_b128 v[32:35], v145 offset:22528
	ds_read_b128 v[36:39], v145 offset:30720
	ds_read_b128 v[40:43], v145 offset:38912
	s_waitcnt lgkmcnt(10)
	v_mul_f32_e32 v183, v179, v48
	v_mul_f32_e32 v238, v179, v60
	v_fmac_f32_e32 v183, v180, v49
	v_fmac_f32_e32 v238, v180, v61
	v_fmac_f32_e32 v183, v181, v50
	v_fmac_f32_e32 v238, v181, v62
	v_fmac_f32_e32 v183, v182, v51
	v_fmac_f32_e32 v238, v182, v63
	v_fmac_f32_e32 v179, v241, v56
	v_add_f32_dpp v183, v183, v183 quad_perm:[1,0,3,2] row_mask:0xf bank_mask:0xf bound_ctrl:1
	v_add_f32_dpp v238, v238, v238 quad_perm:[1,0,3,2] row_mask:0xf bank_mask:0xf bound_ctrl:1
	v_fmac_f32_e32 v180, v241, v57
	v_add_f32_dpp v183, v183, v183 quad_perm:[2,3,0,1] row_mask:0xf bank_mask:0xf bound_ctrl:1
	v_add_f32_dpp v238, v238, v238 quad_perm:[2,3,0,1] row_mask:0xf bank_mask:0xf bound_ctrl:1
	v_fmac_f32_e32 v181, v241, v58
	v_add_f32_dpp v183, v183, v183 row_half_mirror row_mask:0xf bank_mask:0xf bound_ctrl:1
	v_add_f32_dpp v238, v238, v238 row_half_mirror row_mask:0xf bank_mask:0xf bound_ctrl:1
	v_fmac_f32_e32 v182, v241, v59
	v_add_f32_dpp v183, v183, v183 row_mirror row_mask:0xf bank_mask:0xf bound_ctrl:1
	v_fmac_f32_e32 v179, v183, v52
	v_fmac_f32_e32 v180, v183, v53
	v_fmac_f32_e32 v181, v183, v54
	v_fmac_f32_e32 v182, v183, v55
	s_mov_b64 exec, s[8:9]
	ds_write2st64_b32 v152, v184, v238 offset0:54 offset1:52
	s_mov_b64 exec, -1
	ds_read_b128 v[48:51], v145 offset:14080
	ds_read_b128 v[52:55], v145 offset:22272
	ds_read_b128 v[56:59], v145 offset:30464
	ds_read_b128 v[60:63], v145 offset:38656
	ds_read2st64_b32 v[240:241], v151 offset0:215 offset1:214
	s_waitcnt lgkmcnt(10)
	v_mul_f32_e32 v183, v179, v8
	v_mul_f32_e32 v184, v179, v20
	v_fmac_f32_e32 v183, v180, v9
	v_fmac_f32_e32 v184, v180, v21
	v_fmac_f32_e32 v183, v181, v10
	v_fmac_f32_e32 v184, v181, v22
	v_fmac_f32_e32 v183, v182, v11
	v_fmac_f32_e32 v184, v182, v23
	v_fmac_f32_e32 v179, v242, v16
	v_add_f32_dpp v183, v183, v183 quad_perm:[1,0,3,2] row_mask:0xf bank_mask:0xf bound_ctrl:1
	v_add_f32_dpp v184, v184, v184 quad_perm:[1,0,3,2] row_mask:0xf bank_mask:0xf bound_ctrl:1
	v_fmac_f32_e32 v180, v242, v17
	v_add_f32_dpp v183, v183, v183 quad_perm:[2,3,0,1] row_mask:0xf bank_mask:0xf bound_ctrl:1
	v_add_f32_dpp v184, v184, v184 quad_perm:[2,3,0,1] row_mask:0xf bank_mask:0xf bound_ctrl:1
	v_fmac_f32_e32 v181, v242, v18
	v_add_f32_dpp v183, v183, v183 row_half_mirror row_mask:0xf bank_mask:0xf bound_ctrl:1
	v_add_f32_dpp v184, v184, v184 row_half_mirror row_mask:0xf bank_mask:0xf bound_ctrl:1
	v_fmac_f32_e32 v182, v242, v19
	v_add_f32_dpp v183, v183, v183 row_mirror row_mask:0xf bank_mask:0xf bound_ctrl:1
	v_fmac_f32_e32 v179, v183, v12
	v_fmac_f32_e32 v180, v183, v13
	v_fmac_f32_e32 v181, v183, v14
	v_fmac_f32_e32 v182, v183, v15
	ds_read_b128 v[8:11], v145 offset:13824
	ds_read_b128 v[12:15], v145 offset:22016
	ds_read_b128 v[16:19], v145 offset:30208
	ds_read_b128 v[20:23], v145 offset:38400
	s_waitcnt lgkmcnt(10)
	v_mul_f32_e32 v183, v179, v28
	v_mul_f32_e32 v238, v179, v40
	v_fmac_f32_e32 v183, v180, v29
	v_fmac_f32_e32 v238, v180, v41
	v_fmac_f32_e32 v183, v181, v30
	v_fmac_f32_e32 v238, v181, v42
	v_fmac_f32_e32 v183, v182, v31
	v_fmac_f32_e32 v238, v182, v43
	v_fmac_f32_e32 v179, v243, v36
	v_add_f32_dpp v183, v183, v183 quad_perm:[1,0,3,2] row_mask:0xf bank_mask:0xf bound_ctrl:1
	v_add_f32_dpp v238, v238, v238 quad_perm:[1,0,3,2] row_mask:0xf bank_mask:0xf bound_ctrl:1
	v_fmac_f32_e32 v180, v243, v37
	v_add_f32_dpp v183, v183, v183 quad_perm:[2,3,0,1] row_mask:0xf bank_mask:0xf bound_ctrl:1
	v_add_f32_dpp v238, v238, v238 quad_perm:[2,3,0,1] row_mask:0xf bank_mask:0xf bound_ctrl:1
	v_fmac_f32_e32 v181, v243, v38
	v_add_f32_dpp v183, v183, v183 row_half_mirror row_mask:0xf bank_mask:0xf bound_ctrl:1
	v_add_f32_dpp v238, v238, v238 row_half_mirror row_mask:0xf bank_mask:0xf bound_ctrl:1
	v_fmac_f32_e32 v182, v243, v39
	v_add_f32_dpp v183, v183, v183 row_mirror row_mask:0xf bank_mask:0xf bound_ctrl:1
	v_fmac_f32_e32 v179, v183, v32
	v_fmac_f32_e32 v180, v183, v33
	v_fmac_f32_e32 v181, v183, v34
	v_fmac_f32_e32 v182, v183, v35
	s_mov_b64 exec, s[8:9]
	ds_write2st64_b32 v152, v184, v238 offset0:50 offset1:48
	s_mov_b64 exec, -1
	ds_read_b128 v[28:31], v145 offset:13568
	ds_read_b128 v[32:35], v145 offset:21760
	ds_read_b128 v[36:39], v145 offset:29952
	ds_read_b128 v[40:43], v145 offset:38144
	ds_read2st64_b32 v[242:243], v151 offset0:213 offset1:212
	s_waitcnt lgkmcnt(10)
	v_mul_f32_e32 v183, v179, v48
	v_mul_f32_e32 v184, v179, v60
	v_fmac_f32_e32 v183, v180, v49
	v_fmac_f32_e32 v184, v180, v61
	v_fmac_f32_e32 v183, v181, v50
	v_fmac_f32_e32 v184, v181, v62
	v_fmac_f32_e32 v183, v182, v51
	v_fmac_f32_e32 v184, v182, v63
	v_fmac_f32_e32 v179, v240, v56
	v_add_f32_dpp v183, v183, v183 quad_perm:[1,0,3,2] row_mask:0xf bank_mask:0xf bound_ctrl:1
	v_add_f32_dpp v184, v184, v184 quad_perm:[1,0,3,2] row_mask:0xf bank_mask:0xf bound_ctrl:1
	v_fmac_f32_e32 v180, v240, v57
	v_add_f32_dpp v183, v183, v183 quad_perm:[2,3,0,1] row_mask:0xf bank_mask:0xf bound_ctrl:1
	v_add_f32_dpp v184, v184, v184 quad_perm:[2,3,0,1] row_mask:0xf bank_mask:0xf bound_ctrl:1
	v_fmac_f32_e32 v181, v240, v58
	v_add_f32_dpp v183, v183, v183 row_half_mirror row_mask:0xf bank_mask:0xf bound_ctrl:1
	v_add_f32_dpp v184, v184, v184 row_half_mirror row_mask:0xf bank_mask:0xf bound_ctrl:1
	v_fmac_f32_e32 v182, v240, v59
	v_add_f32_dpp v183, v183, v183 row_mirror row_mask:0xf bank_mask:0xf bound_ctrl:1
	v_fmac_f32_e32 v179, v183, v52
	v_fmac_f32_e32 v180, v183, v53
	v_fmac_f32_e32 v181, v183, v54
	v_fmac_f32_e32 v182, v183, v55
	ds_read_b128 v[48:51], v145 offset:13312
	ds_read_b128 v[52:55], v145 offset:21504
	ds_read_b128 v[56:59], v145 offset:29696
	ds_read_b128 v[60:63], v145 offset:37888
	s_waitcnt lgkmcnt(10)
	v_mul_f32_e32 v183, v179, v8
	v_mul_f32_e32 v238, v179, v20
	v_fmac_f32_e32 v183, v180, v9
	v_fmac_f32_e32 v238, v180, v21
	v_fmac_f32_e32 v183, v181, v10
	v_fmac_f32_e32 v238, v181, v22
	v_fmac_f32_e32 v183, v182, v11
	v_fmac_f32_e32 v238, v182, v23
	v_fmac_f32_e32 v179, v241, v16
	v_add_f32_dpp v183, v183, v183 quad_perm:[1,0,3,2] row_mask:0xf bank_mask:0xf bound_ctrl:1
	v_add_f32_dpp v238, v238, v238 quad_perm:[1,0,3,2] row_mask:0xf bank_mask:0xf bound_ctrl:1
	v_fmac_f32_e32 v180, v241, v17
	v_add_f32_dpp v183, v183, v183 quad_perm:[2,3,0,1] row_mask:0xf bank_mask:0xf bound_ctrl:1
	v_add_f32_dpp v238, v238, v238 quad_perm:[2,3,0,1] row_mask:0xf bank_mask:0xf bound_ctrl:1
	v_fmac_f32_e32 v181, v241, v18
	v_add_f32_dpp v183, v183, v183 row_half_mirror row_mask:0xf bank_mask:0xf bound_ctrl:1
	v_add_f32_dpp v238, v238, v238 row_half_mirror row_mask:0xf bank_mask:0xf bound_ctrl:1
	v_fmac_f32_e32 v182, v241, v19
	v_add_f32_dpp v183, v183, v183 row_mirror row_mask:0xf bank_mask:0xf bound_ctrl:1
	v_fmac_f32_e32 v179, v183, v12
	v_fmac_f32_e32 v180, v183, v13
	v_fmac_f32_e32 v181, v183, v14
	v_fmac_f32_e32 v182, v183, v15
	s_mov_b64 exec, s[8:9]
	ds_write2st64_b32 v152, v184, v238 offset0:46 offset1:44
	s_mov_b64 exec, -1
	ds_read_b128 v[8:11], v145 offset:13056
	ds_read_b128 v[12:15], v145 offset:21248
	ds_read_b128 v[16:19], v145 offset:29440
	ds_read_b128 v[20:23], v145 offset:37632
	ds_read2st64_b32 v[240:241], v151 offset0:211 offset1:210
	s_waitcnt lgkmcnt(10)
	v_mul_f32_e32 v183, v179, v28
	v_mul_f32_e32 v184, v179, v40
	v_fmac_f32_e32 v183, v180, v29
	v_fmac_f32_e32 v184, v180, v41
	v_fmac_f32_e32 v183, v181, v30
	v_fmac_f32_e32 v184, v181, v42
	v_fmac_f32_e32 v183, v182, v31
	v_fmac_f32_e32 v184, v182, v43
	v_fmac_f32_e32 v179, v242, v36
	v_add_f32_dpp v183, v183, v183 quad_perm:[1,0,3,2] row_mask:0xf bank_mask:0xf bound_ctrl:1
	v_add_f32_dpp v184, v184, v184 quad_perm:[1,0,3,2] row_mask:0xf bank_mask:0xf bound_ctrl:1
	v_fmac_f32_e32 v180, v242, v37
	v_add_f32_dpp v183, v183, v183 quad_perm:[2,3,0,1] row_mask:0xf bank_mask:0xf bound_ctrl:1
	v_add_f32_dpp v184, v184, v184 quad_perm:[2,3,0,1] row_mask:0xf bank_mask:0xf bound_ctrl:1
	v_fmac_f32_e32 v181, v242, v38
	v_add_f32_dpp v183, v183, v183 row_half_mirror row_mask:0xf bank_mask:0xf bound_ctrl:1
	v_add_f32_dpp v184, v184, v184 row_half_mirror row_mask:0xf bank_mask:0xf bound_ctrl:1
	v_fmac_f32_e32 v182, v242, v39
	v_add_f32_dpp v183, v183, v183 row_mirror row_mask:0xf bank_mask:0xf bound_ctrl:1
	v_fmac_f32_e32 v179, v183, v32
	v_fmac_f32_e32 v180, v183, v33
	v_fmac_f32_e32 v181, v183, v34
	v_fmac_f32_e32 v182, v183, v35
	ds_read_b128 v[28:31], v145 offset:12800
	ds_read_b128 v[32:35], v145 offset:20992
	ds_read_b128 v[36:39], v145 offset:29184
	ds_read_b128 v[40:43], v145 offset:37376
	s_waitcnt lgkmcnt(10)
	v_mul_f32_e32 v183, v179, v48
	v_mul_f32_e32 v238, v179, v60
	v_fmac_f32_e32 v183, v180, v49
	v_fmac_f32_e32 v238, v180, v61
	v_fmac_f32_e32 v183, v181, v50
	v_fmac_f32_e32 v238, v181, v62
	v_fmac_f32_e32 v183, v182, v51
	v_fmac_f32_e32 v238, v182, v63
	v_fmac_f32_e32 v179, v243, v56
	v_add_f32_dpp v183, v183, v183 quad_perm:[1,0,3,2] row_mask:0xf bank_mask:0xf bound_ctrl:1
	v_add_f32_dpp v238, v238, v238 quad_perm:[1,0,3,2] row_mask:0xf bank_mask:0xf bound_ctrl:1
	v_fmac_f32_e32 v180, v243, v57
	v_add_f32_dpp v183, v183, v183 quad_perm:[2,3,0,1] row_mask:0xf bank_mask:0xf bound_ctrl:1
	v_add_f32_dpp v238, v238, v238 quad_perm:[2,3,0,1] row_mask:0xf bank_mask:0xf bound_ctrl:1
	v_fmac_f32_e32 v181, v243, v58
	v_add_f32_dpp v183, v183, v183 row_half_mirror row_mask:0xf bank_mask:0xf bound_ctrl:1
	v_add_f32_dpp v238, v238, v238 row_half_mirror row_mask:0xf bank_mask:0xf bound_ctrl:1
	v_fmac_f32_e32 v182, v243, v59
	v_add_f32_dpp v183, v183, v183 row_mirror row_mask:0xf bank_mask:0xf bound_ctrl:1
	v_fmac_f32_e32 v179, v183, v52
	v_fmac_f32_e32 v180, v183, v53
	v_fmac_f32_e32 v181, v183, v54
	v_fmac_f32_e32 v182, v183, v55
	s_mov_b64 exec, s[8:9]
	ds_write2st64_b32 v152, v184, v238 offset0:42 offset1:40
	s_mov_b64 exec, -1
	ds_read_b128 v[48:51], v145 offset:12544
	ds_read_b128 v[52:55], v145 offset:20736
	ds_read_b128 v[56:59], v145 offset:28928
	ds_read_b128 v[60:63], v145 offset:37120
	ds_read2st64_b32 v[242:243], v151 offset0:209 offset1:208
	s_waitcnt lgkmcnt(10)
	v_mul_f32_e32 v183, v179, v8
	v_mul_f32_e32 v184, v179, v20
	v_fmac_f32_e32 v183, v180, v9
	v_fmac_f32_e32 v184, v180, v21
	v_fmac_f32_e32 v183, v181, v10
	v_fmac_f32_e32 v184, v181, v22
	v_fmac_f32_e32 v183, v182, v11
	v_fmac_f32_e32 v184, v182, v23
	v_fmac_f32_e32 v179, v240, v16
	v_add_f32_dpp v183, v183, v183 quad_perm:[1,0,3,2] row_mask:0xf bank_mask:0xf bound_ctrl:1
	v_add_f32_dpp v184, v184, v184 quad_perm:[1,0,3,2] row_mask:0xf bank_mask:0xf bound_ctrl:1
	v_fmac_f32_e32 v180, v240, v17
	v_add_f32_dpp v183, v183, v183 quad_perm:[2,3,0,1] row_mask:0xf bank_mask:0xf bound_ctrl:1
	v_add_f32_dpp v184, v184, v184 quad_perm:[2,3,0,1] row_mask:0xf bank_mask:0xf bound_ctrl:1
	v_fmac_f32_e32 v181, v240, v18
	v_add_f32_dpp v183, v183, v183 row_half_mirror row_mask:0xf bank_mask:0xf bound_ctrl:1
	v_add_f32_dpp v184, v184, v184 row_half_mirror row_mask:0xf bank_mask:0xf bound_ctrl:1
	v_fmac_f32_e32 v182, v240, v19
	v_add_f32_dpp v183, v183, v183 row_mirror row_mask:0xf bank_mask:0xf bound_ctrl:1
	v_fmac_f32_e32 v179, v183, v12
	v_fmac_f32_e32 v180, v183, v13
	v_fmac_f32_e32 v181, v183, v14
	v_fmac_f32_e32 v182, v183, v15
	ds_read_b128 v[8:11], v145 offset:12288
	ds_read_b128 v[12:15], v145 offset:20480
	ds_read_b128 v[16:19], v145 offset:28672
	ds_read_b128 v[20:23], v145 offset:36864
	s_waitcnt lgkmcnt(10)
	v_mul_f32_e32 v183, v179, v28
	v_mul_f32_e32 v238, v179, v40
	v_fmac_f32_e32 v183, v180, v29
	v_fmac_f32_e32 v238, v180, v41
	v_fmac_f32_e32 v183, v181, v30
	v_fmac_f32_e32 v238, v181, v42
	v_fmac_f32_e32 v183, v182, v31
	v_fmac_f32_e32 v238, v182, v43
	v_fmac_f32_e32 v179, v241, v36
	v_add_f32_dpp v183, v183, v183 quad_perm:[1,0,3,2] row_mask:0xf bank_mask:0xf bound_ctrl:1
	v_add_f32_dpp v238, v238, v238 quad_perm:[1,0,3,2] row_mask:0xf bank_mask:0xf bound_ctrl:1
	v_fmac_f32_e32 v180, v241, v37
	v_add_f32_dpp v183, v183, v183 quad_perm:[2,3,0,1] row_mask:0xf bank_mask:0xf bound_ctrl:1
	v_add_f32_dpp v238, v238, v238 quad_perm:[2,3,0,1] row_mask:0xf bank_mask:0xf bound_ctrl:1
	v_fmac_f32_e32 v181, v241, v38
	v_add_f32_dpp v183, v183, v183 row_half_mirror row_mask:0xf bank_mask:0xf bound_ctrl:1
	v_add_f32_dpp v238, v238, v238 row_half_mirror row_mask:0xf bank_mask:0xf bound_ctrl:1
	v_fmac_f32_e32 v182, v241, v39
	v_add_f32_dpp v183, v183, v183 row_mirror row_mask:0xf bank_mask:0xf bound_ctrl:1
	v_fmac_f32_e32 v179, v183, v32
	v_fmac_f32_e32 v180, v183, v33
	v_fmac_f32_e32 v181, v183, v34
	v_fmac_f32_e32 v182, v183, v35
	s_mov_b64 exec, s[8:9]
	ds_write2st64_b32 v152, v184, v238 offset0:38 offset1:36
	s_mov_b64 exec, -1
	ds_read_b128 v[28:31], v145 offset:12032
	ds_read_b128 v[32:35], v145 offset:20224
	ds_read_b128 v[36:39], v145 offset:28416
	ds_read_b128 v[40:43], v145 offset:36608
	ds_read2st64_b32 v[240:241], v151 offset0:207 offset1:206
	s_waitcnt lgkmcnt(10)
	v_mul_f32_e32 v183, v179, v48
	v_mul_f32_e32 v184, v179, v60
	v_fmac_f32_e32 v183, v180, v49
	v_fmac_f32_e32 v184, v180, v61
	v_fmac_f32_e32 v183, v181, v50
	v_fmac_f32_e32 v184, v181, v62
	v_fmac_f32_e32 v183, v182, v51
	v_fmac_f32_e32 v184, v182, v63
	v_fmac_f32_e32 v179, v242, v56
	v_add_f32_dpp v183, v183, v183 quad_perm:[1,0,3,2] row_mask:0xf bank_mask:0xf bound_ctrl:1
	v_add_f32_dpp v184, v184, v184 quad_perm:[1,0,3,2] row_mask:0xf bank_mask:0xf bound_ctrl:1
	v_fmac_f32_e32 v180, v242, v57
	v_add_f32_dpp v183, v183, v183 quad_perm:[2,3,0,1] row_mask:0xf bank_mask:0xf bound_ctrl:1
	v_add_f32_dpp v184, v184, v184 quad_perm:[2,3,0,1] row_mask:0xf bank_mask:0xf bound_ctrl:1
	v_fmac_f32_e32 v181, v242, v58
	v_add_f32_dpp v183, v183, v183 row_half_mirror row_mask:0xf bank_mask:0xf bound_ctrl:1
	v_add_f32_dpp v184, v184, v184 row_half_mirror row_mask:0xf bank_mask:0xf bound_ctrl:1
	v_fmac_f32_e32 v182, v242, v59
	v_add_f32_dpp v183, v183, v183 row_mirror row_mask:0xf bank_mask:0xf bound_ctrl:1
	v_fmac_f32_e32 v179, v183, v52
	v_fmac_f32_e32 v180, v183, v53
	v_fmac_f32_e32 v181, v183, v54
	v_fmac_f32_e32 v182, v183, v55
	ds_read_b128 v[48:51], v145 offset:11776
	ds_read_b128 v[52:55], v145 offset:19968
	ds_read_b128 v[56:59], v145 offset:28160
	ds_read_b128 v[60:63], v145 offset:36352
	s_waitcnt lgkmcnt(10)
	v_mul_f32_e32 v183, v179, v8
	v_mul_f32_e32 v238, v179, v20
	v_fmac_f32_e32 v183, v180, v9
	v_fmac_f32_e32 v238, v180, v21
	v_fmac_f32_e32 v183, v181, v10
	v_fmac_f32_e32 v238, v181, v22
	v_fmac_f32_e32 v183, v182, v11
	v_fmac_f32_e32 v238, v182, v23
	v_fmac_f32_e32 v179, v243, v16
	v_add_f32_dpp v183, v183, v183 quad_perm:[1,0,3,2] row_mask:0xf bank_mask:0xf bound_ctrl:1
	v_add_f32_dpp v238, v238, v238 quad_perm:[1,0,3,2] row_mask:0xf bank_mask:0xf bound_ctrl:1
	v_fmac_f32_e32 v180, v243, v17
	v_add_f32_dpp v183, v183, v183 quad_perm:[2,3,0,1] row_mask:0xf bank_mask:0xf bound_ctrl:1
	v_add_f32_dpp v238, v238, v238 quad_perm:[2,3,0,1] row_mask:0xf bank_mask:0xf bound_ctrl:1
	v_fmac_f32_e32 v181, v243, v18
	v_add_f32_dpp v183, v183, v183 row_half_mirror row_mask:0xf bank_mask:0xf bound_ctrl:1
	v_add_f32_dpp v238, v238, v238 row_half_mirror row_mask:0xf bank_mask:0xf bound_ctrl:1
	v_fmac_f32_e32 v182, v243, v19
	v_add_f32_dpp v183, v183, v183 row_mirror row_mask:0xf bank_mask:0xf bound_ctrl:1
	v_fmac_f32_e32 v179, v183, v12
	v_fmac_f32_e32 v180, v183, v13
	v_fmac_f32_e32 v181, v183, v14
	v_fmac_f32_e32 v182, v183, v15
	s_mov_b64 exec, s[8:9]
	ds_write2st64_b32 v152, v184, v238 offset0:34 offset1:32
	s_mov_b64 exec, -1
	ds_read_b128 v[8:11], v145 offset:11520
	ds_read_b128 v[12:15], v145 offset:19712
	ds_read_b128 v[16:19], v145 offset:27904
	ds_read_b128 v[20:23], v145 offset:36096
	ds_read2st64_b32 v[242:243], v151 offset0:205 offset1:204
	s_waitcnt lgkmcnt(10)
	v_mul_f32_e32 v183, v179, v28
	v_mul_f32_e32 v184, v179, v40
	v_fmac_f32_e32 v183, v180, v29
	v_fmac_f32_e32 v184, v180, v41
	v_fmac_f32_e32 v183, v181, v30
	v_fmac_f32_e32 v184, v181, v42
	v_fmac_f32_e32 v183, v182, v31
	v_fmac_f32_e32 v184, v182, v43
	v_fmac_f32_e32 v179, v240, v36
	v_add_f32_dpp v183, v183, v183 quad_perm:[1,0,3,2] row_mask:0xf bank_mask:0xf bound_ctrl:1
	v_add_f32_dpp v184, v184, v184 quad_perm:[1,0,3,2] row_mask:0xf bank_mask:0xf bound_ctrl:1
	v_fmac_f32_e32 v180, v240, v37
	v_add_f32_dpp v183, v183, v183 quad_perm:[2,3,0,1] row_mask:0xf bank_mask:0xf bound_ctrl:1
	v_add_f32_dpp v184, v184, v184 quad_perm:[2,3,0,1] row_mask:0xf bank_mask:0xf bound_ctrl:1
	v_fmac_f32_e32 v181, v240, v38
	v_add_f32_dpp v183, v183, v183 row_half_mirror row_mask:0xf bank_mask:0xf bound_ctrl:1
	v_add_f32_dpp v184, v184, v184 row_half_mirror row_mask:0xf bank_mask:0xf bound_ctrl:1
	v_fmac_f32_e32 v182, v240, v39
	v_add_f32_dpp v183, v183, v183 row_mirror row_mask:0xf bank_mask:0xf bound_ctrl:1
	v_fmac_f32_e32 v179, v183, v32
	v_fmac_f32_e32 v180, v183, v33
	v_fmac_f32_e32 v181, v183, v34
	v_fmac_f32_e32 v182, v183, v35
	ds_read_b128 v[28:31], v145 offset:11264
	ds_read_b128 v[32:35], v145 offset:19456
	ds_read_b128 v[36:39], v145 offset:27648
	ds_read_b128 v[40:43], v145 offset:35840
	s_waitcnt lgkmcnt(10)
	v_mul_f32_e32 v183, v179, v48
	v_mul_f32_e32 v238, v179, v60
	v_fmac_f32_e32 v183, v180, v49
	v_fmac_f32_e32 v238, v180, v61
	v_fmac_f32_e32 v183, v181, v50
	v_fmac_f32_e32 v238, v181, v62
	v_fmac_f32_e32 v183, v182, v51
	v_fmac_f32_e32 v238, v182, v63
	v_fmac_f32_e32 v179, v241, v56
	v_add_f32_dpp v183, v183, v183 quad_perm:[1,0,3,2] row_mask:0xf bank_mask:0xf bound_ctrl:1
	v_add_f32_dpp v238, v238, v238 quad_perm:[1,0,3,2] row_mask:0xf bank_mask:0xf bound_ctrl:1
	v_fmac_f32_e32 v180, v241, v57
	v_add_f32_dpp v183, v183, v183 quad_perm:[2,3,0,1] row_mask:0xf bank_mask:0xf bound_ctrl:1
	v_add_f32_dpp v238, v238, v238 quad_perm:[2,3,0,1] row_mask:0xf bank_mask:0xf bound_ctrl:1
	v_fmac_f32_e32 v181, v241, v58
	v_add_f32_dpp v183, v183, v183 row_half_mirror row_mask:0xf bank_mask:0xf bound_ctrl:1
	v_add_f32_dpp v238, v238, v238 row_half_mirror row_mask:0xf bank_mask:0xf bound_ctrl:1
	v_fmac_f32_e32 v182, v241, v59
	v_add_f32_dpp v183, v183, v183 row_mirror row_mask:0xf bank_mask:0xf bound_ctrl:1
	v_fmac_f32_e32 v179, v183, v52
	v_fmac_f32_e32 v180, v183, v53
	v_fmac_f32_e32 v181, v183, v54
	v_fmac_f32_e32 v182, v183, v55
	s_mov_b64 exec, s[8:9]
	ds_write2st64_b32 v152, v184, v238 offset0:30 offset1:28
	s_mov_b64 exec, -1
	ds_read_b128 v[48:51], v145 offset:11008
	ds_read_b128 v[52:55], v145 offset:19200
	ds_read_b128 v[56:59], v145 offset:27392
	ds_read_b128 v[60:63], v145 offset:35584
	ds_read2st64_b32 v[240:241], v151 offset0:203 offset1:202
	s_waitcnt lgkmcnt(10)
	v_mul_f32_e32 v183, v179, v8
	v_mul_f32_e32 v184, v179, v20
	v_fmac_f32_e32 v183, v180, v9
	v_fmac_f32_e32 v184, v180, v21
	v_fmac_f32_e32 v183, v181, v10
	v_fmac_f32_e32 v184, v181, v22
	v_fmac_f32_e32 v183, v182, v11
	v_fmac_f32_e32 v184, v182, v23
	v_fmac_f32_e32 v179, v242, v16
	v_add_f32_dpp v183, v183, v183 quad_perm:[1,0,3,2] row_mask:0xf bank_mask:0xf bound_ctrl:1
	v_add_f32_dpp v184, v184, v184 quad_perm:[1,0,3,2] row_mask:0xf bank_mask:0xf bound_ctrl:1
	v_fmac_f32_e32 v180, v242, v17
	v_add_f32_dpp v183, v183, v183 quad_perm:[2,3,0,1] row_mask:0xf bank_mask:0xf bound_ctrl:1
	v_add_f32_dpp v184, v184, v184 quad_perm:[2,3,0,1] row_mask:0xf bank_mask:0xf bound_ctrl:1
	v_fmac_f32_e32 v181, v242, v18
	v_add_f32_dpp v183, v183, v183 row_half_mirror row_mask:0xf bank_mask:0xf bound_ctrl:1
	v_add_f32_dpp v184, v184, v184 row_half_mirror row_mask:0xf bank_mask:0xf bound_ctrl:1
	v_fmac_f32_e32 v182, v242, v19
	v_add_f32_dpp v183, v183, v183 row_mirror row_mask:0xf bank_mask:0xf bound_ctrl:1
	v_fmac_f32_e32 v179, v183, v12
	v_fmac_f32_e32 v180, v183, v13
	v_fmac_f32_e32 v181, v183, v14
	v_fmac_f32_e32 v182, v183, v15
	ds_read_b128 v[8:11], v145 offset:10752
	ds_read_b128 v[12:15], v145 offset:18944
	ds_read_b128 v[16:19], v145 offset:27136
	ds_read_b128 v[20:23], v145 offset:35328
	s_waitcnt lgkmcnt(10)
	v_mul_f32_e32 v183, v179, v28
	v_mul_f32_e32 v238, v179, v40
	v_fmac_f32_e32 v183, v180, v29
	v_fmac_f32_e32 v238, v180, v41
	v_fmac_f32_e32 v183, v181, v30
	v_fmac_f32_e32 v238, v181, v42
	v_fmac_f32_e32 v183, v182, v31
	v_fmac_f32_e32 v238, v182, v43
	v_fmac_f32_e32 v179, v243, v36
	v_add_f32_dpp v183, v183, v183 quad_perm:[1,0,3,2] row_mask:0xf bank_mask:0xf bound_ctrl:1
	v_add_f32_dpp v238, v238, v238 quad_perm:[1,0,3,2] row_mask:0xf bank_mask:0xf bound_ctrl:1
	v_fmac_f32_e32 v180, v243, v37
	v_add_f32_dpp v183, v183, v183 quad_perm:[2,3,0,1] row_mask:0xf bank_mask:0xf bound_ctrl:1
	v_add_f32_dpp v238, v238, v238 quad_perm:[2,3,0,1] row_mask:0xf bank_mask:0xf bound_ctrl:1
	v_fmac_f32_e32 v181, v243, v38
	v_add_f32_dpp v183, v183, v183 row_half_mirror row_mask:0xf bank_mask:0xf bound_ctrl:1
	v_add_f32_dpp v238, v238, v238 row_half_mirror row_mask:0xf bank_mask:0xf bound_ctrl:1
	v_fmac_f32_e32 v182, v243, v39
	v_add_f32_dpp v183, v183, v183 row_mirror row_mask:0xf bank_mask:0xf bound_ctrl:1
	v_fmac_f32_e32 v179, v183, v32
	v_fmac_f32_e32 v180, v183, v33
	v_fmac_f32_e32 v181, v183, v34
	v_fmac_f32_e32 v182, v183, v35
	s_mov_b64 exec, s[8:9]
	ds_write2st64_b32 v152, v184, v238 offset0:26 offset1:24
	s_mov_b64 exec, -1
	ds_read_b128 v[28:31], v145 offset:10496
	ds_read_b128 v[32:35], v145 offset:18688
	ds_read_b128 v[36:39], v145 offset:26880
	ds_read_b128 v[40:43], v145 offset:35072
	ds_read2st64_b32 v[242:243], v151 offset0:201 offset1:200
	s_waitcnt lgkmcnt(10)
	v_mul_f32_e32 v183, v179, v48
	v_mul_f32_e32 v184, v179, v60
	v_fmac_f32_e32 v183, v180, v49
	v_fmac_f32_e32 v184, v180, v61
	v_fmac_f32_e32 v183, v181, v50
	v_fmac_f32_e32 v184, v181, v62
	v_fmac_f32_e32 v183, v182, v51
	v_fmac_f32_e32 v184, v182, v63
	v_fmac_f32_e32 v179, v240, v56
	v_add_f32_dpp v183, v183, v183 quad_perm:[1,0,3,2] row_mask:0xf bank_mask:0xf bound_ctrl:1
	v_add_f32_dpp v184, v184, v184 quad_perm:[1,0,3,2] row_mask:0xf bank_mask:0xf bound_ctrl:1
	v_fmac_f32_e32 v180, v240, v57
	v_add_f32_dpp v183, v183, v183 quad_perm:[2,3,0,1] row_mask:0xf bank_mask:0xf bound_ctrl:1
	v_add_f32_dpp v184, v184, v184 quad_perm:[2,3,0,1] row_mask:0xf bank_mask:0xf bound_ctrl:1
	v_fmac_f32_e32 v181, v240, v58
	v_add_f32_dpp v183, v183, v183 row_half_mirror row_mask:0xf bank_mask:0xf bound_ctrl:1
	v_add_f32_dpp v184, v184, v184 row_half_mirror row_mask:0xf bank_mask:0xf bound_ctrl:1
	v_fmac_f32_e32 v182, v240, v59
	v_add_f32_dpp v183, v183, v183 row_mirror row_mask:0xf bank_mask:0xf bound_ctrl:1
	v_fmac_f32_e32 v179, v183, v52
	v_fmac_f32_e32 v180, v183, v53
	v_fmac_f32_e32 v181, v183, v54
	v_fmac_f32_e32 v182, v183, v55
	ds_read_b128 v[48:51], v145 offset:10240
	ds_read_b128 v[52:55], v145 offset:18432
	ds_read_b128 v[56:59], v145 offset:26624
	ds_read_b128 v[60:63], v145 offset:34816
	s_waitcnt lgkmcnt(10)
	v_mul_f32_e32 v183, v179, v8
	v_mul_f32_e32 v238, v179, v20
	v_fmac_f32_e32 v183, v180, v9
	v_fmac_f32_e32 v238, v180, v21
	v_fmac_f32_e32 v183, v181, v10
	v_fmac_f32_e32 v238, v181, v22
	v_fmac_f32_e32 v183, v182, v11
	v_fmac_f32_e32 v238, v182, v23
	v_fmac_f32_e32 v179, v241, v16
	v_add_f32_dpp v183, v183, v183 quad_perm:[1,0,3,2] row_mask:0xf bank_mask:0xf bound_ctrl:1
	v_add_f32_dpp v238, v238, v238 quad_perm:[1,0,3,2] row_mask:0xf bank_mask:0xf bound_ctrl:1
	v_fmac_f32_e32 v180, v241, v17
	v_add_f32_dpp v183, v183, v183 quad_perm:[2,3,0,1] row_mask:0xf bank_mask:0xf bound_ctrl:1
	v_add_f32_dpp v238, v238, v238 quad_perm:[2,3,0,1] row_mask:0xf bank_mask:0xf bound_ctrl:1
	v_fmac_f32_e32 v181, v241, v18
	v_add_f32_dpp v183, v183, v183 row_half_mirror row_mask:0xf bank_mask:0xf bound_ctrl:1
	v_add_f32_dpp v238, v238, v238 row_half_mirror row_mask:0xf bank_mask:0xf bound_ctrl:1
	v_fmac_f32_e32 v182, v241, v19
	v_add_f32_dpp v183, v183, v183 row_mirror row_mask:0xf bank_mask:0xf bound_ctrl:1
	v_fmac_f32_e32 v179, v183, v12
	v_fmac_f32_e32 v180, v183, v13
	v_fmac_f32_e32 v181, v183, v14
	v_fmac_f32_e32 v182, v183, v15
	s_mov_b64 exec, s[8:9]
	ds_write2st64_b32 v152, v184, v238 offset0:22 offset1:20
	s_mov_b64 exec, -1
	ds_read_b128 v[8:11], v145 offset:9984
	ds_read_b128 v[12:15], v145 offset:18176
	ds_read_b128 v[16:19], v145 offset:26368
	ds_read_b128 v[20:23], v145 offset:34560
	ds_read2st64_b32 v[240:241], v151 offset0:199 offset1:198
	s_waitcnt lgkmcnt(10)
	v_mul_f32_e32 v183, v179, v28
	v_mul_f32_e32 v184, v179, v40
	v_fmac_f32_e32 v183, v180, v29
	v_fmac_f32_e32 v184, v180, v41
	v_fmac_f32_e32 v183, v181, v30
	v_fmac_f32_e32 v184, v181, v42
	v_fmac_f32_e32 v183, v182, v31
	v_fmac_f32_e32 v184, v182, v43
	v_fmac_f32_e32 v179, v242, v36
	v_add_f32_dpp v183, v183, v183 quad_perm:[1,0,3,2] row_mask:0xf bank_mask:0xf bound_ctrl:1
	v_add_f32_dpp v184, v184, v184 quad_perm:[1,0,3,2] row_mask:0xf bank_mask:0xf bound_ctrl:1
	v_fmac_f32_e32 v180, v242, v37
	v_add_f32_dpp v183, v183, v183 quad_perm:[2,3,0,1] row_mask:0xf bank_mask:0xf bound_ctrl:1
	v_add_f32_dpp v184, v184, v184 quad_perm:[2,3,0,1] row_mask:0xf bank_mask:0xf bound_ctrl:1
	v_fmac_f32_e32 v181, v242, v38
	v_add_f32_dpp v183, v183, v183 row_half_mirror row_mask:0xf bank_mask:0xf bound_ctrl:1
	v_add_f32_dpp v184, v184, v184 row_half_mirror row_mask:0xf bank_mask:0xf bound_ctrl:1
	v_fmac_f32_e32 v182, v242, v39
	v_add_f32_dpp v183, v183, v183 row_mirror row_mask:0xf bank_mask:0xf bound_ctrl:1
	v_fmac_f32_e32 v179, v183, v32
	v_fmac_f32_e32 v180, v183, v33
	v_fmac_f32_e32 v181, v183, v34
	v_fmac_f32_e32 v182, v183, v35
	ds_read_b128 v[28:31], v145 offset:9728
	ds_read_b128 v[32:35], v145 offset:17920
	ds_read_b128 v[36:39], v145 offset:26112
	ds_read_b128 v[40:43], v145 offset:34304
	s_waitcnt lgkmcnt(10)
	v_mul_f32_e32 v183, v179, v48
	v_mul_f32_e32 v238, v179, v60
	v_fmac_f32_e32 v183, v180, v49
	v_fmac_f32_e32 v238, v180, v61
	v_fmac_f32_e32 v183, v181, v50
	v_fmac_f32_e32 v238, v181, v62
	v_fmac_f32_e32 v183, v182, v51
	v_fmac_f32_e32 v238, v182, v63
	v_fmac_f32_e32 v179, v243, v56
	v_add_f32_dpp v183, v183, v183 quad_perm:[1,0,3,2] row_mask:0xf bank_mask:0xf bound_ctrl:1
	v_add_f32_dpp v238, v238, v238 quad_perm:[1,0,3,2] row_mask:0xf bank_mask:0xf bound_ctrl:1
	v_fmac_f32_e32 v180, v243, v57
	v_add_f32_dpp v183, v183, v183 quad_perm:[2,3,0,1] row_mask:0xf bank_mask:0xf bound_ctrl:1
	v_add_f32_dpp v238, v238, v238 quad_perm:[2,3,0,1] row_mask:0xf bank_mask:0xf bound_ctrl:1
	v_fmac_f32_e32 v181, v243, v58
	v_add_f32_dpp v183, v183, v183 row_half_mirror row_mask:0xf bank_mask:0xf bound_ctrl:1
	v_add_f32_dpp v238, v238, v238 row_half_mirror row_mask:0xf bank_mask:0xf bound_ctrl:1
	v_fmac_f32_e32 v182, v243, v59
	v_add_f32_dpp v183, v183, v183 row_mirror row_mask:0xf bank_mask:0xf bound_ctrl:1
	v_fmac_f32_e32 v179, v183, v52
	v_fmac_f32_e32 v180, v183, v53
	v_fmac_f32_e32 v181, v183, v54
	v_fmac_f32_e32 v182, v183, v55
	s_mov_b64 exec, s[8:9]
	ds_write2st64_b32 v152, v184, v238 offset0:18 offset1:16
	s_mov_b64 exec, -1
	ds_read_b128 v[48:51], v145 offset:9472
	ds_read_b128 v[52:55], v145 offset:17664
	ds_read_b128 v[56:59], v145 offset:25856
	ds_read_b128 v[60:63], v145 offset:34048
	ds_read2st64_b32 v[242:243], v151 offset0:197 offset1:196
	s_waitcnt lgkmcnt(10)
	v_mul_f32_e32 v183, v179, v8
	v_mul_f32_e32 v184, v179, v20
	v_fmac_f32_e32 v183, v180, v9
	v_fmac_f32_e32 v184, v180, v21
	v_fmac_f32_e32 v183, v181, v10
	v_fmac_f32_e32 v184, v181, v22
	v_fmac_f32_e32 v183, v182, v11
	v_fmac_f32_e32 v184, v182, v23
	v_fmac_f32_e32 v179, v240, v16
	v_add_f32_dpp v183, v183, v183 quad_perm:[1,0,3,2] row_mask:0xf bank_mask:0xf bound_ctrl:1
	v_add_f32_dpp v184, v184, v184 quad_perm:[1,0,3,2] row_mask:0xf bank_mask:0xf bound_ctrl:1
	v_fmac_f32_e32 v180, v240, v17
	v_add_f32_dpp v183, v183, v183 quad_perm:[2,3,0,1] row_mask:0xf bank_mask:0xf bound_ctrl:1
	v_add_f32_dpp v184, v184, v184 quad_perm:[2,3,0,1] row_mask:0xf bank_mask:0xf bound_ctrl:1
	v_fmac_f32_e32 v181, v240, v18
	v_add_f32_dpp v183, v183, v183 row_half_mirror row_mask:0xf bank_mask:0xf bound_ctrl:1
	v_add_f32_dpp v184, v184, v184 row_half_mirror row_mask:0xf bank_mask:0xf bound_ctrl:1
	v_fmac_f32_e32 v182, v240, v19
	v_add_f32_dpp v183, v183, v183 row_mirror row_mask:0xf bank_mask:0xf bound_ctrl:1
	v_fmac_f32_e32 v179, v183, v12
	v_fmac_f32_e32 v180, v183, v13
	v_fmac_f32_e32 v181, v183, v14
	v_fmac_f32_e32 v182, v183, v15
	ds_read_b128 v[8:11], v145 offset:9216
	ds_read_b128 v[12:15], v145 offset:17408
	ds_read_b128 v[16:19], v145 offset:25600
	ds_read_b128 v[20:23], v145 offset:33792
	s_waitcnt lgkmcnt(10)
	v_mul_f32_e32 v183, v179, v28
	v_mul_f32_e32 v238, v179, v40
	v_fmac_f32_e32 v183, v180, v29
	v_fmac_f32_e32 v238, v180, v41
	v_fmac_f32_e32 v183, v181, v30
	v_fmac_f32_e32 v238, v181, v42
	v_fmac_f32_e32 v183, v182, v31
	v_fmac_f32_e32 v238, v182, v43
	v_fmac_f32_e32 v179, v241, v36
	v_add_f32_dpp v183, v183, v183 quad_perm:[1,0,3,2] row_mask:0xf bank_mask:0xf bound_ctrl:1
	v_add_f32_dpp v238, v238, v238 quad_perm:[1,0,3,2] row_mask:0xf bank_mask:0xf bound_ctrl:1
	v_fmac_f32_e32 v180, v241, v37
	v_add_f32_dpp v183, v183, v183 quad_perm:[2,3,0,1] row_mask:0xf bank_mask:0xf bound_ctrl:1
	v_add_f32_dpp v238, v238, v238 quad_perm:[2,3,0,1] row_mask:0xf bank_mask:0xf bound_ctrl:1
	v_fmac_f32_e32 v181, v241, v38
	v_add_f32_dpp v183, v183, v183 row_half_mirror row_mask:0xf bank_mask:0xf bound_ctrl:1
	v_add_f32_dpp v238, v238, v238 row_half_mirror row_mask:0xf bank_mask:0xf bound_ctrl:1
	v_fmac_f32_e32 v182, v241, v39
	v_add_f32_dpp v183, v183, v183 row_mirror row_mask:0xf bank_mask:0xf bound_ctrl:1
	v_fmac_f32_e32 v179, v183, v32
	v_fmac_f32_e32 v180, v183, v33
	v_fmac_f32_e32 v181, v183, v34
	v_fmac_f32_e32 v182, v183, v35
	s_mov_b64 exec, s[8:9]
	ds_write2st64_b32 v152, v184, v238 offset0:14 offset1:12
	s_mov_b64 exec, -1
	ds_read_b128 v[28:31], v145 offset:8960
	ds_read_b128 v[32:35], v145 offset:17152
	ds_read_b128 v[36:39], v145 offset:25344
	ds_read_b128 v[40:43], v145 offset:33536
	ds_read2st64_b32 v[240:241], v151 offset0:195 offset1:194
	s_waitcnt lgkmcnt(10)
	v_mul_f32_e32 v183, v179, v48
	v_mul_f32_e32 v184, v179, v60
	v_fmac_f32_e32 v183, v180, v49
	v_fmac_f32_e32 v184, v180, v61
	v_fmac_f32_e32 v183, v181, v50
	v_fmac_f32_e32 v184, v181, v62
	v_fmac_f32_e32 v183, v182, v51
	v_fmac_f32_e32 v184, v182, v63
	v_fmac_f32_e32 v179, v242, v56
	v_add_f32_dpp v183, v183, v183 quad_perm:[1,0,3,2] row_mask:0xf bank_mask:0xf bound_ctrl:1
	v_add_f32_dpp v184, v184, v184 quad_perm:[1,0,3,2] row_mask:0xf bank_mask:0xf bound_ctrl:1
	v_fmac_f32_e32 v180, v242, v57
	v_add_f32_dpp v183, v183, v183 quad_perm:[2,3,0,1] row_mask:0xf bank_mask:0xf bound_ctrl:1
	v_add_f32_dpp v184, v184, v184 quad_perm:[2,3,0,1] row_mask:0xf bank_mask:0xf bound_ctrl:1
	v_fmac_f32_e32 v181, v242, v58
	v_add_f32_dpp v183, v183, v183 row_half_mirror row_mask:0xf bank_mask:0xf bound_ctrl:1
	v_add_f32_dpp v184, v184, v184 row_half_mirror row_mask:0xf bank_mask:0xf bound_ctrl:1
	v_fmac_f32_e32 v182, v242, v59
	v_add_f32_dpp v183, v183, v183 row_mirror row_mask:0xf bank_mask:0xf bound_ctrl:1
	v_fmac_f32_e32 v179, v183, v52
	v_fmac_f32_e32 v180, v183, v53
	v_fmac_f32_e32 v181, v183, v54
	v_fmac_f32_e32 v182, v183, v55
	ds_read_b128 v[48:51], v145 offset:8704
	ds_read_b128 v[52:55], v145 offset:16896
	ds_read_b128 v[56:59], v145 offset:25088
	ds_read_b128 v[60:63], v145 offset:33280
	s_waitcnt lgkmcnt(10)
	v_mul_f32_e32 v183, v179, v8
	v_mul_f32_e32 v238, v179, v20
	v_fmac_f32_e32 v183, v180, v9
	v_fmac_f32_e32 v238, v180, v21
	v_fmac_f32_e32 v183, v181, v10
	v_fmac_f32_e32 v238, v181, v22
	v_fmac_f32_e32 v183, v182, v11
	v_fmac_f32_e32 v238, v182, v23
	v_fmac_f32_e32 v179, v243, v16
	v_add_f32_dpp v183, v183, v183 quad_perm:[1,0,3,2] row_mask:0xf bank_mask:0xf bound_ctrl:1
	v_add_f32_dpp v238, v238, v238 quad_perm:[1,0,3,2] row_mask:0xf bank_mask:0xf bound_ctrl:1
	v_fmac_f32_e32 v180, v243, v17
	v_add_f32_dpp v183, v183, v183 quad_perm:[2,3,0,1] row_mask:0xf bank_mask:0xf bound_ctrl:1
	v_add_f32_dpp v238, v238, v238 quad_perm:[2,3,0,1] row_mask:0xf bank_mask:0xf bound_ctrl:1
	v_fmac_f32_e32 v181, v243, v18
	v_add_f32_dpp v183, v183, v183 row_half_mirror row_mask:0xf bank_mask:0xf bound_ctrl:1
	v_add_f32_dpp v238, v238, v238 row_half_mirror row_mask:0xf bank_mask:0xf bound_ctrl:1
	v_fmac_f32_e32 v182, v243, v19
	v_add_f32_dpp v183, v183, v183 row_mirror row_mask:0xf bank_mask:0xf bound_ctrl:1
	v_fmac_f32_e32 v179, v183, v12
	v_fmac_f32_e32 v180, v183, v13
	v_fmac_f32_e32 v181, v183, v14
	v_fmac_f32_e32 v182, v183, v15
	s_mov_b64 exec, s[8:9]
	ds_write2st64_b32 v152, v184, v238 offset0:10 offset1:8
	s_mov_b64 exec, -1
	ds_read_b128 v[8:11], v145 offset:8448
	ds_read_b128 v[12:15], v145 offset:16640
	ds_read_b128 v[16:19], v145 offset:24832
	ds_read_b128 v[20:23], v145 offset:33024
	ds_read2st64_b32 v[242:243], v151 offset0:193 offset1:192
	s_waitcnt lgkmcnt(10)
	v_mul_f32_e32 v183, v179, v28
	v_mul_f32_e32 v184, v179, v40
	v_fmac_f32_e32 v183, v180, v29
	v_fmac_f32_e32 v184, v180, v41
	v_fmac_f32_e32 v183, v181, v30
	v_fmac_f32_e32 v184, v181, v42
	v_fmac_f32_e32 v183, v182, v31
	v_fmac_f32_e32 v184, v182, v43
	v_fmac_f32_e32 v179, v240, v36
	v_add_f32_dpp v183, v183, v183 quad_perm:[1,0,3,2] row_mask:0xf bank_mask:0xf bound_ctrl:1
	v_add_f32_dpp v184, v184, v184 quad_perm:[1,0,3,2] row_mask:0xf bank_mask:0xf bound_ctrl:1
	v_fmac_f32_e32 v180, v240, v37
	v_add_f32_dpp v183, v183, v183 quad_perm:[2,3,0,1] row_mask:0xf bank_mask:0xf bound_ctrl:1
	v_add_f32_dpp v184, v184, v184 quad_perm:[2,3,0,1] row_mask:0xf bank_mask:0xf bound_ctrl:1
	v_fmac_f32_e32 v181, v240, v38
	v_add_f32_dpp v183, v183, v183 row_half_mirror row_mask:0xf bank_mask:0xf bound_ctrl:1
	v_add_f32_dpp v184, v184, v184 row_half_mirror row_mask:0xf bank_mask:0xf bound_ctrl:1
	v_fmac_f32_e32 v182, v240, v39
	v_add_f32_dpp v183, v183, v183 row_mirror row_mask:0xf bank_mask:0xf bound_ctrl:1
	v_fmac_f32_e32 v179, v183, v32
	v_fmac_f32_e32 v180, v183, v33
	v_fmac_f32_e32 v181, v183, v34
	v_fmac_f32_e32 v182, v183, v35
	ds_read_b128 v[28:31], v145 offset:8192
	ds_read_b128 v[32:35], v145 offset:16384
	ds_read_b128 v[36:39], v145 offset:24576
	ds_read_b128 v[40:43], v145 offset:32768
	s_waitcnt lgkmcnt(10)
	v_mul_f32_e32 v183, v179, v48
	v_mul_f32_e32 v238, v179, v60
	v_fmac_f32_e32 v183, v180, v49
	v_fmac_f32_e32 v238, v180, v61
	v_fmac_f32_e32 v183, v181, v50
	v_fmac_f32_e32 v238, v181, v62
	v_fmac_f32_e32 v183, v182, v51
	v_fmac_f32_e32 v238, v182, v63
	v_fmac_f32_e32 v179, v241, v56
	v_add_f32_dpp v183, v183, v183 quad_perm:[1,0,3,2] row_mask:0xf bank_mask:0xf bound_ctrl:1
	v_add_f32_dpp v238, v238, v238 quad_perm:[1,0,3,2] row_mask:0xf bank_mask:0xf bound_ctrl:1
	v_fmac_f32_e32 v180, v241, v57
	v_add_f32_dpp v183, v183, v183 quad_perm:[2,3,0,1] row_mask:0xf bank_mask:0xf bound_ctrl:1
	v_add_f32_dpp v238, v238, v238 quad_perm:[2,3,0,1] row_mask:0xf bank_mask:0xf bound_ctrl:1
	v_fmac_f32_e32 v181, v241, v58
	v_add_f32_dpp v183, v183, v183 row_half_mirror row_mask:0xf bank_mask:0xf bound_ctrl:1
	v_add_f32_dpp v238, v238, v238 row_half_mirror row_mask:0xf bank_mask:0xf bound_ctrl:1
	v_fmac_f32_e32 v182, v241, v59
	v_add_f32_dpp v183, v183, v183 row_mirror row_mask:0xf bank_mask:0xf bound_ctrl:1
	v_fmac_f32_e32 v179, v183, v52
	v_fmac_f32_e32 v180, v183, v53
	v_fmac_f32_e32 v181, v183, v54
	v_fmac_f32_e32 v182, v183, v55
	s_mov_b64 exec, s[8:9]
	ds_write2st64_b32 v152, v184, v238 offset0:6 offset1:4
	s_mov_b64 exec, -1
	s_waitcnt lgkmcnt(5)
	v_mul_f32_e32 v183, v179, v8
	v_mul_f32_e32 v184, v179, v20
	v_fmac_f32_e32 v183, v180, v9
	v_fmac_f32_e32 v184, v180, v21
	v_fmac_f32_e32 v183, v181, v10
	v_fmac_f32_e32 v184, v181, v22
	v_fmac_f32_e32 v183, v182, v11
	v_fmac_f32_e32 v184, v182, v23
	v_fmac_f32_e32 v179, v242, v16
	v_add_f32_dpp v183, v183, v183 quad_perm:[1,0,3,2] row_mask:0xf bank_mask:0xf bound_ctrl:1
	v_add_f32_dpp v184, v184, v184 quad_perm:[1,0,3,2] row_mask:0xf bank_mask:0xf bound_ctrl:1
	v_fmac_f32_e32 v180, v242, v17
	v_add_f32_dpp v183, v183, v183 quad_perm:[2,3,0,1] row_mask:0xf bank_mask:0xf bound_ctrl:1
	v_add_f32_dpp v184, v184, v184 quad_perm:[2,3,0,1] row_mask:0xf bank_mask:0xf bound_ctrl:1
	v_fmac_f32_e32 v181, v242, v18
	v_add_f32_dpp v183, v183, v183 row_half_mirror row_mask:0xf bank_mask:0xf bound_ctrl:1
	v_add_f32_dpp v184, v184, v184 row_half_mirror row_mask:0xf bank_mask:0xf bound_ctrl:1
	v_fmac_f32_e32 v182, v242, v19
	v_add_f32_dpp v183, v183, v183 row_mirror row_mask:0xf bank_mask:0xf bound_ctrl:1
	v_fmac_f32_e32 v179, v183, v12
	v_fmac_f32_e32 v180, v183, v13
	v_fmac_f32_e32 v181, v183, v14
	v_fmac_f32_e32 v182, v183, v15
	s_waitcnt lgkmcnt(1)
	v_mul_f32_e32 v183, v179, v28
	v_mul_f32_e32 v238, v179, v40
	v_fmac_f32_e32 v183, v180, v29
	v_fmac_f32_e32 v238, v180, v41
	v_fmac_f32_e32 v183, v181, v30
	v_fmac_f32_e32 v238, v181, v42
	v_fmac_f32_e32 v183, v182, v31
	v_fmac_f32_e32 v238, v182, v43
	v_fmac_f32_e32 v179, v243, v36
	v_add_f32_dpp v183, v183, v183 quad_perm:[1,0,3,2] row_mask:0xf bank_mask:0xf bound_ctrl:1
	v_add_f32_dpp v238, v238, v238 quad_perm:[1,0,3,2] row_mask:0xf bank_mask:0xf bound_ctrl:1
	v_fmac_f32_e32 v180, v243, v37
	v_add_f32_dpp v183, v183, v183 quad_perm:[2,3,0,1] row_mask:0xf bank_mask:0xf bound_ctrl:1
	v_add_f32_dpp v238, v238, v238 quad_perm:[2,3,0,1] row_mask:0xf bank_mask:0xf bound_ctrl:1
	v_fmac_f32_e32 v181, v243, v38
	v_add_f32_dpp v183, v183, v183 row_half_mirror row_mask:0xf bank_mask:0xf bound_ctrl:1
	v_add_f32_dpp v238, v238, v238 row_half_mirror row_mask:0xf bank_mask:0xf bound_ctrl:1
	v_fmac_f32_e32 v182, v243, v39
	v_add_f32_dpp v183, v183, v183 row_mirror row_mask:0xf bank_mask:0xf bound_ctrl:1
	v_fmac_f32_e32 v179, v183, v32
	v_fmac_f32_e32 v180, v183, v33
	v_fmac_f32_e32 v181, v183, v34
	v_fmac_f32_e32 v182, v183, v35
	s_mov_b64 exec, s[8:9]
	ds_write2st64_b32 v152, v184, v238 offset0:2 offset1:0
	s_mov_b64 exec, -1
	ds_read_b128 v[4:7], v145 offset:57344
	s_waitcnt lgkmcnt(0)
	v_mul_f32_e32 v179, v179, v4
	v_mul_f32_e32 v180, v180, v5
	v_mul_f32_e32 v181, v181, v6
	v_mul_f32_e32 v182, v182, v7
	s_waitcnt lgkmcnt(0)
	s_barrier
	s_and_saveexec_b64 s[12:13], s[10:11]
	s_cbranch_execz .LBB0_265
	ds_read_b128 v[4:7], v153
	ds_read_b128 v[8:11], v153 offset:256
	s_waitcnt lgkmcnt(0)
	v_pk_add_f32 v[10:11], v[6:7], v[10:11]
	v_pk_add_f32 v[8:9], v[4:5], v[8:9]
	ds_read_b128 v[4:7], v150
	s_waitcnt lgkmcnt(0)
	v_pk_add_f32 v[6:7], v[10:11], v[6:7]
	v_pk_add_f32 v[4:5], v[8:9], v[4:5]
	s_nop 0
	v_cvt_pk_bf16_f32 v4, v4, v5
	v_cvt_pk_bf16_f32 v5, v6, v7
	v_lshlrev_b64 v[6:7], 11, v[124:125]
	v_lshl_add_u64 v[6:7], v[106:107], 0, v[6:7]
	global_store_dwordx2 v[6:7], v[4:5], off
	s_branch .LBB0_265

.LBB0_376:
	s_andn2_b64 vcc, exec, s[10:11]
	s_cbranch_vccnz .LBB0_378
	v_mul_f32_e32 v4, 0xbf60028a, v4
	v_mul_f32_e32 v5, 0xbf60028a, v5
	v_exp_f32_e32 v4, v4
	v_exp_f32_e32 v5, v5
	v_mul_f32_e32 v6, 0xbf60028a, v6
	v_mul_f32_e32 v7, 0xbf60028a, v7
	v_exp_f32_e32 v6, v6
	v_exp_f32_e32 v7, v7
	v_mul_f32_e32 v8, 0xbf60028a, v8
	v_mul_f32_e32 v9, 0xbf60028a, v9
	v_exp_f32_e32 v8, v8
	v_exp_f32_e32 v9, v9
	v_mul_f32_e32 v10, 0xbf60028a, v10
	v_mul_f32_e32 v11, 0xbf60028a, v11
	v_exp_f32_e32 v10, v10
	v_exp_f32_e32 v11, v11
	s_nop 1
	v_mul_f32_e32 v198, v4, v5
	v_mul_f32_e32 v201, v8, v9
	v_mul_f32_e32 v199, v198, v6
	v_mul_f32_e32 v202, v201, v10
	v_mul_f32_e32 v200, v199, v7
	v_mul_f32_e32 v203, v202, v11
	v_mov_b32_e32 v227, v4
	v_mbcnt_lo_u32_b32 v204, -1, 0
	v_mbcnt_hi_u32_b32 v204, -1, v204
	v_and_b32_e32 v205, 15, v204
	v_lshlrev_b32_e32 v205, 2, v205
	v_add_u32_e32 v206, 64, v205
	v_add_u32_e32 v207, 128, v205
	v_add_u32_e32 v208, 192, v205
	v_mov_b32_e32 v217, 1.0
	ds_bpermute_b32 v209, v205, v200
	ds_bpermute_b32 v210, v206, v200
	ds_bpermute_b32 v211, v207, v200
	ds_bpermute_b32 v212, v208, v200
	ds_bpermute_b32 v213, v205, v203
	ds_bpermute_b32 v214, v206, v203
	ds_bpermute_b32 v215, v207, v203
	ds_bpermute_b32 v216, v208, v203
	s_waitcnt lgkmcnt(7)
	v_mul_f32_e32 v15, v29, v4
	s_waitcnt lgkmcnt(7)
	v_mul_f32_e32 v4, v28, v5
	ds_write2st64_b32 v129, v15, v4 offset0:128 offset1:129
	s_waitcnt lgkmcnt(7)
	v_mul_f32_e32 v4, v26, v6
	s_waitcnt lgkmcnt(6)
	v_mul_f32_e32 v5, v25, v7
	ds_write2st64_b32 v129, v4, v5 offset0:130 offset1:131
	s_waitcnt lgkmcnt(6)
	v_mul_f32_e32 v4, v24, v8
	s_waitcnt lgkmcnt(5)
	v_mul_f32_e32 v5, v14, v9
	ds_write2st64_b32 v129, v4, v5 offset0:144 offset1:145
	s_waitcnt lgkmcnt(5)
	v_mul_f32_e32 v4, v13, v10
	s_waitcnt lgkmcnt(4)
	v_mul_f32_e32 v5, v12, v11
	ds_write2st64_b32 v129, v4, v5 offset0:146 offset1:147
	s_waitcnt lgkmcnt(0)
	v_cmp_lt_u32_e32 vcc, 15, v204
	v_cndmask_b32_e32 v218, v217, v209, vcc
	v_cndmask_b32_e32 v221, v217, v213, vcc
	v_cmp_lt_u32_e32 vcc, 31, v204
	v_cndmask_b32_e32 v219, v217, v210, vcc
	v_cndmask_b32_e32 v222, v217, v214, vcc
	v_cmp_lt_u32_e32 vcc, 47, v204
	v_cndmask_b32_e32 v220, v217, v211, vcc
	v_cndmask_b32_e32 v223, v217, v215, vcc
	v_mul_f32_e32 v224, v218, v219
	v_mul_f32_e32 v225, v221, v222
	v_mul_f32_e32 v226, v209, v210
	v_mul_f32_e32 v224, v224, v220
	v_mul_f32_e32 v225, v225, v223
	v_mul_f32_e32 v226, v226, v211
	v_mul_f32_e32 v226, v226, v212
	v_mul_f32_e32 v225, v225, v226
	v_mul_f32_e32 v230, v227, v224
	v_mul_f32_e32 v231, v198, v224
	v_mul_f32_e32 v232, v199, v224
	v_mul_f32_e32 v233, v200, v224
	v_mul_f32_e32 v234, v8, v225
	v_mul_f32_e32 v235, v201, v225
	v_mul_f32_e32 v236, v202, v225
	v_mul_f32_e32 v237, v203, v225
	ds_write2st64_b32 v129, v230, v231 offset0:224 offset1:225
	ds_write2st64_b32 v129, v232, v233 offset0:226 offset1:227
	ds_write2st64_b32 v129, v234, v235 offset0:240 offset1:241
	ds_write2st64_b32 v129, v236, v237 offset0:242 offset1:243
.LBB0_378:
	s_waitcnt lgkmcnt(0)
	s_barrier
	v_add_u32_e32 v227, 0xffffff00, v143
	ds_read_b128 v[198:201], v143 offset:57344
	ds_read_b128 v[202:205], v227 offset:57344
	ds_read_b128 v[206:209], v143 offset:8192
	ds_read_b128 v[210:213], v143 offset:16384
	ds_read_b128 v[214:217], v143 offset:24576
	ds_read_b128 v[4:7], v143 offset:40960
	ds_read_b128 v[8:11], v143 offset:16384
	s_waitcnt lgkmcnt(2)
	ds_read_b128 v[12:15], v143 offset:24576
	ds_read_b128 v[16:19], v146
	s_lshl_b32 s10, s68, 5
	s_add_i32 s10, s10, s86
	s_waitcnt lgkmcnt(2)
	v_pk_mul_f32 v[8:9], v[4:5], v[8:9]
	s_waitcnt lgkmcnt(1)
	v_pk_mul_f32 v[4:5], v[4:5], v[12:13]
	v_add_f32_e32 v8, 0, v8
	v_pk_mul_f32 v[10:11], v[6:7], v[10:11]
	v_add_f32_e32 v8, v9, v8
	v_add_f32_e32 v9, 0, v4
	s_waitcnt lgkmcnt(0)
	v_fma_f32 v4, v16, v4, 0
	v_add_f32_e32 v9, v5, v9
	v_fmac_f32_e32 v4, v17, v5
	v_add_f32_e32 v5, v10, v8
	v_add_f32_e32 v5, v11, v5
	v_pk_mul_f32 v[6:7], v[6:7], v[14:15]
	v_add_u32_e32 v120, s10, v125
	v_add_f32_dpp v5, v5, v5 quad_perm:[1,0,3,2] row_mask:0xf bank_mask:0xf bound_ctrl:1
	v_add_f32_e32 v8, v6, v9
	v_fmac_f32_e32 v4, v18, v6
	v_add_f32_dpp v5, v5, v5 quad_perm:[2,3,0,1] row_mask:0xf bank_mask:0xf bound_ctrl:1
	v_add_f32_e32 v6, v7, v8
	v_fmac_f32_e32 v4, v19, v7
	v_add_f32_dpp v5, v5, v5 row_half_mirror row_mask:0xf bank_mask:0xf bound_ctrl:1
	v_ashrrev_i32_e32 v121, 31, v120
	v_add_f32_dpp v4, v4, v4 quad_perm:[1,0,3,2] row_mask:0xf bank_mask:0xf bound_ctrl:1
	v_add_f32_dpp v14, v5, v5 row_mirror row_mask:0xf bank_mask:0xf bound_ctrl:1
	v_add_f32_dpp v5, v6, v6 quad_perm:[1,0,3,2] row_mask:0xf bank_mask:0xf bound_ctrl:1
	ds_read_b128 v[6:9], v143 offset:8192
	ds_read_b128 v[10:13], v143 offset:32768
	v_add_f32_dpp v5, v5, v5 quad_perm:[2,3,0,1] row_mask:0xf bank_mask:0xf bound_ctrl:1
	v_add_f32_dpp v4, v4, v4 quad_perm:[2,3,0,1] row_mask:0xf bank_mask:0xf bound_ctrl:1
	s_waitcnt lgkmcnt(0)
	v_pk_fma_f32 v[8:9], v[14:15], v[8:9], v[12:13] op_sel_hi:[0,1,1]
	v_pk_fma_f32 v[6:7], v[14:15], v[6:7], v[10:11] op_sel_hi:[0,1,1]
	s_waitcnt lgkmcnt(0)
	v_mov_b32_e32 v226, 1.0
	v_cmp_gt_u32_e32 vcc, 16, v134
	v_rcp_f32_e32 v222, v198
	v_rcp_f32_e32 v223, v199
	v_rcp_f32_e32 v224, v200
	v_rcp_f32_e32 v225, v201
	v_cndmask_b32_e32 v202, v202, v226, vcc
	v_cndmask_b32_e32 v203, v203, v226, vcc
	v_cndmask_b32_e32 v204, v204, v226, vcc
	v_cndmask_b32_e32 v205, v205, v226, vcc
	v_mul_f32_e32 v206, v206, v202
	v_mul_f32_e32 v207, v207, v203
	v_mul_f32_e32 v208, v208, v204
	v_mul_f32_e32 v209, v209, v205
	v_mul_f32_e32 v6, v6, v202
	v_mul_f32_e32 v7, v7, v203
	v_mul_f32_e32 v8, v8, v204
	v_mul_f32_e32 v9, v9, v205
	v_mul_f32_e32 v210, v210, v222
	v_mul_f32_e32 v211, v211, v223
	v_mul_f32_e32 v212, v212, v224
	v_mul_f32_e32 v213, v213, v225
	v_mul_f32_e32 v214, v214, v222
	v_mul_f32_e32 v215, v215, v223
	v_mul_f32_e32 v216, v216, v224
	v_mul_f32_e32 v217, v217, v225
	ds_write_b128 v143, v[206:209] offset:8192
	ds_write_b128 v143, v[210:213] offset:16384
	ds_write_b128 v143, v[214:217] offset:24576
	ds_write_b128 v143, v[6:9] offset:32768
	ds_read_b128 v[6:9], v143 offset:49152
	v_add_f32_dpp v5, v5, v5 row_half_mirror row_mask:0xf bank_mask:0xf bound_ctrl:1
	v_add_f32_dpp v4, v4, v4 row_half_mirror row_mask:0xf bank_mask:0xf bound_ctrl:1
	s_nop 0
	v_add_f32_dpp v16, v5, v5 row_mirror row_mask:0xf bank_mask:0xf bound_ctrl:1
	v_mov_b32_dpp v5, v4 row_mirror row_mask:0xf bank_mask:0xf bound_ctrl:1
	s_waitcnt lgkmcnt(0)
	v_pk_mul_f32 v[8:9], v[16:17], v[8:9] op_sel_hi:[0,1]
	v_pk_mul_f32 v[6:7], v[16:17], v[6:7] op_sel_hi:[0,1]
	ds_write_b128 v147, v[6:9]
	s_and_saveexec_b64 s[10:11], s[4:5]
	s_cbranch_execz .LBB0_380
	v_lshlrev_b64 v[6:7], 6, v[120:121]
	v_lshl_add_u64 v[6:7], s[12:13], 0, v[6:7]
	v_add_f32_e32 v4, v4, v5
	global_store_dword v[6:7], v4, off
.LBB0_380:
	s_or_b64 exec, exec, s[10:11]
	s_waitcnt lgkmcnt(0)
	s_barrier
	v_mbcnt_lo_u32_b32 v177, -1, 0
	v_mbcnt_hi_u32_b32 v177, -1, v177
	v_lshlrev_b32_e32 v177, 2, v177
	v_add_u32_e32 v177, 0xe000, v177
	v_cndmask_b32_e64 v176, v177, v149, s[6:7]
	ds_read_b128 v[8:11], v142 offset:8192
	ds_read_b128 v[12:15], v142 offset:16384
	ds_read_b128 v[16:19], v142 offset:24576
	ds_read_b128 v[20:23], v142 offset:32768
	ds_read2st64_b32 v[240:241], v148 offset0:192 offset1:193
	ds_read_b128 v[28:31], v142 offset:8448
	ds_read_b128 v[32:35], v142 offset:16640
	ds_read_b128 v[36:39], v142 offset:24832
	ds_read_b128 v[40:43], v142 offset:33024
	ds_read_b128 v[48:51], v142 offset:8704
	ds_read_b128 v[52:55], v142 offset:16896
	ds_read_b128 v[56:59], v142 offset:25088
	ds_read_b128 v[60:63], v142 offset:33280
	ds_read2st64_b32 v[242:243], v148 offset0:194 offset1:195
	s_waitcnt lgkmcnt(9)
	v_mul_f32_e32 v174, v170, v8
	v_mul_f32_e32 v175, v170, v20
	v_fmac_f32_e32 v174, v171, v9
	v_fmac_f32_e32 v175, v171, v21
	v_fmac_f32_e32 v174, v172, v10
	v_fmac_f32_e32 v175, v172, v22
	v_fmac_f32_e32 v174, v173, v11
	v_fmac_f32_e32 v175, v173, v23
	v_fmac_f32_e32 v170, v240, v16
	v_add_f32_dpp v174, v174, v174 quad_perm:[1,0,3,2] row_mask:0xf bank_mask:0xf bound_ctrl:1
	v_add_f32_dpp v175, v175, v175 quad_perm:[1,0,3,2] row_mask:0xf bank_mask:0xf bound_ctrl:1
	v_fmac_f32_e32 v171, v240, v17
	v_add_f32_dpp v174, v174, v174 quad_perm:[2,3,0,1] row_mask:0xf bank_mask:0xf bound_ctrl:1
	v_add_f32_dpp v175, v175, v175 quad_perm:[2,3,0,1] row_mask:0xf bank_mask:0xf bound_ctrl:1
	v_fmac_f32_e32 v172, v240, v18
	v_add_f32_dpp v174, v174, v174 row_half_mirror row_mask:0xf bank_mask:0xf bound_ctrl:1
	v_add_f32_dpp v175, v175, v175 row_half_mirror row_mask:0xf bank_mask:0xf bound_ctrl:1
	v_fmac_f32_e32 v173, v240, v19
	v_add_f32_dpp v174, v174, v174 row_mirror row_mask:0xf bank_mask:0xf bound_ctrl:1
	v_fmac_f32_e32 v170, v174, v12
	v_fmac_f32_e32 v171, v174, v13
	v_fmac_f32_e32 v172, v174, v14
	v_fmac_f32_e32 v173, v174, v15
	ds_read_b128 v[8:11], v142 offset:8960
	ds_read_b128 v[12:15], v142 offset:17152
	ds_read_b128 v[16:19], v142 offset:25344
	ds_read_b128 v[20:23], v142 offset:33536
	s_waitcnt lgkmcnt(9)
	v_mul_f32_e32 v174, v170, v28
	v_mul_f32_e32 v238, v170, v40
	v_fmac_f32_e32 v174, v171, v29
	v_fmac_f32_e32 v238, v171, v41
	v_fmac_f32_e32 v174, v172, v30
	v_fmac_f32_e32 v238, v172, v42
	v_fmac_f32_e32 v174, v173, v31
	v_fmac_f32_e32 v238, v173, v43
	v_fmac_f32_e32 v170, v241, v36
	v_add_f32_dpp v174, v174, v174 quad_perm:[1,0,3,2] row_mask:0xf bank_mask:0xf bound_ctrl:1
	v_add_f32_dpp v238, v238, v238 quad_perm:[1,0,3,2] row_mask:0xf bank_mask:0xf bound_ctrl:1
	v_fmac_f32_e32 v171, v241, v37
	v_add_f32_dpp v174, v174, v174 quad_perm:[2,3,0,1] row_mask:0xf bank_mask:0xf bound_ctrl:1
	v_add_f32_dpp v238, v238, v238 quad_perm:[2,3,0,1] row_mask:0xf bank_mask:0xf bound_ctrl:1
	v_fmac_f32_e32 v172, v241, v38
	v_add_f32_dpp v174, v174, v174 row_half_mirror row_mask:0xf bank_mask:0xf bound_ctrl:1
	v_add_f32_dpp v238, v238, v238 row_half_mirror row_mask:0xf bank_mask:0xf bound_ctrl:1
	v_fmac_f32_e32 v173, v241, v39
	v_add_f32_dpp v174, v174, v174 row_mirror row_mask:0xf bank_mask:0xf bound_ctrl:1
	v_fmac_f32_e32 v170, v174, v32
	v_fmac_f32_e32 v171, v174, v33
	v_fmac_f32_e32 v172, v174, v34
	v_fmac_f32_e32 v173, v174, v35
	s_mov_b64 exec, s[6:7]
	ds_write2st64_b32 v149, v175, v238 offset0:0 offset1:2
	s_mov_b64 exec, -1
	ds_read_b128 v[28:31], v142 offset:9216
	ds_read_b128 v[32:35], v142 offset:17408
	ds_read_b128 v[36:39], v142 offset:25600
	ds_read_b128 v[40:43], v142 offset:33792
	ds_read2st64_b32 v[240:241], v148 offset0:196 offset1:197
	s_waitcnt lgkmcnt(10)
	v_mul_f32_e32 v174, v170, v48
	v_mul_f32_e32 v175, v170, v60
	v_fmac_f32_e32 v174, v171, v49
	v_fmac_f32_e32 v175, v171, v61
	v_fmac_f32_e32 v174, v172, v50
	v_fmac_f32_e32 v175, v172, v62
	v_fmac_f32_e32 v174, v173, v51
	v_fmac_f32_e32 v175, v173, v63
	v_fmac_f32_e32 v170, v242, v56
	v_add_f32_dpp v174, v174, v174 quad_perm:[1,0,3,2] row_mask:0xf bank_mask:0xf bound_ctrl:1
	v_add_f32_dpp v175, v175, v175 quad_perm:[1,0,3,2] row_mask:0xf bank_mask:0xf bound_ctrl:1
	v_fmac_f32_e32 v171, v242, v57
	v_add_f32_dpp v174, v174, v174 quad_perm:[2,3,0,1] row_mask:0xf bank_mask:0xf bound_ctrl:1
	v_add_f32_dpp v175, v175, v175 quad_perm:[2,3,0,1] row_mask:0xf bank_mask:0xf bound_ctrl:1
	v_fmac_f32_e32 v172, v242, v58
	v_add_f32_dpp v174, v174, v174 row_half_mirror row_mask:0xf bank_mask:0xf bound_ctrl:1
	v_add_f32_dpp v175, v175, v175 row_half_mirror row_mask:0xf bank_mask:0xf bound_ctrl:1
	v_fmac_f32_e32 v173, v242, v59
	v_add_f32_dpp v174, v174, v174 row_mirror row_mask:0xf bank_mask:0xf bound_ctrl:1
	v_fmac_f32_e32 v170, v174, v52
	v_fmac_f32_e32 v171, v174, v53
	v_fmac_f32_e32 v172, v174, v54
	v_fmac_f32_e32 v173, v174, v55
	ds_read_b128 v[48:51], v142 offset:9472
	ds_read_b128 v[52:55], v142 offset:17664
	ds_read_b128 v[56:59], v142 offset:25856
	ds_read_b128 v[60:63], v142 offset:34048
	s_waitcnt lgkmcnt(10)
	v_mul_f32_e32 v174, v170, v8
	v_mul_f32_e32 v238, v170, v20
	v_fmac_f32_e32 v174, v171, v9
	v_fmac_f32_e32 v238, v171, v21
	v_fmac_f32_e32 v174, v172, v10
	v_fmac_f32_e32 v238, v172, v22
	v_fmac_f32_e32 v174, v173, v11
	v_fmac_f32_e32 v238, v173, v23
	v_fmac_f32_e32 v170, v243, v16
	v_add_f32_dpp v174, v174, v174 quad_perm:[1,0,3,2] row_mask:0xf bank_mask:0xf bound_ctrl:1
	v_add_f32_dpp v238, v238, v238 quad_perm:[1,0,3,2] row_mask:0xf bank_mask:0xf bound_ctrl:1
	v_fmac_f32_e32 v171, v243, v17
	v_add_f32_dpp v174, v174, v174 quad_perm:[2,3,0,1] row_mask:0xf bank_mask:0xf bound_ctrl:1
	v_add_f32_dpp v238, v238, v238 quad_perm:[2,3,0,1] row_mask:0xf bank_mask:0xf bound_ctrl:1
	v_fmac_f32_e32 v172, v243, v18
	v_add_f32_dpp v174, v174, v174 row_half_mirror row_mask:0xf bank_mask:0xf bound_ctrl:1
	v_add_f32_dpp v238, v238, v238 row_half_mirror row_mask:0xf bank_mask:0xf bound_ctrl:1
	v_fmac_f32_e32 v173, v243, v19
	v_add_f32_dpp v174, v174, v174 row_mirror row_mask:0xf bank_mask:0xf bound_ctrl:1
	v_fmac_f32_e32 v170, v174, v12
	v_fmac_f32_e32 v171, v174, v13
	v_fmac_f32_e32 v172, v174, v14
	v_fmac_f32_e32 v173, v174, v15
	s_mov_b64 exec, s[6:7]
	ds_write2st64_b32 v149, v175, v238 offset0:4 offset1:6
	s_mov_b64 exec, -1
	ds_read_b128 v[8:11], v142 offset:9728
	ds_read_b128 v[12:15], v142 offset:17920
	ds_read_b128 v[16:19], v142 offset:26112
	ds_read_b128 v[20:23], v142 offset:34304
	ds_read2st64_b32 v[242:243], v148 offset0:198 offset1:199
	s_waitcnt lgkmcnt(10)
	v_mul_f32_e32 v174, v170, v28
	v_mul_f32_e32 v175, v170, v40
	v_fmac_f32_e32 v174, v171, v29
	v_fmac_f32_e32 v175, v171, v41
	v_fmac_f32_e32 v174, v172, v30
	v_fmac_f32_e32 v175, v172, v42
	v_fmac_f32_e32 v174, v173, v31
	v_fmac_f32_e32 v175, v173, v43
	v_fmac_f32_e32 v170, v240, v36
	v_add_f32_dpp v174, v174, v174 quad_perm:[1,0,3,2] row_mask:0xf bank_mask:0xf bound_ctrl:1
	v_add_f32_dpp v175, v175, v175 quad_perm:[1,0,3,2] row_mask:0xf bank_mask:0xf bound_ctrl:1
	v_fmac_f32_e32 v171, v240, v37
	v_add_f32_dpp v174, v174, v174 quad_perm:[2,3,0,1] row_mask:0xf bank_mask:0xf bound_ctrl:1
	v_add_f32_dpp v175, v175, v175 quad_perm:[2,3,0,1] row_mask:0xf bank_mask:0xf bound_ctrl:1
	v_fmac_f32_e32 v172, v240, v38
	v_add_f32_dpp v174, v174, v174 row_half_mirror row_mask:0xf bank_mask:0xf bound_ctrl:1
	v_add_f32_dpp v175, v175, v175 row_half_mirror row_mask:0xf bank_mask:0xf bound_ctrl:1
	v_fmac_f32_e32 v173, v240, v39
	v_add_f32_dpp v174, v174, v174 row_mirror row_mask:0xf bank_mask:0xf bound_ctrl:1
	v_fmac_f32_e32 v170, v174, v32
	v_fmac_f32_e32 v171, v174, v33
	v_fmac_f32_e32 v172, v174, v34
	v_fmac_f32_e32 v173, v174, v35
	ds_read_b128 v[28:31], v142 offset:9984
	ds_read_b128 v[32:35], v142 offset:18176
	ds_read_b128 v[36:39], v142 offset:26368
	ds_read_b128 v[40:43], v142 offset:34560
	s_waitcnt lgkmcnt(10)
	v_mul_f32_e32 v174, v170, v48
	v_mul_f32_e32 v238, v170, v60
	v_fmac_f32_e32 v174, v171, v49
	v_fmac_f32_e32 v238, v171, v61
	v_fmac_f32_e32 v174, v172, v50
	v_fmac_f32_e32 v238, v172, v62
	v_fmac_f32_e32 v174, v173, v51
	v_fmac_f32_e32 v238, v173, v63
	v_fmac_f32_e32 v170, v241, v56
	v_add_f32_dpp v174, v174, v174 quad_perm:[1,0,3,2] row_mask:0xf bank_mask:0xf bound_ctrl:1
	v_add_f32_dpp v238, v238, v238 quad_perm:[1,0,3,2] row_mask:0xf bank_mask:0xf bound_ctrl:1
	v_fmac_f32_e32 v171, v241, v57
	v_add_f32_dpp v174, v174, v174 quad_perm:[2,3,0,1] row_mask:0xf bank_mask:0xf bound_ctrl:1
	v_add_f32_dpp v238, v238, v238 quad_perm:[2,3,0,1] row_mask:0xf bank_mask:0xf bound_ctrl:1
	v_fmac_f32_e32 v172, v241, v58
	v_add_f32_dpp v174, v174, v174 row_half_mirror row_mask:0xf bank_mask:0xf bound_ctrl:1
	v_add_f32_dpp v238, v238, v238 row_half_mirror row_mask:0xf bank_mask:0xf bound_ctrl:1
	v_fmac_f32_e32 v173, v241, v59
	v_add_f32_dpp v174, v174, v174 row_mirror row_mask:0xf bank_mask:0xf bound_ctrl:1
	v_fmac_f32_e32 v170, v174, v52
	v_fmac_f32_e32 v171, v174, v53
	v_fmac_f32_e32 v172, v174, v54
	v_fmac_f32_e32 v173, v174, v55
	s_mov_b64 exec, s[6:7]
	ds_write2st64_b32 v149, v175, v238 offset0:8 offset1:10
	s_mov_b64 exec, -1
	ds_read_b128 v[48:51], v142 offset:10240
	ds_read_b128 v[52:55], v142 offset:18432
	ds_read_b128 v[56:59], v142 offset:26624
	ds_read_b128 v[60:63], v142 offset:34816
	ds_read2st64_b32 v[240:241], v148 offset0:200 offset1:201
	s_waitcnt lgkmcnt(10)
	v_mul_f32_e32 v174, v170, v8
	v_mul_f32_e32 v175, v170, v20
	v_fmac_f32_e32 v174, v171, v9
	v_fmac_f32_e32 v175, v171, v21
	v_fmac_f32_e32 v174, v172, v10
	v_fmac_f32_e32 v175, v172, v22
	v_fmac_f32_e32 v174, v173, v11
	v_fmac_f32_e32 v175, v173, v23
	v_fmac_f32_e32 v170, v242, v16
	v_add_f32_dpp v174, v174, v174 quad_perm:[1,0,3,2] row_mask:0xf bank_mask:0xf bound_ctrl:1
	v_add_f32_dpp v175, v175, v175 quad_perm:[1,0,3,2] row_mask:0xf bank_mask:0xf bound_ctrl:1
	v_fmac_f32_e32 v171, v242, v17
	v_add_f32_dpp v174, v174, v174 quad_perm:[2,3,0,1] row_mask:0xf bank_mask:0xf bound_ctrl:1
	v_add_f32_dpp v175, v175, v175 quad_perm:[2,3,0,1] row_mask:0xf bank_mask:0xf bound_ctrl:1
	v_fmac_f32_e32 v172, v242, v18
	v_add_f32_dpp v174, v174, v174 row_half_mirror row_mask:0xf bank_mask:0xf bound_ctrl:1
	v_add_f32_dpp v175, v175, v175 row_half_mirror row_mask:0xf bank_mask:0xf bound_ctrl:1
	v_fmac_f32_e32 v173, v242, v19
	v_add_f32_dpp v174, v174, v174 row_mirror row_mask:0xf bank_mask:0xf bound_ctrl:1
	v_fmac_f32_e32 v170, v174, v12
	v_fmac_f32_e32 v171, v174, v13
	v_fmac_f32_e32 v172, v174, v14
	v_fmac_f32_e32 v173, v174, v15
	ds_read_b128 v[8:11], v142 offset:10496
	ds_read_b128 v[12:15], v142 offset:18688
	ds_read_b128 v[16:19], v142 offset:26880
	ds_read_b128 v[20:23], v142 offset:35072
	s_waitcnt lgkmcnt(10)
	v_mul_f32_e32 v174, v170, v28
	v_mul_f32_e32 v238, v170, v40
	v_fmac_f32_e32 v174, v171, v29
	v_fmac_f32_e32 v238, v171, v41
	v_fmac_f32_e32 v174, v172, v30
	v_fmac_f32_e32 v238, v172, v42
	v_fmac_f32_e32 v174, v173, v31
	v_fmac_f32_e32 v238, v173, v43
	v_fmac_f32_e32 v170, v243, v36
	v_add_f32_dpp v174, v174, v174 quad_perm:[1,0,3,2] row_mask:0xf bank_mask:0xf bound_ctrl:1
	v_add_f32_dpp v238, v238, v238 quad_perm:[1,0,3,2] row_mask:0xf bank_mask:0xf bound_ctrl:1
	v_fmac_f32_e32 v171, v243, v37
	v_add_f32_dpp v174, v174, v174 quad_perm:[2,3,0,1] row_mask:0xf bank_mask:0xf bound_ctrl:1
	v_add_f32_dpp v238, v238, v238 quad_perm:[2,3,0,1] row_mask:0xf bank_mask:0xf bound_ctrl:1
	v_fmac_f32_e32 v172, v243, v38
	v_add_f32_dpp v174, v174, v174 row_half_mirror row_mask:0xf bank_mask:0xf bound_ctrl:1
	v_add_f32_dpp v238, v238, v238 row_half_mirror row_mask:0xf bank_mask:0xf bound_ctrl:1
	v_fmac_f32_e32 v173, v243, v39
	v_add_f32_dpp v174, v174, v174 row_mirror row_mask:0xf bank_mask:0xf bound_ctrl:1
	v_fmac_f32_e32 v170, v174, v32
	v_fmac_f32_e32 v171, v174, v33
	v_fmac_f32_e32 v172, v174, v34
	v_fmac_f32_e32 v173, v174, v35
	s_mov_b64 exec, s[6:7]
	ds_write2st64_b32 v149, v175, v238 offset0:12 offset1:14
	s_mov_b64 exec, -1
	ds_read_b128 v[28:31], v142 offset:10752
	ds_read_b128 v[32:35], v142 offset:18944
	ds_read_b128 v[36:39], v142 offset:27136
	ds_read_b128 v[40:43], v142 offset:35328
	ds_read2st64_b32 v[242:243], v148 offset0:202 offset1:203
	s_waitcnt lgkmcnt(10)
	v_mul_f32_e32 v174, v170, v48
	v_mul_f32_e32 v175, v170, v60
	v_fmac_f32_e32 v174, v171, v49
	v_fmac_f32_e32 v175, v171, v61
	v_fmac_f32_e32 v174, v172, v50
	v_fmac_f32_e32 v175, v172, v62
	v_fmac_f32_e32 v174, v173, v51
	v_fmac_f32_e32 v175, v173, v63
	v_fmac_f32_e32 v170, v240, v56
	v_add_f32_dpp v174, v174, v174 quad_perm:[1,0,3,2] row_mask:0xf bank_mask:0xf bound_ctrl:1
	v_add_f32_dpp v175, v175, v175 quad_perm:[1,0,3,2] row_mask:0xf bank_mask:0xf bound_ctrl:1
	v_fmac_f32_e32 v171, v240, v57
	v_add_f32_dpp v174, v174, v174 quad_perm:[2,3,0,1] row_mask:0xf bank_mask:0xf bound_ctrl:1
	v_add_f32_dpp v175, v175, v175 quad_perm:[2,3,0,1] row_mask:0xf bank_mask:0xf bound_ctrl:1
	v_fmac_f32_e32 v172, v240, v58
	v_add_f32_dpp v174, v174, v174 row_half_mirror row_mask:0xf bank_mask:0xf bound_ctrl:1
	v_add_f32_dpp v175, v175, v175 row_half_mirror row_mask:0xf bank_mask:0xf bound_ctrl:1
	v_fmac_f32_e32 v173, v240, v59
	v_add_f32_dpp v174, v174, v174 row_mirror row_mask:0xf bank_mask:0xf bound_ctrl:1
	v_fmac_f32_e32 v170, v174, v52
	v_fmac_f32_e32 v171, v174, v53
	v_fmac_f32_e32 v172, v174, v54
	v_fmac_f32_e32 v173, v174, v55
	ds_read_b128 v[48:51], v142 offset:11008
	ds_read_b128 v[52:55], v142 offset:19200
	ds_read_b128 v[56:59], v142 offset:27392
	ds_read_b128 v[60:63], v142 offset:35584
	s_waitcnt lgkmcnt(10)
	v_mul_f32_e32 v174, v170, v8
	v_mul_f32_e32 v238, v170, v20
	v_fmac_f32_e32 v174, v171, v9
	v_fmac_f32_e32 v238, v171, v21
	v_fmac_f32_e32 v174, v172, v10
	v_fmac_f32_e32 v238, v172, v22
	v_fmac_f32_e32 v174, v173, v11
	v_fmac_f32_e32 v238, v173, v23
	v_fmac_f32_e32 v170, v241, v16
	v_add_f32_dpp v174, v174, v174 quad_perm:[1,0,3,2] row_mask:0xf bank_mask:0xf bound_ctrl:1
	v_add_f32_dpp v238, v238, v238 quad_perm:[1,0,3,2] row_mask:0xf bank_mask:0xf bound_ctrl:1
	v_fmac_f32_e32 v171, v241, v17
	v_add_f32_dpp v174, v174, v174 quad_perm:[2,3,0,1] row_mask:0xf bank_mask:0xf bound_ctrl:1
	v_add_f32_dpp v238, v238, v238 quad_perm:[2,3,0,1] row_mask:0xf bank_mask:0xf bound_ctrl:1
	v_fmac_f32_e32 v172, v241, v18
	v_add_f32_dpp v174, v174, v174 row_half_mirror row_mask:0xf bank_mask:0xf bound_ctrl:1
	v_add_f32_dpp v238, v238, v238 row_half_mirror row_mask:0xf bank_mask:0xf bound_ctrl:1
	v_fmac_f32_e32 v173, v241, v19
	v_add_f32_dpp v174, v174, v174 row_mirror row_mask:0xf bank_mask:0xf bound_ctrl:1
	v_fmac_f32_e32 v170, v174, v12
	v_fmac_f32_e32 v171, v174, v13
	v_fmac_f32_e32 v172, v174, v14
	v_fmac_f32_e32 v173, v174, v15
	s_mov_b64 exec, s[6:7]
	ds_write2st64_b32 v149, v175, v238 offset0:16 offset1:18
	s_mov_b64 exec, -1
	ds_read_b128 v[8:11], v142 offset:11264
	ds_read_b128 v[12:15], v142 offset:19456
	ds_read_b128 v[16:19], v142 offset:27648
	ds_read_b128 v[20:23], v142 offset:35840
	ds_read2st64_b32 v[240:241], v148 offset0:204 offset1:205
	s_waitcnt lgkmcnt(10)
	v_mul_f32_e32 v174, v170, v28
	v_mul_f32_e32 v175, v170, v40
	v_fmac_f32_e32 v174, v171, v29
	v_fmac_f32_e32 v175, v171, v41
	v_fmac_f32_e32 v174, v172, v30
	v_fmac_f32_e32 v175, v172, v42
	v_fmac_f32_e32 v174, v173, v31
	v_fmac_f32_e32 v175, v173, v43
	v_fmac_f32_e32 v170, v242, v36
	v_add_f32_dpp v174, v174, v174 quad_perm:[1,0,3,2] row_mask:0xf bank_mask:0xf bound_ctrl:1
	v_add_f32_dpp v175, v175, v175 quad_perm:[1,0,3,2] row_mask:0xf bank_mask:0xf bound_ctrl:1
	v_fmac_f32_e32 v171, v242, v37
	v_add_f32_dpp v174, v174, v174 quad_perm:[2,3,0,1] row_mask:0xf bank_mask:0xf bound_ctrl:1
	v_add_f32_dpp v175, v175, v175 quad_perm:[2,3,0,1] row_mask:0xf bank_mask:0xf bound_ctrl:1
	v_fmac_f32_e32 v172, v242, v38
	v_add_f32_dpp v174, v174, v174 row_half_mirror row_mask:0xf bank_mask:0xf bound_ctrl:1
	v_add_f32_dpp v175, v175, v175 row_half_mirror row_mask:0xf bank_mask:0xf bound_ctrl:1
	v_fmac_f32_e32 v173, v242, v39
	v_add_f32_dpp v174, v174, v174 row_mirror row_mask:0xf bank_mask:0xf bound_ctrl:1
	v_fmac_f32_e32 v170, v174, v32
	v_fmac_f32_e32 v171, v174, v33
	v_fmac_f32_e32 v172, v174, v34
	v_fmac_f32_e32 v173, v174, v35
	ds_read_b128 v[28:31], v142 offset:11520
	ds_read_b128 v[32:35], v142 offset:19712
	ds_read_b128 v[36:39], v142 offset:27904
	ds_read_b128 v[40:43], v142 offset:36096
	s_waitcnt lgkmcnt(10)
	v_mul_f32_e32 v174, v170, v48
	v_mul_f32_e32 v238, v170, v60
	v_fmac_f32_e32 v174, v171, v49
	v_fmac_f32_e32 v238, v171, v61
	v_fmac_f32_e32 v174, v172, v50
	v_fmac_f32_e32 v238, v172, v62
	v_fmac_f32_e32 v174, v173, v51
	v_fmac_f32_e32 v238, v173, v63
	v_fmac_f32_e32 v170, v243, v56
	v_add_f32_dpp v174, v174, v174 quad_perm:[1,0,3,2] row_mask:0xf bank_mask:0xf bound_ctrl:1
	v_add_f32_dpp v238, v238, v238 quad_perm:[1,0,3,2] row_mask:0xf bank_mask:0xf bound_ctrl:1
	v_fmac_f32_e32 v171, v243, v57
	v_add_f32_dpp v174, v174, v174 quad_perm:[2,3,0,1] row_mask:0xf bank_mask:0xf bound_ctrl:1
	v_add_f32_dpp v238, v238, v238 quad_perm:[2,3,0,1] row_mask:0xf bank_mask:0xf bound_ctrl:1
	v_fmac_f32_e32 v172, v243, v58
	v_add_f32_dpp v174, v174, v174 row_half_mirror row_mask:0xf bank_mask:0xf bound_ctrl:1
	v_add_f32_dpp v238, v238, v238 row_half_mirror row_mask:0xf bank_mask:0xf bound_ctrl:1
	v_fmac_f32_e32 v173, v243, v59
	v_add_f32_dpp v174, v174, v174 row_mirror row_mask:0xf bank_mask:0xf bound_ctrl:1
	v_fmac_f32_e32 v170, v174, v52
	v_fmac_f32_e32 v171, v174, v53
	v_fmac_f32_e32 v172, v174, v54
	v_fmac_f32_e32 v173, v174, v55
	s_mov_b64 exec, s[6:7]
	ds_write2st64_b32 v149, v175, v238 offset0:20 offset1:22
	s_mov_b64 exec, -1
	ds_read_b128 v[48:51], v142 offset:11776
	ds_read_b128 v[52:55], v142 offset:19968
	ds_read_b128 v[56:59], v142 offset:28160
	ds_read_b128 v[60:63], v142 offset:36352
	ds_read2st64_b32 v[242:243], v148 offset0:206 offset1:207
	s_waitcnt lgkmcnt(10)
	v_mul_f32_e32 v174, v170, v8
	v_mul_f32_e32 v175, v170, v20
	v_fmac_f32_e32 v174, v171, v9
	v_fmac_f32_e32 v175, v171, v21
	v_fmac_f32_e32 v174, v172, v10
	v_fmac_f32_e32 v175, v172, v22
	v_fmac_f32_e32 v174, v173, v11
	v_fmac_f32_e32 v175, v173, v23
	v_fmac_f32_e32 v170, v240, v16
	v_add_f32_dpp v174, v174, v174 quad_perm:[1,0,3,2] row_mask:0xf bank_mask:0xf bound_ctrl:1
	v_add_f32_dpp v175, v175, v175 quad_perm:[1,0,3,2] row_mask:0xf bank_mask:0xf bound_ctrl:1
	v_fmac_f32_e32 v171, v240, v17
	v_add_f32_dpp v174, v174, v174 quad_perm:[2,3,0,1] row_mask:0xf bank_mask:0xf bound_ctrl:1
	v_add_f32_dpp v175, v175, v175 quad_perm:[2,3,0,1] row_mask:0xf bank_mask:0xf bound_ctrl:1
	v_fmac_f32_e32 v172, v240, v18
	v_add_f32_dpp v174, v174, v174 row_half_mirror row_mask:0xf bank_mask:0xf bound_ctrl:1
	v_add_f32_dpp v175, v175, v175 row_half_mirror row_mask:0xf bank_mask:0xf bound_ctrl:1
	v_fmac_f32_e32 v173, v240, v19
	v_add_f32_dpp v174, v174, v174 row_mirror row_mask:0xf bank_mask:0xf bound_ctrl:1
	v_fmac_f32_e32 v170, v174, v12
	v_fmac_f32_e32 v171, v174, v13
	v_fmac_f32_e32 v172, v174, v14
	v_fmac_f32_e32 v173, v174, v15
	ds_read_b128 v[8:11], v142 offset:12032
	ds_read_b128 v[12:15], v142 offset:20224
	ds_read_b128 v[16:19], v142 offset:28416
	ds_read_b128 v[20:23], v142 offset:36608
	s_waitcnt lgkmcnt(10)
	v_mul_f32_e32 v174, v170, v28
	v_mul_f32_e32 v238, v170, v40
	v_fmac_f32_e32 v174, v171, v29
	v_fmac_f32_e32 v238, v171, v41
	v_fmac_f32_e32 v174, v172, v30
	v_fmac_f32_e32 v238, v172, v42
	v_fmac_f32_e32 v174, v173, v31
	v_fmac_f32_e32 v238, v173, v43
	v_fmac_f32_e32 v170, v241, v36
	v_add_f32_dpp v174, v174, v174 quad_perm:[1,0,3,2] row_mask:0xf bank_mask:0xf bound_ctrl:1
	v_add_f32_dpp v238, v238, v238 quad_perm:[1,0,3,2] row_mask:0xf bank_mask:0xf bound_ctrl:1
	v_fmac_f32_e32 v171, v241, v37
	v_add_f32_dpp v174, v174, v174 quad_perm:[2,3,0,1] row_mask:0xf bank_mask:0xf bound_ctrl:1
	v_add_f32_dpp v238, v238, v238 quad_perm:[2,3,0,1] row_mask:0xf bank_mask:0xf bound_ctrl:1
	v_fmac_f32_e32 v172, v241, v38
	v_add_f32_dpp v174, v174, v174 row_half_mirror row_mask:0xf bank_mask:0xf bound_ctrl:1
	v_add_f32_dpp v238, v238, v238 row_half_mirror row_mask:0xf bank_mask:0xf bound_ctrl:1
	v_fmac_f32_e32 v173, v241, v39
	v_add_f32_dpp v174, v174, v174 row_mirror row_mask:0xf bank_mask:0xf bound_ctrl:1
	v_fmac_f32_e32 v170, v174, v32
	v_fmac_f32_e32 v171, v174, v33
	v_fmac_f32_e32 v172, v174, v34
	v_fmac_f32_e32 v173, v174, v35
	s_mov_b64 exec, s[6:7]
	ds_write2st64_b32 v149, v175, v238 offset0:24 offset1:26
	s_mov_b64 exec, -1
	ds_read_b128 v[28:31], v142 offset:12288
	ds_read_b128 v[32:35], v142 offset:20480
	ds_read_b128 v[36:39], v142 offset:28672
	ds_read_b128 v[40:43], v142 offset:36864
	ds_read2st64_b32 v[240:241], v148 offset0:208 offset1:209
	s_waitcnt lgkmcnt(10)
	v_mul_f32_e32 v174, v170, v48
	v_mul_f32_e32 v175, v170, v60
	v_fmac_f32_e32 v174, v171, v49
	v_fmac_f32_e32 v175, v171, v61
	v_fmac_f32_e32 v174, v172, v50
	v_fmac_f32_e32 v175, v172, v62
	v_fmac_f32_e32 v174, v173, v51
	v_fmac_f32_e32 v175, v173, v63
	v_fmac_f32_e32 v170, v242, v56
	v_add_f32_dpp v174, v174, v174 quad_perm:[1,0,3,2] row_mask:0xf bank_mask:0xf bound_ctrl:1
	v_add_f32_dpp v175, v175, v175 quad_perm:[1,0,3,2] row_mask:0xf bank_mask:0xf bound_ctrl:1
	v_fmac_f32_e32 v171, v242, v57
	v_add_f32_dpp v174, v174, v174 quad_perm:[2,3,0,1] row_mask:0xf bank_mask:0xf bound_ctrl:1
	v_add_f32_dpp v175, v175, v175 quad_perm:[2,3,0,1] row_mask:0xf bank_mask:0xf bound_ctrl:1
	v_fmac_f32_e32 v172, v242, v58
	v_add_f32_dpp v174, v174, v174 row_half_mirror row_mask:0xf bank_mask:0xf bound_ctrl:1
	v_add_f32_dpp v175, v175, v175 row_half_mirror row_mask:0xf bank_mask:0xf bound_ctrl:1
	v_fmac_f32_e32 v173, v242, v59
	v_add_f32_dpp v174, v174, v174 row_mirror row_mask:0xf bank_mask:0xf bound_ctrl:1
	v_fmac_f32_e32 v170, v174, v52
	v_fmac_f32_e32 v171, v174, v53
	v_fmac_f32_e32 v172, v174, v54
	v_fmac_f32_e32 v173, v174, v55
	ds_read_b128 v[48:51], v142 offset:12544
	ds_read_b128 v[52:55], v142 offset:20736
	ds_read_b128 v[56:59], v142 offset:28928
	ds_read_b128 v[60:63], v142 offset:37120
	s_waitcnt lgkmcnt(10)
	v_mul_f32_e32 v174, v170, v8
	v_mul_f32_e32 v238, v170, v20
	v_fmac_f32_e32 v174, v171, v9
	v_fmac_f32_e32 v238, v171, v21
	v_fmac_f32_e32 v174, v172, v10
	v_fmac_f32_e32 v238, v172, v22
	v_fmac_f32_e32 v174, v173, v11
	v_fmac_f32_e32 v238, v173, v23
	v_fmac_f32_e32 v170, v243, v16
	v_add_f32_dpp v174, v174, v174 quad_perm:[1,0,3,2] row_mask:0xf bank_mask:0xf bound_ctrl:1
	v_add_f32_dpp v238, v238, v238 quad_perm:[1,0,3,2] row_mask:0xf bank_mask:0xf bound_ctrl:1
	v_fmac_f32_e32 v171, v243, v17
	v_add_f32_dpp v174, v174, v174 quad_perm:[2,3,0,1] row_mask:0xf bank_mask:0xf bound_ctrl:1
	v_add_f32_dpp v238, v238, v238 quad_perm:[2,3,0,1] row_mask:0xf bank_mask:0xf bound_ctrl:1
	v_fmac_f32_e32 v172, v243, v18
	v_add_f32_dpp v174, v174, v174 row_half_mirror row_mask:0xf bank_mask:0xf bound_ctrl:1
	v_add_f32_dpp v238, v238, v238 row_half_mirror row_mask:0xf bank_mask:0xf bound_ctrl:1
	v_fmac_f32_e32 v173, v243, v19
	v_add_f32_dpp v174, v174, v174 row_mirror row_mask:0xf bank_mask:0xf bound_ctrl:1
	v_fmac_f32_e32 v170, v174, v12
	v_fmac_f32_e32 v171, v174, v13
	v_fmac_f32_e32 v172, v174, v14
	v_fmac_f32_e32 v173, v174, v15
	s_mov_b64 exec, s[6:7]
	ds_write2st64_b32 v149, v175, v238 offset0:28 offset1:30
	s_mov_b64 exec, -1
	ds_read_b128 v[8:11], v142 offset:12800
	ds_read_b128 v[12:15], v142 offset:20992
	ds_read_b128 v[16:19], v142 offset:29184
	ds_read_b128 v[20:23], v142 offset:37376
	ds_read2st64_b32 v[242:243], v148 offset0:210 offset1:211
	s_waitcnt lgkmcnt(10)
	v_mul_f32_e32 v174, v170, v28
	v_mul_f32_e32 v175, v170, v40
	v_fmac_f32_e32 v174, v171, v29
	v_fmac_f32_e32 v175, v171, v41
	v_fmac_f32_e32 v174, v172, v30
	v_fmac_f32_e32 v175, v172, v42
	v_fmac_f32_e32 v174, v173, v31
	v_fmac_f32_e32 v175, v173, v43
	v_fmac_f32_e32 v170, v240, v36
	v_add_f32_dpp v174, v174, v174 quad_perm:[1,0,3,2] row_mask:0xf bank_mask:0xf bound_ctrl:1
	v_add_f32_dpp v175, v175, v175 quad_perm:[1,0,3,2] row_mask:0xf bank_mask:0xf bound_ctrl:1
	v_fmac_f32_e32 v171, v240, v37
	v_add_f32_dpp v174, v174, v174 quad_perm:[2,3,0,1] row_mask:0xf bank_mask:0xf bound_ctrl:1
	v_add_f32_dpp v175, v175, v175 quad_perm:[2,3,0,1] row_mask:0xf bank_mask:0xf bound_ctrl:1
	v_fmac_f32_e32 v172, v240, v38
	v_add_f32_dpp v174, v174, v174 row_half_mirror row_mask:0xf bank_mask:0xf bound_ctrl:1
	v_add_f32_dpp v175, v175, v175 row_half_mirror row_mask:0xf bank_mask:0xf bound_ctrl:1
	v_fmac_f32_e32 v173, v240, v39
	v_add_f32_dpp v174, v174, v174 row_mirror row_mask:0xf bank_mask:0xf bound_ctrl:1
	v_fmac_f32_e32 v170, v174, v32
	v_fmac_f32_e32 v171, v174, v33
	v_fmac_f32_e32 v172, v174, v34
	v_fmac_f32_e32 v173, v174, v35
	ds_read_b128 v[28:31], v142 offset:13056
	ds_read_b128 v[32:35], v142 offset:21248
	ds_read_b128 v[36:39], v142 offset:29440
	ds_read_b128 v[40:43], v142 offset:37632
	s_waitcnt lgkmcnt(10)
	v_mul_f32_e32 v174, v170, v48
	v_mul_f32_e32 v238, v170, v60
	v_fmac_f32_e32 v174, v171, v49
	v_fmac_f32_e32 v238, v171, v61
	v_fmac_f32_e32 v174, v172, v50
	v_fmac_f32_e32 v238, v172, v62
	v_fmac_f32_e32 v174, v173, v51
	v_fmac_f32_e32 v238, v173, v63
	v_fmac_f32_e32 v170, v241, v56
	v_add_f32_dpp v174, v174, v174 quad_perm:[1,0,3,2] row_mask:0xf bank_mask:0xf bound_ctrl:1
	v_add_f32_dpp v238, v238, v238 quad_perm:[1,0,3,2] row_mask:0xf bank_mask:0xf bound_ctrl:1
	v_fmac_f32_e32 v171, v241, v57
	v_add_f32_dpp v174, v174, v174 quad_perm:[2,3,0,1] row_mask:0xf bank_mask:0xf bound_ctrl:1
	v_add_f32_dpp v238, v238, v238 quad_perm:[2,3,0,1] row_mask:0xf bank_mask:0xf bound_ctrl:1
	v_fmac_f32_e32 v172, v241, v58
	v_add_f32_dpp v174, v174, v174 row_half_mirror row_mask:0xf bank_mask:0xf bound_ctrl:1
	v_add_f32_dpp v238, v238, v238 row_half_mirror row_mask:0xf bank_mask:0xf bound_ctrl:1
	v_fmac_f32_e32 v173, v241, v59
	v_add_f32_dpp v174, v174, v174 row_mirror row_mask:0xf bank_mask:0xf bound_ctrl:1
	v_fmac_f32_e32 v170, v174, v52
	v_fmac_f32_e32 v171, v174, v53
	v_fmac_f32_e32 v172, v174, v54
	v_fmac_f32_e32 v173, v174, v55
	s_mov_b64 exec, s[6:7]
	ds_write2st64_b32 v149, v175, v238 offset0:32 offset1:34
	s_mov_b64 exec, -1
	ds_read_b128 v[48:51], v142 offset:13312
	ds_read_b128 v[52:55], v142 offset:21504
	ds_read_b128 v[56:59], v142 offset:29696
	ds_read_b128 v[60:63], v142 offset:37888
	ds_read2st64_b32 v[240:241], v148 offset0:212 offset1:213
	s_waitcnt lgkmcnt(10)
	v_mul_f32_e32 v174, v170, v8
	v_mul_f32_e32 v175, v170, v20
	v_fmac_f32_e32 v174, v171, v9
	v_fmac_f32_e32 v175, v171, v21
	v_fmac_f32_e32 v174, v172, v10
	v_fmac_f32_e32 v175, v172, v22
	v_fmac_f32_e32 v174, v173, v11
	v_fmac_f32_e32 v175, v173, v23
	v_fmac_f32_e32 v170, v242, v16
	v_add_f32_dpp v174, v174, v174 quad_perm:[1,0,3,2] row_mask:0xf bank_mask:0xf bound_ctrl:1
	v_add_f32_dpp v175, v175, v175 quad_perm:[1,0,3,2] row_mask:0xf bank_mask:0xf bound_ctrl:1
	v_fmac_f32_e32 v171, v242, v17
	v_add_f32_dpp v174, v174, v174 quad_perm:[2,3,0,1] row_mask:0xf bank_mask:0xf bound_ctrl:1
	v_add_f32_dpp v175, v175, v175 quad_perm:[2,3,0,1] row_mask:0xf bank_mask:0xf bound_ctrl:1
	v_fmac_f32_e32 v172, v242, v18
	v_add_f32_dpp v174, v174, v174 row_half_mirror row_mask:0xf bank_mask:0xf bound_ctrl:1
	v_add_f32_dpp v175, v175, v175 row_half_mirror row_mask:0xf bank_mask:0xf bound_ctrl:1
	v_fmac_f32_e32 v173, v242, v19
	v_add_f32_dpp v174, v174, v174 row_mirror row_mask:0xf bank_mask:0xf bound_ctrl:1
	v_fmac_f32_e32 v170, v174, v12
	v_fmac_f32_e32 v171, v174, v13
	v_fmac_f32_e32 v172, v174, v14
	v_fmac_f32_e32 v173, v174, v15
	ds_read_b128 v[8:11], v142 offset:13568
	ds_read_b128 v[12:15], v142 offset:21760
	ds_read_b128 v[16:19], v142 offset:29952
	ds_read_b128 v[20:23], v142 offset:38144
	s_waitcnt lgkmcnt(10)
	v_mul_f32_e32 v174, v170, v28
	v_mul_f32_e32 v238, v170, v40
	v_fmac_f32_e32 v174, v171, v29
	v_fmac_f32_e32 v238, v171, v41
	v_fmac_f32_e32 v174, v172, v30
	v_fmac_f32_e32 v238, v172, v42
	v_fmac_f32_e32 v174, v173, v31
	v_fmac_f32_e32 v238, v173, v43
	v_fmac_f32_e32 v170, v243, v36
	v_add_f32_dpp v174, v174, v174 quad_perm:[1,0,3,2] row_mask:0xf bank_mask:0xf bound_ctrl:1
	v_add_f32_dpp v238, v238, v238 quad_perm:[1,0,3,2] row_mask:0xf bank_mask:0xf bound_ctrl:1
	v_fmac_f32_e32 v171, v243, v37
	v_add_f32_dpp v174, v174, v174 quad_perm:[2,3,0,1] row_mask:0xf bank_mask:0xf bound_ctrl:1
	v_add_f32_dpp v238, v238, v238 quad_perm:[2,3,0,1] row_mask:0xf bank_mask:0xf bound_ctrl:1
	v_fmac_f32_e32 v172, v243, v38
	v_add_f32_dpp v174, v174, v174 row_half_mirror row_mask:0xf bank_mask:0xf bound_ctrl:1
	v_add_f32_dpp v238, v238, v238 row_half_mirror row_mask:0xf bank_mask:0xf bound_ctrl:1
	v_fmac_f32_e32 v173, v243, v39
	v_add_f32_dpp v174, v174, v174 row_mirror row_mask:0xf bank_mask:0xf bound_ctrl:1
	v_fmac_f32_e32 v170, v174, v32
	v_fmac_f32_e32 v171, v174, v33
	v_fmac_f32_e32 v172, v174, v34
	v_fmac_f32_e32 v173, v174, v35
	s_mov_b64 exec, s[6:7]
	ds_write2st64_b32 v149, v175, v238 offset0:36 offset1:38
	s_mov_b64 exec, -1
	ds_read_b128 v[28:31], v142 offset:13824
	ds_read_b128 v[32:35], v142 offset:22016
	ds_read_b128 v[36:39], v142 offset:30208
	ds_read_b128 v[40:43], v142 offset:38400
	ds_read2st64_b32 v[242:243], v148 offset0:214 offset1:215
	s_waitcnt lgkmcnt(10)
	v_mul_f32_e32 v174, v170, v48
	v_mul_f32_e32 v175, v170, v60
	v_fmac_f32_e32 v174, v171, v49
	v_fmac_f32_e32 v175, v171, v61
	v_fmac_f32_e32 v174, v172, v50
	v_fmac_f32_e32 v175, v172, v62
	v_fmac_f32_e32 v174, v173, v51
	v_fmac_f32_e32 v175, v173, v63
	v_fmac_f32_e32 v170, v240, v56
	v_add_f32_dpp v174, v174, v174 quad_perm:[1,0,3,2] row_mask:0xf bank_mask:0xf bound_ctrl:1
	v_add_f32_dpp v175, v175, v175 quad_perm:[1,0,3,2] row_mask:0xf bank_mask:0xf bound_ctrl:1
	v_fmac_f32_e32 v171, v240, v57
	v_add_f32_dpp v174, v174, v174 quad_perm:[2,3,0,1] row_mask:0xf bank_mask:0xf bound_ctrl:1
	v_add_f32_dpp v175, v175, v175 quad_perm:[2,3,0,1] row_mask:0xf bank_mask:0xf bound_ctrl:1
	v_fmac_f32_e32 v172, v240, v58
	v_add_f32_dpp v174, v174, v174 row_half_mirror row_mask:0xf bank_mask:0xf bound_ctrl:1
	v_add_f32_dpp v175, v175, v175 row_half_mirror row_mask:0xf bank_mask:0xf bound_ctrl:1
	v_fmac_f32_e32 v173, v240, v59
	v_add_f32_dpp v174, v174, v174 row_mirror row_mask:0xf bank_mask:0xf bound_ctrl:1
	v_fmac_f32_e32 v170, v174, v52
	v_fmac_f32_e32 v171, v174, v53
	v_fmac_f32_e32 v172, v174, v54
	v_fmac_f32_e32 v173, v174, v55
	ds_read_b128 v[48:51], v142 offset:14080
	ds_read_b128 v[52:55], v142 offset:22272
	ds_read_b128 v[56:59], v142 offset:30464
	ds_read_b128 v[60:63], v142 offset:38656
	s_waitcnt lgkmcnt(10)
	v_mul_f32_e32 v174, v170, v8
	v_mul_f32_e32 v238, v170, v20
	v_fmac_f32_e32 v174, v171, v9
	v_fmac_f32_e32 v238, v171, v21
	v_fmac_f32_e32 v174, v172, v10
	v_fmac_f32_e32 v238, v172, v22
	v_fmac_f32_e32 v174, v173, v11
	v_fmac_f32_e32 v238, v173, v23
	v_fmac_f32_e32 v170, v241, v16
	v_add_f32_dpp v174, v174, v174 quad_perm:[1,0,3,2] row_mask:0xf bank_mask:0xf bound_ctrl:1
	v_add_f32_dpp v238, v238, v238 quad_perm:[1,0,3,2] row_mask:0xf bank_mask:0xf bound_ctrl:1
	v_fmac_f32_e32 v171, v241, v17
	v_add_f32_dpp v174, v174, v174 quad_perm:[2,3,0,1] row_mask:0xf bank_mask:0xf bound_ctrl:1
	v_add_f32_dpp v238, v238, v238 quad_perm:[2,3,0,1] row_mask:0xf bank_mask:0xf bound_ctrl:1
	v_fmac_f32_e32 v172, v241, v18
	v_add_f32_dpp v174, v174, v174 row_half_mirror row_mask:0xf bank_mask:0xf bound_ctrl:1
	v_add_f32_dpp v238, v238, v238 row_half_mirror row_mask:0xf bank_mask:0xf bound_ctrl:1
	v_fmac_f32_e32 v173, v241, v19
	v_add_f32_dpp v174, v174, v174 row_mirror row_mask:0xf bank_mask:0xf bound_ctrl:1
	v_fmac_f32_e32 v170, v174, v12
	v_fmac_f32_e32 v171, v174, v13
	v_fmac_f32_e32 v172, v174, v14
	v_fmac_f32_e32 v173, v174, v15
	s_mov_b64 exec, s[6:7]
	ds_write2st64_b32 v149, v175, v238 offset0:40 offset1:42
	s_mov_b64 exec, -1
	ds_read_b128 v[8:11], v142 offset:14336
	ds_read_b128 v[12:15], v142 offset:22528
	ds_read_b128 v[16:19], v142 offset:30720
	ds_read_b128 v[20:23], v142 offset:38912
	ds_read2st64_b32 v[240:241], v148 offset0:216 offset1:217
	s_waitcnt lgkmcnt(10)
	v_mul_f32_e32 v174, v170, v28
	v_mul_f32_e32 v175, v170, v40
	v_fmac_f32_e32 v174, v171, v29
	v_fmac_f32_e32 v175, v171, v41
	v_fmac_f32_e32 v174, v172, v30
	v_fmac_f32_e32 v175, v172, v42
	v_fmac_f32_e32 v174, v173, v31
	v_fmac_f32_e32 v175, v173, v43
	v_fmac_f32_e32 v170, v242, v36
	v_add_f32_dpp v174, v174, v174 quad_perm:[1,0,3,2] row_mask:0xf bank_mask:0xf bound_ctrl:1
	v_add_f32_dpp v175, v175, v175 quad_perm:[1,0,3,2] row_mask:0xf bank_mask:0xf bound_ctrl:1
	v_fmac_f32_e32 v171, v242, v37
	v_add_f32_dpp v174, v174, v174 quad_perm:[2,3,0,1] row_mask:0xf bank_mask:0xf bound_ctrl:1
	v_add_f32_dpp v175, v175, v175 quad_perm:[2,3,0,1] row_mask:0xf bank_mask:0xf bound_ctrl:1
	v_fmac_f32_e32 v172, v242, v38
	v_add_f32_dpp v174, v174, v174 row_half_mirror row_mask:0xf bank_mask:0xf bound_ctrl:1
	v_add_f32_dpp v175, v175, v175 row_half_mirror row_mask:0xf bank_mask:0xf bound_ctrl:1
	v_fmac_f32_e32 v173, v242, v39
	v_add_f32_dpp v174, v174, v174 row_mirror row_mask:0xf bank_mask:0xf bound_ctrl:1
	v_fmac_f32_e32 v170, v174, v32
	v_fmac_f32_e32 v171, v174, v33
	v_fmac_f32_e32 v172, v174, v34
	v_fmac_f32_e32 v173, v174, v35
	ds_read_b128 v[28:31], v142 offset:14592
	ds_read_b128 v[32:35], v142 offset:22784
	ds_read_b128 v[36:39], v142 offset:30976
	ds_read_b128 v[40:43], v142 offset:39168
	s_waitcnt lgkmcnt(10)
	v_mul_f32_e32 v174, v170, v48
	v_mul_f32_e32 v238, v170, v60
	v_fmac_f32_e32 v174, v171, v49
	v_fmac_f32_e32 v238, v171, v61
	v_fmac_f32_e32 v174, v172, v50
	v_fmac_f32_e32 v238, v172, v62
	v_fmac_f32_e32 v174, v173, v51
	v_fmac_f32_e32 v238, v173, v63
	v_fmac_f32_e32 v170, v243, v56
	v_add_f32_dpp v174, v174, v174 quad_perm:[1,0,3,2] row_mask:0xf bank_mask:0xf bound_ctrl:1
	v_add_f32_dpp v238, v238, v238 quad_perm:[1,0,3,2] row_mask:0xf bank_mask:0xf bound_ctrl:1
	v_fmac_f32_e32 v171, v243, v57
	v_add_f32_dpp v174, v174, v174 quad_perm:[2,3,0,1] row_mask:0xf bank_mask:0xf bound_ctrl:1
	v_add_f32_dpp v238, v238, v238 quad_perm:[2,3,0,1] row_mask:0xf bank_mask:0xf bound_ctrl:1
	v_fmac_f32_e32 v172, v243, v58
	v_add_f32_dpp v174, v174, v174 row_half_mirror row_mask:0xf bank_mask:0xf bound_ctrl:1
	v_add_f32_dpp v238, v238, v238 row_half_mirror row_mask:0xf bank_mask:0xf bound_ctrl:1
	v_fmac_f32_e32 v173, v243, v59
	v_add_f32_dpp v174, v174, v174 row_mirror row_mask:0xf bank_mask:0xf bound_ctrl:1
	v_fmac_f32_e32 v170, v174, v52
	v_fmac_f32_e32 v171, v174, v53
	v_fmac_f32_e32 v172, v174, v54
	v_fmac_f32_e32 v173, v174, v55
	s_mov_b64 exec, s[6:7]
	ds_write2st64_b32 v149, v175, v238 offset0:44 offset1:46
	s_mov_b64 exec, -1
	ds_read_b128 v[48:51], v142 offset:14848
	ds_read_b128 v[52:55], v142 offset:23040
	ds_read_b128 v[56:59], v142 offset:31232
	ds_read_b128 v[60:63], v142 offset:39424
	ds_read2st64_b32 v[242:243], v148 offset0:218 offset1:219
	s_waitcnt lgkmcnt(10)
	v_mul_f32_e32 v174, v170, v8
	v_mul_f32_e32 v175, v170, v20
	v_fmac_f32_e32 v174, v171, v9
	v_fmac_f32_e32 v175, v171, v21
	v_fmac_f32_e32 v174, v172, v10
	v_fmac_f32_e32 v175, v172, v22
	v_fmac_f32_e32 v174, v173, v11
	v_fmac_f32_e32 v175, v173, v23
	v_fmac_f32_e32 v170, v240, v16
	v_add_f32_dpp v174, v174, v174 quad_perm:[1,0,3,2] row_mask:0xf bank_mask:0xf bound_ctrl:1
	v_add_f32_dpp v175, v175, v175 quad_perm:[1,0,3,2] row_mask:0xf bank_mask:0xf bound_ctrl:1
	v_fmac_f32_e32 v171, v240, v17
	v_add_f32_dpp v174, v174, v174 quad_perm:[2,3,0,1] row_mask:0xf bank_mask:0xf bound_ctrl:1
	v_add_f32_dpp v175, v175, v175 quad_perm:[2,3,0,1] row_mask:0xf bank_mask:0xf bound_ctrl:1
	v_fmac_f32_e32 v172, v240, v18
	v_add_f32_dpp v174, v174, v174 row_half_mirror row_mask:0xf bank_mask:0xf bound_ctrl:1
	v_add_f32_dpp v175, v175, v175 row_half_mirror row_mask:0xf bank_mask:0xf bound_ctrl:1
	v_fmac_f32_e32 v173, v240, v19
	v_add_f32_dpp v174, v174, v174 row_mirror row_mask:0xf bank_mask:0xf bound_ctrl:1
	v_fmac_f32_e32 v170, v174, v12
	v_fmac_f32_e32 v171, v174, v13
	v_fmac_f32_e32 v172, v174, v14
	v_fmac_f32_e32 v173, v174, v15
	ds_read_b128 v[8:11], v142 offset:15104
	ds_read_b128 v[12:15], v142 offset:23296
	ds_read_b128 v[16:19], v142 offset:31488
	ds_read_b128 v[20:23], v142 offset:39680
	s_waitcnt lgkmcnt(10)
	v_mul_f32_e32 v174, v170, v28
	v_mul_f32_e32 v238, v170, v40
	v_fmac_f32_e32 v174, v171, v29
	v_fmac_f32_e32 v238, v171, v41
	v_fmac_f32_e32 v174, v172, v30
	v_fmac_f32_e32 v238, v172, v42
	v_fmac_f32_e32 v174, v173, v31
	v_fmac_f32_e32 v238, v173, v43
	v_fmac_f32_e32 v170, v241, v36
	v_add_f32_dpp v174, v174, v174 quad_perm:[1,0,3,2] row_mask:0xf bank_mask:0xf bound_ctrl:1
	v_add_f32_dpp v238, v238, v238 quad_perm:[1,0,3,2] row_mask:0xf bank_mask:0xf bound_ctrl:1
	v_fmac_f32_e32 v171, v241, v37
	v_add_f32_dpp v174, v174, v174 quad_perm:[2,3,0,1] row_mask:0xf bank_mask:0xf bound_ctrl:1
	v_add_f32_dpp v238, v238, v238 quad_perm:[2,3,0,1] row_mask:0xf bank_mask:0xf bound_ctrl:1
	v_fmac_f32_e32 v172, v241, v38
	v_add_f32_dpp v174, v174, v174 row_half_mirror row_mask:0xf bank_mask:0xf bound_ctrl:1
	v_add_f32_dpp v238, v238, v238 row_half_mirror row_mask:0xf bank_mask:0xf bound_ctrl:1
	v_fmac_f32_e32 v173, v241, v39
	v_add_f32_dpp v174, v174, v174 row_mirror row_mask:0xf bank_mask:0xf bound_ctrl:1
	v_fmac_f32_e32 v170, v174, v32
	v_fmac_f32_e32 v171, v174, v33
	v_fmac_f32_e32 v172, v174, v34
	v_fmac_f32_e32 v173, v174, v35
	s_mov_b64 exec, s[6:7]
	ds_write2st64_b32 v149, v175, v238 offset0:48 offset1:50
	s_mov_b64 exec, -1
	ds_read_b128 v[28:31], v142 offset:15360
	ds_read_b128 v[32:35], v142 offset:23552
	ds_read_b128 v[36:39], v142 offset:31744
	ds_read_b128 v[40:43], v142 offset:39936
	ds_read2st64_b32 v[240:241], v148 offset0:220 offset1:221
	s_waitcnt lgkmcnt(10)
	v_mul_f32_e32 v174, v170, v48
	v_mul_f32_e32 v175, v170, v60
	v_fmac_f32_e32 v174, v171, v49
	v_fmac_f32_e32 v175, v171, v61
	v_fmac_f32_e32 v174, v172, v50
	v_fmac_f32_e32 v175, v172, v62
	v_fmac_f32_e32 v174, v173, v51
	v_fmac_f32_e32 v175, v173, v63
	v_fmac_f32_e32 v170, v242, v56
	v_add_f32_dpp v174, v174, v174 quad_perm:[1,0,3,2] row_mask:0xf bank_mask:0xf bound_ctrl:1
	v_add_f32_dpp v175, v175, v175 quad_perm:[1,0,3,2] row_mask:0xf bank_mask:0xf bound_ctrl:1
	v_fmac_f32_e32 v171, v242, v57
	v_add_f32_dpp v174, v174, v174 quad_perm:[2,3,0,1] row_mask:0xf bank_mask:0xf bound_ctrl:1
	v_add_f32_dpp v175, v175, v175 quad_perm:[2,3,0,1] row_mask:0xf bank_mask:0xf bound_ctrl:1
	v_fmac_f32_e32 v172, v242, v58
	v_add_f32_dpp v174, v174, v174 row_half_mirror row_mask:0xf bank_mask:0xf bound_ctrl:1
	v_add_f32_dpp v175, v175, v175 row_half_mirror row_mask:0xf bank_mask:0xf bound_ctrl:1
	v_fmac_f32_e32 v173, v242, v59
	v_add_f32_dpp v174, v174, v174 row_mirror row_mask:0xf bank_mask:0xf bound_ctrl:1
	v_fmac_f32_e32 v170, v174, v52
	v_fmac_f32_e32 v171, v174, v53
	v_fmac_f32_e32 v172, v174, v54
	v_fmac_f32_e32 v173, v174, v55
	ds_read_b128 v[48:51], v142 offset:15616
	ds_read_b128 v[52:55], v142 offset:23808
	ds_read_b128 v[56:59], v142 offset:32000
	ds_read_b128 v[60:63], v142 offset:40192
	s_waitcnt lgkmcnt(10)
	v_mul_f32_e32 v174, v170, v8
	v_mul_f32_e32 v238, v170, v20
	v_fmac_f32_e32 v174, v171, v9
	v_fmac_f32_e32 v238, v171, v21
	v_fmac_f32_e32 v174, v172, v10
	v_fmac_f32_e32 v238, v172, v22
	v_fmac_f32_e32 v174, v173, v11
	v_fmac_f32_e32 v238, v173, v23
	v_fmac_f32_e32 v170, v243, v16
	v_add_f32_dpp v174, v174, v174 quad_perm:[1,0,3,2] row_mask:0xf bank_mask:0xf bound_ctrl:1
	v_add_f32_dpp v238, v238, v238 quad_perm:[1,0,3,2] row_mask:0xf bank_mask:0xf bound_ctrl:1
	v_fmac_f32_e32 v171, v243, v17
	v_add_f32_dpp v174, v174, v174 quad_perm:[2,3,0,1] row_mask:0xf bank_mask:0xf bound_ctrl:1
	v_add_f32_dpp v238, v238, v238 quad_perm:[2,3,0,1] row_mask:0xf bank_mask:0xf bound_ctrl:1
	v_fmac_f32_e32 v172, v243, v18
	v_add_f32_dpp v174, v174, v174 row_half_mirror row_mask:0xf bank_mask:0xf bound_ctrl:1
	v_add_f32_dpp v238, v238, v238 row_half_mirror row_mask:0xf bank_mask:0xf bound_ctrl:1
	v_fmac_f32_e32 v173, v243, v19
	v_add_f32_dpp v174, v174, v174 row_mirror row_mask:0xf bank_mask:0xf bound_ctrl:1
	v_fmac_f32_e32 v170, v174, v12
	v_fmac_f32_e32 v171, v174, v13
	v_fmac_f32_e32 v172, v174, v14
	v_fmac_f32_e32 v173, v174, v15
	s_mov_b64 exec, s[6:7]
	ds_write2st64_b32 v149, v175, v238 offset0:52 offset1:54
	s_mov_b64 exec, -1
	ds_read_b128 v[8:11], v142 offset:15872
	ds_read_b128 v[12:15], v142 offset:24064
	ds_read_b128 v[16:19], v142 offset:32256
	ds_read_b128 v[20:23], v142 offset:40448
	ds_read2st64_b32 v[242:243], v148 offset0:222 offset1:223
	s_waitcnt lgkmcnt(10)
	v_mul_f32_e32 v174, v170, v28
	v_mul_f32_e32 v175, v170, v40
	v_fmac_f32_e32 v174, v171, v29
	v_fmac_f32_e32 v175, v171, v41
	v_fmac_f32_e32 v174, v172, v30
	v_fmac_f32_e32 v175, v172, v42
	v_fmac_f32_e32 v174, v173, v31
	v_fmac_f32_e32 v175, v173, v43
	v_fmac_f32_e32 v170, v240, v36
	v_add_f32_dpp v174, v174, v174 quad_perm:[1,0,3,2] row_mask:0xf bank_mask:0xf bound_ctrl:1
	v_add_f32_dpp v175, v175, v175 quad_perm:[1,0,3,2] row_mask:0xf bank_mask:0xf bound_ctrl:1
	v_fmac_f32_e32 v171, v240, v37
	v_add_f32_dpp v174, v174, v174 quad_perm:[2,3,0,1] row_mask:0xf bank_mask:0xf bound_ctrl:1
	v_add_f32_dpp v175, v175, v175 quad_perm:[2,3,0,1] row_mask:0xf bank_mask:0xf bound_ctrl:1
	v_fmac_f32_e32 v172, v240, v38
	v_add_f32_dpp v174, v174, v174 row_half_mirror row_mask:0xf bank_mask:0xf bound_ctrl:1
	v_add_f32_dpp v175, v175, v175 row_half_mirror row_mask:0xf bank_mask:0xf bound_ctrl:1
	v_fmac_f32_e32 v173, v240, v39
	v_add_f32_dpp v174, v174, v174 row_mirror row_mask:0xf bank_mask:0xf bound_ctrl:1
	v_fmac_f32_e32 v170, v174, v32
	v_fmac_f32_e32 v171, v174, v33
	v_fmac_f32_e32 v172, v174, v34
	v_fmac_f32_e32 v173, v174, v35
	ds_read_b128 v[28:31], v142 offset:16128
	ds_read_b128 v[32:35], v142 offset:24320
	ds_read_b128 v[36:39], v142 offset:32512
	ds_read_b128 v[40:43], v142 offset:40704
	s_waitcnt lgkmcnt(10)
	v_mul_f32_e32 v174, v170, v48
	v_mul_f32_e32 v238, v170, v60
	v_fmac_f32_e32 v174, v171, v49
	v_fmac_f32_e32 v238, v171, v61
	v_fmac_f32_e32 v174, v172, v50
	v_fmac_f32_e32 v238, v172, v62
	v_fmac_f32_e32 v174, v173, v51
	v_fmac_f32_e32 v238, v173, v63
	v_fmac_f32_e32 v170, v241, v56
	v_add_f32_dpp v174, v174, v174 quad_perm:[1,0,3,2] row_mask:0xf bank_mask:0xf bound_ctrl:1
	v_add_f32_dpp v238, v238, v238 quad_perm:[1,0,3,2] row_mask:0xf bank_mask:0xf bound_ctrl:1
	v_fmac_f32_e32 v171, v241, v57
	v_add_f32_dpp v174, v174, v174 quad_perm:[2,3,0,1] row_mask:0xf bank_mask:0xf bound_ctrl:1
	v_add_f32_dpp v238, v238, v238 quad_perm:[2,3,0,1] row_mask:0xf bank_mask:0xf bound_ctrl:1
	v_fmac_f32_e32 v172, v241, v58
	v_add_f32_dpp v174, v174, v174 row_half_mirror row_mask:0xf bank_mask:0xf bound_ctrl:1
	v_add_f32_dpp v238, v238, v238 row_half_mirror row_mask:0xf bank_mask:0xf bound_ctrl:1
	v_fmac_f32_e32 v173, v241, v59
	v_add_f32_dpp v174, v174, v174 row_mirror row_mask:0xf bank_mask:0xf bound_ctrl:1
	v_fmac_f32_e32 v170, v174, v52
	v_fmac_f32_e32 v171, v174, v53
	v_fmac_f32_e32 v172, v174, v54
	v_fmac_f32_e32 v173, v174, v55
	s_mov_b64 exec, s[6:7]
	ds_write2st64_b32 v149, v175, v238 offset0:56 offset1:58
	s_mov_b64 exec, -1
	s_waitcnt lgkmcnt(5)
	v_mul_f32_e32 v174, v170, v8
	v_mul_f32_e32 v175, v170, v20
	v_fmac_f32_e32 v174, v171, v9
	v_fmac_f32_e32 v175, v171, v21
	v_fmac_f32_e32 v174, v172, v10
	v_fmac_f32_e32 v175, v172, v22
	v_fmac_f32_e32 v174, v173, v11
	v_fmac_f32_e32 v175, v173, v23
	v_fmac_f32_e32 v170, v242, v16
	v_add_f32_dpp v174, v174, v174 quad_perm:[1,0,3,2] row_mask:0xf bank_mask:0xf bound_ctrl:1
	v_add_f32_dpp v175, v175, v175 quad_perm:[1,0,3,2] row_mask:0xf bank_mask:0xf bound_ctrl:1
	v_fmac_f32_e32 v171, v242, v17
	v_add_f32_dpp v174, v174, v174 quad_perm:[2,3,0,1] row_mask:0xf bank_mask:0xf bound_ctrl:1
	v_add_f32_dpp v175, v175, v175 quad_perm:[2,3,0,1] row_mask:0xf bank_mask:0xf bound_ctrl:1
	v_fmac_f32_e32 v172, v242, v18
	v_add_f32_dpp v174, v174, v174 row_half_mirror row_mask:0xf bank_mask:0xf bound_ctrl:1
	v_add_f32_dpp v175, v175, v175 row_half_mirror row_mask:0xf bank_mask:0xf bound_ctrl:1
	v_fmac_f32_e32 v173, v242, v19
	v_add_f32_dpp v174, v174, v174 row_mirror row_mask:0xf bank_mask:0xf bound_ctrl:1
	v_fmac_f32_e32 v170, v174, v12
	v_fmac_f32_e32 v171, v174, v13
	v_fmac_f32_e32 v172, v174, v14
	v_fmac_f32_e32 v173, v174, v15
	s_waitcnt lgkmcnt(1)
	v_mul_f32_e32 v174, v170, v28
	v_mul_f32_e32 v238, v170, v40
	v_fmac_f32_e32 v174, v171, v29
	v_fmac_f32_e32 v238, v171, v41
	v_fmac_f32_e32 v174, v172, v30
	v_fmac_f32_e32 v238, v172, v42
	v_fmac_f32_e32 v174, v173, v31
	v_fmac_f32_e32 v238, v173, v43
	v_fmac_f32_e32 v170, v243, v36
	v_add_f32_dpp v174, v174, v174 quad_perm:[1,0,3,2] row_mask:0xf bank_mask:0xf bound_ctrl:1
	v_add_f32_dpp v238, v238, v238 quad_perm:[1,0,3,2] row_mask:0xf bank_mask:0xf bound_ctrl:1
	v_fmac_f32_e32 v171, v243, v37
	v_add_f32_dpp v174, v174, v174 quad_perm:[2,3,0,1] row_mask:0xf bank_mask:0xf bound_ctrl:1
	v_add_f32_dpp v238, v238, v238 quad_perm:[2,3,0,1] row_mask:0xf bank_mask:0xf bound_ctrl:1
	v_fmac_f32_e32 v172, v243, v38
	v_add_f32_dpp v174, v174, v174 row_half_mirror row_mask:0xf bank_mask:0xf bound_ctrl:1
	v_add_f32_dpp v238, v238, v238 row_half_mirror row_mask:0xf bank_mask:0xf bound_ctrl:1
	v_fmac_f32_e32 v173, v243, v39
	v_add_f32_dpp v174, v174, v174 row_mirror row_mask:0xf bank_mask:0xf bound_ctrl:1
	v_fmac_f32_e32 v170, v174, v32
	v_fmac_f32_e32 v171, v174, v33
	v_fmac_f32_e32 v172, v174, v34
	v_fmac_f32_e32 v173, v174, v35
	s_mov_b64 exec, s[6:7]
	ds_write2st64_b32 v149, v175, v238 offset0:60 offset1:62
	s_mov_b64 exec, -1
	ds_read_b128 v[4:7], v142 offset:65280
	s_waitcnt lgkmcnt(0)
	v_mul_f32_e32 v170, v170, v4
	v_mul_f32_e32 v171, v171, v5
	v_mul_f32_e32 v172, v172, v6
	v_mul_f32_e32 v173, v173, v7
	s_waitcnt lgkmcnt(0)
	s_barrier
	s_and_saveexec_b64 s[10:11], s[8:9]
	s_cbranch_execz .LBB0_349
	ds_read_b128 v[4:7], v150
	ds_read_b128 v[8:11], v150 offset:256
	s_waitcnt lgkmcnt(0)
	v_pk_add_f32 v[10:11], v[6:7], v[10:11]
	v_pk_add_f32 v[8:9], v[4:5], v[8:9]
	ds_read_b128 v[4:7], v147
	s_waitcnt lgkmcnt(0)
	v_pk_add_f32 v[6:7], v[10:11], v[6:7]
	v_pk_add_f32 v[4:5], v[8:9], v[4:5]
	s_nop 0
	v_cvt_pk_bf16_f32 v4, v4, v5
	v_cvt_pk_bf16_f32 v5, v6, v7
	v_lshlrev_b64 v[6:7], 11, v[120:121]
	v_lshl_add_u64 v[6:7], v[102:103], 0, v[6:7]
	global_store_dwordx2 v[6:7], v[4:5], off
	s_branch .LBB0_349
